# nt hint on wide stores of all seam-crossing tensors (second measurement)
# baseline (speedup 1.0000x reference)
.LBB7_24:
	s_mul_hi_i32 s14, s49, 0x2e8ba2e9
	s_lshr_b32 s15, s14, 31
	s_ashr_i32 s14, s14, 4
	s_add_i32 s14, s14, s15
	s_mul_i32 s15, s14, 0x58
	s_sub_i32 s15, s49, s15
	s_bfe_i32 s50, s15, 0x80000
	s_lshl_b32 s48, s15, 5
	s_bfe_u32 s50, s50, 0x2000d
	ds_write2_b32 v77, v43, v42 offset1:66
	ds_write2_b32 v77, v45, v44 offset0:132 offset1:198
	ds_write2_b32 v32, v47, v46 offset0:8 offset1:74
	ds_write2_b32 v32, v49, v48 offset0:140 offset1:206
	ds_write2_b32 v35, v51, v50 offset0:16 offset1:82
	ds_write2_b32 v35, v53, v52 offset0:148 offset1:214
	ds_write2_b32 v37, v55, v54 offset0:24 offset1:90
	ds_write2_b32 v37, v57, v56 offset0:156 offset1:222
	ds_write2_b32 v84, v59, v58 offset0:32 offset1:98
	ds_write2_b32 v84, v61, v60 offset0:164 offset1:230
	ds_write2_b32 v85, v63, v62 offset0:40 offset1:106
	ds_write2_b32 v85, v65, v64 offset0:172 offset1:238
	ds_write2_b32 v86, v67, v66 offset0:48 offset1:114
	ds_write2_b32 v86, v69, v68 offset0:180 offset1:246
	ds_write2_b32 v87, v71, v70 offset0:56 offset1:122
	ds_write2_b32 v87, v73, v72 offset0:188 offset1:254
	s_add_i32 s15, s15, s50
	s_sext_i32_i16 s50, s48
	s_waitcnt lgkmcnt(0)
	s_bfe_u32 s50, s50, 0x70018
	s_bfe_i32 s15, s15, 0x80000
	s_add_i32 s50, s48, s50
	ds_read2_b32 v[74:75], v79 offset1:33
	s_sext_i32_i16 s15, s15
	s_and_b32 s50, s50, 0xff80
	s_waitcnt lgkmcnt(0)
	v_cvt_pk_bf16_f32 v84, v74, v75
	ds_read2_b32 v[74:75], v79 offset0:66 offset1:99
	s_lshl_b32 s15, s15, 6
	s_sub_i32 s48, s48, s50
	s_and_b32 s15, s15, 0xffffff00
	s_waitcnt lgkmcnt(0)
	v_cvt_pk_bf16_f32 v85, v74, v75
	ds_read2_b32 v[74:75], v79 offset0:132 offset1:165
	s_sext_i32_i16 s48, s48
	s_waitcnt lgkmcnt(0)
	v_cvt_pk_bf16_f32 v86, v74, v75
	ds_read2_b32 v[74:75], v79 offset0:198 offset1:231
	s_add_i32 s50, s15, s48
	s_lshl_b32 s14, s14, 6
	s_waitcnt lgkmcnt(0)
	v_cvt_pk_bf16_f32 v87, v74, v75
	v_or_b32_e32 v74, s50, v78
	s_ashr_i32 s15, s14, 31
	v_ashrrev_i32_e32 v75, 31, v74
	v_lshl_add_u64 v[88:89], s[14:15], 1, v[40:41]
	v_lshlrev_b64 v[74:75], 11, v[74:75]
	v_lshl_add_u64 v[74:75], v[88:89], 0, v[74:75]
	ds_read2_b32 v[90:91], v79 offset0:8 offset1:41
	global_store_dwordx4 v[74:75], v[84:87], off nt
	s_add_i32 s48, s49, s72
	s_cmpk_gt_i32 s48, 0x57f
	s_waitcnt lgkmcnt(0)
	v_cvt_pk_bf16_f32 v84, v90, v91
	ds_read2_b32 v[74:75], v79 offset0:74 offset1:107
	s_waitcnt lgkmcnt(0)
	v_cvt_pk_bf16_f32 v85, v74, v75
	ds_read2_b32 v[74:75], v79 offset0:140 offset1:173
	s_waitcnt lgkmcnt(0)
	v_cvt_pk_bf16_f32 v86, v74, v75
	ds_read2_b32 v[74:75], v79 offset0:206 offset1:239
	s_waitcnt lgkmcnt(0)
	v_cvt_pk_bf16_f32 v87, v74, v75
	v_or_b32_e32 v74, s50, v80
	v_ashrrev_i32_e32 v75, 31, v74
	v_lshlrev_b64 v[74:75], 11, v[74:75]
	v_lshl_add_u64 v[74:75], v[88:89], 0, v[74:75]
	ds_read2_b32 v[90:91], v79 offset0:16 offset1:49
	global_store_dwordx4 v[74:75], v[84:87], off nt
	s_cselect_b64 s[14:15], -1, 0
	s_waitcnt lgkmcnt(0)
	v_cvt_pk_bf16_f32 v84, v90, v91
	ds_read2_b32 v[74:75], v79 offset0:82 offset1:115
	s_waitcnt lgkmcnt(0)
	v_cvt_pk_bf16_f32 v85, v74, v75
	ds_read2_b32 v[74:75], v79 offset0:148 offset1:181
	s_waitcnt lgkmcnt(0)
	v_cvt_pk_bf16_f32 v86, v74, v75
	ds_read2_b32 v[74:75], v79 offset0:214 offset1:247
	s_waitcnt lgkmcnt(0)
	v_cvt_pk_bf16_f32 v87, v74, v75
	v_or_b32_e32 v74, s50, v81
	v_ashrrev_i32_e32 v75, 31, v74
	v_lshlrev_b64 v[74:75], 11, v[74:75]
	v_lshl_add_u64 v[74:75], v[88:89], 0, v[74:75]
	ds_read2_b32 v[90:91], v79 offset0:24 offset1:57
	global_store_dwordx4 v[74:75], v[84:87], off nt
	s_waitcnt lgkmcnt(0)
	s_nop 0
	v_cvt_pk_bf16_f32 v84, v90, v91
	ds_read2_b32 v[74:75], v79 offset0:90 offset1:123
	s_waitcnt lgkmcnt(0)
	v_cvt_pk_bf16_f32 v85, v74, v75
	ds_read2_b32 v[74:75], v79 offset0:156 offset1:189
	s_waitcnt lgkmcnt(0)
	v_cvt_pk_bf16_f32 v86, v74, v75
	ds_read2_b32 v[74:75], v79 offset0:222 offset1:255
	s_waitcnt lgkmcnt(0)
	v_cvt_pk_bf16_f32 v87, v74, v75
	v_or_b32_e32 v74, s50, v82
	v_ashrrev_i32_e32 v75, 31, v74
	v_lshlrev_b64 v[74:75], 11, v[74:75]
	v_lshl_add_u64 v[74:75], v[88:89], 0, v[74:75]
	global_store_dwordx4 v[74:75], v[84:87], off nt
	s_waitcnt lgkmcnt(0)

.LBB7_29:
	s_mul_hi_i32 s50, s48, 0x2e8ba2e9
	s_lshr_b32 s51, s50, 31
	s_ashr_i32 s50, s50, 4
	s_add_i32 s50, s50, s51
	s_mul_i32 s51, s50, 0x58
	s_sub_i32 s51, s48, s51
	s_bfe_i32 s65, s51, 0x80000
	s_lshl_b32 s64, s51, 5
	v_add_u32_e32 v32, 0x400, v77
	v_add_u32_e32 v35, 0x800, v77
	v_add_u32_e32 v37, 0xc00, v77
	v_add_u32_e32 v84, 0x1000, v77
	v_add_u32_e32 v85, 0x1400, v77
	v_add_u32_e32 v86, 0x1800, v77
	v_add_u32_e32 v87, 0x1c00, v77
	s_bfe_u32 s65, s65, 0x2000d
	s_waitcnt vmcnt(30)
	ds_write2_b32 v77, v0, v1 offset1:66
	s_waitcnt vmcnt(28)
	ds_write2_b32 v77, v2, v3 offset0:132 offset1:198
	s_waitcnt vmcnt(26)
	ds_write2_b32 v32, v4, v5 offset0:8 offset1:74
	s_waitcnt vmcnt(24)
	ds_write2_b32 v32, v6, v7 offset0:140 offset1:206
	s_waitcnt vmcnt(22)
	ds_write2_b32 v35, v8, v9 offset0:16 offset1:82
	s_waitcnt vmcnt(20)
	ds_write2_b32 v35, v10, v11 offset0:148 offset1:214
	s_waitcnt vmcnt(18)
	ds_write2_b32 v37, v12, v13 offset0:24 offset1:90
	s_waitcnt vmcnt(16)
	ds_write2_b32 v37, v14, v15 offset0:156 offset1:222
	s_waitcnt vmcnt(14)
	ds_write2_b32 v84, v16, v17 offset0:32 offset1:98
	s_waitcnt vmcnt(12)
	ds_write2_b32 v84, v18, v19 offset0:164 offset1:230
	s_waitcnt vmcnt(10)
	ds_write2_b32 v85, v20, v21 offset0:40 offset1:106
	s_waitcnt vmcnt(8)
	ds_write2_b32 v85, v22, v23 offset0:172 offset1:238
	s_waitcnt vmcnt(6)
	ds_write2_b32 v86, v24, v25 offset0:48 offset1:114
	s_waitcnt vmcnt(4)
	ds_write2_b32 v86, v26, v27 offset0:180 offset1:246
	s_waitcnt vmcnt(2)
	ds_write2_b32 v87, v28, v29 offset0:56 offset1:122
	s_waitcnt vmcnt(0)
	ds_write2_b32 v87, v30, v31 offset0:188 offset1:254
	s_add_i32 s51, s51, s65
	s_sext_i32_i16 s65, s64
	s_waitcnt lgkmcnt(0)
	s_bfe_u32 s65, s65, 0x70018
	s_bfe_i32 s51, s51, 0x80000
	s_add_i32 s65, s64, s65
	ds_read2_b32 v[74:75], v79 offset1:33
	s_sext_i32_i16 s51, s51
	s_and_b32 s65, s65, 0xff80
	s_waitcnt lgkmcnt(0)
	v_cvt_pk_bf16_f32 v88, v74, v75
	ds_read2_b32 v[74:75], v79 offset0:66 offset1:99
	s_lshl_b32 s51, s51, 6
	s_sub_i32 s64, s64, s65
	s_and_b32 s51, s51, 0xffffff00
	s_waitcnt lgkmcnt(0)
	v_cvt_pk_bf16_f32 v89, v74, v75
	ds_read2_b32 v[74:75], v79 offset0:132 offset1:165
	s_sext_i32_i16 s64, s64
	s_waitcnt lgkmcnt(0)
	v_cvt_pk_bf16_f32 v90, v74, v75
	ds_read2_b32 v[74:75], v79 offset0:198 offset1:231
	s_add_i32 s64, s51, s64
	s_lshl_b32 s50, s50, 6
	s_waitcnt lgkmcnt(0)
	v_cvt_pk_bf16_f32 v91, v74, v75
	v_or_b32_e32 v74, s64, v78
	s_ashr_i32 s51, s50, 31
	v_ashrrev_i32_e32 v75, 31, v74
	v_lshl_add_u64 v[92:93], s[50:51], 1, v[40:41]
	v_lshlrev_b64 v[74:75], 11, v[74:75]
	v_lshl_add_u64 v[74:75], v[92:93], 0, v[74:75]
	ds_read2_b32 v[94:95], v79 offset0:8 offset1:41
	global_store_dwordx4 v[74:75], v[88:91], off nt
	s_andn2_b64 vcc, exec, s[14:15]
	s_mov_b64 s[14:15], -1
	s_waitcnt lgkmcnt(0)
	v_cvt_pk_bf16_f32 v88, v94, v95
	ds_read2_b32 v[74:75], v79 offset0:74 offset1:107
	s_waitcnt lgkmcnt(0)
	v_cvt_pk_bf16_f32 v89, v74, v75
	ds_read2_b32 v[74:75], v79 offset0:140 offset1:173
	s_waitcnt lgkmcnt(0)
	v_cvt_pk_bf16_f32 v90, v74, v75
	ds_read2_b32 v[74:75], v79 offset0:206 offset1:239
	s_waitcnt lgkmcnt(0)
	v_cvt_pk_bf16_f32 v91, v74, v75
	v_or_b32_e32 v74, s64, v80
	v_ashrrev_i32_e32 v75, 31, v74
	v_lshlrev_b64 v[74:75], 11, v[74:75]
	v_lshl_add_u64 v[74:75], v[92:93], 0, v[74:75]
	ds_read2_b32 v[94:95], v79 offset0:16 offset1:49
	global_store_dwordx4 v[74:75], v[88:91], off nt
	s_waitcnt lgkmcnt(0)
	s_nop 0
	v_cvt_pk_bf16_f32 v88, v94, v95
	ds_read2_b32 v[74:75], v79 offset0:82 offset1:115
	s_waitcnt lgkmcnt(0)
	v_cvt_pk_bf16_f32 v89, v74, v75
	ds_read2_b32 v[74:75], v79 offset0:148 offset1:181
	s_waitcnt lgkmcnt(0)
	v_cvt_pk_bf16_f32 v90, v74, v75
	ds_read2_b32 v[74:75], v79 offset0:214 offset1:247
	s_waitcnt lgkmcnt(0)
	v_cvt_pk_bf16_f32 v91, v74, v75
	v_or_b32_e32 v74, s64, v81
	v_ashrrev_i32_e32 v75, 31, v74
	v_lshlrev_b64 v[74:75], 11, v[74:75]
	v_lshl_add_u64 v[74:75], v[92:93], 0, v[74:75]
	ds_read2_b32 v[94:95], v79 offset0:24 offset1:57
	global_store_dwordx4 v[74:75], v[88:91], off nt
	s_waitcnt lgkmcnt(0)
	s_nop 0
	v_cvt_pk_bf16_f32 v88, v94, v95
	ds_read2_b32 v[74:75], v79 offset0:90 offset1:123
	s_waitcnt lgkmcnt(0)
	v_cvt_pk_bf16_f32 v89, v74, v75
	ds_read2_b32 v[74:75], v79 offset0:156 offset1:189
	s_waitcnt lgkmcnt(0)
	v_cvt_pk_bf16_f32 v90, v74, v75
	ds_read2_b32 v[74:75], v79 offset0:222 offset1:255
	s_waitcnt lgkmcnt(0)
	v_cvt_pk_bf16_f32 v91, v74, v75
	v_or_b32_e32 v74, s64, v82
	v_ashrrev_i32_e32 v75, 31, v74
	v_lshlrev_b64 v[74:75], 11, v[74:75]
	v_lshl_add_u64 v[74:75], v[92:93], 0, v[74:75]
	global_store_dwordx4 v[74:75], v[88:91], off nt
	s_waitcnt lgkmcnt(0)
	s_cbranch_vccnz .LBB7_25
	s_add_i32 s14, s55, s48
	s_cmpk_gt_i32 s14, 0x57f
	s_cbranch_scc1 .LBB7_24
	s_mul_hi_i32 s15, s14, 0x2e8ba2e9
	s_lshr_b32 s48, s15, 31
	s_ashr_i32 s15, s15, 4
	s_add_i32 s15, s15, s48
	s_mul_i32 s48, s15, 0x58
	s_sub_i32 s14, s14, s48
	s_lshl_b32 s14, s14, 5
	v_lshl_or_b32 v74, s15, 6, v76
	s_ashr_i32 s15, s14, 31
	v_lshl_add_u64 v[24:25], s[14:15], 2, v[38:39]
	v_or_b32_e32 v2, 2, v74
	v_or_b32_e32 v4, 4, v74
	v_or_b32_e32 v6, 6, v74
	v_or_b32_e32 v8, 8, v74
	v_or_b32_e32 v10, 10, v74
	v_or_b32_e32 v12, 12, v74
	v_or_b32_e32 v14, 14, v74
	v_mad_i64_i32 v[0:1], s[14:15], v74, s56, v[24:25]
	v_mad_i64_i32 v[2:3], s[14:15], v2, s56, v[24:25]
	v_mad_i64_i32 v[4:5], s[14:15], v4, s56, v[24:25]
	v_mad_i64_i32 v[6:7], s[14:15], v6, s56, v[24:25]
	v_mad_i64_i32 v[8:9], s[14:15], v8, s56, v[24:25]
	v_mad_i64_i32 v[10:11], s[14:15], v10, s56, v[24:25]
	v_mad_i64_i32 v[12:13], s[14:15], v12, s56, v[24:25]
	v_mad_i64_i32 v[14:15], s[14:15], v14, s56, v[24:25]
	global_load_dword v0, v[0:1], off nt
	s_nop 0
	global_load_dword v1, v[2:3], off nt
	s_nop 0
	global_load_dword v2, v[4:5], off nt
	global_load_dword v3, v[6:7], off nt
	s_nop 0
	global_load_dword v4, v[8:9], off nt
	global_load_dword v5, v[10:11], off nt
	global_load_dword v6, v[12:13], off nt
	global_load_dword v7, v[14:15], off nt
	v_or_b32_e32 v8, 16, v74
	v_or_b32_e32 v10, 18, v74
	v_or_b32_e32 v12, 20, v74
	v_or_b32_e32 v14, 22, v74
	v_or_b32_e32 v16, 24, v74
	v_or_b32_e32 v18, 26, v74
	v_or_b32_e32 v20, 28, v74
	v_or_b32_e32 v22, 30, v74
	v_mad_i64_i32 v[8:9], s[14:15], v8, s56, v[24:25]
	v_mad_i64_i32 v[10:11], s[14:15], v10, s56, v[24:25]
	v_mad_i64_i32 v[12:13], s[14:15], v12, s56, v[24:25]
	v_mad_i64_i32 v[14:15], s[14:15], v14, s56, v[24:25]
	v_mad_i64_i32 v[16:17], s[14:15], v16, s56, v[24:25]
	v_mad_i64_i32 v[18:19], s[14:15], v18, s56, v[24:25]
	v_mad_i64_i32 v[20:21], s[14:15], v20, s56, v[24:25]
	v_mad_i64_i32 v[22:23], s[14:15], v22, s56, v[24:25]
	global_load_dword v8, v[8:9], off nt
	s_nop 0
	global_load_dword v9, v[10:11], off nt
	s_nop 0
	global_load_dword v10, v[12:13], off nt
	global_load_dword v11, v[14:15], off nt
	s_nop 0
	global_load_dword v12, v[16:17], off nt
	global_load_dword v13, v[18:19], off nt
	global_load_dword v14, v[20:21], off nt
	global_load_dword v15, v[22:23], off nt
	v_or_b32_e32 v16, 32, v74
	v_or_b32_e32 v18, 34, v74
	v_or_b32_e32 v20, 36, v74
	v_or_b32_e32 v22, 38, v74
	v_or_b32_e32 v75, 46, v74
	v_mad_i64_i32 v[16:17], s[14:15], v16, s56, v[24:25]
	v_mad_i64_i32 v[18:19], s[14:15], v18, s56, v[24:25]
	v_mad_i64_i32 v[20:21], s[14:15], v20, s56, v[24:25]
	v_mad_i64_i32 v[22:23], s[14:15], v22, s56, v[24:25]
	v_or_b32_e32 v26, 40, v74
	v_or_b32_e32 v28, 42, v74
	v_or_b32_e32 v30, 44, v74
	v_mad_i64_i32 v[88:89], s[14:15], v75, s56, v[24:25]
	v_or_b32_e32 v75, 54, v74
	v_mad_i64_i32 v[26:27], s[14:15], v26, s56, v[24:25]
	v_mad_i64_i32 v[28:29], s[14:15], v28, s56, v[24:25]
	v_mad_i64_i32 v[30:31], s[14:15], v30, s56, v[24:25]
	global_load_dword v16, v[16:17], off nt
	s_nop 0
	global_load_dword v17, v[18:19], off nt
	s_nop 0
	global_load_dword v18, v[20:21], off nt
	global_load_dword v19, v[22:23], off nt
	s_nop 0
	global_load_dword v20, v[26:27], off nt
	global_load_dword v21, v[28:29], off nt
	global_load_dword v22, v[30:31], off nt
	global_load_dword v23, v[88:89], off nt
	v_mad_i64_i32 v[88:89], s[14:15], v75, s56, v[24:25]
	v_or_b32_e32 v75, 56, v74
	v_mad_i64_i32 v[90:91], s[14:15], v75, s56, v[24:25]
	v_or_b32_e32 v75, 58, v74
	v_or_b32_e32 v26, 48, v74
	v_or_b32_e32 v28, 50, v74
	v_or_b32_e32 v30, 52, v74
	v_mad_i64_i32 v[92:93], s[14:15], v75, s56, v[24:25]
	v_or_b32_e32 v75, 60, v74
	v_mad_i64_i32 v[26:27], s[14:15], v26, s56, v[24:25]
	v_mad_i64_i32 v[28:29], s[14:15], v28, s56, v[24:25]
	v_mad_i64_i32 v[30:31], s[14:15], v30, s56, v[24:25]
	v_mad_i64_i32 v[94:95], s[14:15], v75, s56, v[24:25]
	v_or_b32_e32 v75, 62, v74
	v_mad_i64_i32 v[96:97], s[14:15], v75, s56, v[24:25]
	global_load_dword v24, v[26:27], off nt
	global_load_dword v25, v[28:29], off nt
	s_nop 0
	global_load_dword v26, v[30:31], off nt
	global_load_dword v27, v[88:89], off nt
	global_load_dword v28, v[90:91], off nt
	global_load_dword v29, v[92:93], off nt
	s_nop 0
	global_load_dword v30, v[94:95], off nt
	global_load_dword v31, v[96:97], off nt
	s_and_b64 vcc, exec, s[6:7]
	s_cbranch_vccnz .LBB7_24
	v_ashrrev_i32_e32 v75, 31, v74
	v_lshl_add_u64 v[74:75], v[74:75], 2, s[12:13]
	global_load_dword v88, v[74:75], off
	global_load_dword v89, v[74:75], off offset:8
	global_load_dword v90, v[74:75], off offset:16
	global_load_dword v91, v[74:75], off offset:24
	global_load_dword v92, v[74:75], off offset:32
	global_load_dword v93, v[74:75], off offset:40
	global_load_dword v94, v[74:75], off offset:48
	global_load_dword v95, v[74:75], off offset:56
	global_load_dword v96, v[74:75], off offset:64
	global_load_dword v97, v[74:75], off offset:72
	global_load_dword v98, v[74:75], off offset:80
	global_load_dword v99, v[74:75], off offset:88
	global_load_dword v100, v[74:75], off offset:96
	global_load_dword v101, v[74:75], off offset:104
	global_load_dword v102, v[74:75], off offset:112
	global_load_dword v103, v[74:75], off offset:120
	global_load_dword v104, v[74:75], off offset:128
	global_load_dword v105, v[74:75], off offset:136
	global_load_dword v106, v[74:75], off offset:144
	global_load_dword v107, v[74:75], off offset:152
	global_load_dword v108, v[74:75], off offset:160
	global_load_dword v109, v[74:75], off offset:168
	global_load_dword v110, v[74:75], off offset:176
	global_load_dword v111, v[74:75], off offset:184
	global_load_dword v112, v[74:75], off offset:192
	global_load_dword v113, v[74:75], off offset:200
	global_load_dword v114, v[74:75], off offset:208
	global_load_dword v115, v[74:75], off offset:216
	global_load_dword v116, v[74:75], off offset:224
	global_load_dword v117, v[74:75], off offset:232
	global_load_dword v118, v[74:75], off offset:240
	global_load_dword v119, v[74:75], off offset:248
	s_waitcnt vmcnt(30)
	v_pk_mul_f32 v[0:1], v[0:1], v[88:89]
	s_waitcnt vmcnt(28)
	v_pk_mul_f32 v[2:3], v[2:3], v[90:91]
	s_waitcnt vmcnt(26)
	v_pk_mul_f32 v[4:5], v[4:5], v[92:93]
	s_waitcnt vmcnt(24)
	v_pk_mul_f32 v[6:7], v[6:7], v[94:95]
	s_waitcnt vmcnt(22)
	v_pk_mul_f32 v[8:9], v[8:9], v[96:97]
	s_waitcnt vmcnt(20)
	v_pk_mul_f32 v[10:11], v[10:11], v[98:99]
	s_waitcnt vmcnt(18)
	v_pk_mul_f32 v[12:13], v[12:13], v[100:101]
	s_waitcnt vmcnt(16)
	v_pk_mul_f32 v[14:15], v[14:15], v[102:103]
	s_waitcnt vmcnt(14)
	v_pk_mul_f32 v[16:17], v[16:17], v[104:105]
	s_waitcnt vmcnt(12)
	v_pk_mul_f32 v[18:19], v[18:19], v[106:107]
	s_waitcnt vmcnt(10)
	v_pk_mul_f32 v[20:21], v[20:21], v[108:109]
	s_waitcnt vmcnt(8)
	v_pk_mul_f32 v[22:23], v[22:23], v[110:111]
	s_waitcnt vmcnt(6)
	v_pk_mul_f32 v[24:25], v[24:25], v[112:113]
	s_waitcnt vmcnt(4)
	v_pk_mul_f32 v[26:27], v[26:27], v[114:115]
	s_waitcnt vmcnt(2)
	v_pk_mul_f32 v[28:29], v[28:29], v[116:117]
	s_waitcnt vmcnt(0)
	v_pk_mul_f32 v[30:31], v[30:31], v[118:119]
	s_branch .LBB7_24

.LBB7_37:
	s_mul_hi_i32 s14, s49, 0x2e8ba2e9
	s_lshr_b32 s15, s14, 31
	s_ashr_i32 s14, s14, 4
	s_add_i32 s14, s14, s15
	s_mul_i32 s15, s14, 0x58
	s_sub_i32 s15, s49, s15
	s_bfe_i32 s50, s15, 0x80000
	s_lshl_b32 s48, s15, 5
	s_bfe_u32 s50, s50, 0x2000d
	s_add_i32 s15, s15, s50
	s_sext_i32_i16 s50, s48
	ds_write2_b32 v77, v43, v42 offset1:66
	ds_write2_b32 v77, v45, v44 offset0:132 offset1:198
	ds_write2_b32 v32, v47, v46 offset0:8 offset1:74
	ds_write2_b32 v32, v49, v48 offset0:140 offset1:206
	ds_write2_b32 v35, v51, v50 offset0:16 offset1:82
	ds_write2_b32 v35, v53, v52 offset0:148 offset1:214
	ds_write2_b32 v37, v55, v54 offset0:24 offset1:90
	ds_write2_b32 v37, v57, v56 offset0:156 offset1:222
	ds_write2_b32 v84, v59, v58 offset0:32 offset1:98
	ds_write2_b32 v84, v61, v60 offset0:164 offset1:230
	ds_write2_b32 v85, v63, v62 offset0:40 offset1:106
	ds_write2_b32 v85, v65, v64 offset0:172 offset1:238
	ds_write2_b32 v86, v67, v66 offset0:48 offset1:114
	ds_write2_b32 v86, v69, v68 offset0:180 offset1:246
	ds_write2_b32 v87, v71, v70 offset0:56 offset1:122
	ds_write2_b32 v87, v73, v72 offset0:188 offset1:254
	s_bfe_u32 s50, s50, 0x70018
	s_waitcnt lgkmcnt(0)
	s_add_i32 s50, s48, s50
	s_bfe_i32 s15, s15, 0x80000
	s_and_b32 s50, s50, 0xff80
	ds_read2_b32 v[74:75], v79 offset1:33
	s_sext_i32_i16 s15, s15
	s_sub_i32 s48, s48, s50
	s_waitcnt lgkmcnt(0)
	v_cvt_pk_bf16_f32 v84, v74, v75
	ds_read2_b32 v[74:75], v79 offset0:66 offset1:99
	s_lshl_b32 s15, s15, 6
	s_addk_i32 s48, 0x80
	s_and_b32 s15, s15, 0xffffff00
	s_waitcnt lgkmcnt(0)
	v_cvt_pk_bf16_f32 v85, v74, v75
	ds_read2_b32 v[74:75], v79 offset0:132 offset1:165
	s_and_b32 s48, s48, 0xffe0
	s_waitcnt lgkmcnt(0)
	v_cvt_pk_bf16_f32 v86, v74, v75
	ds_read2_b32 v[74:75], v79 offset0:198 offset1:231
	s_add_i32 s50, s15, s48
	s_lshl_b32 s14, s14, 6
	s_waitcnt lgkmcnt(0)
	v_cvt_pk_bf16_f32 v87, v74, v75
	v_or_b32_e32 v74, s50, v78
	s_ashr_i32 s15, s14, 31
	v_ashrrev_i32_e32 v75, 31, v74
	v_lshl_add_u64 v[88:89], s[14:15], 1, v[40:41]
	v_lshlrev_b64 v[74:75], 11, v[74:75]
	v_lshl_add_u64 v[74:75], v[88:89], 0, v[74:75]
	ds_read2_b32 v[90:91], v79 offset0:8 offset1:41
	global_store_dwordx4 v[74:75], v[84:87], off nt
	s_add_i32 s48, s49, s72
	s_cmpk_gt_i32 s48, 0x57f
	s_waitcnt lgkmcnt(0)
	v_cvt_pk_bf16_f32 v84, v90, v91
	ds_read2_b32 v[74:75], v79 offset0:74 offset1:107
	s_waitcnt lgkmcnt(0)
	v_cvt_pk_bf16_f32 v85, v74, v75
	ds_read2_b32 v[74:75], v79 offset0:140 offset1:173
	s_waitcnt lgkmcnt(0)
	v_cvt_pk_bf16_f32 v86, v74, v75
	ds_read2_b32 v[74:75], v79 offset0:206 offset1:239
	s_waitcnt lgkmcnt(0)
	v_cvt_pk_bf16_f32 v87, v74, v75
	v_or_b32_e32 v74, s50, v80
	v_ashrrev_i32_e32 v75, 31, v74
	v_lshlrev_b64 v[74:75], 11, v[74:75]
	v_lshl_add_u64 v[74:75], v[88:89], 0, v[74:75]
	ds_read2_b32 v[90:91], v79 offset0:16 offset1:49
	global_store_dwordx4 v[74:75], v[84:87], off nt
	s_cselect_b64 s[14:15], -1, 0
	s_waitcnt lgkmcnt(0)
	v_cvt_pk_bf16_f32 v84, v90, v91
	ds_read2_b32 v[74:75], v79 offset0:82 offset1:115
	s_waitcnt lgkmcnt(0)
	v_cvt_pk_bf16_f32 v85, v74, v75
	ds_read2_b32 v[74:75], v79 offset0:148 offset1:181
	s_waitcnt lgkmcnt(0)
	v_cvt_pk_bf16_f32 v86, v74, v75
	ds_read2_b32 v[74:75], v79 offset0:214 offset1:247
	s_waitcnt lgkmcnt(0)
	v_cvt_pk_bf16_f32 v87, v74, v75
	v_or_b32_e32 v74, s50, v81
	v_ashrrev_i32_e32 v75, 31, v74
	v_lshlrev_b64 v[74:75], 11, v[74:75]
	v_lshl_add_u64 v[74:75], v[88:89], 0, v[74:75]
	ds_read2_b32 v[90:91], v79 offset0:24 offset1:57
	global_store_dwordx4 v[74:75], v[84:87], off nt
	s_waitcnt lgkmcnt(0)
	s_nop 0
	v_cvt_pk_bf16_f32 v84, v90, v91
	ds_read2_b32 v[74:75], v79 offset0:90 offset1:123
	s_waitcnt lgkmcnt(0)
	v_cvt_pk_bf16_f32 v85, v74, v75
	ds_read2_b32 v[74:75], v79 offset0:156 offset1:189
	s_waitcnt lgkmcnt(0)
	v_cvt_pk_bf16_f32 v86, v74, v75
	ds_read2_b32 v[74:75], v79 offset0:222 offset1:255
	s_waitcnt lgkmcnt(0)
	v_cvt_pk_bf16_f32 v87, v74, v75
	v_or_b32_e32 v74, s50, v82
	v_ashrrev_i32_e32 v75, 31, v74
	v_lshlrev_b64 v[74:75], 11, v[74:75]
	v_lshl_add_u64 v[74:75], v[88:89], 0, v[74:75]
	global_store_dwordx4 v[74:75], v[84:87], off nt
	s_waitcnt lgkmcnt(0)

.LBB7_42:
	s_mul_hi_i32 s50, s48, 0x2e8ba2e9
	s_lshr_b32 s51, s50, 31
	s_ashr_i32 s50, s50, 4
	s_add_i32 s50, s50, s51
	s_mul_i32 s51, s50, 0x58
	s_sub_i32 s51, s48, s51
	s_bfe_i32 s65, s51, 0x80000
	s_lshl_b32 s64, s51, 5
	s_bfe_u32 s65, s65, 0x2000d
	v_add_u32_e32 v32, 0x400, v77
	v_add_u32_e32 v35, 0x800, v77
	v_add_u32_e32 v37, 0xc00, v77
	v_add_u32_e32 v84, 0x1000, v77
	v_add_u32_e32 v85, 0x1400, v77
	v_add_u32_e32 v86, 0x1800, v77
	v_add_u32_e32 v87, 0x1c00, v77
	s_add_i32 s51, s51, s65
	s_sext_i32_i16 s65, s64
	s_waitcnt vmcnt(30)
	ds_write2_b32 v77, v0, v1 offset1:66
	s_waitcnt vmcnt(28)
	ds_write2_b32 v77, v2, v3 offset0:132 offset1:198
	s_waitcnt vmcnt(26)
	ds_write2_b32 v32, v4, v5 offset0:8 offset1:74
	s_waitcnt vmcnt(24)
	ds_write2_b32 v32, v6, v7 offset0:140 offset1:206
	s_waitcnt vmcnt(22)
	ds_write2_b32 v35, v8, v9 offset0:16 offset1:82
	s_waitcnt vmcnt(20)
	ds_write2_b32 v35, v10, v11 offset0:148 offset1:214
	s_waitcnt vmcnt(18)
	ds_write2_b32 v37, v12, v13 offset0:24 offset1:90
	s_waitcnt vmcnt(16)
	ds_write2_b32 v37, v14, v15 offset0:156 offset1:222
	s_waitcnt vmcnt(14)
	ds_write2_b32 v84, v16, v17 offset0:32 offset1:98
	s_waitcnt vmcnt(12)
	ds_write2_b32 v84, v18, v19 offset0:164 offset1:230
	s_waitcnt vmcnt(10)
	ds_write2_b32 v85, v20, v21 offset0:40 offset1:106
	s_waitcnt vmcnt(8)
	ds_write2_b32 v85, v22, v23 offset0:172 offset1:238
	s_waitcnt vmcnt(6)
	ds_write2_b32 v86, v24, v25 offset0:48 offset1:114
	s_waitcnt vmcnt(4)
	ds_write2_b32 v86, v26, v27 offset0:180 offset1:246
	s_waitcnt vmcnt(2)
	ds_write2_b32 v87, v28, v29 offset0:56 offset1:122
	s_waitcnt vmcnt(0)
	ds_write2_b32 v87, v30, v31 offset0:188 offset1:254
	s_bfe_u32 s65, s65, 0x70018
	s_waitcnt lgkmcnt(0)
	s_add_i32 s65, s64, s65
	s_bfe_i32 s51, s51, 0x80000
	s_and_b32 s65, s65, 0xff80
	ds_read2_b32 v[74:75], v79 offset1:33
	s_sext_i32_i16 s51, s51
	s_sub_i32 s64, s64, s65
	s_waitcnt lgkmcnt(0)
	v_cvt_pk_bf16_f32 v88, v74, v75
	ds_read2_b32 v[74:75], v79 offset0:66 offset1:99
	s_lshl_b32 s51, s51, 6
	s_addk_i32 s64, 0x80
	s_and_b32 s51, s51, 0xffffff00
	s_waitcnt lgkmcnt(0)
	v_cvt_pk_bf16_f32 v89, v74, v75
	ds_read2_b32 v[74:75], v79 offset0:132 offset1:165
	s_and_b32 s64, s64, 0xffe0
	s_waitcnt lgkmcnt(0)
	v_cvt_pk_bf16_f32 v90, v74, v75
	ds_read2_b32 v[74:75], v79 offset0:198 offset1:231
	s_add_i32 s64, s51, s64
	s_lshl_b32 s50, s50, 6
	s_waitcnt lgkmcnt(0)
	v_cvt_pk_bf16_f32 v91, v74, v75
	v_or_b32_e32 v74, s64, v78
	s_ashr_i32 s51, s50, 31
	v_ashrrev_i32_e32 v75, 31, v74
	v_lshl_add_u64 v[92:93], s[50:51], 1, v[40:41]
	v_lshlrev_b64 v[74:75], 11, v[74:75]
	v_lshl_add_u64 v[74:75], v[92:93], 0, v[74:75]
	ds_read2_b32 v[94:95], v79 offset0:8 offset1:41
	global_store_dwordx4 v[74:75], v[88:91], off nt
	s_andn2_b64 vcc, exec, s[14:15]
	s_mov_b64 s[14:15], -1
	s_waitcnt lgkmcnt(0)
	v_cvt_pk_bf16_f32 v88, v94, v95
	ds_read2_b32 v[74:75], v79 offset0:74 offset1:107
	s_waitcnt lgkmcnt(0)
	v_cvt_pk_bf16_f32 v89, v74, v75
	ds_read2_b32 v[74:75], v79 offset0:140 offset1:173
	s_waitcnt lgkmcnt(0)
	v_cvt_pk_bf16_f32 v90, v74, v75
	ds_read2_b32 v[74:75], v79 offset0:206 offset1:239
	s_waitcnt lgkmcnt(0)
	v_cvt_pk_bf16_f32 v91, v74, v75
	v_or_b32_e32 v74, s64, v80
	v_ashrrev_i32_e32 v75, 31, v74
	v_lshlrev_b64 v[74:75], 11, v[74:75]
	v_lshl_add_u64 v[74:75], v[92:93], 0, v[74:75]
	ds_read2_b32 v[94:95], v79 offset0:16 offset1:49
	global_store_dwordx4 v[74:75], v[88:91], off nt
	s_waitcnt lgkmcnt(0)
	s_nop 0
	v_cvt_pk_bf16_f32 v88, v94, v95
	ds_read2_b32 v[74:75], v79 offset0:82 offset1:115
	s_waitcnt lgkmcnt(0)
	v_cvt_pk_bf16_f32 v89, v74, v75
	ds_read2_b32 v[74:75], v79 offset0:148 offset1:181
	s_waitcnt lgkmcnt(0)
	v_cvt_pk_bf16_f32 v90, v74, v75
	ds_read2_b32 v[74:75], v79 offset0:214 offset1:247
	s_waitcnt lgkmcnt(0)
	v_cvt_pk_bf16_f32 v91, v74, v75
	v_or_b32_e32 v74, s64, v81
	v_ashrrev_i32_e32 v75, 31, v74
	v_lshlrev_b64 v[74:75], 11, v[74:75]
	v_lshl_add_u64 v[74:75], v[92:93], 0, v[74:75]
	ds_read2_b32 v[94:95], v79 offset0:24 offset1:57
	global_store_dwordx4 v[74:75], v[88:91], off nt
	s_waitcnt lgkmcnt(0)
	s_nop 0
	v_cvt_pk_bf16_f32 v88, v94, v95
	ds_read2_b32 v[74:75], v79 offset0:90 offset1:123
	s_waitcnt lgkmcnt(0)
	v_cvt_pk_bf16_f32 v89, v74, v75
	ds_read2_b32 v[74:75], v79 offset0:156 offset1:189
	s_waitcnt lgkmcnt(0)
	v_cvt_pk_bf16_f32 v90, v74, v75
	ds_read2_b32 v[74:75], v79 offset0:222 offset1:255
	s_waitcnt lgkmcnt(0)
	v_cvt_pk_bf16_f32 v91, v74, v75
	v_or_b32_e32 v74, s64, v82
	v_ashrrev_i32_e32 v75, 31, v74
	v_lshlrev_b64 v[74:75], 11, v[74:75]
	v_lshl_add_u64 v[74:75], v[92:93], 0, v[74:75]
	global_store_dwordx4 v[74:75], v[88:91], off nt
	s_waitcnt lgkmcnt(0)
	s_cbranch_vccnz .LBB7_38
	s_add_i32 s14, s55, s48
	s_cmpk_gt_i32 s14, 0x57f
	s_cbranch_scc1 .LBB7_37
	s_mul_hi_i32 s15, s14, 0x2e8ba2e9
	s_lshr_b32 s48, s15, 31
	s_ashr_i32 s15, s15, 4
	s_add_i32 s15, s15, s48
	s_mul_i32 s48, s15, 0x58
	s_sub_i32 s14, s14, s48
	s_lshl_b32 s14, s14, 5
	v_lshl_or_b32 v74, s15, 6, v76
	s_ashr_i32 s15, s14, 31
	v_lshl_add_u64 v[24:25], s[14:15], 2, v[38:39]
	v_or_b32_e32 v2, 2, v74
	v_or_b32_e32 v4, 4, v74
	v_or_b32_e32 v6, 6, v74
	v_or_b32_e32 v8, 8, v74
	v_or_b32_e32 v10, 10, v74
	v_or_b32_e32 v12, 12, v74
	v_or_b32_e32 v14, 14, v74
	v_mad_i64_i32 v[0:1], s[14:15], v74, s56, v[24:25]
	v_mad_i64_i32 v[2:3], s[14:15], v2, s56, v[24:25]
	v_mad_i64_i32 v[4:5], s[14:15], v4, s56, v[24:25]
	v_mad_i64_i32 v[6:7], s[14:15], v6, s56, v[24:25]
	v_mad_i64_i32 v[8:9], s[14:15], v8, s56, v[24:25]
	v_mad_i64_i32 v[10:11], s[14:15], v10, s56, v[24:25]
	v_mad_i64_i32 v[12:13], s[14:15], v12, s56, v[24:25]
	v_mad_i64_i32 v[14:15], s[14:15], v14, s56, v[24:25]
	global_load_dword v0, v[0:1], off nt
	s_nop 0
	global_load_dword v1, v[2:3], off nt
	s_nop 0
	global_load_dword v2, v[4:5], off nt
	global_load_dword v3, v[6:7], off nt
	s_nop 0
	global_load_dword v4, v[8:9], off nt
	global_load_dword v5, v[10:11], off nt
	global_load_dword v6, v[12:13], off nt
	global_load_dword v7, v[14:15], off nt
	v_or_b32_e32 v8, 16, v74
	v_or_b32_e32 v10, 18, v74
	v_or_b32_e32 v12, 20, v74
	v_or_b32_e32 v14, 22, v74
	v_or_b32_e32 v16, 24, v74
	v_or_b32_e32 v18, 26, v74
	v_or_b32_e32 v20, 28, v74
	v_or_b32_e32 v22, 30, v74
	v_mad_i64_i32 v[8:9], s[14:15], v8, s56, v[24:25]
	v_mad_i64_i32 v[10:11], s[14:15], v10, s56, v[24:25]
	v_mad_i64_i32 v[12:13], s[14:15], v12, s56, v[24:25]
	v_mad_i64_i32 v[14:15], s[14:15], v14, s56, v[24:25]
	v_mad_i64_i32 v[16:17], s[14:15], v16, s56, v[24:25]
	v_mad_i64_i32 v[18:19], s[14:15], v18, s56, v[24:25]
	v_mad_i64_i32 v[20:21], s[14:15], v20, s56, v[24:25]
	v_mad_i64_i32 v[22:23], s[14:15], v22, s56, v[24:25]
	global_load_dword v8, v[8:9], off nt
	s_nop 0
	global_load_dword v9, v[10:11], off nt
	s_nop 0
	global_load_dword v10, v[12:13], off nt
	global_load_dword v11, v[14:15], off nt
	s_nop 0
	global_load_dword v12, v[16:17], off nt
	global_load_dword v13, v[18:19], off nt
	global_load_dword v14, v[20:21], off nt
	global_load_dword v15, v[22:23], off nt
	v_or_b32_e32 v16, 32, v74
	v_or_b32_e32 v18, 34, v74
	v_or_b32_e32 v20, 36, v74
	v_or_b32_e32 v22, 38, v74
	v_or_b32_e32 v75, 46, v74
	v_mad_i64_i32 v[16:17], s[14:15], v16, s56, v[24:25]
	v_mad_i64_i32 v[18:19], s[14:15], v18, s56, v[24:25]
	v_mad_i64_i32 v[20:21], s[14:15], v20, s56, v[24:25]
	v_mad_i64_i32 v[22:23], s[14:15], v22, s56, v[24:25]
	v_or_b32_e32 v26, 40, v74
	v_or_b32_e32 v28, 42, v74
	v_or_b32_e32 v30, 44, v74
	v_mad_i64_i32 v[88:89], s[14:15], v75, s56, v[24:25]
	v_or_b32_e32 v75, 54, v74
	v_mad_i64_i32 v[26:27], s[14:15], v26, s56, v[24:25]
	v_mad_i64_i32 v[28:29], s[14:15], v28, s56, v[24:25]
	v_mad_i64_i32 v[30:31], s[14:15], v30, s56, v[24:25]
	global_load_dword v16, v[16:17], off nt
	s_nop 0
	global_load_dword v17, v[18:19], off nt
	s_nop 0
	global_load_dword v18, v[20:21], off nt
	global_load_dword v19, v[22:23], off nt
	s_nop 0
	global_load_dword v20, v[26:27], off nt
	global_load_dword v21, v[28:29], off nt
	global_load_dword v22, v[30:31], off nt
	global_load_dword v23, v[88:89], off nt
	v_mad_i64_i32 v[88:89], s[14:15], v75, s56, v[24:25]
	v_or_b32_e32 v75, 56, v74
	v_mad_i64_i32 v[90:91], s[14:15], v75, s56, v[24:25]
	v_or_b32_e32 v75, 58, v74
	v_or_b32_e32 v26, 48, v74
	v_or_b32_e32 v28, 50, v74
	v_or_b32_e32 v30, 52, v74
	v_mad_i64_i32 v[92:93], s[14:15], v75, s56, v[24:25]
	v_or_b32_e32 v75, 60, v74
	v_mad_i64_i32 v[26:27], s[14:15], v26, s56, v[24:25]
	v_mad_i64_i32 v[28:29], s[14:15], v28, s56, v[24:25]
	v_mad_i64_i32 v[30:31], s[14:15], v30, s56, v[24:25]
	v_mad_i64_i32 v[94:95], s[14:15], v75, s56, v[24:25]
	v_or_b32_e32 v75, 62, v74
	v_mad_i64_i32 v[96:97], s[14:15], v75, s56, v[24:25]
	global_load_dword v24, v[26:27], off nt
	global_load_dword v25, v[28:29], off nt
	s_nop 0
	global_load_dword v26, v[30:31], off nt
	global_load_dword v27, v[88:89], off nt
	global_load_dword v28, v[90:91], off nt
	global_load_dword v29, v[92:93], off nt
	s_nop 0
	global_load_dword v30, v[94:95], off nt
	global_load_dword v31, v[96:97], off nt
	s_and_b64 vcc, exec, s[6:7]
	s_cbranch_vccnz .LBB7_37
	v_ashrrev_i32_e32 v75, 31, v74
	v_lshl_add_u64 v[74:75], v[74:75], 2, s[12:13]
	global_load_dword v88, v[74:75], off
	global_load_dword v89, v[74:75], off offset:8
	global_load_dword v90, v[74:75], off offset:16
	global_load_dword v91, v[74:75], off offset:24
	global_load_dword v92, v[74:75], off offset:32
	global_load_dword v93, v[74:75], off offset:40
	global_load_dword v94, v[74:75], off offset:48
	global_load_dword v95, v[74:75], off offset:56
	global_load_dword v96, v[74:75], off offset:64
	global_load_dword v97, v[74:75], off offset:72
	global_load_dword v98, v[74:75], off offset:80
	global_load_dword v99, v[74:75], off offset:88
	global_load_dword v100, v[74:75], off offset:96
	global_load_dword v101, v[74:75], off offset:104
	global_load_dword v102, v[74:75], off offset:112
	global_load_dword v103, v[74:75], off offset:120
	global_load_dword v104, v[74:75], off offset:128
	global_load_dword v105, v[74:75], off offset:136
	global_load_dword v106, v[74:75], off offset:144
	global_load_dword v107, v[74:75], off offset:152
	global_load_dword v108, v[74:75], off offset:160
	global_load_dword v109, v[74:75], off offset:168
	global_load_dword v110, v[74:75], off offset:176
	global_load_dword v111, v[74:75], off offset:184
	global_load_dword v112, v[74:75], off offset:192
	global_load_dword v113, v[74:75], off offset:200
	global_load_dword v114, v[74:75], off offset:208
	global_load_dword v115, v[74:75], off offset:216
	global_load_dword v116, v[74:75], off offset:224
	global_load_dword v117, v[74:75], off offset:232
	global_load_dword v118, v[74:75], off offset:240
	global_load_dword v119, v[74:75], off offset:248
	s_waitcnt vmcnt(30)
	v_pk_mul_f32 v[0:1], v[0:1], v[88:89]
	s_waitcnt vmcnt(28)
	v_pk_mul_f32 v[2:3], v[2:3], v[90:91]
	s_waitcnt vmcnt(26)
	v_pk_mul_f32 v[4:5], v[4:5], v[92:93]
	s_waitcnt vmcnt(24)
	v_pk_mul_f32 v[6:7], v[6:7], v[94:95]
	s_waitcnt vmcnt(22)
	v_pk_mul_f32 v[8:9], v[8:9], v[96:97]
	s_waitcnt vmcnt(20)
	v_pk_mul_f32 v[10:11], v[10:11], v[98:99]
	s_waitcnt vmcnt(18)
	v_pk_mul_f32 v[12:13], v[12:13], v[100:101]
	s_waitcnt vmcnt(16)
	v_pk_mul_f32 v[14:15], v[14:15], v[102:103]
	s_waitcnt vmcnt(14)
	v_pk_mul_f32 v[16:17], v[16:17], v[104:105]
	s_waitcnt vmcnt(12)
	v_pk_mul_f32 v[18:19], v[18:19], v[106:107]
	s_waitcnt vmcnt(10)
	v_pk_mul_f32 v[20:21], v[20:21], v[108:109]
	s_waitcnt vmcnt(8)
	v_pk_mul_f32 v[22:23], v[22:23], v[110:111]
	s_waitcnt vmcnt(6)
	v_pk_mul_f32 v[24:25], v[24:25], v[112:113]
	s_waitcnt vmcnt(4)
	v_pk_mul_f32 v[26:27], v[26:27], v[114:115]
	s_waitcnt vmcnt(2)
	v_pk_mul_f32 v[28:29], v[28:29], v[116:117]
	s_waitcnt vmcnt(0)
	v_pk_mul_f32 v[30:31], v[30:31], v[118:119]
	s_branch .LBB7_37

.LBB7_48:
	s_ashr_i32 s6, s45, 31
	s_lshr_b32 s6, s6, 27
	s_add_i32 s7, s45, s6
	s_ashr_i32 s6, s7, 5
	s_andn2_b32 s7, s7, 31
	s_sub_i32 s48, s45, s7
	s_ashr_i32 s7, s6, 31
	s_lshl_b32 s49, s48, 5
	s_add_i32 s15, s45, s72
	s_lshl_b64 s[6:7], s[6:7], 15
	s_add_u32 s45, s13, s6
	s_addc_u32 s50, s14, s7
	s_lshr_b32 s6, s48, 3
	ds_write2_b32 v77, v37, v40 offset1:66
	ds_write2_b32 v77, v41, v42 offset0:132 offset1:198
	ds_write2_b32 v71, v43, v44 offset0:8 offset1:74
	ds_write2_b32 v71, v45, v46 offset0:140 offset1:206
	ds_write2_b32 v72, v47, v48 offset0:16 offset1:82
	ds_write2_b32 v72, v49, v50 offset0:148 offset1:214
	ds_write2_b32 v73, v51, v52 offset0:24 offset1:90
	ds_write2_b32 v73, v53, v54 offset0:156 offset1:222
	ds_write2_b32 v74, v55, v56 offset0:32 offset1:98
	ds_write2_b32 v74, v57, v58 offset0:164 offset1:230
	ds_write2_b32 v75, v59, v60 offset0:40 offset1:106
	ds_write2_b32 v75, v61, v62 offset0:172 offset1:238
	ds_write2_b32 v84, v63, v64 offset0:48 offset1:114
	ds_write2_b32 v84, v65, v66 offset0:180 offset1:246
	ds_write2_b32 v85, v67, v68 offset0:56 offset1:122
	ds_write2_b32 v85, v69, v70 offset0:188 offset1:254
	s_mul_i32 s6, s6, 0xb0000
	s_waitcnt lgkmcnt(0)
	s_ashr_i32 s7, s6, 31
	v_or_b32_e32 v32, s49, v78
	s_lshl_b64 s[6:7], s[6:7], 1
	ds_read2_b32 v[72:73], v79 offset1:33
	s_add_u32 s6, s45, s6
	v_lshlrev_b32_e32 v32, 7, v32
	s_waitcnt lgkmcnt(0)
	v_cvt_pk_bf16_f32 v72, v72, v73
	ds_read2_b32 v[74:75], v79 offset0:66 offset1:99
	s_addc_u32 s7, s50, s7
	v_and_b32_e32 v32, 0x7380, v32
	s_waitcnt lgkmcnt(0)
	v_cvt_pk_bf16_f32 v73, v74, v75
	ds_read2_b32 v[74:75], v79 offset0:132 offset1:165
	v_lshl_add_u64 v[86:87], s[6:7], 0, v[32:33]
	v_mov_b32_e32 v35, v33
	v_or_b32_e32 v32, s49, v80
	s_waitcnt lgkmcnt(0)
	v_cvt_pk_bf16_f32 v74, v74, v75
	ds_read2_b32 v[84:85], v79 offset0:198 offset1:231
	s_waitcnt lgkmcnt(0)
	v_cvt_pk_bf16_f32 v75, v84, v85
	v_lshl_add_u64 v[86:87], v[86:87], 0, v[34:35]
	v_lshlrev_b32_e32 v32, 7, v32
	ds_read2_b32 v[84:85], v79 offset0:8 offset1:41
	global_store_dwordx4 v[86:87], v[72:75], off nt
	v_and_b32_e32 v32, 0x7780, v32
	v_lshl_add_u64 v[86:87], s[6:7], 0, v[32:33]
	s_waitcnt lgkmcnt(0)
	v_cvt_pk_bf16_f32 v72, v84, v85
	ds_read2_b32 v[74:75], v79 offset0:74 offset1:107
	s_waitcnt lgkmcnt(0)
	v_cvt_pk_bf16_f32 v73, v74, v75
	ds_read2_b32 v[74:75], v79 offset0:140 offset1:173
	v_or_b32_e32 v32, s49, v81
	s_waitcnt lgkmcnt(0)
	v_cvt_pk_bf16_f32 v74, v74, v75
	ds_read2_b32 v[84:85], v79 offset0:206 offset1:239
	s_waitcnt lgkmcnt(0)
	v_cvt_pk_bf16_f32 v75, v84, v85
	v_lshl_add_u64 v[86:87], v[86:87], 0, v[34:35]
	v_lshlrev_b32_e32 v32, 7, v32
	ds_read2_b32 v[84:85], v79 offset0:16 offset1:49
	global_store_dwordx4 v[86:87], v[72:75], off nt
	v_and_b32_e32 v32, 0x7b80, v32
	v_lshl_add_u64 v[86:87], s[6:7], 0, v[32:33]
	s_waitcnt lgkmcnt(0)
	v_cvt_pk_bf16_f32 v72, v84, v85
	ds_read2_b32 v[74:75], v79 offset0:82 offset1:115
	s_waitcnt lgkmcnt(0)
	v_cvt_pk_bf16_f32 v73, v74, v75
	ds_read2_b32 v[74:75], v79 offset0:148 offset1:181
	s_waitcnt lgkmcnt(0)
	v_cvt_pk_bf16_f32 v74, v74, v75
	ds_read2_b32 v[84:85], v79 offset0:214 offset1:247
	s_waitcnt lgkmcnt(0)
	v_cvt_pk_bf16_f32 v75, v84, v85
	v_lshl_add_u64 v[86:87], v[86:87], 0, v[34:35]
	ds_read2_b32 v[84:85], v79 offset0:24 offset1:57
	global_store_dwordx4 v[86:87], v[72:75], off nt
	v_or_b32_e32 v32, s49, v82
	v_lshlrev_b32_e32 v32, 7, v32
	s_waitcnt lgkmcnt(0)
	v_cvt_pk_bf16_f32 v72, v84, v85
	ds_read2_b32 v[74:75], v79 offset0:90 offset1:123
	s_waitcnt lgkmcnt(0)
	v_cvt_pk_bf16_f32 v73, v74, v75
	ds_read2_b32 v[74:75], v79 offset0:156 offset1:189
	s_waitcnt lgkmcnt(0)
	v_cvt_pk_bf16_f32 v74, v74, v75
	ds_read2_b32 v[84:85], v79 offset0:222 offset1:255
	v_and_b32_e32 v32, 0x7f80, v32
	s_waitcnt lgkmcnt(0)
	v_cvt_pk_bf16_f32 v75, v84, v85
	v_lshl_add_u64 v[84:85], s[6:7], 0, v[32:33]
	v_lshl_add_u64 v[84:85], v[84:85], 0, v[34:35]
	global_store_dwordx4 v[84:85], v[72:75], off nt
	s_waitcnt lgkmcnt(0)
	s_cmpk_gt_i32 s15, 0x57f
	s_cselect_b64 s[6:7], -1, 0

.LBB7_52:
	s_ashr_i32 s48, s15, 31
	s_lshr_b32 s48, s48, 27
	s_add_i32 s48, s15, s48
	s_and_b32 s49, s48, 0xffffffe0
	s_ashr_i32 s48, s48, 5
	s_sub_i32 s50, s15, s49
	s_ashr_i32 s49, s48, 31
	v_add_u32_e32 v71, 0x400, v77
	v_add_u32_e32 v72, 0x800, v77
	v_add_u32_e32 v73, 0xc00, v77
	v_add_u32_e32 v74, 0x1000, v77
	v_add_u32_e32 v75, 0x1400, v77
	v_add_u32_e32 v84, 0x1800, v77
	v_add_u32_e32 v85, 0x1c00, v77
	s_lshl_b32 s51, s50, 5
	s_lshl_b64 s[48:49], s[48:49], 15
	s_waitcnt vmcnt(30)
	ds_write2_b32 v77, v0, v1 offset1:66
	s_waitcnt vmcnt(28)
	ds_write2_b32 v77, v2, v3 offset0:132 offset1:198
	s_waitcnt vmcnt(26)
	ds_write2_b32 v71, v4, v5 offset0:8 offset1:74
	s_waitcnt vmcnt(24)
	ds_write2_b32 v71, v6, v7 offset0:140 offset1:206
	s_waitcnt vmcnt(22)
	ds_write2_b32 v72, v8, v9 offset0:16 offset1:82
	s_waitcnt vmcnt(20)
	ds_write2_b32 v72, v10, v11 offset0:148 offset1:214
	s_waitcnt vmcnt(18)
	ds_write2_b32 v73, v12, v13 offset0:24 offset1:90
	s_waitcnt vmcnt(16)
	ds_write2_b32 v73, v14, v15 offset0:156 offset1:222
	s_waitcnt vmcnt(14)
	ds_write2_b32 v74, v16, v17 offset0:32 offset1:98
	s_waitcnt vmcnt(12)
	ds_write2_b32 v74, v18, v19 offset0:164 offset1:230
	s_waitcnt vmcnt(10)
	ds_write2_b32 v75, v20, v21 offset0:40 offset1:106
	s_waitcnt vmcnt(8)
	ds_write2_b32 v75, v22, v23 offset0:172 offset1:238
	s_waitcnt vmcnt(6)
	ds_write2_b32 v84, v24, v25 offset0:48 offset1:114
	s_waitcnt vmcnt(4)
	ds_write2_b32 v84, v26, v27 offset0:180 offset1:246
	s_waitcnt vmcnt(2)
	ds_write2_b32 v85, v28, v29 offset0:56 offset1:122
	s_waitcnt vmcnt(0)
	ds_write2_b32 v85, v30, v31 offset0:188 offset1:254
	s_add_u32 s64, s13, s48
	s_waitcnt lgkmcnt(0)
	s_addc_u32 s65, s14, s49
	s_lshr_b32 s48, s50, 3
	s_mul_i32 s48, s48, 0xb0000
	ds_read2_b32 v[86:87], v79 offset1:33
	s_ashr_i32 s49, s48, 31
	s_waitcnt lgkmcnt(0)
	v_cvt_pk_bf16_f32 v86, v86, v87
	ds_read2_b32 v[88:89], v79 offset0:66 offset1:99
	v_or_b32_e32 v32, s51, v78
	s_lshl_b64 s[48:49], s[48:49], 1
	s_waitcnt lgkmcnt(0)
	v_cvt_pk_bf16_f32 v87, v88, v89
	ds_read2_b32 v[88:89], v79 offset0:132 offset1:165
	v_lshlrev_b32_e32 v32, 7, v32
	s_add_u32 s48, s64, s48
	s_waitcnt lgkmcnt(0)
	v_cvt_pk_bf16_f32 v88, v88, v89
	ds_read2_b32 v[90:91], v79 offset0:198 offset1:231
	v_and_b32_e32 v32, 0x7380, v32
	s_addc_u32 s49, s65, s49
	s_waitcnt lgkmcnt(0)
	v_cvt_pk_bf16_f32 v89, v90, v91
	v_mov_b32_e32 v35, v33
	v_lshl_add_u64 v[90:91], s[48:49], 0, v[32:33]
	v_lshl_add_u64 v[90:91], v[90:91], 0, v[34:35]
	global_store_dwordx4 v[90:91], v[86:89], off nt
	ds_read2_b32 v[86:87], v79 offset0:8 offset1:41
	v_or_b32_e32 v32, s51, v80
	s_waitcnt lgkmcnt(0)
	v_cvt_pk_bf16_f32 v86, v86, v87
	ds_read2_b32 v[88:89], v79 offset0:74 offset1:107
	s_waitcnt lgkmcnt(0)
	v_cvt_pk_bf16_f32 v87, v88, v89
	ds_read2_b32 v[88:89], v79 offset0:140 offset1:173
	v_lshlrev_b32_e32 v32, 7, v32
	s_waitcnt lgkmcnt(0)
	v_cvt_pk_bf16_f32 v88, v88, v89
	ds_read2_b32 v[90:91], v79 offset0:206 offset1:239
	v_and_b32_e32 v32, 0x7780, v32
	s_waitcnt lgkmcnt(0)
	v_cvt_pk_bf16_f32 v89, v90, v91
	v_lshl_add_u64 v[90:91], s[48:49], 0, v[32:33]
	v_lshl_add_u64 v[90:91], v[90:91], 0, v[34:35]
	global_store_dwordx4 v[90:91], v[86:89], off nt
	ds_read2_b32 v[86:87], v79 offset0:16 offset1:49
	v_or_b32_e32 v32, s51, v81
	s_waitcnt lgkmcnt(0)
	v_cvt_pk_bf16_f32 v86, v86, v87
	ds_read2_b32 v[88:89], v79 offset0:82 offset1:115
	s_waitcnt lgkmcnt(0)
	v_cvt_pk_bf16_f32 v87, v88, v89
	ds_read2_b32 v[88:89], v79 offset0:148 offset1:181
	v_lshlrev_b32_e32 v32, 7, v32
	s_waitcnt lgkmcnt(0)
	v_cvt_pk_bf16_f32 v88, v88, v89
	ds_read2_b32 v[90:91], v79 offset0:214 offset1:247
	v_and_b32_e32 v32, 0x7b80, v32
	s_waitcnt lgkmcnt(0)
	v_cvt_pk_bf16_f32 v89, v90, v91
	v_lshl_add_u64 v[90:91], s[48:49], 0, v[32:33]
	v_lshl_add_u64 v[90:91], v[90:91], 0, v[34:35]
	global_store_dwordx4 v[90:91], v[86:89], off nt
	ds_read2_b32 v[86:87], v79 offset0:24 offset1:57
	v_or_b32_e32 v32, s51, v82
	s_waitcnt lgkmcnt(0)
	v_cvt_pk_bf16_f32 v86, v86, v87
	ds_read2_b32 v[88:89], v79 offset0:90 offset1:123
	s_waitcnt lgkmcnt(0)
	v_cvt_pk_bf16_f32 v87, v88, v89
	ds_read2_b32 v[88:89], v79 offset0:156 offset1:189
	v_lshlrev_b32_e32 v32, 7, v32
	s_waitcnt lgkmcnt(0)
	v_cvt_pk_bf16_f32 v88, v88, v89
	ds_read2_b32 v[90:91], v79 offset0:222 offset1:255
	v_and_b32_e32 v32, 0x7f80, v32
	s_waitcnt lgkmcnt(0)
	v_cvt_pk_bf16_f32 v89, v90, v91
	v_lshl_add_u64 v[90:91], s[48:49], 0, v[32:33]
	v_lshl_add_u64 v[90:91], v[90:91], 0, v[34:35]
	global_store_dwordx4 v[90:91], v[86:89], off nt
	s_waitcnt lgkmcnt(0)
	s_andn2_b64 vcc, exec, s[6:7]
	s_mov_b64 s[6:7], -1
	s_cbranch_vccnz .LBB7_49
	s_add_i32 s6, s55, s15
	s_cmpk_gt_i32 s6, 0x57f
	s_cbranch_scc1 .LBB7_48
	s_ashr_i32 s7, s6, 31
	s_lshr_b32 s7, s7, 27
	s_add_i32 s7, s6, s7
	s_and_b32 s15, s7, 0x7ffffe0
	s_lshl_b32 s7, s7, 1
	s_andn2_b32 s7, s7, 63
	s_sub_i32 s6, s6, s15
	v_or_b32_e32 v0, s7, v76
	s_lshl_b32 s6, s6, 5
	v_ashrrev_i32_e32 v1, 31, v0
	v_or_b32_e32 v6, 2, v0
	v_or_b32_e32 v8, 4, v0
	v_or_b32_e32 v10, 6, v0
	v_or_b32_e32 v12, 8, v0
	v_or_b32_e32 v14, 10, v0
	v_or_b32_e32 v16, 12, v0
	v_or_b32_e32 v18, 14, v0
	v_or_b32_e32 v20, 16, v0
	v_or_b32_e32 v22, 18, v0
	v_or_b32_e32 v24, 20, v0
	v_or_b32_e32 v26, 22, v0
	v_or_b32_e32 v28, 24, v0
	v_or_b32_e32 v30, 26, v0
	s_ashr_i32 s7, s6, 31
	v_lshlrev_b64 v[4:5], 12, v[0:1]
	v_ashrrev_i32_e32 v7, 31, v6
	v_ashrrev_i32_e32 v9, 31, v8
	v_ashrrev_i32_e32 v11, 31, v10
	v_ashrrev_i32_e32 v13, 31, v12
	v_ashrrev_i32_e32 v15, 31, v14
	v_ashrrev_i32_e32 v17, 31, v16
	v_ashrrev_i32_e32 v19, 31, v18
	v_ashrrev_i32_e32 v21, 31, v20
	v_ashrrev_i32_e32 v23, 31, v22
	v_ashrrev_i32_e32 v25, 31, v24
	v_ashrrev_i32_e32 v27, 31, v26
	v_ashrrev_i32_e32 v29, 31, v28
	v_ashrrev_i32_e32 v31, 31, v30
	v_or_b32_e32 v86, 28, v0
	v_or_b32_e32 v88, 30, v0
	v_or_b32_e32 v90, 32, v0
	v_or_b32_e32 v92, 34, v0
	v_or_b32_e32 v94, 36, v0
	v_or_b32_e32 v96, 38, v0
	v_or_b32_e32 v98, 40, v0
	v_or_b32_e32 v100, 42, v0
	v_or_b32_e32 v102, 44, v0
	v_or_b32_e32 v104, 46, v0
	v_or_b32_e32 v106, 48, v0
	v_or_b32_e32 v108, 50, v0
	v_or_b32_e32 v110, 52, v0
	v_or_b32_e32 v112, 54, v0
	v_or_b32_e32 v114, 56, v0
	v_or_b32_e32 v116, 58, v0
	v_or_b32_e32 v118, 60, v0
	v_or_b32_e32 v0, 62, v0
	v_lshl_add_u64 v[2:3], s[6:7], 2, v[38:39]
	v_lshlrev_b64 v[6:7], 12, v[6:7]
	v_lshlrev_b64 v[8:9], 12, v[8:9]
	v_lshlrev_b64 v[10:11], 12, v[10:11]
	v_lshlrev_b64 v[12:13], 12, v[12:13]
	v_lshlrev_b64 v[14:15], 12, v[14:15]
	v_lshlrev_b64 v[16:17], 12, v[16:17]
	v_lshlrev_b64 v[18:19], 12, v[18:19]
	v_lshlrev_b64 v[20:21], 12, v[20:21]
	v_lshlrev_b64 v[22:23], 12, v[22:23]
	v_lshlrev_b64 v[24:25], 12, v[24:25]
	v_lshlrev_b64 v[26:27], 12, v[26:27]
	v_lshlrev_b64 v[28:29], 12, v[28:29]
	v_lshlrev_b64 v[30:31], 12, v[30:31]
	v_ashrrev_i32_e32 v87, 31, v86
	v_ashrrev_i32_e32 v89, 31, v88
	v_ashrrev_i32_e32 v91, 31, v90
	v_ashrrev_i32_e32 v93, 31, v92
	v_ashrrev_i32_e32 v95, 31, v94
	v_ashrrev_i32_e32 v97, 31, v96
	v_ashrrev_i32_e32 v99, 31, v98
	v_ashrrev_i32_e32 v101, 31, v100
	v_ashrrev_i32_e32 v103, 31, v102
	v_ashrrev_i32_e32 v105, 31, v104
	v_ashrrev_i32_e32 v107, 31, v106
	v_ashrrev_i32_e32 v109, 31, v108
	v_ashrrev_i32_e32 v111, 31, v110
	v_ashrrev_i32_e32 v113, 31, v112
	v_ashrrev_i32_e32 v115, 31, v114
	v_ashrrev_i32_e32 v117, 31, v116
	v_ashrrev_i32_e32 v119, 31, v118
	v_ashrrev_i32_e32 v1, 31, v0
	v_lshl_add_u64 v[4:5], v[2:3], 0, v[4:5]
	v_lshl_add_u64 v[6:7], v[2:3], 0, v[6:7]
	v_lshl_add_u64 v[8:9], v[2:3], 0, v[8:9]
	v_lshl_add_u64 v[10:11], v[2:3], 0, v[10:11]
	v_lshl_add_u64 v[12:13], v[2:3], 0, v[12:13]
	v_lshl_add_u64 v[14:15], v[2:3], 0, v[14:15]
	v_lshl_add_u64 v[16:17], v[2:3], 0, v[16:17]
	v_lshl_add_u64 v[18:19], v[2:3], 0, v[18:19]
	v_lshl_add_u64 v[20:21], v[2:3], 0, v[20:21]
	v_lshl_add_u64 v[22:23], v[2:3], 0, v[22:23]
	v_lshl_add_u64 v[24:25], v[2:3], 0, v[24:25]
	v_lshl_add_u64 v[26:27], v[2:3], 0, v[26:27]
	v_lshl_add_u64 v[28:29], v[2:3], 0, v[28:29]
	v_lshl_add_u64 v[30:31], v[2:3], 0, v[30:31]
	v_lshlrev_b64 v[86:87], 12, v[86:87]
	v_lshlrev_b64 v[88:89], 12, v[88:89]
	v_lshlrev_b64 v[90:91], 12, v[90:91]
	v_lshlrev_b64 v[92:93], 12, v[92:93]
	v_lshlrev_b64 v[94:95], 12, v[94:95]
	v_lshlrev_b64 v[96:97], 12, v[96:97]
	v_lshlrev_b64 v[98:99], 12, v[98:99]
	v_lshlrev_b64 v[100:101], 12, v[100:101]
	v_lshlrev_b64 v[102:103], 12, v[102:103]
	v_lshlrev_b64 v[104:105], 12, v[104:105]
	v_lshlrev_b64 v[106:107], 12, v[106:107]
	v_lshlrev_b64 v[108:109], 12, v[108:109]
	v_lshlrev_b64 v[110:111], 12, v[110:111]
	v_lshlrev_b64 v[112:113], 12, v[112:113]
	v_lshlrev_b64 v[114:115], 12, v[114:115]
	v_lshlrev_b64 v[116:117], 12, v[116:117]
	v_lshlrev_b64 v[118:119], 12, v[118:119]
	v_lshlrev_b64 v[0:1], 12, v[0:1]
	v_lshl_add_u64 v[86:87], v[2:3], 0, v[86:87]
	v_lshl_add_u64 v[88:89], v[2:3], 0, v[88:89]
	v_lshl_add_u64 v[90:91], v[2:3], 0, v[90:91]
	v_lshl_add_u64 v[92:93], v[2:3], 0, v[92:93]
	v_lshl_add_u64 v[94:95], v[2:3], 0, v[94:95]
	v_lshl_add_u64 v[96:97], v[2:3], 0, v[96:97]
	v_lshl_add_u64 v[98:99], v[2:3], 0, v[98:99]
	v_lshl_add_u64 v[100:101], v[2:3], 0, v[100:101]
	v_lshl_add_u64 v[102:103], v[2:3], 0, v[102:103]
	v_lshl_add_u64 v[104:105], v[2:3], 0, v[104:105]
	v_lshl_add_u64 v[106:107], v[2:3], 0, v[106:107]
	v_lshl_add_u64 v[108:109], v[2:3], 0, v[108:109]
	v_lshl_add_u64 v[110:111], v[2:3], 0, v[110:111]
	v_lshl_add_u64 v[112:113], v[2:3], 0, v[112:113]
	v_lshl_add_u64 v[114:115], v[2:3], 0, v[114:115]
	v_lshl_add_u64 v[116:117], v[2:3], 0, v[116:117]
	v_lshl_add_u64 v[118:119], v[2:3], 0, v[118:119]
	v_lshl_add_u64 v[120:121], v[2:3], 0, v[0:1]
	global_load_dword v0, v[4:5], off nt
	global_load_dword v1, v[6:7], off nt
	global_load_dword v2, v[8:9], off nt
	global_load_dword v3, v[10:11], off nt
	s_nop 0
	global_load_dword v4, v[12:13], off nt
	global_load_dword v5, v[14:15], off nt
	global_load_dword v6, v[16:17], off nt
	global_load_dword v7, v[18:19], off nt
	global_load_dword v8, v[20:21], off nt
	global_load_dword v9, v[22:23], off nt
	global_load_dword v10, v[24:25], off nt
	global_load_dword v11, v[26:27], off nt
	global_load_dword v12, v[28:29], off nt
	global_load_dword v13, v[30:31], off nt
	global_load_dword v14, v[86:87], off nt
	global_load_dword v15, v[88:89], off nt
	global_load_dword v16, v[90:91], off nt
	global_load_dword v17, v[92:93], off nt
	global_load_dword v18, v[94:95], off nt
	global_load_dword v19, v[96:97], off nt
	global_load_dword v20, v[98:99], off nt
	global_load_dword v21, v[100:101], off nt
	global_load_dword v22, v[102:103], off nt
	global_load_dword v23, v[104:105], off nt
	global_load_dword v24, v[106:107], off nt
	global_load_dword v25, v[108:109], off nt
	global_load_dword v26, v[110:111], off nt
	global_load_dword v27, v[112:113], off nt
	global_load_dword v28, v[114:115], off nt
	global_load_dword v29, v[116:117], off nt
	global_load_dword v30, v[118:119], off nt
	global_load_dword v31, v[120:121], off nt
	s_branch .LBB7_48

.LBB7_59:
	s_mul_hi_i32 s50, s65, 0x2e8ba2e9
	s_lshr_b32 s51, s50, 31
	s_ashr_i32 s50, s50, 4
	s_add_i32 s50, s50, s51
	s_mul_i32 s51, s50, 0x58
	s_sub_i32 s51, s65, s51
	s_bfe_i32 s66, s51, 0x80000
	s_lshl_b32 s64, s51, 5
	s_bfe_u32 s66, s66, 0x2000d
	ds_write2_b32 v77, v43, v42 offset1:66
	ds_write2_b32 v77, v45, v44 offset0:132 offset1:198
	ds_write2_b32 v32, v47, v46 offset0:8 offset1:74
	ds_write2_b32 v32, v49, v48 offset0:140 offset1:206
	ds_write2_b32 v35, v51, v50 offset0:16 offset1:82
	ds_write2_b32 v35, v53, v52 offset0:148 offset1:214
	ds_write2_b32 v37, v55, v54 offset0:24 offset1:90
	ds_write2_b32 v37, v57, v56 offset0:156 offset1:222
	ds_write2_b32 v84, v59, v58 offset0:32 offset1:98
	ds_write2_b32 v84, v61, v60 offset0:164 offset1:230
	ds_write2_b32 v85, v63, v62 offset0:40 offset1:106
	ds_write2_b32 v85, v65, v64 offset0:172 offset1:238
	ds_write2_b32 v86, v67, v66 offset0:48 offset1:114
	ds_write2_b32 v86, v69, v68 offset0:180 offset1:246
	ds_write2_b32 v87, v71, v70 offset0:56 offset1:122
	ds_write2_b32 v87, v73, v72 offset0:188 offset1:254
	s_add_i32 s51, s51, s66
	s_sext_i32_i16 s66, s64
	s_waitcnt lgkmcnt(0)
	s_bfe_u32 s66, s66, 0x70018
	s_bfe_i32 s51, s51, 0x80000
	s_add_i32 s66, s64, s66
	ds_read2_b32 v[74:75], v79 offset1:33
	s_sext_i32_i16 s51, s51
	s_and_b32 s66, s66, 0xff80
	s_waitcnt lgkmcnt(0)
	v_cvt_pk_bf16_f32 v84, v74, v75
	ds_read2_b32 v[74:75], v79 offset0:66 offset1:99
	s_lshl_b32 s51, s51, 6
	s_sub_i32 s64, s64, s66
	s_and_b32 s51, s51, 0xffffff00
	s_waitcnt lgkmcnt(0)
	v_cvt_pk_bf16_f32 v85, v74, v75
	ds_read2_b32 v[74:75], v79 offset0:132 offset1:165
	s_sext_i32_i16 s64, s64
	s_waitcnt lgkmcnt(0)
	v_cvt_pk_bf16_f32 v86, v74, v75
	ds_read2_b32 v[74:75], v79 offset0:198 offset1:231
	s_add_i32 s66, s51, s64
	s_lshl_b32 s50, s50, 6
	s_waitcnt lgkmcnt(0)
	v_cvt_pk_bf16_f32 v87, v74, v75
	v_or_b32_e32 v74, s66, v78
	s_ashr_i32 s51, s50, 31
	v_ashrrev_i32_e32 v75, 31, v74
	v_lshl_add_u64 v[88:89], s[50:51], 1, v[40:41]
	v_lshlrev_b64 v[74:75], 11, v[74:75]
	v_lshl_add_u64 v[74:75], v[88:89], 0, v[74:75]
	ds_read2_b32 v[90:91], v79 offset0:8 offset1:41
	global_store_dwordx4 v[74:75], v[84:87], off nt
	s_add_i32 s64, s65, s72
	s_cmpk_gt_i32 s64, 0x57f
	s_waitcnt lgkmcnt(0)
	v_cvt_pk_bf16_f32 v84, v90, v91
	ds_read2_b32 v[74:75], v79 offset0:74 offset1:107
	s_waitcnt lgkmcnt(0)
	v_cvt_pk_bf16_f32 v85, v74, v75
	ds_read2_b32 v[74:75], v79 offset0:140 offset1:173
	s_waitcnt lgkmcnt(0)
	v_cvt_pk_bf16_f32 v86, v74, v75
	ds_read2_b32 v[74:75], v79 offset0:206 offset1:239
	s_waitcnt lgkmcnt(0)
	v_cvt_pk_bf16_f32 v87, v74, v75
	v_or_b32_e32 v74, s66, v80
	v_ashrrev_i32_e32 v75, 31, v74
	v_lshlrev_b64 v[74:75], 11, v[74:75]
	v_lshl_add_u64 v[74:75], v[88:89], 0, v[74:75]
	ds_read2_b32 v[90:91], v79 offset0:16 offset1:49
	global_store_dwordx4 v[74:75], v[84:87], off nt
	s_cselect_b64 s[50:51], -1, 0
	s_waitcnt lgkmcnt(0)
	v_cvt_pk_bf16_f32 v84, v90, v91
	ds_read2_b32 v[74:75], v79 offset0:82 offset1:115
	s_waitcnt lgkmcnt(0)
	v_cvt_pk_bf16_f32 v85, v74, v75
	ds_read2_b32 v[74:75], v79 offset0:148 offset1:181
	s_waitcnt lgkmcnt(0)
	v_cvt_pk_bf16_f32 v86, v74, v75
	ds_read2_b32 v[74:75], v79 offset0:214 offset1:247
	s_waitcnt lgkmcnt(0)
	v_cvt_pk_bf16_f32 v87, v74, v75
	v_or_b32_e32 v74, s66, v81
	v_ashrrev_i32_e32 v75, 31, v74
	v_lshlrev_b64 v[74:75], 11, v[74:75]
	v_lshl_add_u64 v[74:75], v[88:89], 0, v[74:75]
	ds_read2_b32 v[90:91], v79 offset0:24 offset1:57
	global_store_dwordx4 v[74:75], v[84:87], off nt
	s_waitcnt lgkmcnt(0)
	s_nop 0
	v_cvt_pk_bf16_f32 v84, v90, v91
	ds_read2_b32 v[74:75], v79 offset0:90 offset1:123
	s_waitcnt lgkmcnt(0)
	v_cvt_pk_bf16_f32 v85, v74, v75
	ds_read2_b32 v[74:75], v79 offset0:156 offset1:189
	s_waitcnt lgkmcnt(0)
	v_cvt_pk_bf16_f32 v86, v74, v75
	ds_read2_b32 v[74:75], v79 offset0:222 offset1:255
	s_waitcnt lgkmcnt(0)
	v_cvt_pk_bf16_f32 v87, v74, v75
	v_or_b32_e32 v74, s66, v82
	v_ashrrev_i32_e32 v75, 31, v74
	v_lshlrev_b64 v[74:75], 11, v[74:75]
	v_lshl_add_u64 v[74:75], v[88:89], 0, v[74:75]
	global_store_dwordx4 v[74:75], v[84:87], off nt
	s_waitcnt lgkmcnt(0)

.LBB7_64:
	s_mul_hi_i32 s66, s64, 0x2e8ba2e9
	s_lshr_b32 s67, s66, 31
	s_ashr_i32 s66, s66, 4
	s_add_i32 s66, s66, s67
	s_mul_i32 s67, s66, 0x58
	s_sub_i32 s67, s64, s67
	s_bfe_i32 s69, s67, 0x80000
	s_lshl_b32 s68, s67, 5
	v_add_u32_e32 v32, 0x400, v77
	v_add_u32_e32 v35, 0x800, v77
	v_add_u32_e32 v37, 0xc00, v77
	v_add_u32_e32 v84, 0x1000, v77
	v_add_u32_e32 v85, 0x1400, v77
	v_add_u32_e32 v86, 0x1800, v77
	v_add_u32_e32 v87, 0x1c00, v77
	s_bfe_u32 s69, s69, 0x2000d
	s_waitcnt vmcnt(30)
	ds_write2_b32 v77, v0, v1 offset1:66
	s_waitcnt vmcnt(28)
	ds_write2_b32 v77, v2, v3 offset0:132 offset1:198
	s_waitcnt vmcnt(26)
	ds_write2_b32 v32, v4, v5 offset0:8 offset1:74
	s_waitcnt vmcnt(24)
	ds_write2_b32 v32, v6, v7 offset0:140 offset1:206
	s_waitcnt vmcnt(22)
	ds_write2_b32 v35, v8, v9 offset0:16 offset1:82
	s_waitcnt vmcnt(20)
	ds_write2_b32 v35, v10, v11 offset0:148 offset1:214
	s_waitcnt vmcnt(18)
	ds_write2_b32 v37, v12, v13 offset0:24 offset1:90
	s_waitcnt vmcnt(16)
	ds_write2_b32 v37, v14, v15 offset0:156 offset1:222
	s_waitcnt vmcnt(14)
	ds_write2_b32 v84, v16, v17 offset0:32 offset1:98
	s_waitcnt vmcnt(12)
	ds_write2_b32 v84, v18, v19 offset0:164 offset1:230
	s_waitcnt vmcnt(10)
	ds_write2_b32 v85, v20, v21 offset0:40 offset1:106
	s_waitcnt vmcnt(8)
	ds_write2_b32 v85, v22, v23 offset0:172 offset1:238
	s_waitcnt vmcnt(6)
	ds_write2_b32 v86, v24, v25 offset0:48 offset1:114
	s_waitcnt vmcnt(4)
	ds_write2_b32 v86, v26, v27 offset0:180 offset1:246
	s_waitcnt vmcnt(2)
	ds_write2_b32 v87, v28, v29 offset0:56 offset1:122
	s_waitcnt vmcnt(0)
	ds_write2_b32 v87, v30, v31 offset0:188 offset1:254
	s_add_i32 s67, s67, s69
	s_sext_i32_i16 s69, s68
	s_waitcnt lgkmcnt(0)
	s_bfe_u32 s69, s69, 0x70018
	s_bfe_i32 s67, s67, 0x80000
	s_add_i32 s69, s68, s69
	ds_read2_b32 v[74:75], v79 offset1:33
	s_sext_i32_i16 s67, s67
	s_and_b32 s69, s69, 0xff80
	s_waitcnt lgkmcnt(0)
	v_cvt_pk_bf16_f32 v88, v74, v75
	ds_read2_b32 v[74:75], v79 offset0:66 offset1:99
	s_lshl_b32 s67, s67, 6
	s_sub_i32 s68, s68, s69
	s_and_b32 s67, s67, 0xffffff00
	s_waitcnt lgkmcnt(0)
	v_cvt_pk_bf16_f32 v89, v74, v75
	ds_read2_b32 v[74:75], v79 offset0:132 offset1:165
	s_sext_i32_i16 s68, s68
	s_waitcnt lgkmcnt(0)
	v_cvt_pk_bf16_f32 v90, v74, v75
	ds_read2_b32 v[74:75], v79 offset0:198 offset1:231
	s_add_i32 s68, s67, s68
	s_lshl_b32 s66, s66, 6
	s_waitcnt lgkmcnt(0)
	v_cvt_pk_bf16_f32 v91, v74, v75
	v_or_b32_e32 v74, s68, v78
	s_ashr_i32 s67, s66, 31
	v_ashrrev_i32_e32 v75, 31, v74
	v_lshl_add_u64 v[92:93], s[66:67], 1, v[40:41]
	v_lshlrev_b64 v[74:75], 11, v[74:75]
	v_lshl_add_u64 v[74:75], v[92:93], 0, v[74:75]
	ds_read2_b32 v[94:95], v79 offset0:8 offset1:41
	global_store_dwordx4 v[74:75], v[88:91], off nt
	s_andn2_b64 vcc, exec, s[50:51]
	s_mov_b64 s[50:51], -1
	s_waitcnt lgkmcnt(0)
	v_cvt_pk_bf16_f32 v88, v94, v95
	ds_read2_b32 v[74:75], v79 offset0:74 offset1:107
	s_waitcnt lgkmcnt(0)
	v_cvt_pk_bf16_f32 v89, v74, v75
	ds_read2_b32 v[74:75], v79 offset0:140 offset1:173
	s_waitcnt lgkmcnt(0)
	v_cvt_pk_bf16_f32 v90, v74, v75
	ds_read2_b32 v[74:75], v79 offset0:206 offset1:239
	s_waitcnt lgkmcnt(0)
	v_cvt_pk_bf16_f32 v91, v74, v75
	v_or_b32_e32 v74, s68, v80
	v_ashrrev_i32_e32 v75, 31, v74
	v_lshlrev_b64 v[74:75], 11, v[74:75]
	v_lshl_add_u64 v[74:75], v[92:93], 0, v[74:75]
	ds_read2_b32 v[94:95], v79 offset0:16 offset1:49
	global_store_dwordx4 v[74:75], v[88:91], off nt
	s_waitcnt lgkmcnt(0)
	s_nop 0
	v_cvt_pk_bf16_f32 v88, v94, v95
	ds_read2_b32 v[74:75], v79 offset0:82 offset1:115
	s_waitcnt lgkmcnt(0)
	v_cvt_pk_bf16_f32 v89, v74, v75
	ds_read2_b32 v[74:75], v79 offset0:148 offset1:181
	s_waitcnt lgkmcnt(0)
	v_cvt_pk_bf16_f32 v90, v74, v75
	ds_read2_b32 v[74:75], v79 offset0:214 offset1:247
	s_waitcnt lgkmcnt(0)
	v_cvt_pk_bf16_f32 v91, v74, v75
	v_or_b32_e32 v74, s68, v81
	v_ashrrev_i32_e32 v75, 31, v74
	v_lshlrev_b64 v[74:75], 11, v[74:75]
	v_lshl_add_u64 v[74:75], v[92:93], 0, v[74:75]
	ds_read2_b32 v[94:95], v79 offset0:24 offset1:57
	global_store_dwordx4 v[74:75], v[88:91], off nt
	s_waitcnt lgkmcnt(0)
	s_nop 0
	v_cvt_pk_bf16_f32 v88, v94, v95
	ds_read2_b32 v[74:75], v79 offset0:90 offset1:123
	s_waitcnt lgkmcnt(0)
	v_cvt_pk_bf16_f32 v89, v74, v75
	ds_read2_b32 v[74:75], v79 offset0:156 offset1:189
	s_waitcnt lgkmcnt(0)
	v_cvt_pk_bf16_f32 v90, v74, v75
	ds_read2_b32 v[74:75], v79 offset0:222 offset1:255
	s_waitcnt lgkmcnt(0)
	v_cvt_pk_bf16_f32 v91, v74, v75
	v_or_b32_e32 v74, s68, v82
	v_ashrrev_i32_e32 v75, 31, v74
	v_lshlrev_b64 v[74:75], 11, v[74:75]
	v_lshl_add_u64 v[74:75], v[92:93], 0, v[74:75]
	global_store_dwordx4 v[74:75], v[88:91], off nt
	s_waitcnt lgkmcnt(0)
	s_cbranch_vccnz .LBB7_60
	s_add_i32 s50, s55, s64
	s_cmpk_gt_i32 s50, 0x57f
	s_cbranch_scc1 .LBB7_59
	s_mul_hi_i32 s51, s50, 0x2e8ba2e9
	s_lshr_b32 s64, s51, 31
	s_ashr_i32 s51, s51, 4
	s_add_i32 s51, s51, s64
	s_mul_i32 s64, s51, 0x58
	s_sub_i32 s50, s50, s64
	s_lshl_b32 s50, s50, 5
	v_lshl_or_b32 v74, s51, 6, v76
	s_ashr_i32 s51, s50, 31
	v_lshl_add_u64 v[24:25], s[50:51], 2, v[38:39]
	v_or_b32_e32 v2, 2, v74
	v_or_b32_e32 v4, 4, v74
	v_or_b32_e32 v6, 6, v74
	v_or_b32_e32 v8, 8, v74
	v_or_b32_e32 v10, 10, v74
	v_or_b32_e32 v12, 12, v74
	v_or_b32_e32 v14, 14, v74
	v_mad_i64_i32 v[0:1], s[50:51], v74, s56, v[24:25]
	v_mad_i64_i32 v[2:3], s[50:51], v2, s56, v[24:25]
	v_mad_i64_i32 v[4:5], s[50:51], v4, s56, v[24:25]
	v_mad_i64_i32 v[6:7], s[50:51], v6, s56, v[24:25]
	v_mad_i64_i32 v[8:9], s[50:51], v8, s56, v[24:25]
	v_mad_i64_i32 v[10:11], s[50:51], v10, s56, v[24:25]
	v_mad_i64_i32 v[12:13], s[50:51], v12, s56, v[24:25]
	v_mad_i64_i32 v[14:15], s[50:51], v14, s56, v[24:25]
	global_load_dword v0, v[0:1], off nt
	s_nop 0
	global_load_dword v1, v[2:3], off nt
	s_nop 0
	global_load_dword v2, v[4:5], off nt
	global_load_dword v3, v[6:7], off nt
	s_nop 0
	global_load_dword v4, v[8:9], off nt
	global_load_dword v5, v[10:11], off nt
	global_load_dword v6, v[12:13], off nt
	global_load_dword v7, v[14:15], off nt
	v_or_b32_e32 v8, 16, v74
	v_or_b32_e32 v10, 18, v74
	v_or_b32_e32 v12, 20, v74
	v_or_b32_e32 v14, 22, v74
	v_or_b32_e32 v16, 24, v74
	v_or_b32_e32 v18, 26, v74
	v_or_b32_e32 v20, 28, v74
	v_or_b32_e32 v22, 30, v74
	v_mad_i64_i32 v[8:9], s[50:51], v8, s56, v[24:25]
	v_mad_i64_i32 v[10:11], s[50:51], v10, s56, v[24:25]
	v_mad_i64_i32 v[12:13], s[50:51], v12, s56, v[24:25]
	v_mad_i64_i32 v[14:15], s[50:51], v14, s56, v[24:25]
	v_mad_i64_i32 v[16:17], s[50:51], v16, s56, v[24:25]
	v_mad_i64_i32 v[18:19], s[50:51], v18, s56, v[24:25]
	v_mad_i64_i32 v[20:21], s[50:51], v20, s56, v[24:25]
	v_mad_i64_i32 v[22:23], s[50:51], v22, s56, v[24:25]
	global_load_dword v8, v[8:9], off nt
	s_nop 0
	global_load_dword v9, v[10:11], off nt
	s_nop 0
	global_load_dword v10, v[12:13], off nt
	global_load_dword v11, v[14:15], off nt
	s_nop 0
	global_load_dword v12, v[16:17], off nt
	global_load_dword v13, v[18:19], off nt
	global_load_dword v14, v[20:21], off nt
	global_load_dword v15, v[22:23], off nt
	v_or_b32_e32 v16, 32, v74
	v_or_b32_e32 v18, 34, v74
	v_or_b32_e32 v20, 36, v74
	v_or_b32_e32 v22, 38, v74
	v_or_b32_e32 v75, 46, v74
	v_mad_i64_i32 v[16:17], s[50:51], v16, s56, v[24:25]
	v_mad_i64_i32 v[18:19], s[50:51], v18, s56, v[24:25]
	v_mad_i64_i32 v[20:21], s[50:51], v20, s56, v[24:25]
	v_mad_i64_i32 v[22:23], s[50:51], v22, s56, v[24:25]
	v_or_b32_e32 v26, 40, v74
	v_or_b32_e32 v28, 42, v74
	v_or_b32_e32 v30, 44, v74
	v_mad_i64_i32 v[88:89], s[50:51], v75, s56, v[24:25]
	v_or_b32_e32 v75, 54, v74
	v_mad_i64_i32 v[26:27], s[50:51], v26, s56, v[24:25]
	v_mad_i64_i32 v[28:29], s[50:51], v28, s56, v[24:25]
	v_mad_i64_i32 v[30:31], s[50:51], v30, s56, v[24:25]
	global_load_dword v16, v[16:17], off nt
	s_nop 0
	global_load_dword v17, v[18:19], off nt
	s_nop 0
	global_load_dword v18, v[20:21], off nt
	global_load_dword v19, v[22:23], off nt
	s_nop 0
	global_load_dword v20, v[26:27], off nt
	global_load_dword v21, v[28:29], off nt
	global_load_dword v22, v[30:31], off nt
	global_load_dword v23, v[88:89], off nt
	v_mad_i64_i32 v[88:89], s[50:51], v75, s56, v[24:25]
	v_or_b32_e32 v75, 56, v74
	v_mad_i64_i32 v[90:91], s[50:51], v75, s56, v[24:25]
	v_or_b32_e32 v75, 58, v74
	v_or_b32_e32 v26, 48, v74
	v_or_b32_e32 v28, 50, v74
	v_or_b32_e32 v30, 52, v74
	v_mad_i64_i32 v[92:93], s[50:51], v75, s56, v[24:25]
	v_or_b32_e32 v75, 60, v74
	v_mad_i64_i32 v[26:27], s[50:51], v26, s56, v[24:25]
	v_mad_i64_i32 v[28:29], s[50:51], v28, s56, v[24:25]
	v_mad_i64_i32 v[30:31], s[50:51], v30, s56, v[24:25]
	v_mad_i64_i32 v[94:95], s[50:51], v75, s56, v[24:25]
	v_or_b32_e32 v75, 62, v74
	v_mad_i64_i32 v[96:97], s[50:51], v75, s56, v[24:25]
	global_load_dword v24, v[26:27], off nt
	global_load_dword v25, v[28:29], off nt
	s_nop 0
	global_load_dword v26, v[30:31], off nt
	global_load_dword v27, v[88:89], off nt
	global_load_dword v28, v[90:91], off nt
	global_load_dword v29, v[92:93], off nt
	s_nop 0
	global_load_dword v30, v[94:95], off nt
	global_load_dword v31, v[96:97], off nt
	s_andn2_b64 vcc, exec, s[48:49]
	s_cbranch_vccnz .LBB7_59
	v_ashrrev_i32_e32 v75, 31, v74
	v_lshl_add_u64 v[74:75], v[74:75], 2, s[6:7]
	global_load_dword v88, v[74:75], off
	global_load_dword v89, v[74:75], off offset:8
	global_load_dword v90, v[74:75], off offset:16
	global_load_dword v91, v[74:75], off offset:24
	global_load_dword v92, v[74:75], off offset:32
	global_load_dword v93, v[74:75], off offset:40
	global_load_dword v94, v[74:75], off offset:48
	global_load_dword v95, v[74:75], off offset:56
	global_load_dword v96, v[74:75], off offset:64
	global_load_dword v97, v[74:75], off offset:72
	global_load_dword v98, v[74:75], off offset:80
	global_load_dword v99, v[74:75], off offset:88
	global_load_dword v100, v[74:75], off offset:96
	global_load_dword v101, v[74:75], off offset:104
	global_load_dword v102, v[74:75], off offset:112
	global_load_dword v103, v[74:75], off offset:120
	global_load_dword v104, v[74:75], off offset:128
	global_load_dword v105, v[74:75], off offset:136
	global_load_dword v106, v[74:75], off offset:144
	global_load_dword v107, v[74:75], off offset:152
	global_load_dword v108, v[74:75], off offset:160
	global_load_dword v109, v[74:75], off offset:168
	global_load_dword v110, v[74:75], off offset:176
	global_load_dword v111, v[74:75], off offset:184
	global_load_dword v112, v[74:75], off offset:192
	global_load_dword v113, v[74:75], off offset:200
	global_load_dword v114, v[74:75], off offset:208
	global_load_dword v115, v[74:75], off offset:216
	global_load_dword v116, v[74:75], off offset:224
	global_load_dword v117, v[74:75], off offset:232
	global_load_dword v118, v[74:75], off offset:240
	global_load_dword v119, v[74:75], off offset:248
	s_waitcnt vmcnt(30)
	v_pk_mul_f32 v[0:1], v[0:1], v[88:89]
	s_waitcnt vmcnt(28)
	v_pk_mul_f32 v[2:3], v[2:3], v[90:91]
	s_waitcnt vmcnt(26)
	v_pk_mul_f32 v[4:5], v[4:5], v[92:93]
	s_waitcnt vmcnt(24)
	v_pk_mul_f32 v[6:7], v[6:7], v[94:95]
	s_waitcnt vmcnt(22)
	v_pk_mul_f32 v[8:9], v[8:9], v[96:97]
	s_waitcnt vmcnt(20)
	v_pk_mul_f32 v[10:11], v[10:11], v[98:99]
	s_waitcnt vmcnt(18)
	v_pk_mul_f32 v[12:13], v[12:13], v[100:101]
	s_waitcnt vmcnt(16)
	v_pk_mul_f32 v[14:15], v[14:15], v[102:103]
	s_waitcnt vmcnt(14)
	v_pk_mul_f32 v[16:17], v[16:17], v[104:105]
	s_waitcnt vmcnt(12)
	v_pk_mul_f32 v[18:19], v[18:19], v[106:107]
	s_waitcnt vmcnt(10)
	v_pk_mul_f32 v[20:21], v[20:21], v[108:109]
	s_waitcnt vmcnt(8)
	v_pk_mul_f32 v[22:23], v[22:23], v[110:111]
	s_waitcnt vmcnt(6)
	v_pk_mul_f32 v[24:25], v[24:25], v[112:113]
	s_waitcnt vmcnt(4)
	v_pk_mul_f32 v[26:27], v[26:27], v[114:115]
	s_waitcnt vmcnt(2)
	v_pk_mul_f32 v[28:29], v[28:29], v[116:117]
	s_waitcnt vmcnt(0)
	v_pk_mul_f32 v[30:31], v[30:31], v[118:119]
	s_branch .LBB7_59

.LBB7_72:
	s_mul_hi_i32 s12, s14, 0x2e8ba2e9
	s_lshr_b32 s13, s12, 31
	s_ashr_i32 s12, s12, 4
	s_add_i32 s12, s12, s13
	s_mul_i32 s13, s12, 0x58
	s_sub_i32 s13, s14, s13
	s_bfe_i32 s50, s13, 0x80000
	s_lshl_b32 s15, s13, 5
	s_bfe_u32 s50, s50, 0x2000d
	s_add_i32 s13, s13, s50
	s_sext_i32_i16 s50, s15
	ds_write2_b32 v77, v43, v42 offset1:66
	ds_write2_b32 v77, v45, v44 offset0:132 offset1:198
	ds_write2_b32 v32, v47, v46 offset0:8 offset1:74
	ds_write2_b32 v32, v49, v48 offset0:140 offset1:206
	ds_write2_b32 v35, v51, v50 offset0:16 offset1:82
	ds_write2_b32 v35, v53, v52 offset0:148 offset1:214
	ds_write2_b32 v37, v55, v54 offset0:24 offset1:90
	ds_write2_b32 v37, v57, v56 offset0:156 offset1:222
	ds_write2_b32 v84, v59, v58 offset0:32 offset1:98
	ds_write2_b32 v84, v61, v60 offset0:164 offset1:230
	ds_write2_b32 v85, v63, v62 offset0:40 offset1:106
	ds_write2_b32 v85, v65, v64 offset0:172 offset1:238
	ds_write2_b32 v86, v67, v66 offset0:48 offset1:114
	ds_write2_b32 v86, v69, v68 offset0:180 offset1:246
	ds_write2_b32 v87, v71, v70 offset0:56 offset1:122
	ds_write2_b32 v87, v73, v72 offset0:188 offset1:254
	s_bfe_u32 s50, s50, 0x70018
	s_waitcnt lgkmcnt(0)
	s_add_i32 s50, s15, s50
	s_bfe_i32 s13, s13, 0x80000
	s_and_b32 s50, s50, 0xff80
	ds_read2_b32 v[74:75], v79 offset1:33
	s_sext_i32_i16 s13, s13
	s_sub_i32 s15, s15, s50
	s_waitcnt lgkmcnt(0)
	v_cvt_pk_bf16_f32 v84, v74, v75
	ds_read2_b32 v[74:75], v79 offset0:66 offset1:99
	s_lshl_b32 s13, s13, 6
	s_addk_i32 s15, 0x80
	s_and_b32 s13, s13, 0xffffff00
	s_waitcnt lgkmcnt(0)
	v_cvt_pk_bf16_f32 v85, v74, v75
	ds_read2_b32 v[74:75], v79 offset0:132 offset1:165
	s_and_b32 s15, s15, 0xffe0
	s_waitcnt lgkmcnt(0)
	v_cvt_pk_bf16_f32 v86, v74, v75
	ds_read2_b32 v[74:75], v79 offset0:198 offset1:231
	s_add_i32 s15, s13, s15
	s_lshl_b32 s12, s12, 6
	s_waitcnt lgkmcnt(0)
	v_cvt_pk_bf16_f32 v87, v74, v75
	v_or_b32_e32 v74, s15, v78
	s_ashr_i32 s13, s12, 31
	v_ashrrev_i32_e32 v75, 31, v74
	v_lshl_add_u64 v[88:89], s[12:13], 1, v[40:41]
	v_lshlrev_b64 v[74:75], 11, v[74:75]
	v_lshl_add_u64 v[74:75], v[88:89], 0, v[74:75]
	ds_read2_b32 v[90:91], v79 offset0:8 offset1:41
	global_store_dwordx4 v[74:75], v[84:87], off nt
	s_add_i32 s64, s14, s72
	s_cmpk_gt_i32 s64, 0x57f
	s_waitcnt lgkmcnt(0)
	v_cvt_pk_bf16_f32 v84, v90, v91
	ds_read2_b32 v[74:75], v79 offset0:74 offset1:107
	s_waitcnt lgkmcnt(0)
	v_cvt_pk_bf16_f32 v85, v74, v75
	ds_read2_b32 v[74:75], v79 offset0:140 offset1:173
	s_waitcnt lgkmcnt(0)
	v_cvt_pk_bf16_f32 v86, v74, v75
	ds_read2_b32 v[74:75], v79 offset0:206 offset1:239
	s_waitcnt lgkmcnt(0)
	v_cvt_pk_bf16_f32 v87, v74, v75
	v_or_b32_e32 v74, s15, v80
	v_ashrrev_i32_e32 v75, 31, v74
	v_lshlrev_b64 v[74:75], 11, v[74:75]
	v_lshl_add_u64 v[74:75], v[88:89], 0, v[74:75]
	ds_read2_b32 v[90:91], v79 offset0:16 offset1:49
	global_store_dwordx4 v[74:75], v[84:87], off nt
	s_cselect_b64 s[12:13], -1, 0
	s_waitcnt lgkmcnt(0)
	v_cvt_pk_bf16_f32 v84, v90, v91
	ds_read2_b32 v[74:75], v79 offset0:82 offset1:115
	s_waitcnt lgkmcnt(0)
	v_cvt_pk_bf16_f32 v85, v74, v75
	ds_read2_b32 v[74:75], v79 offset0:148 offset1:181
	s_waitcnt lgkmcnt(0)
	v_cvt_pk_bf16_f32 v86, v74, v75
	ds_read2_b32 v[74:75], v79 offset0:214 offset1:247
	s_waitcnt lgkmcnt(0)
	v_cvt_pk_bf16_f32 v87, v74, v75
	v_or_b32_e32 v74, s15, v81
	v_ashrrev_i32_e32 v75, 31, v74
	v_lshlrev_b64 v[74:75], 11, v[74:75]
	v_lshl_add_u64 v[74:75], v[88:89], 0, v[74:75]
	ds_read2_b32 v[90:91], v79 offset0:24 offset1:57
	global_store_dwordx4 v[74:75], v[84:87], off nt
	s_waitcnt lgkmcnt(0)
	s_nop 0
	v_cvt_pk_bf16_f32 v84, v90, v91
	ds_read2_b32 v[74:75], v79 offset0:90 offset1:123
	s_waitcnt lgkmcnt(0)
	v_cvt_pk_bf16_f32 v85, v74, v75
	ds_read2_b32 v[74:75], v79 offset0:156 offset1:189
	s_waitcnt lgkmcnt(0)
	v_cvt_pk_bf16_f32 v86, v74, v75
	ds_read2_b32 v[74:75], v79 offset0:222 offset1:255
	s_waitcnt lgkmcnt(0)
	v_cvt_pk_bf16_f32 v87, v74, v75
	v_or_b32_e32 v74, s15, v82
	v_ashrrev_i32_e32 v75, 31, v74
	v_lshlrev_b64 v[74:75], 11, v[74:75]
	v_lshl_add_u64 v[74:75], v[88:89], 0, v[74:75]
	global_store_dwordx4 v[74:75], v[84:87], off nt
	s_waitcnt lgkmcnt(0)

.LBB7_77:
	s_mul_hi_i32 s15, s64, 0x2e8ba2e9
	s_lshr_b32 s50, s15, 31
	s_ashr_i32 s15, s15, 4
	s_add_i32 s15, s15, s50
	s_mul_i32 s50, s15, 0x58
	s_sub_i32 s51, s64, s50
	s_bfe_i32 s65, s51, 0x80000
	s_lshl_b32 s50, s15, 6
	s_lshl_b32 s15, s51, 5
	s_bfe_u32 s65, s65, 0x2000d
	v_add_u32_e32 v32, 0x400, v77
	v_add_u32_e32 v35, 0x800, v77
	v_add_u32_e32 v37, 0xc00, v77
	v_add_u32_e32 v84, 0x1000, v77
	v_add_u32_e32 v85, 0x1400, v77
	v_add_u32_e32 v86, 0x1800, v77
	v_add_u32_e32 v87, 0x1c00, v77
	s_add_i32 s51, s51, s65
	s_sext_i32_i16 s65, s15
	s_waitcnt vmcnt(30)
	ds_write2_b32 v77, v0, v1 offset1:66
	s_waitcnt vmcnt(28)
	ds_write2_b32 v77, v2, v3 offset0:132 offset1:198
	s_waitcnt vmcnt(26)
	ds_write2_b32 v32, v4, v5 offset0:8 offset1:74
	s_waitcnt vmcnt(24)
	ds_write2_b32 v32, v6, v7 offset0:140 offset1:206
	s_waitcnt vmcnt(22)
	ds_write2_b32 v35, v8, v9 offset0:16 offset1:82
	s_waitcnt vmcnt(20)
	ds_write2_b32 v35, v10, v11 offset0:148 offset1:214
	s_waitcnt vmcnt(18)
	ds_write2_b32 v37, v12, v13 offset0:24 offset1:90
	s_waitcnt vmcnt(16)
	ds_write2_b32 v37, v14, v15 offset0:156 offset1:222
	s_waitcnt vmcnt(14)
	ds_write2_b32 v84, v16, v17 offset0:32 offset1:98
	s_waitcnt vmcnt(12)
	ds_write2_b32 v84, v18, v19 offset0:164 offset1:230
	s_waitcnt vmcnt(10)
	ds_write2_b32 v85, v20, v21 offset0:40 offset1:106
	s_waitcnt vmcnt(8)
	ds_write2_b32 v85, v22, v23 offset0:172 offset1:238
	s_waitcnt vmcnt(6)
	ds_write2_b32 v86, v24, v25 offset0:48 offset1:114
	s_waitcnt vmcnt(4)
	ds_write2_b32 v86, v26, v27 offset0:180 offset1:246
	s_waitcnt vmcnt(2)
	ds_write2_b32 v87, v28, v29 offset0:56 offset1:122
	s_waitcnt vmcnt(0)
	ds_write2_b32 v87, v30, v31 offset0:188 offset1:254
	s_bfe_u32 s65, s65, 0x70018
	s_waitcnt lgkmcnt(0)
	s_add_i32 s65, s15, s65
	s_bfe_i32 s51, s51, 0x80000
	s_and_b32 s65, s65, 0xff80
	ds_read2_b32 v[74:75], v79 offset1:33
	s_sext_i32_i16 s51, s51
	s_sub_i32 s15, s15, s65
	s_waitcnt lgkmcnt(0)
	v_cvt_pk_bf16_f32 v88, v74, v75
	ds_read2_b32 v[74:75], v79 offset0:66 offset1:99
	s_lshl_b32 s51, s51, 6
	s_addk_i32 s15, 0x80
	s_and_b32 s51, s51, 0xffffff00
	s_waitcnt lgkmcnt(0)
	v_cvt_pk_bf16_f32 v89, v74, v75
	ds_read2_b32 v[74:75], v79 offset0:132 offset1:165
	s_and_b32 s15, s15, 0xffe0
	s_waitcnt lgkmcnt(0)
	v_cvt_pk_bf16_f32 v90, v74, v75
	ds_read2_b32 v[74:75], v79 offset0:198 offset1:231
	s_add_i32 s15, s51, s15
	s_waitcnt lgkmcnt(0)
	v_cvt_pk_bf16_f32 v91, v74, v75
	v_or_b32_e32 v74, s15, v78
	s_ashr_i32 s51, s50, 31
	v_ashrrev_i32_e32 v75, 31, v74
	v_lshl_add_u64 v[92:93], s[50:51], 1, v[40:41]
	v_lshlrev_b64 v[74:75], 11, v[74:75]
	v_lshl_add_u64 v[74:75], v[92:93], 0, v[74:75]
	ds_read2_b32 v[94:95], v79 offset0:8 offset1:41
	global_store_dwordx4 v[74:75], v[88:91], off nt
	s_andn2_b64 vcc, exec, s[12:13]
	s_mov_b64 s[12:13], -1
	s_waitcnt lgkmcnt(0)
	v_cvt_pk_bf16_f32 v88, v94, v95
	ds_read2_b32 v[74:75], v79 offset0:74 offset1:107
	s_waitcnt lgkmcnt(0)
	v_cvt_pk_bf16_f32 v89, v74, v75
	ds_read2_b32 v[74:75], v79 offset0:140 offset1:173
	s_waitcnt lgkmcnt(0)
	v_cvt_pk_bf16_f32 v90, v74, v75
	ds_read2_b32 v[74:75], v79 offset0:206 offset1:239
	s_waitcnt lgkmcnt(0)
	v_cvt_pk_bf16_f32 v91, v74, v75
	v_or_b32_e32 v74, s15, v80
	v_ashrrev_i32_e32 v75, 31, v74
	v_lshlrev_b64 v[74:75], 11, v[74:75]
	v_lshl_add_u64 v[74:75], v[92:93], 0, v[74:75]
	ds_read2_b32 v[94:95], v79 offset0:16 offset1:49
	global_store_dwordx4 v[74:75], v[88:91], off nt
	s_waitcnt lgkmcnt(0)
	s_nop 0
	v_cvt_pk_bf16_f32 v88, v94, v95
	ds_read2_b32 v[74:75], v79 offset0:82 offset1:115
	s_waitcnt lgkmcnt(0)
	v_cvt_pk_bf16_f32 v89, v74, v75
	ds_read2_b32 v[74:75], v79 offset0:148 offset1:181
	s_waitcnt lgkmcnt(0)
	v_cvt_pk_bf16_f32 v90, v74, v75
	ds_read2_b32 v[74:75], v79 offset0:214 offset1:247
	s_waitcnt lgkmcnt(0)
	v_cvt_pk_bf16_f32 v91, v74, v75
	v_or_b32_e32 v74, s15, v81
	v_ashrrev_i32_e32 v75, 31, v74
	v_lshlrev_b64 v[74:75], 11, v[74:75]
	v_lshl_add_u64 v[74:75], v[92:93], 0, v[74:75]
	ds_read2_b32 v[94:95], v79 offset0:24 offset1:57
	global_store_dwordx4 v[74:75], v[88:91], off nt
	s_waitcnt lgkmcnt(0)
	s_nop 0
	v_cvt_pk_bf16_f32 v88, v94, v95
	ds_read2_b32 v[74:75], v79 offset0:90 offset1:123
	s_waitcnt lgkmcnt(0)
	v_cvt_pk_bf16_f32 v89, v74, v75
	ds_read2_b32 v[74:75], v79 offset0:156 offset1:189
	s_waitcnt lgkmcnt(0)
	v_cvt_pk_bf16_f32 v90, v74, v75
	ds_read2_b32 v[74:75], v79 offset0:222 offset1:255
	s_waitcnt lgkmcnt(0)
	v_cvt_pk_bf16_f32 v91, v74, v75
	v_or_b32_e32 v74, s15, v82
	v_ashrrev_i32_e32 v75, 31, v74
	v_lshlrev_b64 v[74:75], 11, v[74:75]
	v_lshl_add_u64 v[74:75], v[92:93], 0, v[74:75]
	global_store_dwordx4 v[74:75], v[88:91], off nt
	s_waitcnt lgkmcnt(0)
	s_cbranch_vccnz .LBB7_73
	s_add_i32 s12, s55, s64
	s_cmpk_gt_i32 s12, 0x57f
	s_cbranch_scc1 .LBB7_72
	s_mul_hi_i32 s13, s12, 0x2e8ba2e9
	s_lshr_b32 s15, s13, 31
	s_ashr_i32 s13, s13, 4
	s_add_i32 s13, s13, s15
	s_mul_i32 s15, s13, 0x58
	s_sub_i32 s12, s12, s15
	s_lshl_b32 s12, s12, 5
	v_lshl_or_b32 v74, s13, 6, v76
	s_ashr_i32 s13, s12, 31
	v_lshl_add_u64 v[24:25], s[12:13], 2, v[38:39]
	v_or_b32_e32 v2, 2, v74
	v_or_b32_e32 v4, 4, v74
	v_or_b32_e32 v6, 6, v74
	v_or_b32_e32 v8, 8, v74
	v_or_b32_e32 v10, 10, v74
	v_or_b32_e32 v12, 12, v74
	v_or_b32_e32 v14, 14, v74
	v_mad_i64_i32 v[0:1], s[12:13], v74, s56, v[24:25]
	v_mad_i64_i32 v[2:3], s[12:13], v2, s56, v[24:25]
	v_mad_i64_i32 v[4:5], s[12:13], v4, s56, v[24:25]
	v_mad_i64_i32 v[6:7], s[12:13], v6, s56, v[24:25]
	v_mad_i64_i32 v[8:9], s[12:13], v8, s56, v[24:25]
	v_mad_i64_i32 v[10:11], s[12:13], v10, s56, v[24:25]
	v_mad_i64_i32 v[12:13], s[12:13], v12, s56, v[24:25]
	v_mad_i64_i32 v[14:15], s[12:13], v14, s56, v[24:25]
	global_load_dword v0, v[0:1], off nt
	s_nop 0
	global_load_dword v1, v[2:3], off nt
	s_nop 0
	global_load_dword v2, v[4:5], off nt
	global_load_dword v3, v[6:7], off nt
	s_nop 0
	global_load_dword v4, v[8:9], off nt
	global_load_dword v5, v[10:11], off nt
	global_load_dword v6, v[12:13], off nt
	global_load_dword v7, v[14:15], off nt
	v_or_b32_e32 v8, 16, v74
	v_or_b32_e32 v10, 18, v74
	v_or_b32_e32 v12, 20, v74
	v_or_b32_e32 v14, 22, v74
	v_or_b32_e32 v16, 24, v74
	v_or_b32_e32 v18, 26, v74
	v_or_b32_e32 v20, 28, v74
	v_or_b32_e32 v22, 30, v74
	v_mad_i64_i32 v[8:9], s[12:13], v8, s56, v[24:25]
	v_mad_i64_i32 v[10:11], s[12:13], v10, s56, v[24:25]
	v_mad_i64_i32 v[12:13], s[12:13], v12, s56, v[24:25]
	v_mad_i64_i32 v[14:15], s[12:13], v14, s56, v[24:25]
	v_mad_i64_i32 v[16:17], s[12:13], v16, s56, v[24:25]
	v_mad_i64_i32 v[18:19], s[12:13], v18, s56, v[24:25]
	v_mad_i64_i32 v[20:21], s[12:13], v20, s56, v[24:25]
	v_mad_i64_i32 v[22:23], s[12:13], v22, s56, v[24:25]
	global_load_dword v8, v[8:9], off nt
	s_nop 0
	global_load_dword v9, v[10:11], off nt
	s_nop 0
	global_load_dword v10, v[12:13], off nt
	global_load_dword v11, v[14:15], off nt
	s_nop 0
	global_load_dword v12, v[16:17], off nt
	global_load_dword v13, v[18:19], off nt
	global_load_dword v14, v[20:21], off nt
	global_load_dword v15, v[22:23], off nt
	v_or_b32_e32 v16, 32, v74
	v_or_b32_e32 v18, 34, v74
	v_or_b32_e32 v20, 36, v74
	v_or_b32_e32 v22, 38, v74
	v_or_b32_e32 v75, 46, v74
	v_mad_i64_i32 v[16:17], s[12:13], v16, s56, v[24:25]
	v_mad_i64_i32 v[18:19], s[12:13], v18, s56, v[24:25]
	v_mad_i64_i32 v[20:21], s[12:13], v20, s56, v[24:25]
	v_mad_i64_i32 v[22:23], s[12:13], v22, s56, v[24:25]
	v_or_b32_e32 v26, 40, v74
	v_or_b32_e32 v28, 42, v74
	v_or_b32_e32 v30, 44, v74
	v_mad_i64_i32 v[88:89], s[12:13], v75, s56, v[24:25]
	v_or_b32_e32 v75, 54, v74
	v_mad_i64_i32 v[26:27], s[12:13], v26, s56, v[24:25]
	v_mad_i64_i32 v[28:29], s[12:13], v28, s56, v[24:25]
	v_mad_i64_i32 v[30:31], s[12:13], v30, s56, v[24:25]
	global_load_dword v16, v[16:17], off nt
	s_nop 0
	global_load_dword v17, v[18:19], off nt
	s_nop 0
	global_load_dword v18, v[20:21], off nt
	global_load_dword v19, v[22:23], off nt
	s_nop 0
	global_load_dword v20, v[26:27], off nt
	global_load_dword v21, v[28:29], off nt
	global_load_dword v22, v[30:31], off nt
	global_load_dword v23, v[88:89], off nt
	v_mad_i64_i32 v[88:89], s[12:13], v75, s56, v[24:25]
	v_or_b32_e32 v75, 56, v74
	v_mad_i64_i32 v[90:91], s[12:13], v75, s56, v[24:25]
	v_or_b32_e32 v75, 58, v74
	v_or_b32_e32 v26, 48, v74
	v_or_b32_e32 v28, 50, v74
	v_or_b32_e32 v30, 52, v74
	v_mad_i64_i32 v[92:93], s[12:13], v75, s56, v[24:25]
	v_or_b32_e32 v75, 60, v74
	v_mad_i64_i32 v[26:27], s[12:13], v26, s56, v[24:25]
	v_mad_i64_i32 v[28:29], s[12:13], v28, s56, v[24:25]
	v_mad_i64_i32 v[30:31], s[12:13], v30, s56, v[24:25]
	v_mad_i64_i32 v[94:95], s[12:13], v75, s56, v[24:25]
	v_or_b32_e32 v75, 62, v74
	v_mad_i64_i32 v[96:97], s[12:13], v75, s56, v[24:25]
	global_load_dword v24, v[26:27], off nt
	global_load_dword v25, v[28:29], off nt
	s_nop 0
	global_load_dword v26, v[30:31], off nt
	global_load_dword v27, v[88:89], off nt
	global_load_dword v28, v[90:91], off nt
	global_load_dword v29, v[92:93], off nt
	s_nop 0
	global_load_dword v30, v[94:95], off nt
	global_load_dword v31, v[96:97], off nt
	s_andn2_b64 vcc, exec, s[48:49]
	s_cbranch_vccnz .LBB7_72
	v_ashrrev_i32_e32 v75, 31, v74
	v_lshl_add_u64 v[74:75], v[74:75], 2, s[6:7]
	global_load_dword v88, v[74:75], off
	global_load_dword v89, v[74:75], off offset:8
	global_load_dword v90, v[74:75], off offset:16
	global_load_dword v91, v[74:75], off offset:24
	global_load_dword v92, v[74:75], off offset:32
	global_load_dword v93, v[74:75], off offset:40
	global_load_dword v94, v[74:75], off offset:48
	global_load_dword v95, v[74:75], off offset:56
	global_load_dword v96, v[74:75], off offset:64
	global_load_dword v97, v[74:75], off offset:72
	global_load_dword v98, v[74:75], off offset:80
	global_load_dword v99, v[74:75], off offset:88
	global_load_dword v100, v[74:75], off offset:96
	global_load_dword v101, v[74:75], off offset:104
	global_load_dword v102, v[74:75], off offset:112
	global_load_dword v103, v[74:75], off offset:120
	global_load_dword v104, v[74:75], off offset:128
	global_load_dword v105, v[74:75], off offset:136
	global_load_dword v106, v[74:75], off offset:144
	global_load_dword v107, v[74:75], off offset:152
	global_load_dword v108, v[74:75], off offset:160
	global_load_dword v109, v[74:75], off offset:168
	global_load_dword v110, v[74:75], off offset:176
	global_load_dword v111, v[74:75], off offset:184
	global_load_dword v112, v[74:75], off offset:192
	global_load_dword v113, v[74:75], off offset:200
	global_load_dword v114, v[74:75], off offset:208
	global_load_dword v115, v[74:75], off offset:216
	global_load_dword v116, v[74:75], off offset:224
	global_load_dword v117, v[74:75], off offset:232
	global_load_dword v118, v[74:75], off offset:240
	global_load_dword v119, v[74:75], off offset:248
	s_waitcnt vmcnt(30)
	v_pk_mul_f32 v[0:1], v[0:1], v[88:89]
	s_waitcnt vmcnt(28)
	v_pk_mul_f32 v[2:3], v[2:3], v[90:91]
	s_waitcnt vmcnt(26)
	v_pk_mul_f32 v[4:5], v[4:5], v[92:93]
	s_waitcnt vmcnt(24)
	v_pk_mul_f32 v[6:7], v[6:7], v[94:95]
	s_waitcnt vmcnt(22)
	v_pk_mul_f32 v[8:9], v[8:9], v[96:97]
	s_waitcnt vmcnt(20)
	v_pk_mul_f32 v[10:11], v[10:11], v[98:99]
	s_waitcnt vmcnt(18)
	v_pk_mul_f32 v[12:13], v[12:13], v[100:101]
	s_waitcnt vmcnt(16)
	v_pk_mul_f32 v[14:15], v[14:15], v[102:103]
	s_waitcnt vmcnt(14)
	v_pk_mul_f32 v[16:17], v[16:17], v[104:105]
	s_waitcnt vmcnt(12)
	v_pk_mul_f32 v[18:19], v[18:19], v[106:107]
	s_waitcnt vmcnt(10)
	v_pk_mul_f32 v[20:21], v[20:21], v[108:109]
	s_waitcnt vmcnt(8)
	v_pk_mul_f32 v[22:23], v[22:23], v[110:111]
	s_waitcnt vmcnt(6)
	v_pk_mul_f32 v[24:25], v[24:25], v[112:113]
	s_waitcnt vmcnt(4)
	v_pk_mul_f32 v[26:27], v[26:27], v[114:115]
	s_waitcnt vmcnt(2)
	v_pk_mul_f32 v[28:29], v[28:29], v[116:117]
	s_waitcnt vmcnt(0)
	v_pk_mul_f32 v[30:31], v[30:31], v[118:119]
	s_branch .LBB7_72

.LBB7_83:
	s_ashr_i32 s6, s16, 31
	s_lshr_b32 s6, s6, 27
	s_add_i32 s7, s16, s6
	s_ashr_i32 s6, s7, 5
	s_andn2_b32 s7, s7, 31
	s_sub_i32 s45, s16, s7
	s_ashr_i32 s7, s6, 31
	s_lshl_b32 s48, s45, 5
	s_add_i32 s15, s16, s72
	s_lshl_b64 s[6:7], s[6:7], 15
	s_add_u32 s16, s13, s6
	s_addc_u32 s49, s14, s7
	s_lshr_b32 s6, s45, 3
	ds_write2_b32 v77, v37, v40 offset1:66
	ds_write2_b32 v77, v41, v42 offset0:132 offset1:198
	ds_write2_b32 v71, v43, v44 offset0:8 offset1:74
	ds_write2_b32 v71, v45, v46 offset0:140 offset1:206
	ds_write2_b32 v72, v47, v48 offset0:16 offset1:82
	ds_write2_b32 v72, v49, v50 offset0:148 offset1:214
	ds_write2_b32 v73, v51, v52 offset0:24 offset1:90
	ds_write2_b32 v73, v53, v54 offset0:156 offset1:222
	ds_write2_b32 v74, v55, v56 offset0:32 offset1:98
	ds_write2_b32 v74, v57, v58 offset0:164 offset1:230
	ds_write2_b32 v75, v59, v60 offset0:40 offset1:106
	ds_write2_b32 v75, v61, v62 offset0:172 offset1:238
	ds_write2_b32 v84, v63, v64 offset0:48 offset1:114
	ds_write2_b32 v84, v65, v66 offset0:180 offset1:246
	ds_write2_b32 v85, v67, v68 offset0:56 offset1:122
	ds_write2_b32 v85, v69, v70 offset0:188 offset1:254
	s_mul_i32 s6, s6, 0xb0000
	s_waitcnt lgkmcnt(0)
	s_ashr_i32 s7, s6, 31
	v_or_b32_e32 v32, s48, v78
	s_lshl_b64 s[6:7], s[6:7], 1
	ds_read2_b32 v[72:73], v79 offset1:33
	s_add_u32 s6, s16, s6
	v_lshlrev_b32_e32 v32, 7, v32
	s_waitcnt lgkmcnt(0)
	v_cvt_pk_bf16_f32 v72, v72, v73
	ds_read2_b32 v[74:75], v79 offset0:66 offset1:99
	s_addc_u32 s7, s49, s7
	v_and_b32_e32 v32, 0x7380, v32
	s_waitcnt lgkmcnt(0)
	v_cvt_pk_bf16_f32 v73, v74, v75
	ds_read2_b32 v[74:75], v79 offset0:132 offset1:165
	v_lshl_add_u64 v[86:87], s[6:7], 0, v[32:33]
	v_mov_b32_e32 v35, v33
	v_or_b32_e32 v32, s48, v80
	s_waitcnt lgkmcnt(0)
	v_cvt_pk_bf16_f32 v74, v74, v75
	ds_read2_b32 v[84:85], v79 offset0:198 offset1:231
	s_waitcnt lgkmcnt(0)
	v_cvt_pk_bf16_f32 v75, v84, v85
	v_lshl_add_u64 v[86:87], v[86:87], 0, v[34:35]
	v_lshlrev_b32_e32 v32, 7, v32
	ds_read2_b32 v[84:85], v79 offset0:8 offset1:41
	global_store_dwordx4 v[86:87], v[72:75], off nt
	v_and_b32_e32 v32, 0x7780, v32
	v_lshl_add_u64 v[86:87], s[6:7], 0, v[32:33]
	s_waitcnt lgkmcnt(0)
	v_cvt_pk_bf16_f32 v72, v84, v85
	ds_read2_b32 v[74:75], v79 offset0:74 offset1:107
	s_waitcnt lgkmcnt(0)
	v_cvt_pk_bf16_f32 v73, v74, v75
	ds_read2_b32 v[74:75], v79 offset0:140 offset1:173
	v_or_b32_e32 v32, s48, v81
	s_waitcnt lgkmcnt(0)
	v_cvt_pk_bf16_f32 v74, v74, v75
	ds_read2_b32 v[84:85], v79 offset0:206 offset1:239
	s_waitcnt lgkmcnt(0)
	v_cvt_pk_bf16_f32 v75, v84, v85
	v_lshl_add_u64 v[86:87], v[86:87], 0, v[34:35]
	v_lshlrev_b32_e32 v32, 7, v32
	ds_read2_b32 v[84:85], v79 offset0:16 offset1:49
	global_store_dwordx4 v[86:87], v[72:75], off nt
	v_and_b32_e32 v32, 0x7b80, v32
	v_lshl_add_u64 v[86:87], s[6:7], 0, v[32:33]
	s_waitcnt lgkmcnt(0)
	v_cvt_pk_bf16_f32 v72, v84, v85
	ds_read2_b32 v[74:75], v79 offset0:82 offset1:115
	s_waitcnt lgkmcnt(0)
	v_cvt_pk_bf16_f32 v73, v74, v75
	ds_read2_b32 v[74:75], v79 offset0:148 offset1:181
	s_waitcnt lgkmcnt(0)
	v_cvt_pk_bf16_f32 v74, v74, v75
	ds_read2_b32 v[84:85], v79 offset0:214 offset1:247
	s_waitcnt lgkmcnt(0)
	v_cvt_pk_bf16_f32 v75, v84, v85
	v_lshl_add_u64 v[86:87], v[86:87], 0, v[34:35]
	ds_read2_b32 v[84:85], v79 offset0:24 offset1:57
	global_store_dwordx4 v[86:87], v[72:75], off nt
	v_or_b32_e32 v32, s48, v82
	v_lshlrev_b32_e32 v32, 7, v32
	s_waitcnt lgkmcnt(0)
	v_cvt_pk_bf16_f32 v72, v84, v85
	ds_read2_b32 v[74:75], v79 offset0:90 offset1:123
	s_waitcnt lgkmcnt(0)
	v_cvt_pk_bf16_f32 v73, v74, v75
	ds_read2_b32 v[74:75], v79 offset0:156 offset1:189
	s_waitcnt lgkmcnt(0)
	v_cvt_pk_bf16_f32 v74, v74, v75
	ds_read2_b32 v[84:85], v79 offset0:222 offset1:255
	v_and_b32_e32 v32, 0x7f80, v32
	s_waitcnt lgkmcnt(0)
	v_cvt_pk_bf16_f32 v75, v84, v85
	v_lshl_add_u64 v[84:85], s[6:7], 0, v[32:33]
	v_lshl_add_u64 v[84:85], v[84:85], 0, v[34:35]
	global_store_dwordx4 v[84:85], v[72:75], off nt
	s_waitcnt lgkmcnt(0)
	s_cmpk_gt_i32 s15, 0x57f
	s_cselect_b64 s[6:7], -1, 0

.LBB7_87:
	s_ashr_i32 s45, s15, 31
	s_lshr_b32 s45, s45, 27
	s_add_i32 s45, s15, s45
	s_and_b32 s48, s45, 0xffffffe0
	s_sub_i32 s50, s15, s48
	s_ashr_i32 s48, s45, 5
	s_ashr_i32 s49, s48, 31
	v_add_u32_e32 v71, 0x400, v77
	v_add_u32_e32 v72, 0x800, v77
	v_add_u32_e32 v73, 0xc00, v77
	v_add_u32_e32 v74, 0x1000, v77
	v_add_u32_e32 v75, 0x1400, v77
	v_add_u32_e32 v84, 0x1800, v77
	v_add_u32_e32 v85, 0x1c00, v77
	s_lshl_b32 s51, s50, 5
	s_lshl_b64 s[48:49], s[48:49], 15
	s_waitcnt vmcnt(30)
	ds_write2_b32 v77, v0, v1 offset1:66
	s_waitcnt vmcnt(28)
	ds_write2_b32 v77, v2, v3 offset0:132 offset1:198
	s_waitcnt vmcnt(26)
	ds_write2_b32 v71, v4, v5 offset0:8 offset1:74
	s_waitcnt vmcnt(24)
	ds_write2_b32 v71, v6, v7 offset0:140 offset1:206
	s_waitcnt vmcnt(22)
	ds_write2_b32 v72, v8, v9 offset0:16 offset1:82
	s_waitcnt vmcnt(20)
	ds_write2_b32 v72, v10, v11 offset0:148 offset1:214
	s_waitcnt vmcnt(18)
	ds_write2_b32 v73, v12, v13 offset0:24 offset1:90
	s_waitcnt vmcnt(16)
	ds_write2_b32 v73, v14, v15 offset0:156 offset1:222
	s_waitcnt vmcnt(14)
	ds_write2_b32 v74, v16, v17 offset0:32 offset1:98
	s_waitcnt vmcnt(12)
	ds_write2_b32 v74, v18, v19 offset0:164 offset1:230
	s_waitcnt vmcnt(10)
	ds_write2_b32 v75, v20, v21 offset0:40 offset1:106
	s_waitcnt vmcnt(8)
	ds_write2_b32 v75, v22, v23 offset0:172 offset1:238
	s_waitcnt vmcnt(6)
	ds_write2_b32 v84, v24, v25 offset0:48 offset1:114
	s_waitcnt vmcnt(4)
	ds_write2_b32 v84, v26, v27 offset0:180 offset1:246
	s_waitcnt vmcnt(2)
	ds_write2_b32 v85, v28, v29 offset0:56 offset1:122
	s_waitcnt vmcnt(0)
	ds_write2_b32 v85, v30, v31 offset0:188 offset1:254
	s_add_u32 s45, s13, s48
	s_waitcnt lgkmcnt(0)
	s_addc_u32 s64, s14, s49
	s_lshr_b32 s48, s50, 3
	s_mul_i32 s48, s48, 0xb0000
	ds_read2_b32 v[86:87], v79 offset1:33
	s_ashr_i32 s49, s48, 31
	s_waitcnt lgkmcnt(0)
	v_cvt_pk_bf16_f32 v86, v86, v87
	ds_read2_b32 v[88:89], v79 offset0:66 offset1:99
	v_or_b32_e32 v32, s51, v78
	s_lshl_b64 s[48:49], s[48:49], 1
	s_waitcnt lgkmcnt(0)
	v_cvt_pk_bf16_f32 v87, v88, v89
	ds_read2_b32 v[88:89], v79 offset0:132 offset1:165
	v_lshlrev_b32_e32 v32, 7, v32
	s_add_u32 s48, s45, s48
	s_waitcnt lgkmcnt(0)
	v_cvt_pk_bf16_f32 v88, v88, v89
	ds_read2_b32 v[90:91], v79 offset0:198 offset1:231
	v_and_b32_e32 v32, 0x7380, v32
	s_addc_u32 s49, s64, s49
	s_waitcnt lgkmcnt(0)
	v_cvt_pk_bf16_f32 v89, v90, v91
	v_mov_b32_e32 v35, v33
	v_lshl_add_u64 v[90:91], s[48:49], 0, v[32:33]
	v_lshl_add_u64 v[90:91], v[90:91], 0, v[34:35]
	global_store_dwordx4 v[90:91], v[86:89], off nt
	ds_read2_b32 v[86:87], v79 offset0:8 offset1:41
	v_or_b32_e32 v32, s51, v80
	s_waitcnt lgkmcnt(0)
	v_cvt_pk_bf16_f32 v86, v86, v87
	ds_read2_b32 v[88:89], v79 offset0:74 offset1:107
	s_waitcnt lgkmcnt(0)
	v_cvt_pk_bf16_f32 v87, v88, v89
	ds_read2_b32 v[88:89], v79 offset0:140 offset1:173
	v_lshlrev_b32_e32 v32, 7, v32
	s_waitcnt lgkmcnt(0)
	v_cvt_pk_bf16_f32 v88, v88, v89
	ds_read2_b32 v[90:91], v79 offset0:206 offset1:239
	v_and_b32_e32 v32, 0x7780, v32
	s_waitcnt lgkmcnt(0)
	v_cvt_pk_bf16_f32 v89, v90, v91
	v_lshl_add_u64 v[90:91], s[48:49], 0, v[32:33]
	v_lshl_add_u64 v[90:91], v[90:91], 0, v[34:35]
	global_store_dwordx4 v[90:91], v[86:89], off nt
	ds_read2_b32 v[86:87], v79 offset0:16 offset1:49
	v_or_b32_e32 v32, s51, v81
	s_waitcnt lgkmcnt(0)
	v_cvt_pk_bf16_f32 v86, v86, v87
	ds_read2_b32 v[88:89], v79 offset0:82 offset1:115
	s_waitcnt lgkmcnt(0)
	v_cvt_pk_bf16_f32 v87, v88, v89
	ds_read2_b32 v[88:89], v79 offset0:148 offset1:181
	v_lshlrev_b32_e32 v32, 7, v32
	s_waitcnt lgkmcnt(0)
	v_cvt_pk_bf16_f32 v88, v88, v89
	ds_read2_b32 v[90:91], v79 offset0:214 offset1:247
	v_and_b32_e32 v32, 0x7b80, v32
	s_waitcnt lgkmcnt(0)
	v_cvt_pk_bf16_f32 v89, v90, v91
	v_lshl_add_u64 v[90:91], s[48:49], 0, v[32:33]
	v_lshl_add_u64 v[90:91], v[90:91], 0, v[34:35]
	global_store_dwordx4 v[90:91], v[86:89], off nt
	ds_read2_b32 v[86:87], v79 offset0:24 offset1:57
	v_or_b32_e32 v32, s51, v82
	s_waitcnt lgkmcnt(0)
	v_cvt_pk_bf16_f32 v86, v86, v87
	ds_read2_b32 v[88:89], v79 offset0:90 offset1:123
	s_waitcnt lgkmcnt(0)
	v_cvt_pk_bf16_f32 v87, v88, v89
	ds_read2_b32 v[88:89], v79 offset0:156 offset1:189
	v_lshlrev_b32_e32 v32, 7, v32
	s_waitcnt lgkmcnt(0)
	v_cvt_pk_bf16_f32 v88, v88, v89
	ds_read2_b32 v[90:91], v79 offset0:222 offset1:255
	v_and_b32_e32 v32, 0x7f80, v32
	s_waitcnt lgkmcnt(0)
	v_cvt_pk_bf16_f32 v89, v90, v91
	v_lshl_add_u64 v[90:91], s[48:49], 0, v[32:33]
	v_lshl_add_u64 v[90:91], v[90:91], 0, v[34:35]
	global_store_dwordx4 v[90:91], v[86:89], off nt
	s_waitcnt lgkmcnt(0)
	s_andn2_b64 vcc, exec, s[6:7]
	s_mov_b64 s[6:7], -1
	s_cbranch_vccnz .LBB7_84
	s_add_i32 s6, s55, s15
	s_cmpk_gt_i32 s6, 0x57f
	s_cbranch_scc1 .LBB7_83
	s_ashr_i32 s7, s6, 31
	s_lshr_b32 s7, s7, 27
	s_add_i32 s7, s6, s7
	s_and_b32 s15, s7, 0x7ffffe0
	s_lshl_b32 s7, s7, 1
	s_andn2_b32 s7, s7, 63
	s_sub_i32 s6, s6, s15
	v_or_b32_e32 v0, s7, v76
	s_lshl_b32 s6, s6, 5
	v_ashrrev_i32_e32 v1, 31, v0
	v_or_b32_e32 v6, 2, v0
	v_or_b32_e32 v8, 4, v0
	v_or_b32_e32 v10, 6, v0
	v_or_b32_e32 v12, 8, v0
	v_or_b32_e32 v14, 10, v0
	v_or_b32_e32 v16, 12, v0
	v_or_b32_e32 v18, 14, v0
	v_or_b32_e32 v20, 16, v0
	v_or_b32_e32 v22, 18, v0
	v_or_b32_e32 v24, 20, v0
	v_or_b32_e32 v26, 22, v0
	v_or_b32_e32 v28, 24, v0
	v_or_b32_e32 v30, 26, v0
	s_ashr_i32 s7, s6, 31
	v_lshlrev_b64 v[4:5], 12, v[0:1]
	v_ashrrev_i32_e32 v7, 31, v6
	v_ashrrev_i32_e32 v9, 31, v8
	v_ashrrev_i32_e32 v11, 31, v10
	v_ashrrev_i32_e32 v13, 31, v12
	v_ashrrev_i32_e32 v15, 31, v14
	v_ashrrev_i32_e32 v17, 31, v16
	v_ashrrev_i32_e32 v19, 31, v18
	v_ashrrev_i32_e32 v21, 31, v20
	v_ashrrev_i32_e32 v23, 31, v22
	v_ashrrev_i32_e32 v25, 31, v24
	v_ashrrev_i32_e32 v27, 31, v26
	v_ashrrev_i32_e32 v29, 31, v28
	v_ashrrev_i32_e32 v31, 31, v30
	v_or_b32_e32 v86, 28, v0
	v_or_b32_e32 v88, 30, v0
	v_or_b32_e32 v90, 32, v0
	v_or_b32_e32 v92, 34, v0
	v_or_b32_e32 v94, 36, v0
	v_or_b32_e32 v96, 38, v0
	v_or_b32_e32 v98, 40, v0
	v_or_b32_e32 v100, 42, v0
	v_or_b32_e32 v102, 44, v0
	v_or_b32_e32 v104, 46, v0
	v_or_b32_e32 v106, 48, v0
	v_or_b32_e32 v108, 50, v0
	v_or_b32_e32 v110, 52, v0
	v_or_b32_e32 v112, 54, v0
	v_or_b32_e32 v114, 56, v0
	v_or_b32_e32 v116, 58, v0
	v_or_b32_e32 v118, 60, v0
	v_or_b32_e32 v0, 62, v0
	v_lshl_add_u64 v[2:3], s[6:7], 2, v[38:39]
	v_lshlrev_b64 v[6:7], 12, v[6:7]
	v_lshlrev_b64 v[8:9], 12, v[8:9]
	v_lshlrev_b64 v[10:11], 12, v[10:11]
	v_lshlrev_b64 v[12:13], 12, v[12:13]
	v_lshlrev_b64 v[14:15], 12, v[14:15]
	v_lshlrev_b64 v[16:17], 12, v[16:17]
	v_lshlrev_b64 v[18:19], 12, v[18:19]
	v_lshlrev_b64 v[20:21], 12, v[20:21]
	v_lshlrev_b64 v[22:23], 12, v[22:23]
	v_lshlrev_b64 v[24:25], 12, v[24:25]
	v_lshlrev_b64 v[26:27], 12, v[26:27]
	v_lshlrev_b64 v[28:29], 12, v[28:29]
	v_lshlrev_b64 v[30:31], 12, v[30:31]
	v_ashrrev_i32_e32 v87, 31, v86
	v_ashrrev_i32_e32 v89, 31, v88
	v_ashrrev_i32_e32 v91, 31, v90
	v_ashrrev_i32_e32 v93, 31, v92
	v_ashrrev_i32_e32 v95, 31, v94
	v_ashrrev_i32_e32 v97, 31, v96
	v_ashrrev_i32_e32 v99, 31, v98
	v_ashrrev_i32_e32 v101, 31, v100
	v_ashrrev_i32_e32 v103, 31, v102
	v_ashrrev_i32_e32 v105, 31, v104
	v_ashrrev_i32_e32 v107, 31, v106
	v_ashrrev_i32_e32 v109, 31, v108
	v_ashrrev_i32_e32 v111, 31, v110
	v_ashrrev_i32_e32 v113, 31, v112
	v_ashrrev_i32_e32 v115, 31, v114
	v_ashrrev_i32_e32 v117, 31, v116
	v_ashrrev_i32_e32 v119, 31, v118
	v_ashrrev_i32_e32 v1, 31, v0
	v_lshl_add_u64 v[4:5], v[2:3], 0, v[4:5]
	v_lshl_add_u64 v[6:7], v[2:3], 0, v[6:7]
	v_lshl_add_u64 v[8:9], v[2:3], 0, v[8:9]
	v_lshl_add_u64 v[10:11], v[2:3], 0, v[10:11]
	v_lshl_add_u64 v[12:13], v[2:3], 0, v[12:13]
	v_lshl_add_u64 v[14:15], v[2:3], 0, v[14:15]
	v_lshl_add_u64 v[16:17], v[2:3], 0, v[16:17]
	v_lshl_add_u64 v[18:19], v[2:3], 0, v[18:19]
	v_lshl_add_u64 v[20:21], v[2:3], 0, v[20:21]
	v_lshl_add_u64 v[22:23], v[2:3], 0, v[22:23]
	v_lshl_add_u64 v[24:25], v[2:3], 0, v[24:25]
	v_lshl_add_u64 v[26:27], v[2:3], 0, v[26:27]
	v_lshl_add_u64 v[28:29], v[2:3], 0, v[28:29]
	v_lshl_add_u64 v[30:31], v[2:3], 0, v[30:31]
	v_lshlrev_b64 v[86:87], 12, v[86:87]
	v_lshlrev_b64 v[88:89], 12, v[88:89]
	v_lshlrev_b64 v[90:91], 12, v[90:91]
	v_lshlrev_b64 v[92:93], 12, v[92:93]
	v_lshlrev_b64 v[94:95], 12, v[94:95]
	v_lshlrev_b64 v[96:97], 12, v[96:97]
	v_lshlrev_b64 v[98:99], 12, v[98:99]
	v_lshlrev_b64 v[100:101], 12, v[100:101]
	v_lshlrev_b64 v[102:103], 12, v[102:103]
	v_lshlrev_b64 v[104:105], 12, v[104:105]
	v_lshlrev_b64 v[106:107], 12, v[106:107]
	v_lshlrev_b64 v[108:109], 12, v[108:109]
	v_lshlrev_b64 v[110:111], 12, v[110:111]
	v_lshlrev_b64 v[112:113], 12, v[112:113]
	v_lshlrev_b64 v[114:115], 12, v[114:115]
	v_lshlrev_b64 v[116:117], 12, v[116:117]
	v_lshlrev_b64 v[118:119], 12, v[118:119]
	v_lshlrev_b64 v[0:1], 12, v[0:1]
	v_lshl_add_u64 v[86:87], v[2:3], 0, v[86:87]
	v_lshl_add_u64 v[88:89], v[2:3], 0, v[88:89]
	v_lshl_add_u64 v[90:91], v[2:3], 0, v[90:91]
	v_lshl_add_u64 v[92:93], v[2:3], 0, v[92:93]
	v_lshl_add_u64 v[94:95], v[2:3], 0, v[94:95]
	v_lshl_add_u64 v[96:97], v[2:3], 0, v[96:97]
	v_lshl_add_u64 v[98:99], v[2:3], 0, v[98:99]
	v_lshl_add_u64 v[100:101], v[2:3], 0, v[100:101]
	v_lshl_add_u64 v[102:103], v[2:3], 0, v[102:103]
	v_lshl_add_u64 v[104:105], v[2:3], 0, v[104:105]
	v_lshl_add_u64 v[106:107], v[2:3], 0, v[106:107]
	v_lshl_add_u64 v[108:109], v[2:3], 0, v[108:109]
	v_lshl_add_u64 v[110:111], v[2:3], 0, v[110:111]
	v_lshl_add_u64 v[112:113], v[2:3], 0, v[112:113]
	v_lshl_add_u64 v[114:115], v[2:3], 0, v[114:115]
	v_lshl_add_u64 v[116:117], v[2:3], 0, v[116:117]
	v_lshl_add_u64 v[118:119], v[2:3], 0, v[118:119]
	v_lshl_add_u64 v[120:121], v[2:3], 0, v[0:1]
	global_load_dword v0, v[4:5], off nt
	global_load_dword v1, v[6:7], off nt
	global_load_dword v2, v[8:9], off nt
	global_load_dword v3, v[10:11], off nt
	s_nop 0
	global_load_dword v4, v[12:13], off nt
	global_load_dword v5, v[14:15], off nt
	global_load_dword v6, v[16:17], off nt
	global_load_dword v7, v[18:19], off nt
	global_load_dword v8, v[20:21], off nt
	global_load_dword v9, v[22:23], off nt
	global_load_dword v10, v[24:25], off nt
	global_load_dword v11, v[26:27], off nt
	global_load_dword v12, v[28:29], off nt
	global_load_dword v13, v[30:31], off nt
	global_load_dword v14, v[86:87], off nt
	global_load_dword v15, v[88:89], off nt
	global_load_dword v16, v[90:91], off nt
	global_load_dword v17, v[92:93], off nt
	global_load_dword v18, v[94:95], off nt
	global_load_dword v19, v[96:97], off nt
	global_load_dword v20, v[98:99], off nt
	global_load_dword v21, v[100:101], off nt
	global_load_dword v22, v[102:103], off nt
	global_load_dword v23, v[104:105], off nt
	global_load_dword v24, v[106:107], off nt
	global_load_dword v25, v[108:109], off nt
	global_load_dword v26, v[110:111], off nt
	global_load_dword v27, v[112:113], off nt
	global_load_dword v28, v[114:115], off nt
	global_load_dword v29, v[116:117], off nt
	global_load_dword v30, v[118:119], off nt
	global_load_dword v31, v[120:121], off nt
	s_branch .LBB7_83

.LBB7_94:
	ds_write2_b32 v77, v43, v42 offset1:66
	ds_write2_b32 v77, v45, v44 offset0:132 offset1:198
	ds_write2_b32 v32, v47, v46 offset0:8 offset1:74
	ds_write2_b32 v32, v49, v48 offset0:140 offset1:206
	ds_write2_b32 v35, v51, v50 offset0:16 offset1:82
	ds_write2_b32 v35, v53, v52 offset0:148 offset1:214
	ds_write2_b32 v37, v55, v54 offset0:24 offset1:90
	ds_write2_b32 v37, v57, v56 offset0:156 offset1:222
	ds_write2_b32 v84, v59, v58 offset0:32 offset1:98
	ds_write2_b32 v84, v61, v60 offset0:164 offset1:230
	ds_write2_b32 v85, v63, v62 offset0:40 offset1:106
	ds_write2_b32 v85, v65, v64 offset0:172 offset1:238
	ds_write2_b32 v86, v67, v66 offset0:48 offset1:114
	ds_write2_b32 v86, v69, v68 offset0:180 offset1:246
	ds_write2_b32 v87, v71, v70 offset0:56 offset1:122
	ds_write2_b32 v87, v73, v72 offset0:188 offset1:254
	s_waitcnt lgkmcnt(0)
	s_mul_hi_i32 s12, s48, 0x2e8ba2e9
	s_lshr_b32 s13, s12, 31
	s_ashr_i32 s12, s12, 3
	ds_read2_b32 v[74:75], v79 offset1:33
	s_add_i32 s12, s12, s13
	s_waitcnt lgkmcnt(0)
	v_cvt_pk_bf16_f32 v84, v74, v75
	ds_read2_b32 v[74:75], v79 offset0:66 offset1:99
	s_mul_i32 s13, s12, 44
	s_waitcnt lgkmcnt(0)
	v_cvt_pk_bf16_f32 v85, v74, v75
	ds_read2_b32 v[74:75], v79 offset0:132 offset1:165
	s_sub_i32 s13, s48, s13
	s_waitcnt lgkmcnt(0)
	v_cvt_pk_bf16_f32 v86, v74, v75
	ds_read2_b32 v[74:75], v79 offset0:198 offset1:231
	s_lshl_b32 s49, s13, 5
	s_lshl_b32 s12, s12, 6
	s_waitcnt lgkmcnt(0)
	v_cvt_pk_bf16_f32 v87, v74, v75
	v_or_b32_e32 v74, s49, v78
	s_ashr_i32 s13, s12, 31
	v_ashrrev_i32_e32 v75, 31, v74
	v_lshl_add_u64 v[88:89], s[12:13], 1, v[40:41]
	v_lshlrev_b64 v[74:75], 11, v[74:75]
	v_lshl_add_u64 v[74:75], v[88:89], 0, v[74:75]
	ds_read2_b32 v[90:91], v79 offset0:8 offset1:41
	global_store_dwordx4 v[74:75], v[84:87], off nt
	s_add_i32 s50, s48, s72
	s_cmpk_gt_i32 s50, 0x2bf
	s_waitcnt lgkmcnt(0)
	v_cvt_pk_bf16_f32 v84, v90, v91
	ds_read2_b32 v[74:75], v79 offset0:74 offset1:107
	s_waitcnt lgkmcnt(0)
	v_cvt_pk_bf16_f32 v85, v74, v75
	ds_read2_b32 v[74:75], v79 offset0:140 offset1:173
	s_waitcnt lgkmcnt(0)
	v_cvt_pk_bf16_f32 v86, v74, v75
	ds_read2_b32 v[74:75], v79 offset0:206 offset1:239
	s_waitcnt lgkmcnt(0)
	v_cvt_pk_bf16_f32 v87, v74, v75
	v_or_b32_e32 v74, s49, v80
	v_ashrrev_i32_e32 v75, 31, v74
	v_lshlrev_b64 v[74:75], 11, v[74:75]
	ds_read2_b32 v[90:91], v79 offset0:16 offset1:49
	v_lshl_add_u64 v[74:75], v[88:89], 0, v[74:75]
	global_store_dwordx4 v[74:75], v[84:87], off nt
	s_cselect_b64 s[12:13], -1, 0
	s_waitcnt lgkmcnt(0)
	v_cvt_pk_bf16_f32 v84, v90, v91
	ds_read2_b32 v[74:75], v79 offset0:82 offset1:115
	v_or_b32_e32 v90, s49, v81
	s_waitcnt lgkmcnt(0)
	v_cvt_pk_bf16_f32 v85, v74, v75
	ds_read2_b32 v[74:75], v79 offset0:148 offset1:181
	v_ashrrev_i32_e32 v91, 31, v90
	s_waitcnt lgkmcnt(0)
	v_cvt_pk_bf16_f32 v86, v74, v75
	ds_read2_b32 v[74:75], v79 offset0:214 offset1:247
	v_lshlrev_b64 v[90:91], 11, v[90:91]
	s_waitcnt lgkmcnt(0)
	v_cvt_pk_bf16_f32 v87, v74, v75
	ds_read2_b32 v[74:75], v79 offset0:24 offset1:57
	v_lshl_add_u64 v[90:91], v[88:89], 0, v[90:91]
	global_store_dwordx4 v[90:91], v[84:87], off nt
	v_or_b32_e32 v90, s49, v82
	v_ashrrev_i32_e32 v91, 31, v90
	s_waitcnt lgkmcnt(0)
	v_cvt_pk_bf16_f32 v84, v74, v75
	ds_read2_b32 v[74:75], v79 offset0:90 offset1:123
	s_waitcnt lgkmcnt(0)
	v_cvt_pk_bf16_f32 v85, v74, v75
	ds_read2_b32 v[74:75], v79 offset0:156 offset1:189
	s_waitcnt lgkmcnt(0)
	v_cvt_pk_bf16_f32 v86, v74, v75
	ds_read2_b32 v[74:75], v79 offset0:222 offset1:255
	v_lshlrev_b64 v[90:91], 11, v[90:91]
	s_waitcnt lgkmcnt(0)
	v_cvt_pk_bf16_f32 v87, v74, v75
	v_lshl_add_u64 v[74:75], v[88:89], 0, v[90:91]
	global_store_dwordx4 v[74:75], v[84:87], off nt
	s_waitcnt lgkmcnt(0)

.LBB7_99:
	v_add_u32_e32 v32, 0x400, v77
	v_add_u32_e32 v35, 0x800, v77
	v_add_u32_e32 v37, 0xc00, v77
	v_add_u32_e32 v84, 0x1000, v77
	v_add_u32_e32 v85, 0x1400, v77
	v_add_u32_e32 v86, 0x1800, v77
	v_add_u32_e32 v87, 0x1c00, v77
	s_waitcnt vmcnt(30)
	ds_write2_b32 v77, v0, v1 offset1:66
	s_waitcnt vmcnt(28)
	ds_write2_b32 v77, v2, v3 offset0:132 offset1:198
	s_waitcnt vmcnt(26)
	ds_write2_b32 v32, v4, v5 offset0:8 offset1:74
	s_waitcnt vmcnt(24)
	ds_write2_b32 v32, v6, v7 offset0:140 offset1:206
	s_waitcnt vmcnt(22)
	ds_write2_b32 v35, v8, v9 offset0:16 offset1:82
	s_waitcnt vmcnt(20)
	ds_write2_b32 v35, v10, v11 offset0:148 offset1:214
	s_waitcnt vmcnt(18)
	ds_write2_b32 v37, v12, v13 offset0:24 offset1:90
	s_waitcnt vmcnt(16)
	ds_write2_b32 v37, v14, v15 offset0:156 offset1:222
	s_waitcnt vmcnt(14)
	ds_write2_b32 v84, v16, v17 offset0:32 offset1:98
	s_waitcnt vmcnt(12)
	ds_write2_b32 v84, v18, v19 offset0:164 offset1:230
	s_waitcnt vmcnt(10)
	ds_write2_b32 v85, v20, v21 offset0:40 offset1:106
	s_waitcnt vmcnt(8)
	ds_write2_b32 v85, v22, v23 offset0:172 offset1:238
	s_waitcnt vmcnt(6)
	ds_write2_b32 v86, v24, v25 offset0:48 offset1:114
	s_waitcnt vmcnt(4)
	ds_write2_b32 v86, v26, v27 offset0:180 offset1:246
	s_waitcnt vmcnt(2)
	ds_write2_b32 v87, v28, v29 offset0:56 offset1:122
	s_waitcnt vmcnt(0)
	ds_write2_b32 v87, v30, v31 offset0:188 offset1:254
	s_waitcnt lgkmcnt(0)
	s_mul_hi_i32 s49, s50, 0x2e8ba2e9
	s_lshr_b32 s51, s49, 31
	s_ashr_i32 s49, s49, 3
	ds_read2_b32 v[74:75], v79 offset1:33
	s_add_i32 s49, s49, s51
	s_waitcnt lgkmcnt(0)
	v_cvt_pk_bf16_f32 v88, v74, v75
	ds_read2_b32 v[74:75], v79 offset0:66 offset1:99
	s_mul_i32 s51, s49, 44
	s_waitcnt lgkmcnt(0)
	v_cvt_pk_bf16_f32 v89, v74, v75
	ds_read2_b32 v[74:75], v79 offset0:132 offset1:165
	s_sub_i32 s51, s50, s51
	s_waitcnt lgkmcnt(0)
	v_cvt_pk_bf16_f32 v90, v74, v75
	ds_read2_b32 v[74:75], v79 offset0:198 offset1:231
	s_lshl_b32 s64, s49, 6
	s_lshl_b32 s49, s51, 5
	s_waitcnt lgkmcnt(0)
	v_cvt_pk_bf16_f32 v91, v74, v75
	v_or_b32_e32 v74, s49, v78
	s_ashr_i32 s65, s64, 31
	v_ashrrev_i32_e32 v75, 31, v74
	v_lshl_add_u64 v[92:93], s[64:65], 1, v[40:41]
	v_lshlrev_b64 v[74:75], 11, v[74:75]
	v_lshl_add_u64 v[74:75], v[92:93], 0, v[74:75]
	ds_read2_b32 v[94:95], v79 offset0:8 offset1:41
	global_store_dwordx4 v[74:75], v[88:91], off nt
	s_andn2_b64 vcc, exec, s[12:13]
	s_mov_b64 s[12:13], -1
	s_waitcnt lgkmcnt(0)
	v_cvt_pk_bf16_f32 v88, v94, v95
	ds_read2_b32 v[74:75], v79 offset0:74 offset1:107
	s_waitcnt lgkmcnt(0)
	v_cvt_pk_bf16_f32 v89, v74, v75
	ds_read2_b32 v[74:75], v79 offset0:140 offset1:173
	s_waitcnt lgkmcnt(0)
	v_cvt_pk_bf16_f32 v90, v74, v75
	ds_read2_b32 v[74:75], v79 offset0:206 offset1:239
	s_waitcnt lgkmcnt(0)
	v_cvt_pk_bf16_f32 v91, v74, v75
	v_or_b32_e32 v74, s49, v80
	v_ashrrev_i32_e32 v75, 31, v74
	v_lshlrev_b64 v[74:75], 11, v[74:75]
	v_lshl_add_u64 v[74:75], v[92:93], 0, v[74:75]
	ds_read2_b32 v[94:95], v79 offset0:16 offset1:49
	global_store_dwordx4 v[74:75], v[88:91], off nt
	s_waitcnt lgkmcnt(0)
	s_nop 0
	v_cvt_pk_bf16_f32 v88, v94, v95
	ds_read2_b32 v[74:75], v79 offset0:82 offset1:115
	s_waitcnt lgkmcnt(0)
	v_cvt_pk_bf16_f32 v89, v74, v75
	ds_read2_b32 v[74:75], v79 offset0:148 offset1:181
	s_waitcnt lgkmcnt(0)
	v_cvt_pk_bf16_f32 v90, v74, v75
	ds_read2_b32 v[74:75], v79 offset0:214 offset1:247
	s_waitcnt lgkmcnt(0)
	v_cvt_pk_bf16_f32 v91, v74, v75
	v_or_b32_e32 v74, s49, v81
	v_ashrrev_i32_e32 v75, 31, v74
	v_lshlrev_b64 v[74:75], 11, v[74:75]
	ds_read2_b32 v[94:95], v79 offset0:24 offset1:57
	v_lshl_add_u64 v[74:75], v[92:93], 0, v[74:75]
	global_store_dwordx4 v[74:75], v[88:91], off nt
	s_waitcnt lgkmcnt(0)
	s_nop 0
	v_cvt_pk_bf16_f32 v88, v94, v95
	ds_read2_b32 v[74:75], v79 offset0:90 offset1:123
	v_or_b32_e32 v94, s49, v82
	s_waitcnt lgkmcnt(0)
	v_cvt_pk_bf16_f32 v89, v74, v75
	ds_read2_b32 v[74:75], v79 offset0:156 offset1:189
	v_ashrrev_i32_e32 v95, 31, v94
	s_waitcnt lgkmcnt(0)
	v_cvt_pk_bf16_f32 v90, v74, v75
	ds_read2_b32 v[74:75], v79 offset0:222 offset1:255
	v_lshlrev_b64 v[94:95], 11, v[94:95]
	s_waitcnt lgkmcnt(0)
	v_cvt_pk_bf16_f32 v91, v74, v75
	v_lshl_add_u64 v[74:75], v[92:93], 0, v[94:95]
	global_store_dwordx4 v[74:75], v[88:91], off nt
	s_waitcnt lgkmcnt(0)
	s_cbranch_vccnz .LBB7_95
	s_add_i32 s12, s55, s50
	s_cmpk_gt_i32 s12, 0x2bf
	s_cbranch_scc1 .LBB7_94
	s_mul_hi_i32 s13, s12, 0x2e8ba2e9
	s_lshr_b32 s49, s13, 31
	s_ashr_i32 s13, s13, 3
	s_add_i32 s13, s13, s49
	s_mul_i32 s49, s13, 44
	s_sub_i32 s12, s12, s49
	s_lshl_b32 s12, s12, 5
	v_lshl_or_b32 v74, s13, 6, v76
	s_ashr_i32 s13, s12, 31
	v_lshl_add_u64 v[24:25], s[12:13], 2, v[38:39]
	v_or_b32_e32 v2, 2, v74
	v_or_b32_e32 v4, 4, v74
	v_or_b32_e32 v6, 6, v74
	v_or_b32_e32 v8, 8, v74
	v_or_b32_e32 v10, 10, v74
	v_or_b32_e32 v12, 12, v74
	v_or_b32_e32 v14, 14, v74
	v_mad_i64_i32 v[0:1], s[12:13], v74, s57, v[24:25]
	v_mad_i64_i32 v[2:3], s[12:13], v2, s57, v[24:25]
	v_mad_i64_i32 v[4:5], s[12:13], v4, s57, v[24:25]
	v_mad_i64_i32 v[6:7], s[12:13], v6, s57, v[24:25]
	v_mad_i64_i32 v[8:9], s[12:13], v8, s57, v[24:25]
	v_mad_i64_i32 v[10:11], s[12:13], v10, s57, v[24:25]
	v_mad_i64_i32 v[12:13], s[12:13], v12, s57, v[24:25]
	v_mad_i64_i32 v[14:15], s[12:13], v14, s57, v[24:25]
	global_load_dword v0, v[0:1], off nt
	s_nop 0
	global_load_dword v1, v[2:3], off nt
	s_nop 0
	global_load_dword v2, v[4:5], off nt
	global_load_dword v3, v[6:7], off nt
	s_nop 0
	global_load_dword v4, v[8:9], off nt
	global_load_dword v5, v[10:11], off nt
	global_load_dword v6, v[12:13], off nt
	global_load_dword v7, v[14:15], off nt
	v_or_b32_e32 v8, 16, v74
	v_or_b32_e32 v10, 18, v74
	v_or_b32_e32 v12, 20, v74
	v_or_b32_e32 v14, 22, v74
	v_or_b32_e32 v16, 24, v74
	v_or_b32_e32 v18, 26, v74
	v_or_b32_e32 v20, 28, v74
	v_or_b32_e32 v22, 30, v74
	v_mad_i64_i32 v[8:9], s[12:13], v8, s57, v[24:25]
	v_mad_i64_i32 v[10:11], s[12:13], v10, s57, v[24:25]
	v_mad_i64_i32 v[12:13], s[12:13], v12, s57, v[24:25]
	v_mad_i64_i32 v[14:15], s[12:13], v14, s57, v[24:25]
	v_mad_i64_i32 v[16:17], s[12:13], v16, s57, v[24:25]
	v_mad_i64_i32 v[18:19], s[12:13], v18, s57, v[24:25]
	v_mad_i64_i32 v[20:21], s[12:13], v20, s57, v[24:25]
	v_mad_i64_i32 v[22:23], s[12:13], v22, s57, v[24:25]
	global_load_dword v8, v[8:9], off nt
	s_nop 0
	global_load_dword v9, v[10:11], off nt
	s_nop 0
	global_load_dword v10, v[12:13], off nt
	global_load_dword v11, v[14:15], off nt
	s_nop 0
	global_load_dword v12, v[16:17], off nt
	global_load_dword v13, v[18:19], off nt
	global_load_dword v14, v[20:21], off nt
	global_load_dword v15, v[22:23], off nt
	v_or_b32_e32 v16, 32, v74
	v_or_b32_e32 v18, 34, v74
	v_or_b32_e32 v20, 36, v74
	v_or_b32_e32 v22, 38, v74
	v_or_b32_e32 v75, 46, v74
	v_mad_i64_i32 v[16:17], s[12:13], v16, s57, v[24:25]
	v_mad_i64_i32 v[18:19], s[12:13], v18, s57, v[24:25]
	v_mad_i64_i32 v[20:21], s[12:13], v20, s57, v[24:25]
	v_mad_i64_i32 v[22:23], s[12:13], v22, s57, v[24:25]
	v_or_b32_e32 v26, 40, v74
	v_or_b32_e32 v28, 42, v74
	v_or_b32_e32 v30, 44, v74
	v_mad_i64_i32 v[88:89], s[12:13], v75, s57, v[24:25]
	v_or_b32_e32 v75, 54, v74
	v_mad_i64_i32 v[26:27], s[12:13], v26, s57, v[24:25]
	v_mad_i64_i32 v[28:29], s[12:13], v28, s57, v[24:25]
	v_mad_i64_i32 v[30:31], s[12:13], v30, s57, v[24:25]
	global_load_dword v16, v[16:17], off nt
	s_nop 0
	global_load_dword v17, v[18:19], off nt
	s_nop 0
	global_load_dword v18, v[20:21], off nt
	global_load_dword v19, v[22:23], off nt
	s_nop 0
	global_load_dword v20, v[26:27], off nt
	global_load_dword v21, v[28:29], off nt
	global_load_dword v22, v[30:31], off nt
	global_load_dword v23, v[88:89], off nt
	v_mad_i64_i32 v[88:89], s[12:13], v75, s57, v[24:25]
	v_or_b32_e32 v75, 56, v74
	v_mad_i64_i32 v[90:91], s[12:13], v75, s57, v[24:25]
	v_or_b32_e32 v75, 58, v74
	v_or_b32_e32 v26, 48, v74
	v_or_b32_e32 v28, 50, v74
	v_or_b32_e32 v30, 52, v74
	v_mad_i64_i32 v[92:93], s[12:13], v75, s57, v[24:25]
	v_or_b32_e32 v75, 60, v74
	v_mad_i64_i32 v[26:27], s[12:13], v26, s57, v[24:25]
	v_mad_i64_i32 v[28:29], s[12:13], v28, s57, v[24:25]
	v_mad_i64_i32 v[30:31], s[12:13], v30, s57, v[24:25]
	v_mad_i64_i32 v[94:95], s[12:13], v75, s57, v[24:25]
	v_or_b32_e32 v75, 62, v74
	v_mad_i64_i32 v[96:97], s[12:13], v75, s57, v[24:25]
	global_load_dword v24, v[26:27], off nt
	global_load_dword v25, v[28:29], off nt
	s_nop 0
	global_load_dword v26, v[30:31], off nt
	global_load_dword v27, v[88:89], off nt
	global_load_dword v28, v[90:91], off nt
	global_load_dword v29, v[92:93], off nt
	s_nop 0
	global_load_dword v30, v[94:95], off nt
	global_load_dword v31, v[96:97], off nt
	s_andn2_b64 vcc, exec, s[14:15]
	s_cbranch_vccnz .LBB7_94
	v_ashrrev_i32_e32 v75, 31, v74
	v_lshl_add_u64 v[74:75], v[74:75], 2, s[6:7]
	global_load_dword v88, v[74:75], off
	global_load_dword v89, v[74:75], off offset:8
	global_load_dword v90, v[74:75], off offset:16
	global_load_dword v91, v[74:75], off offset:24
	global_load_dword v92, v[74:75], off offset:32
	global_load_dword v93, v[74:75], off offset:40
	global_load_dword v94, v[74:75], off offset:48
	global_load_dword v95, v[74:75], off offset:56
	global_load_dword v96, v[74:75], off offset:64
	global_load_dword v97, v[74:75], off offset:72
	global_load_dword v98, v[74:75], off offset:80
	global_load_dword v99, v[74:75], off offset:88
	global_load_dword v100, v[74:75], off offset:96
	global_load_dword v101, v[74:75], off offset:104
	global_load_dword v102, v[74:75], off offset:112
	global_load_dword v103, v[74:75], off offset:120
	global_load_dword v104, v[74:75], off offset:128
	global_load_dword v105, v[74:75], off offset:136
	global_load_dword v106, v[74:75], off offset:144
	global_load_dword v107, v[74:75], off offset:152
	global_load_dword v108, v[74:75], off offset:160
	global_load_dword v109, v[74:75], off offset:168
	global_load_dword v110, v[74:75], off offset:176
	global_load_dword v111, v[74:75], off offset:184
	global_load_dword v112, v[74:75], off offset:192
	global_load_dword v113, v[74:75], off offset:200
	global_load_dword v114, v[74:75], off offset:208
	global_load_dword v115, v[74:75], off offset:216
	global_load_dword v116, v[74:75], off offset:224
	global_load_dword v117, v[74:75], off offset:232
	global_load_dword v118, v[74:75], off offset:240
	global_load_dword v119, v[74:75], off offset:248
	s_waitcnt vmcnt(30)
	v_pk_mul_f32 v[0:1], v[0:1], v[88:89]
	s_waitcnt vmcnt(28)
	v_pk_mul_f32 v[2:3], v[2:3], v[90:91]
	s_waitcnt vmcnt(26)
	v_pk_mul_f32 v[4:5], v[4:5], v[92:93]
	s_waitcnt vmcnt(24)
	v_pk_mul_f32 v[6:7], v[6:7], v[94:95]
	s_waitcnt vmcnt(22)
	v_pk_mul_f32 v[8:9], v[8:9], v[96:97]
	s_waitcnt vmcnt(20)
	v_pk_mul_f32 v[10:11], v[10:11], v[98:99]
	s_waitcnt vmcnt(18)
	v_pk_mul_f32 v[12:13], v[12:13], v[100:101]
	s_waitcnt vmcnt(16)
	v_pk_mul_f32 v[14:15], v[14:15], v[102:103]
	s_waitcnt vmcnt(14)
	v_pk_mul_f32 v[16:17], v[16:17], v[104:105]
	s_waitcnt vmcnt(12)
	v_pk_mul_f32 v[18:19], v[18:19], v[106:107]
	s_waitcnt vmcnt(10)
	v_pk_mul_f32 v[20:21], v[20:21], v[108:109]
	s_waitcnt vmcnt(8)
	v_pk_mul_f32 v[22:23], v[22:23], v[110:111]
	s_waitcnt vmcnt(6)
	v_pk_mul_f32 v[24:25], v[24:25], v[112:113]
	s_waitcnt vmcnt(4)
	v_pk_mul_f32 v[26:27], v[26:27], v[114:115]
	s_waitcnt vmcnt(2)
	v_pk_mul_f32 v[28:29], v[28:29], v[116:117]
	s_waitcnt vmcnt(0)
	v_pk_mul_f32 v[30:31], v[30:31], v[118:119]
	s_branch .LBB7_94

.LBB7_105:
	s_ashr_i32 s12, s15, 31
	ds_write2_b32 v77, v32, v35 offset1:66
	ds_write2_b32 v77, v37, v42 offset0:132 offset1:198
	ds_write2_b32 v71, v43, v44 offset0:8 offset1:74
	ds_write2_b32 v71, v45, v46 offset0:140 offset1:206
	ds_write2_b32 v72, v47, v48 offset0:16 offset1:82
	ds_write2_b32 v72, v49, v50 offset0:148 offset1:214
	ds_write2_b32 v73, v51, v52 offset0:24 offset1:90
	ds_write2_b32 v73, v53, v54 offset0:156 offset1:222
	ds_write2_b32 v74, v55, v56 offset0:32 offset1:98
	ds_write2_b32 v74, v57, v58 offset0:164 offset1:230
	ds_write2_b32 v75, v59, v60 offset0:40 offset1:106
	ds_write2_b32 v75, v61, v62 offset0:172 offset1:238
	ds_write2_b32 v84, v63, v64 offset0:48 offset1:114
	ds_write2_b32 v84, v65, v66 offset0:180 offset1:246
	ds_write2_b32 v85, v67, v68 offset0:56 offset1:122
	ds_write2_b32 v85, v69, v70 offset0:188 offset1:254
	s_lshr_b32 s12, s12, 27
	s_waitcnt lgkmcnt(0)
	s_add_i32 s12, s15, s12
	s_lshr_b32 s13, s12, 5
	s_and_b32 s12, s12, 0x7ffffe0
	ds_read2_b32 v[72:73], v79 offset1:33
	s_sub_i32 s16, s15, s12
	s_waitcnt lgkmcnt(0)
	v_cvt_pk_bf16_f32 v72, v72, v73
	ds_read2_b32 v[74:75], v79 offset0:66 offset1:99
	s_cmpk_lt_i32 s15, 0xc0
	s_waitcnt lgkmcnt(0)
	v_cvt_pk_bf16_f32 v73, v74, v75
	ds_read2_b32 v[74:75], v79 offset0:132 offset1:165
	s_cselect_b32 s12, 0, 4
	s_add_i32 s12, s12, s13
	s_waitcnt lgkmcnt(0)
	v_cvt_pk_bf16_f32 v74, v74, v75
	ds_read2_b32 v[84:85], v79 offset0:198 offset1:231
	s_lshl_b32 s45, s16, 5
	s_lshl_b32 s12, s12, 6
	s_waitcnt lgkmcnt(0)
	v_cvt_pk_bf16_f32 v75, v84, v85
	v_or_b32_e32 v84, s45, v78
	s_ashr_i32 s13, s12, 31
	v_ashrrev_i32_e32 v85, 31, v84
	v_lshl_add_u64 v[86:87], s[12:13], 1, v[40:41]
	v_lshlrev_b64 v[84:85], 11, v[84:85]
	v_lshl_add_u64 v[84:85], v[86:87], 0, v[84:85]
	ds_read2_b32 v[88:89], v79 offset0:8 offset1:41
	global_store_dwordx4 v[84:85], v[72:75], off nt
	s_add_i32 s16, s15, s72
	s_cmpk_gt_i32 s16, 0x17f
	s_waitcnt lgkmcnt(0)
	v_cvt_pk_bf16_f32 v72, v88, v89
	ds_read2_b32 v[74:75], v79 offset0:74 offset1:107
	s_waitcnt lgkmcnt(0)
	v_cvt_pk_bf16_f32 v73, v74, v75
	ds_read2_b32 v[74:75], v79 offset0:140 offset1:173
	s_waitcnt lgkmcnt(0)
	v_cvt_pk_bf16_f32 v74, v74, v75
	ds_read2_b32 v[84:85], v79 offset0:206 offset1:239
	s_waitcnt lgkmcnt(0)
	v_cvt_pk_bf16_f32 v75, v84, v85
	v_or_b32_e32 v84, s45, v80
	v_ashrrev_i32_e32 v85, 31, v84
	v_lshlrev_b64 v[84:85], 11, v[84:85]
	v_lshl_add_u64 v[84:85], v[86:87], 0, v[84:85]
	ds_read2_b32 v[88:89], v79 offset0:16 offset1:49
	global_store_dwordx4 v[84:85], v[72:75], off nt
	s_cselect_b64 s[12:13], -1, 0
	s_waitcnt lgkmcnt(0)
	v_cvt_pk_bf16_f32 v72, v88, v89
	ds_read2_b32 v[74:75], v79 offset0:82 offset1:115
	s_waitcnt lgkmcnt(0)
	v_cvt_pk_bf16_f32 v73, v74, v75
	ds_read2_b32 v[74:75], v79 offset0:148 offset1:181
	s_waitcnt lgkmcnt(0)
	v_cvt_pk_bf16_f32 v74, v74, v75
	ds_read2_b32 v[84:85], v79 offset0:214 offset1:247
	s_waitcnt lgkmcnt(0)
	v_cvt_pk_bf16_f32 v75, v84, v85
	v_or_b32_e32 v84, s45, v81
	v_ashrrev_i32_e32 v85, 31, v84
	v_lshlrev_b64 v[84:85], 11, v[84:85]
	ds_read2_b32 v[88:89], v79 offset0:24 offset1:57
	v_lshl_add_u64 v[84:85], v[86:87], 0, v[84:85]
	global_store_dwordx4 v[84:85], v[72:75], off nt
	s_waitcnt lgkmcnt(0)
	s_nop 0
	v_cvt_pk_bf16_f32 v72, v88, v89
	ds_read2_b32 v[74:75], v79 offset0:90 offset1:123
	v_or_b32_e32 v88, s45, v82
	s_waitcnt lgkmcnt(0)
	v_cvt_pk_bf16_f32 v73, v74, v75
	ds_read2_b32 v[74:75], v79 offset0:156 offset1:189
	v_ashrrev_i32_e32 v89, 31, v88
	s_waitcnt lgkmcnt(0)
	v_cvt_pk_bf16_f32 v74, v74, v75
	ds_read2_b32 v[84:85], v79 offset0:222 offset1:255
	v_lshlrev_b64 v[88:89], 11, v[88:89]
	s_waitcnt lgkmcnt(0)
	v_cvt_pk_bf16_f32 v75, v84, v85
	v_lshl_add_u64 v[84:85], v[86:87], 0, v[88:89]
	global_store_dwordx4 v[84:85], v[72:75], off nt
	s_waitcnt lgkmcnt(0)

.LBB7_109:
	v_add_u32_e32 v71, 0x400, v77
	v_add_u32_e32 v72, 0x800, v77
	v_add_u32_e32 v73, 0xc00, v77
	v_add_u32_e32 v74, 0x1000, v77
	v_add_u32_e32 v75, 0x1400, v77
	v_add_u32_e32 v84, 0x1800, v77
	v_add_u32_e32 v85, 0x1c00, v77
	s_ashr_i32 s45, s16, 31
	s_waitcnt vmcnt(30)
	ds_write2_b32 v77, v0, v1 offset1:66
	s_waitcnt vmcnt(28)
	ds_write2_b32 v77, v2, v3 offset0:132 offset1:198
	s_waitcnt vmcnt(26)
	ds_write2_b32 v71, v4, v5 offset0:8 offset1:74
	s_waitcnt vmcnt(24)
	ds_write2_b32 v71, v6, v7 offset0:140 offset1:206
	s_waitcnt vmcnt(22)
	ds_write2_b32 v72, v8, v9 offset0:16 offset1:82
	s_waitcnt vmcnt(20)
	ds_write2_b32 v72, v10, v11 offset0:148 offset1:214
	s_waitcnt vmcnt(18)
	ds_write2_b32 v73, v12, v13 offset0:24 offset1:90
	s_waitcnt vmcnt(16)
	ds_write2_b32 v73, v14, v15 offset0:156 offset1:222
	s_waitcnt vmcnt(14)
	ds_write2_b32 v74, v16, v17 offset0:32 offset1:98
	s_waitcnt vmcnt(12)
	ds_write2_b32 v74, v18, v19 offset0:164 offset1:230
	s_waitcnt vmcnt(10)
	ds_write2_b32 v75, v20, v21 offset0:40 offset1:106
	s_waitcnt vmcnt(8)
	ds_write2_b32 v75, v22, v23 offset0:172 offset1:238
	s_waitcnt vmcnt(6)
	ds_write2_b32 v84, v24, v25 offset0:48 offset1:114
	s_waitcnt vmcnt(4)
	ds_write2_b32 v84, v26, v27 offset0:180 offset1:246
	s_waitcnt vmcnt(2)
	ds_write2_b32 v85, v28, v29 offset0:56 offset1:122
	s_waitcnt vmcnt(0)
	ds_write2_b32 v85, v30, v31 offset0:188 offset1:254
	s_lshr_b32 s45, s45, 27
	s_waitcnt lgkmcnt(0)
	s_add_i32 s45, s16, s45
	s_lshr_b32 s48, s45, 5
	s_and_b32 s45, s45, 0x7ffffe0
	ds_read2_b32 v[86:87], v79 offset1:33
	s_sub_i32 s45, s16, s45
	s_waitcnt lgkmcnt(0)
	v_cvt_pk_bf16_f32 v86, v86, v87
	ds_read2_b32 v[88:89], v79 offset0:66 offset1:99
	s_cmpk_lt_i32 s16, 0xc0
	s_waitcnt lgkmcnt(0)
	v_cvt_pk_bf16_f32 v87, v88, v89
	ds_read2_b32 v[88:89], v79 offset0:132 offset1:165
	s_cselect_b32 s49, 0, 4
	s_waitcnt lgkmcnt(0)
	v_cvt_pk_bf16_f32 v88, v88, v89
	ds_read2_b32 v[90:91], v79 offset0:198 offset1:231
	s_add_i32 s49, s49, s48
	s_lshl_b32 s45, s45, 5
	s_waitcnt lgkmcnt(0)
	v_cvt_pk_bf16_f32 v89, v90, v91
	s_lshl_b32 s48, s49, 6
	v_or_b32_e32 v90, s45, v78
	s_ashr_i32 s49, s48, 31
	v_ashrrev_i32_e32 v91, 31, v90
	v_lshlrev_b64 v[90:91], 11, v[90:91]
	v_lshl_add_u64 v[92:93], s[48:49], 1, v[40:41]
	v_lshl_add_u64 v[90:91], v[92:93], 0, v[90:91]
	global_store_dwordx4 v[90:91], v[86:89], off nt
	ds_read2_b32 v[86:87], v79 offset0:8 offset1:41
	s_andn2_b64 vcc, exec, s[12:13]
	s_waitcnt lgkmcnt(0)
	v_cvt_pk_bf16_f32 v86, v86, v87
	ds_read2_b32 v[88:89], v79 offset0:74 offset1:107
	s_waitcnt lgkmcnt(0)
	v_cvt_pk_bf16_f32 v87, v88, v89
	ds_read2_b32 v[88:89], v79 offset0:140 offset1:173
	s_waitcnt lgkmcnt(0)
	v_cvt_pk_bf16_f32 v88, v88, v89
	ds_read2_b32 v[90:91], v79 offset0:206 offset1:239
	s_waitcnt lgkmcnt(0)
	v_cvt_pk_bf16_f32 v89, v90, v91
	v_or_b32_e32 v90, s45, v80
	v_ashrrev_i32_e32 v91, 31, v90
	v_lshlrev_b64 v[90:91], 11, v[90:91]
	v_lshl_add_u64 v[90:91], v[92:93], 0, v[90:91]
	global_store_dwordx4 v[90:91], v[86:89], off nt
	ds_read2_b32 v[86:87], v79 offset0:16 offset1:49
	s_mov_b64 s[12:13], -1
	s_waitcnt lgkmcnt(0)
	v_cvt_pk_bf16_f32 v86, v86, v87
	ds_read2_b32 v[88:89], v79 offset0:82 offset1:115
	s_waitcnt lgkmcnt(0)
	v_cvt_pk_bf16_f32 v87, v88, v89
	ds_read2_b32 v[88:89], v79 offset0:148 offset1:181
	s_waitcnt lgkmcnt(0)
	v_cvt_pk_bf16_f32 v88, v88, v89
	ds_read2_b32 v[90:91], v79 offset0:214 offset1:247
	s_waitcnt lgkmcnt(0)
	v_cvt_pk_bf16_f32 v89, v90, v91
	v_or_b32_e32 v90, s45, v81
	v_ashrrev_i32_e32 v91, 31, v90
	v_lshlrev_b64 v[90:91], 11, v[90:91]
	v_lshl_add_u64 v[90:91], v[92:93], 0, v[90:91]
	global_store_dwordx4 v[90:91], v[86:89], off nt
	ds_read2_b32 v[86:87], v79 offset0:24 offset1:57
	s_waitcnt lgkmcnt(0)
	v_cvt_pk_bf16_f32 v86, v86, v87
	ds_read2_b32 v[88:89], v79 offset0:90 offset1:123
	s_waitcnt lgkmcnt(0)
	v_cvt_pk_bf16_f32 v87, v88, v89
	ds_read2_b32 v[88:89], v79 offset0:156 offset1:189
	s_waitcnt lgkmcnt(0)
	v_cvt_pk_bf16_f32 v88, v88, v89
	ds_read2_b32 v[90:91], v79 offset0:222 offset1:255
	s_waitcnt lgkmcnt(0)
	v_cvt_pk_bf16_f32 v89, v90, v91
	v_or_b32_e32 v90, s45, v82
	v_ashrrev_i32_e32 v91, 31, v90
	v_lshlrev_b64 v[90:91], 11, v[90:91]
	v_lshl_add_u64 v[90:91], v[92:93], 0, v[90:91]
	global_store_dwordx4 v[90:91], v[86:89], off nt
	s_waitcnt lgkmcnt(0)
	s_cbranch_vccnz .LBB7_106
	s_add_i32 s12, s55, s16
	s_cmpk_gt_i32 s12, 0x17f
	s_cbranch_scc1 .LBB7_105
	s_ashr_i32 s13, s12, 31
	s_lshr_b32 s13, s13, 27
	s_add_i32 s13, s12, s13
	s_lshr_b32 s16, s13, 5
	s_and_b32 s13, s13, 0x7ffffe0
	s_sub_i32 s13, s12, s13
	s_cmpk_lt_i32 s12, 0xc0
	s_cselect_b32 s12, 0, 4
	s_add_i32 s16, s12, s16
	v_lshl_or_b32 v0, s16, 6, v76
	s_lshl_b32 s12, s13, 5
	v_ashrrev_i32_e32 v1, 31, v0
	v_or_b32_e32 v6, 2, v0
	v_or_b32_e32 v8, 4, v0
	v_or_b32_e32 v10, 6, v0
	v_or_b32_e32 v12, 8, v0
	v_or_b32_e32 v14, 10, v0
	v_or_b32_e32 v16, 12, v0
	v_or_b32_e32 v18, 14, v0
	v_or_b32_e32 v20, 16, v0
	v_or_b32_e32 v22, 18, v0
	v_or_b32_e32 v24, 20, v0
	v_or_b32_e32 v26, 22, v0
	v_or_b32_e32 v28, 24, v0
	v_or_b32_e32 v30, 26, v0
	s_ashr_i32 s13, s12, 31
	v_lshlrev_b64 v[4:5], 12, v[0:1]
	v_ashrrev_i32_e32 v7, 31, v6
	v_ashrrev_i32_e32 v9, 31, v8
	v_ashrrev_i32_e32 v11, 31, v10
	v_ashrrev_i32_e32 v13, 31, v12
	v_ashrrev_i32_e32 v15, 31, v14
	v_ashrrev_i32_e32 v17, 31, v16
	v_ashrrev_i32_e32 v19, 31, v18
	v_ashrrev_i32_e32 v21, 31, v20
	v_ashrrev_i32_e32 v23, 31, v22
	v_ashrrev_i32_e32 v25, 31, v24
	v_ashrrev_i32_e32 v27, 31, v26
	v_ashrrev_i32_e32 v29, 31, v28
	v_ashrrev_i32_e32 v31, 31, v30
	v_or_b32_e32 v86, 28, v0
	v_or_b32_e32 v88, 30, v0
	v_or_b32_e32 v90, 32, v0
	v_or_b32_e32 v92, 34, v0
	v_or_b32_e32 v94, 36, v0
	v_or_b32_e32 v96, 38, v0
	v_or_b32_e32 v98, 40, v0
	v_or_b32_e32 v100, 42, v0
	v_or_b32_e32 v102, 44, v0
	v_or_b32_e32 v104, 46, v0
	v_or_b32_e32 v106, 48, v0
	v_or_b32_e32 v108, 50, v0
	v_or_b32_e32 v110, 52, v0
	v_or_b32_e32 v112, 54, v0
	v_or_b32_e32 v114, 56, v0
	v_or_b32_e32 v116, 58, v0
	v_or_b32_e32 v118, 60, v0
	v_or_b32_e32 v0, 62, v0
	v_lshl_add_u64 v[2:3], s[12:13], 2, v[38:39]
	v_lshlrev_b64 v[6:7], 12, v[6:7]
	v_lshlrev_b64 v[8:9], 12, v[8:9]
	v_lshlrev_b64 v[10:11], 12, v[10:11]
	v_lshlrev_b64 v[12:13], 12, v[12:13]
	v_lshlrev_b64 v[14:15], 12, v[14:15]
	v_lshlrev_b64 v[16:17], 12, v[16:17]
	v_lshlrev_b64 v[18:19], 12, v[18:19]
	v_lshlrev_b64 v[20:21], 12, v[20:21]
	v_lshlrev_b64 v[22:23], 12, v[22:23]
	v_lshlrev_b64 v[24:25], 12, v[24:25]
	v_lshlrev_b64 v[26:27], 12, v[26:27]
	v_lshlrev_b64 v[28:29], 12, v[28:29]
	v_lshlrev_b64 v[30:31], 12, v[30:31]
	v_ashrrev_i32_e32 v87, 31, v86
	v_ashrrev_i32_e32 v89, 31, v88
	v_ashrrev_i32_e32 v91, 31, v90
	v_ashrrev_i32_e32 v93, 31, v92
	v_ashrrev_i32_e32 v95, 31, v94
	v_ashrrev_i32_e32 v97, 31, v96
	v_ashrrev_i32_e32 v99, 31, v98
	v_ashrrev_i32_e32 v101, 31, v100
	v_ashrrev_i32_e32 v103, 31, v102
	v_ashrrev_i32_e32 v105, 31, v104
	v_ashrrev_i32_e32 v107, 31, v106
	v_ashrrev_i32_e32 v109, 31, v108
	v_ashrrev_i32_e32 v111, 31, v110
	v_ashrrev_i32_e32 v113, 31, v112
	v_ashrrev_i32_e32 v115, 31, v114
	v_ashrrev_i32_e32 v117, 31, v116
	v_ashrrev_i32_e32 v119, 31, v118
	v_ashrrev_i32_e32 v1, 31, v0
	v_lshl_add_u64 v[4:5], v[2:3], 0, v[4:5]
	v_lshl_add_u64 v[6:7], v[2:3], 0, v[6:7]
	v_lshl_add_u64 v[8:9], v[2:3], 0, v[8:9]
	v_lshl_add_u64 v[10:11], v[2:3], 0, v[10:11]
	v_lshl_add_u64 v[12:13], v[2:3], 0, v[12:13]
	v_lshl_add_u64 v[14:15], v[2:3], 0, v[14:15]
	v_lshl_add_u64 v[16:17], v[2:3], 0, v[16:17]
	v_lshl_add_u64 v[18:19], v[2:3], 0, v[18:19]
	v_lshl_add_u64 v[20:21], v[2:3], 0, v[20:21]
	v_lshl_add_u64 v[22:23], v[2:3], 0, v[22:23]
	v_lshl_add_u64 v[24:25], v[2:3], 0, v[24:25]
	v_lshl_add_u64 v[26:27], v[2:3], 0, v[26:27]
	v_lshl_add_u64 v[28:29], v[2:3], 0, v[28:29]
	v_lshl_add_u64 v[30:31], v[2:3], 0, v[30:31]
	v_lshlrev_b64 v[86:87], 12, v[86:87]
	v_lshlrev_b64 v[88:89], 12, v[88:89]
	v_lshlrev_b64 v[90:91], 12, v[90:91]
	v_lshlrev_b64 v[92:93], 12, v[92:93]
	v_lshlrev_b64 v[94:95], 12, v[94:95]
	v_lshlrev_b64 v[96:97], 12, v[96:97]
	v_lshlrev_b64 v[98:99], 12, v[98:99]
	v_lshlrev_b64 v[100:101], 12, v[100:101]
	v_lshlrev_b64 v[102:103], 12, v[102:103]
	v_lshlrev_b64 v[104:105], 12, v[104:105]
	v_lshlrev_b64 v[106:107], 12, v[106:107]
	v_lshlrev_b64 v[108:109], 12, v[108:109]
	v_lshlrev_b64 v[110:111], 12, v[110:111]
	v_lshlrev_b64 v[112:113], 12, v[112:113]
	v_lshlrev_b64 v[114:115], 12, v[114:115]
	v_lshlrev_b64 v[116:117], 12, v[116:117]
	v_lshlrev_b64 v[118:119], 12, v[118:119]
	v_lshlrev_b64 v[0:1], 12, v[0:1]
	v_lshl_add_u64 v[86:87], v[2:3], 0, v[86:87]
	v_lshl_add_u64 v[88:89], v[2:3], 0, v[88:89]
	v_lshl_add_u64 v[90:91], v[2:3], 0, v[90:91]
	v_lshl_add_u64 v[92:93], v[2:3], 0, v[92:93]
	v_lshl_add_u64 v[94:95], v[2:3], 0, v[94:95]
	v_lshl_add_u64 v[96:97], v[2:3], 0, v[96:97]
	v_lshl_add_u64 v[98:99], v[2:3], 0, v[98:99]
	v_lshl_add_u64 v[100:101], v[2:3], 0, v[100:101]
	v_lshl_add_u64 v[102:103], v[2:3], 0, v[102:103]
	v_lshl_add_u64 v[104:105], v[2:3], 0, v[104:105]
	v_lshl_add_u64 v[106:107], v[2:3], 0, v[106:107]
	v_lshl_add_u64 v[108:109], v[2:3], 0, v[108:109]
	v_lshl_add_u64 v[110:111], v[2:3], 0, v[110:111]
	v_lshl_add_u64 v[112:113], v[2:3], 0, v[112:113]
	v_lshl_add_u64 v[114:115], v[2:3], 0, v[114:115]
	v_lshl_add_u64 v[116:117], v[2:3], 0, v[116:117]
	v_lshl_add_u64 v[118:119], v[2:3], 0, v[118:119]
	v_lshl_add_u64 v[120:121], v[2:3], 0, v[0:1]
	global_load_dword v0, v[4:5], off nt
	global_load_dword v1, v[6:7], off nt
	global_load_dword v2, v[8:9], off nt
	global_load_dword v3, v[10:11], off nt
	s_nop 0
	global_load_dword v4, v[12:13], off nt
	global_load_dword v5, v[14:15], off nt
	global_load_dword v6, v[16:17], off nt
	global_load_dword v7, v[18:19], off nt
	global_load_dword v8, v[20:21], off nt
	global_load_dword v9, v[22:23], off nt
	global_load_dword v10, v[24:25], off nt
	global_load_dword v11, v[26:27], off nt
	global_load_dword v12, v[28:29], off nt
	global_load_dword v13, v[30:31], off nt
	global_load_dword v14, v[86:87], off nt
	global_load_dword v15, v[88:89], off nt
	global_load_dword v16, v[90:91], off nt
	global_load_dword v17, v[92:93], off nt
	global_load_dword v18, v[94:95], off nt
	global_load_dword v19, v[96:97], off nt
	global_load_dword v20, v[98:99], off nt
	global_load_dword v21, v[100:101], off nt
	global_load_dword v22, v[102:103], off nt
	global_load_dword v23, v[104:105], off nt
	global_load_dword v24, v[106:107], off nt
	global_load_dword v25, v[108:109], off nt
	global_load_dword v26, v[110:111], off nt
	global_load_dword v27, v[112:113], off nt
	global_load_dword v28, v[114:115], off nt
	global_load_dword v29, v[116:117], off nt
	global_load_dword v30, v[118:119], off nt
	global_load_dword v31, v[120:121], off nt
	s_branch .LBB7_105

.LBB7_116:
	ds_write2_b32 v77, v43, v42 offset1:66
	ds_write2_b32 v77, v45, v44 offset0:132 offset1:198
	ds_write2_b32 v32, v47, v46 offset0:8 offset1:74
	ds_write2_b32 v32, v49, v48 offset0:140 offset1:206
	ds_write2_b32 v35, v51, v50 offset0:16 offset1:82
	ds_write2_b32 v35, v53, v52 offset0:148 offset1:214
	ds_write2_b32 v37, v55, v54 offset0:24 offset1:90
	ds_write2_b32 v37, v57, v56 offset0:156 offset1:222
	ds_write2_b32 v84, v59, v58 offset0:32 offset1:98
	ds_write2_b32 v84, v61, v60 offset0:164 offset1:230
	ds_write2_b32 v85, v63, v62 offset0:40 offset1:106
	ds_write2_b32 v85, v65, v64 offset0:172 offset1:238
	ds_write2_b32 v86, v67, v66 offset0:48 offset1:114
	ds_write2_b32 v86, v69, v68 offset0:180 offset1:246
	ds_write2_b32 v87, v71, v70 offset0:56 offset1:122
	ds_write2_b32 v87, v73, v72 offset0:188 offset1:254
	s_waitcnt lgkmcnt(0)
	s_ashr_i32 s45, s50, 31
	s_lshr_b32 s45, s45, 27
	ds_read2_b32 v[74:75], v79 offset1:33
	s_add_i32 s45, s50, s45
	s_waitcnt lgkmcnt(0)
	v_cvt_pk_bf16_f32 v84, v74, v75
	ds_read2_b32 v[74:75], v79 offset0:66 offset1:99
	s_and_b32 s48, s45, 0x7ffffe0
	s_waitcnt lgkmcnt(0)
	v_cvt_pk_bf16_f32 v85, v74, v75
	ds_read2_b32 v[74:75], v79 offset0:132 offset1:165
	s_sub_i32 s49, s50, s48
	s_lshl_b32 s45, s45, 1
	s_waitcnt lgkmcnt(0)
	v_cvt_pk_bf16_f32 v86, v74, v75
	ds_read2_b32 v[74:75], v79 offset0:198 offset1:231
	s_lshl_b32 s51, s49, 5
	s_and_b32 s48, s45, 0xffffffc0
	s_waitcnt lgkmcnt(0)
	v_cvt_pk_bf16_f32 v87, v74, v75
	v_or_b32_e32 v74, s51, v78
	s_ashr_i32 s49, s48, 31
	v_ashrrev_i32_e32 v75, 31, v74
	v_lshl_add_u64 v[88:89], s[48:49], 1, v[30:31]
	v_lshlrev_b64 v[74:75], 11, v[74:75]
	v_lshl_add_u64 v[74:75], v[88:89], 0, v[74:75]
	ds_read2_b32 v[90:91], v79 offset0:8 offset1:41
	global_store_dwordx4 v[74:75], v[84:87], off nt
	s_add_i32 s45, s50, s72
	s_cmpk_gt_i32 s45, 0x1ff
	s_waitcnt lgkmcnt(0)
	v_cvt_pk_bf16_f32 v84, v90, v91
	ds_read2_b32 v[74:75], v79 offset0:74 offset1:107
	s_waitcnt lgkmcnt(0)
	v_cvt_pk_bf16_f32 v85, v74, v75
	ds_read2_b32 v[74:75], v79 offset0:140 offset1:173
	s_waitcnt lgkmcnt(0)
	v_cvt_pk_bf16_f32 v86, v74, v75
	ds_read2_b32 v[74:75], v79 offset0:206 offset1:239
	s_waitcnt lgkmcnt(0)
	v_cvt_pk_bf16_f32 v87, v74, v75
	v_or_b32_e32 v74, s51, v80
	v_ashrrev_i32_e32 v75, 31, v74
	v_lshlrev_b64 v[74:75], 11, v[74:75]
	ds_read2_b32 v[90:91], v79 offset0:16 offset1:49
	v_lshl_add_u64 v[74:75], v[88:89], 0, v[74:75]
	global_store_dwordx4 v[74:75], v[84:87], off nt
	s_cselect_b64 s[48:49], -1, 0
	s_waitcnt lgkmcnt(0)
	v_cvt_pk_bf16_f32 v84, v90, v91
	ds_read2_b32 v[74:75], v79 offset0:82 offset1:115
	v_or_b32_e32 v90, s51, v81
	s_waitcnt lgkmcnt(0)
	v_cvt_pk_bf16_f32 v85, v74, v75
	ds_read2_b32 v[74:75], v79 offset0:148 offset1:181
	v_ashrrev_i32_e32 v91, 31, v90
	s_waitcnt lgkmcnt(0)
	v_cvt_pk_bf16_f32 v86, v74, v75
	ds_read2_b32 v[74:75], v79 offset0:214 offset1:247
	v_lshlrev_b64 v[90:91], 11, v[90:91]
	s_waitcnt lgkmcnt(0)
	v_cvt_pk_bf16_f32 v87, v74, v75
	ds_read2_b32 v[74:75], v79 offset0:24 offset1:57
	v_lshl_add_u64 v[90:91], v[88:89], 0, v[90:91]
	global_store_dwordx4 v[90:91], v[84:87], off nt
	v_or_b32_e32 v90, s51, v82
	v_ashrrev_i32_e32 v91, 31, v90
	s_waitcnt lgkmcnt(0)
	v_cvt_pk_bf16_f32 v84, v74, v75
	ds_read2_b32 v[74:75], v79 offset0:90 offset1:123
	s_waitcnt lgkmcnt(0)
	v_cvt_pk_bf16_f32 v85, v74, v75
	ds_read2_b32 v[74:75], v79 offset0:156 offset1:189
	s_waitcnt lgkmcnt(0)
	v_cvt_pk_bf16_f32 v86, v74, v75
	ds_read2_b32 v[74:75], v79 offset0:222 offset1:255
	v_lshlrev_b64 v[90:91], 11, v[90:91]
	s_waitcnt lgkmcnt(0)
	v_cvt_pk_bf16_f32 v87, v74, v75
	v_lshl_add_u64 v[74:75], v[88:89], 0, v[90:91]
	global_store_dwordx4 v[74:75], v[84:87], off nt
	s_waitcnt lgkmcnt(0)

.LBB7_121:
	v_add_u32_e32 v32, 0x400, v77
	v_add_u32_e32 v35, 0x800, v77
	v_add_u32_e32 v37, 0xc00, v77
	v_add_u32_e32 v84, 0x1000, v77
	v_add_u32_e32 v85, 0x1400, v77
	v_add_u32_e32 v86, 0x1800, v77
	v_add_u32_e32 v87, 0x1c00, v77
	s_waitcnt vmcnt(30)
	ds_write2_b32 v77, v0, v1 offset1:66
	s_waitcnt vmcnt(28)
	ds_write2_b32 v77, v2, v3 offset0:132 offset1:198
	s_waitcnt vmcnt(26)
	ds_write2_b32 v32, v4, v5 offset0:8 offset1:74
	s_waitcnt vmcnt(24)
	ds_write2_b32 v32, v6, v7 offset0:140 offset1:206
	s_waitcnt vmcnt(22)
	ds_write2_b32 v35, v8, v9 offset0:16 offset1:82
	s_waitcnt vmcnt(20)
	ds_write2_b32 v35, v10, v11 offset0:148 offset1:214
	s_waitcnt vmcnt(18)
	ds_write2_b32 v37, v12, v13 offset0:24 offset1:90
	s_waitcnt vmcnt(16)
	ds_write2_b32 v37, v14, v15 offset0:156 offset1:222
	s_waitcnt vmcnt(14)
	ds_write2_b32 v84, v16, v17 offset0:32 offset1:98
	s_waitcnt vmcnt(12)
	ds_write2_b32 v84, v18, v19 offset0:164 offset1:230
	s_waitcnt vmcnt(10)
	ds_write2_b32 v85, v20, v21 offset0:40 offset1:106
	s_waitcnt vmcnt(8)
	ds_write2_b32 v85, v22, v23 offset0:172 offset1:238
	s_waitcnt vmcnt(6)
	ds_write2_b32 v86, v24, v25 offset0:48 offset1:114
	s_waitcnt vmcnt(4)
	ds_write2_b32 v86, v28, v29 offset0:180 offset1:246
	s_waitcnt vmcnt(2)
	ds_write2_b32 v87, v38, v39 offset0:56 offset1:122
	s_waitcnt vmcnt(0)
	ds_write2_b32 v87, v40, v41 offset0:188 offset1:254
	s_waitcnt lgkmcnt(0)
	s_ashr_i32 s51, s45, 31
	s_lshr_b32 s51, s51, 27
	ds_read2_b32 v[74:75], v79 offset1:33
	s_add_i32 s51, s45, s51
	s_waitcnt lgkmcnt(0)
	v_cvt_pk_bf16_f32 v88, v74, v75
	ds_read2_b32 v[74:75], v79 offset0:66 offset1:99
	s_and_b32 s64, s51, 0x7ffffe0
	s_waitcnt lgkmcnt(0)
	v_cvt_pk_bf16_f32 v89, v74, v75
	ds_read2_b32 v[74:75], v79 offset0:132 offset1:165
	s_sub_i32 s65, s45, s64
	s_lshl_b32 s51, s51, 1
	s_waitcnt lgkmcnt(0)
	v_cvt_pk_bf16_f32 v90, v74, v75
	ds_read2_b32 v[74:75], v79 offset0:198 offset1:231
	s_and_b32 s64, s51, 0xffffffc0
	s_lshl_b32 s51, s65, 5
	s_waitcnt lgkmcnt(0)
	v_cvt_pk_bf16_f32 v91, v74, v75
	v_or_b32_e32 v74, s51, v78
	s_ashr_i32 s65, s64, 31
	v_ashrrev_i32_e32 v75, 31, v74
	v_lshl_add_u64 v[92:93], s[64:65], 1, v[30:31]
	v_lshlrev_b64 v[74:75], 11, v[74:75]
	v_lshl_add_u64 v[74:75], v[92:93], 0, v[74:75]
	ds_read2_b32 v[94:95], v79 offset0:8 offset1:41
	global_store_dwordx4 v[74:75], v[88:91], off nt
	s_andn2_b64 vcc, exec, s[48:49]
	s_mov_b64 s[48:49], -1
	s_waitcnt lgkmcnt(0)
	v_cvt_pk_bf16_f32 v88, v94, v95
	ds_read2_b32 v[74:75], v79 offset0:74 offset1:107
	s_waitcnt lgkmcnt(0)
	v_cvt_pk_bf16_f32 v89, v74, v75
	ds_read2_b32 v[74:75], v79 offset0:140 offset1:173
	s_waitcnt lgkmcnt(0)
	v_cvt_pk_bf16_f32 v90, v74, v75
	ds_read2_b32 v[74:75], v79 offset0:206 offset1:239
	s_waitcnt lgkmcnt(0)
	v_cvt_pk_bf16_f32 v91, v74, v75
	v_or_b32_e32 v74, s51, v80
	v_ashrrev_i32_e32 v75, 31, v74
	v_lshlrev_b64 v[74:75], 11, v[74:75]
	v_lshl_add_u64 v[74:75], v[92:93], 0, v[74:75]
	ds_read2_b32 v[94:95], v79 offset0:16 offset1:49
	global_store_dwordx4 v[74:75], v[88:91], off nt
	s_waitcnt lgkmcnt(0)
	s_nop 0
	v_cvt_pk_bf16_f32 v88, v94, v95
	ds_read2_b32 v[74:75], v79 offset0:82 offset1:115
	s_waitcnt lgkmcnt(0)
	v_cvt_pk_bf16_f32 v89, v74, v75
	ds_read2_b32 v[74:75], v79 offset0:148 offset1:181
	s_waitcnt lgkmcnt(0)
	v_cvt_pk_bf16_f32 v90, v74, v75
	ds_read2_b32 v[74:75], v79 offset0:214 offset1:247
	s_waitcnt lgkmcnt(0)
	v_cvt_pk_bf16_f32 v91, v74, v75
	v_or_b32_e32 v74, s51, v81
	v_ashrrev_i32_e32 v75, 31, v74
	v_lshlrev_b64 v[74:75], 11, v[74:75]
	ds_read2_b32 v[94:95], v79 offset0:24 offset1:57
	v_lshl_add_u64 v[74:75], v[92:93], 0, v[74:75]
	global_store_dwordx4 v[74:75], v[88:91], off nt
	s_waitcnt lgkmcnt(0)
	s_nop 0
	v_cvt_pk_bf16_f32 v88, v94, v95
	ds_read2_b32 v[74:75], v79 offset0:90 offset1:123
	v_or_b32_e32 v94, s51, v82
	s_waitcnt lgkmcnt(0)
	v_cvt_pk_bf16_f32 v89, v74, v75
	ds_read2_b32 v[74:75], v79 offset0:156 offset1:189
	v_ashrrev_i32_e32 v95, 31, v94
	s_waitcnt lgkmcnt(0)
	v_cvt_pk_bf16_f32 v90, v74, v75
	ds_read2_b32 v[74:75], v79 offset0:222 offset1:255
	v_lshlrev_b64 v[94:95], 11, v[94:95]
	s_waitcnt lgkmcnt(0)
	v_cvt_pk_bf16_f32 v91, v74, v75
	v_lshl_add_u64 v[74:75], v[92:93], 0, v[94:95]
	global_store_dwordx4 v[74:75], v[88:91], off nt
	s_waitcnt lgkmcnt(0)
	s_cbranch_vccnz .LBB7_117
	s_add_i32 s45, s55, s45
	s_cmpk_gt_i32 s45, 0x1ff
	s_cbranch_scc1 .LBB7_116
	s_ashr_i32 s48, s45, 31
	s_lshr_b32 s48, s48, 27
	s_add_i32 s48, s45, s48
	s_and_b32 s49, s48, 0x7ffffe0
	s_lshl_b32 s48, s48, 1
	s_sub_i32 s45, s45, s49
	s_and_b32 s49, s48, 0xffffffc0
	v_or_b32_e32 v74, s49, v76
	s_lshl_b32 s48, s45, 5
	v_or_b32_e32 v2, 2, v74
	v_or_b32_e32 v4, 4, v74
	v_or_b32_e32 v6, 6, v74
	v_or_b32_e32 v8, 8, v74
	v_or_b32_e32 v10, 10, v74
	v_or_b32_e32 v12, 12, v74
	v_or_b32_e32 v14, 14, v74
	s_ashr_i32 s49, s48, 31
	v_ashrrev_i32_e32 v75, 31, v74
	v_ashrrev_i32_e32 v3, 31, v2
	v_ashrrev_i32_e32 v5, 31, v4
	v_ashrrev_i32_e32 v7, 31, v6
	v_ashrrev_i32_e32 v9, 31, v8
	v_ashrrev_i32_e32 v11, 31, v10
	v_ashrrev_i32_e32 v13, 31, v12
	v_ashrrev_i32_e32 v15, 31, v14
	v_lshl_add_u64 v[24:25], s[48:49], 2, v[26:27]
	v_lshlrev_b64 v[0:1], 12, v[74:75]
	v_lshlrev_b64 v[2:3], 12, v[2:3]
	v_lshlrev_b64 v[4:5], 12, v[4:5]
	v_lshlrev_b64 v[6:7], 12, v[6:7]
	v_lshlrev_b64 v[8:9], 12, v[8:9]
	v_lshlrev_b64 v[10:11], 12, v[10:11]
	v_lshlrev_b64 v[12:13], 12, v[12:13]
	v_lshlrev_b64 v[14:15], 12, v[14:15]
	v_lshl_add_u64 v[0:1], v[24:25], 0, v[0:1]
	v_lshl_add_u64 v[2:3], v[24:25], 0, v[2:3]
	v_lshl_add_u64 v[4:5], v[24:25], 0, v[4:5]
	v_lshl_add_u64 v[6:7], v[24:25], 0, v[6:7]
	v_lshl_add_u64 v[8:9], v[24:25], 0, v[8:9]
	v_lshl_add_u64 v[10:11], v[24:25], 0, v[10:11]
	v_lshl_add_u64 v[12:13], v[24:25], 0, v[12:13]
	v_lshl_add_u64 v[14:15], v[24:25], 0, v[14:15]
	global_load_dword v0, v[0:1], off nt
	s_nop 0
	global_load_dword v1, v[2:3], off nt
	s_nop 0
	global_load_dword v2, v[4:5], off nt
	global_load_dword v3, v[6:7], off nt
	s_nop 0
	global_load_dword v4, v[8:9], off nt
	global_load_dword v5, v[10:11], off nt
	global_load_dword v6, v[12:13], off nt
	global_load_dword v7, v[14:15], off nt
	v_or_b32_e32 v8, 16, v74
	v_or_b32_e32 v10, 18, v74
	v_or_b32_e32 v12, 20, v74
	v_or_b32_e32 v14, 22, v74
	v_or_b32_e32 v16, 24, v74
	v_or_b32_e32 v18, 26, v74
	v_or_b32_e32 v20, 28, v74
	v_or_b32_e32 v22, 30, v74
	v_ashrrev_i32_e32 v9, 31, v8
	v_ashrrev_i32_e32 v11, 31, v10
	v_ashrrev_i32_e32 v13, 31, v12
	v_ashrrev_i32_e32 v15, 31, v14
	v_ashrrev_i32_e32 v17, 31, v16
	v_ashrrev_i32_e32 v19, 31, v18
	v_ashrrev_i32_e32 v21, 31, v20
	v_ashrrev_i32_e32 v23, 31, v22
	v_lshlrev_b64 v[8:9], 12, v[8:9]
	v_lshlrev_b64 v[10:11], 12, v[10:11]
	v_lshlrev_b64 v[12:13], 12, v[12:13]
	v_lshlrev_b64 v[14:15], 12, v[14:15]
	v_lshlrev_b64 v[16:17], 12, v[16:17]
	v_lshlrev_b64 v[18:19], 12, v[18:19]
	v_lshlrev_b64 v[20:21], 12, v[20:21]
	v_lshlrev_b64 v[22:23], 12, v[22:23]
	v_lshl_add_u64 v[8:9], v[24:25], 0, v[8:9]
	v_lshl_add_u64 v[10:11], v[24:25], 0, v[10:11]
	v_lshl_add_u64 v[12:13], v[24:25], 0, v[12:13]
	v_lshl_add_u64 v[14:15], v[24:25], 0, v[14:15]
	v_lshl_add_u64 v[16:17], v[24:25], 0, v[16:17]
	v_lshl_add_u64 v[18:19], v[24:25], 0, v[18:19]
	v_lshl_add_u64 v[20:21], v[24:25], 0, v[20:21]
	v_lshl_add_u64 v[22:23], v[24:25], 0, v[22:23]
	global_load_dword v8, v[8:9], off nt
	s_nop 0
	global_load_dword v9, v[10:11], off nt
	s_nop 0
	global_load_dword v10, v[12:13], off nt
	global_load_dword v11, v[14:15], off nt
	s_nop 0
	global_load_dword v12, v[16:17], off nt
	global_load_dword v13, v[18:19], off nt
	global_load_dword v14, v[20:21], off nt
	global_load_dword v15, v[22:23], off nt
	v_or_b32_e32 v16, 32, v74
	v_or_b32_e32 v18, 34, v74
	v_or_b32_e32 v20, 36, v74
	v_or_b32_e32 v22, 38, v74
	v_or_b32_e32 v28, 40, v74
	v_or_b32_e32 v38, 42, v74
	v_or_b32_e32 v40, 44, v74
	v_ashrrev_i32_e32 v17, 31, v16
	v_ashrrev_i32_e32 v19, 31, v18
	v_ashrrev_i32_e32 v21, 31, v20
	v_ashrrev_i32_e32 v23, 31, v22
	v_ashrrev_i32_e32 v29, 31, v28
	v_ashrrev_i32_e32 v39, 31, v38
	v_ashrrev_i32_e32 v41, 31, v40
	v_or_b32_e32 v88, 46, v74
	v_lshlrev_b64 v[16:17], 12, v[16:17]
	v_lshlrev_b64 v[18:19], 12, v[18:19]
	v_lshlrev_b64 v[20:21], 12, v[20:21]
	v_lshlrev_b64 v[22:23], 12, v[22:23]
	v_lshlrev_b64 v[28:29], 12, v[28:29]
	v_lshlrev_b64 v[38:39], 12, v[38:39]
	v_lshlrev_b64 v[40:41], 12, v[40:41]
	v_ashrrev_i32_e32 v89, 31, v88
	v_lshl_add_u64 v[16:17], v[24:25], 0, v[16:17]
	v_lshl_add_u64 v[18:19], v[24:25], 0, v[18:19]
	v_lshl_add_u64 v[20:21], v[24:25], 0, v[20:21]
	v_lshl_add_u64 v[22:23], v[24:25], 0, v[22:23]
	v_lshl_add_u64 v[28:29], v[24:25], 0, v[28:29]
	v_lshl_add_u64 v[38:39], v[24:25], 0, v[38:39]
	v_lshl_add_u64 v[40:41], v[24:25], 0, v[40:41]
	v_lshlrev_b64 v[88:89], 12, v[88:89]
	v_lshl_add_u64 v[88:89], v[24:25], 0, v[88:89]
	global_load_dword v16, v[16:17], off nt
	s_nop 0
	global_load_dword v17, v[18:19], off nt
	s_nop 0
	global_load_dword v18, v[20:21], off nt
	global_load_dword v19, v[22:23], off nt
	s_nop 0
	global_load_dword v20, v[28:29], off nt
	global_load_dword v21, v[38:39], off nt
	global_load_dword v22, v[40:41], off nt
	global_load_dword v23, v[88:89], off nt
	v_or_b32_e32 v28, 48, v74
	v_or_b32_e32 v38, 50, v74
	v_or_b32_e32 v40, 52, v74
	v_ashrrev_i32_e32 v29, 31, v28
	v_ashrrev_i32_e32 v39, 31, v38
	v_ashrrev_i32_e32 v41, 31, v40
	v_or_b32_e32 v88, 54, v74
	v_or_b32_e32 v90, 56, v74
	v_or_b32_e32 v92, 58, v74
	v_or_b32_e32 v94, 60, v74
	v_or_b32_e32 v96, 62, v74
	v_lshlrev_b64 v[28:29], 12, v[28:29]
	v_lshlrev_b64 v[38:39], 12, v[38:39]
	v_lshlrev_b64 v[40:41], 12, v[40:41]
	v_ashrrev_i32_e32 v89, 31, v88
	v_ashrrev_i32_e32 v91, 31, v90
	v_ashrrev_i32_e32 v93, 31, v92
	v_ashrrev_i32_e32 v95, 31, v94
	v_ashrrev_i32_e32 v97, 31, v96
	v_lshl_add_u64 v[28:29], v[24:25], 0, v[28:29]
	v_lshl_add_u64 v[38:39], v[24:25], 0, v[38:39]
	v_lshl_add_u64 v[40:41], v[24:25], 0, v[40:41]
	v_lshlrev_b64 v[88:89], 12, v[88:89]
	v_lshlrev_b64 v[90:91], 12, v[90:91]
	v_lshlrev_b64 v[92:93], 12, v[92:93]
	v_lshlrev_b64 v[94:95], 12, v[94:95]
	v_lshlrev_b64 v[96:97], 12, v[96:97]
	v_lshl_add_u64 v[88:89], v[24:25], 0, v[88:89]
	v_lshl_add_u64 v[90:91], v[24:25], 0, v[90:91]
	v_lshl_add_u64 v[92:93], v[24:25], 0, v[92:93]
	v_lshl_add_u64 v[94:95], v[24:25], 0, v[94:95]
	v_lshl_add_u64 v[96:97], v[24:25], 0, v[96:97]
	global_load_dword v24, v[28:29], off nt
	global_load_dword v25, v[38:39], off nt
	s_nop 0
	global_load_dword v28, v[40:41], off nt
	global_load_dword v29, v[88:89], off nt
	global_load_dword v38, v[90:91], off nt
	global_load_dword v39, v[92:93], off nt
	s_nop 0
	global_load_dword v40, v[94:95], off nt
	global_load_dword v41, v[96:97], off nt
	s_andn2_b64 vcc, exec, s[14:15]
	s_cbranch_vccnz .LBB7_116
	v_lshl_add_u64 v[74:75], v[74:75], 2, s[12:13]
	global_load_dword v88, v[74:75], off
	global_load_dword v89, v[74:75], off offset:8
	global_load_dword v90, v[74:75], off offset:16
	global_load_dword v91, v[74:75], off offset:24
	global_load_dword v92, v[74:75], off offset:32
	global_load_dword v93, v[74:75], off offset:40
	global_load_dword v94, v[74:75], off offset:48
	global_load_dword v95, v[74:75], off offset:56
	global_load_dword v96, v[74:75], off offset:64
	global_load_dword v97, v[74:75], off offset:72
	global_load_dword v98, v[74:75], off offset:80
	global_load_dword v99, v[74:75], off offset:88
	global_load_dword v100, v[74:75], off offset:96
	global_load_dword v101, v[74:75], off offset:104
	global_load_dword v102, v[74:75], off offset:112
	global_load_dword v103, v[74:75], off offset:120
	global_load_dword v104, v[74:75], off offset:128
	global_load_dword v105, v[74:75], off offset:136
	global_load_dword v106, v[74:75], off offset:144
	global_load_dword v107, v[74:75], off offset:152
	global_load_dword v108, v[74:75], off offset:160
	global_load_dword v109, v[74:75], off offset:168
	global_load_dword v110, v[74:75], off offset:176
	global_load_dword v111, v[74:75], off offset:184
	global_load_dword v112, v[74:75], off offset:192
	global_load_dword v113, v[74:75], off offset:200
	global_load_dword v114, v[74:75], off offset:208
	global_load_dword v115, v[74:75], off offset:216
	global_load_dword v116, v[74:75], off offset:224
	global_load_dword v117, v[74:75], off offset:232
	global_load_dword v118, v[74:75], off offset:240
	global_load_dword v119, v[74:75], off offset:248
	s_waitcnt vmcnt(30)
	v_pk_mul_f32 v[0:1], v[0:1], v[88:89]
	s_waitcnt vmcnt(28)
	v_pk_mul_f32 v[2:3], v[2:3], v[90:91]
	s_waitcnt vmcnt(26)
	v_pk_mul_f32 v[4:5], v[4:5], v[92:93]
	s_waitcnt vmcnt(24)
	v_pk_mul_f32 v[6:7], v[6:7], v[94:95]
	s_waitcnt vmcnt(22)
	v_pk_mul_f32 v[8:9], v[8:9], v[96:97]
	s_waitcnt vmcnt(20)
	v_pk_mul_f32 v[10:11], v[10:11], v[98:99]
	s_waitcnt vmcnt(18)
	v_pk_mul_f32 v[12:13], v[12:13], v[100:101]
	s_waitcnt vmcnt(16)
	v_pk_mul_f32 v[14:15], v[14:15], v[102:103]
	s_waitcnt vmcnt(14)
	v_pk_mul_f32 v[16:17], v[16:17], v[104:105]
	s_waitcnt vmcnt(12)
	v_pk_mul_f32 v[18:19], v[18:19], v[106:107]
	s_waitcnt vmcnt(10)
	v_pk_mul_f32 v[20:21], v[20:21], v[108:109]
	s_waitcnt vmcnt(8)
	v_pk_mul_f32 v[22:23], v[22:23], v[110:111]
	s_waitcnt vmcnt(6)
	v_pk_mul_f32 v[24:25], v[24:25], v[112:113]
	s_waitcnt vmcnt(4)
	v_pk_mul_f32 v[28:29], v[28:29], v[114:115]
	s_waitcnt vmcnt(2)
	v_pk_mul_f32 v[38:39], v[38:39], v[116:117]
	s_waitcnt vmcnt(0)
	v_pk_mul_f32 v[40:41], v[40:41], v[118:119]
	s_branch .LBB7_116

.LBB7_134:
	v_add_u32_e32 v32, 0x400, v77
	v_add_u32_e32 v35, 0x800, v77
	v_add_u32_e32 v37, 0xc00, v77
	v_add_u32_e32 v84, 0x1000, v77
	v_add_u32_e32 v85, 0x1400, v77
	v_add_u32_e32 v86, 0x1800, v77
	v_add_u32_e32 v87, 0x1c00, v77
	s_waitcnt vmcnt(30)
	ds_write2_b32 v77, v0, v1 offset1:66
	s_waitcnt vmcnt(28)
	ds_write2_b32 v77, v2, v3 offset0:132 offset1:198
	s_waitcnt vmcnt(26)
	ds_write2_b32 v32, v4, v5 offset0:8 offset1:74
	s_waitcnt vmcnt(24)
	ds_write2_b32 v32, v6, v7 offset0:140 offset1:206
	s_waitcnt vmcnt(22)
	ds_write2_b32 v35, v8, v9 offset0:16 offset1:82
	s_waitcnt vmcnt(20)
	ds_write2_b32 v35, v10, v11 offset0:148 offset1:214
	s_waitcnt vmcnt(18)
	ds_write2_b32 v37, v12, v13 offset0:24 offset1:90
	s_waitcnt vmcnt(16)
	ds_write2_b32 v37, v14, v15 offset0:156 offset1:222
	s_waitcnt vmcnt(14)
	ds_write2_b32 v84, v16, v17 offset0:32 offset1:98
	s_waitcnt vmcnt(12)
	ds_write2_b32 v84, v18, v19 offset0:164 offset1:230
	s_waitcnt vmcnt(10)
	ds_write2_b32 v85, v20, v21 offset0:40 offset1:106
	s_waitcnt vmcnt(8)
	ds_write2_b32 v85, v22, v23 offset0:172 offset1:238
	s_waitcnt vmcnt(6)
	ds_write2_b32 v86, v24, v25 offset0:48 offset1:114
	s_waitcnt vmcnt(4)
	ds_write2_b32 v86, v28, v29 offset0:180 offset1:246
	s_waitcnt vmcnt(2)
	ds_write2_b32 v87, v38, v39 offset0:56 offset1:122
	s_waitcnt vmcnt(0)
	ds_write2_b32 v87, v40, v41 offset0:188 offset1:254
	s_waitcnt lgkmcnt(0)
	s_ashr_i32 s51, s45, 31
	s_lshr_b32 s51, s51, 27
	ds_read2_b32 v[74:75], v79 offset1:33
	s_add_i32 s51, s45, s51
	s_waitcnt lgkmcnt(0)
	v_cvt_pk_bf16_f32 v88, v74, v75
	ds_read2_b32 v[74:75], v79 offset0:66 offset1:99
	s_and_b32 s64, s51, 0x7ffffe0
	s_waitcnt lgkmcnt(0)
	v_cvt_pk_bf16_f32 v89, v74, v75
	ds_read2_b32 v[74:75], v79 offset0:132 offset1:165
	s_sub_i32 s65, s45, s64
	s_lshl_b32 s51, s51, 1
	s_waitcnt lgkmcnt(0)
	v_cvt_pk_bf16_f32 v90, v74, v75
	ds_read2_b32 v[74:75], v79 offset0:198 offset1:231
	s_and_b32 s64, s51, 0xffffffc0
	s_lshl_b32 s51, s65, 5
	s_waitcnt lgkmcnt(0)
	v_cvt_pk_bf16_f32 v91, v74, v75
	v_or_b32_e32 v74, s51, v78
	s_ashr_i32 s65, s64, 31
	v_ashrrev_i32_e32 v75, 31, v74
	v_lshl_add_u64 v[92:93], s[64:65], 1, v[30:31]
	v_lshlrev_b64 v[74:75], 11, v[74:75]
	v_lshl_add_u64 v[74:75], v[92:93], 0, v[74:75]
	ds_read2_b32 v[94:95], v79 offset0:8 offset1:41
	global_store_dwordx4 v[74:75], v[88:91], off nt
	s_andn2_b64 vcc, exec, s[48:49]
	s_mov_b64 s[48:49], -1
	s_waitcnt lgkmcnt(0)
	v_cvt_pk_bf16_f32 v88, v94, v95
	ds_read2_b32 v[74:75], v79 offset0:74 offset1:107
	s_waitcnt lgkmcnt(0)
	v_cvt_pk_bf16_f32 v89, v74, v75
	ds_read2_b32 v[74:75], v79 offset0:140 offset1:173
	s_waitcnt lgkmcnt(0)
	v_cvt_pk_bf16_f32 v90, v74, v75
	ds_read2_b32 v[74:75], v79 offset0:206 offset1:239
	s_waitcnt lgkmcnt(0)
	v_cvt_pk_bf16_f32 v91, v74, v75
	v_or_b32_e32 v74, s51, v80
	v_ashrrev_i32_e32 v75, 31, v74
	v_lshlrev_b64 v[74:75], 11, v[74:75]
	v_lshl_add_u64 v[74:75], v[92:93], 0, v[74:75]
	ds_read2_b32 v[94:95], v79 offset0:16 offset1:49
	global_store_dwordx4 v[74:75], v[88:91], off nt
	s_waitcnt lgkmcnt(0)
	s_nop 0
	v_cvt_pk_bf16_f32 v88, v94, v95
	ds_read2_b32 v[74:75], v79 offset0:82 offset1:115
	s_waitcnt lgkmcnt(0)
	v_cvt_pk_bf16_f32 v89, v74, v75
	ds_read2_b32 v[74:75], v79 offset0:148 offset1:181
	s_waitcnt lgkmcnt(0)
	v_cvt_pk_bf16_f32 v90, v74, v75
	ds_read2_b32 v[74:75], v79 offset0:214 offset1:247
	s_waitcnt lgkmcnt(0)
	v_cvt_pk_bf16_f32 v91, v74, v75
	v_or_b32_e32 v74, s51, v81
	v_ashrrev_i32_e32 v75, 31, v74
	v_lshlrev_b64 v[74:75], 11, v[74:75]
	ds_read2_b32 v[94:95], v79 offset0:24 offset1:57
	v_lshl_add_u64 v[74:75], v[92:93], 0, v[74:75]
	global_store_dwordx4 v[74:75], v[88:91], off nt
	s_waitcnt lgkmcnt(0)
	s_nop 0
	v_cvt_pk_bf16_f32 v88, v94, v95
	ds_read2_b32 v[74:75], v79 offset0:90 offset1:123
	v_or_b32_e32 v94, s51, v82
	s_waitcnt lgkmcnt(0)
	v_cvt_pk_bf16_f32 v89, v74, v75
	ds_read2_b32 v[74:75], v79 offset0:156 offset1:189
	v_ashrrev_i32_e32 v95, 31, v94
	s_waitcnt lgkmcnt(0)
	v_cvt_pk_bf16_f32 v90, v74, v75
	ds_read2_b32 v[74:75], v79 offset0:222 offset1:255
	v_lshlrev_b64 v[94:95], 11, v[94:95]
	s_waitcnt lgkmcnt(0)
	v_cvt_pk_bf16_f32 v91, v74, v75
	v_lshl_add_u64 v[74:75], v[92:93], 0, v[94:95]
	global_store_dwordx4 v[74:75], v[88:91], off nt
	s_waitcnt lgkmcnt(0)
	s_cbranch_vccnz .LBB7_130
	s_add_i32 s45, s55, s45
	s_cmpk_gt_i32 s45, 0x1ff
	s_cbranch_scc1 .LBB7_129
	s_ashr_i32 s48, s45, 31
	s_lshr_b32 s48, s48, 27
	s_add_i32 s48, s45, s48
	s_and_b32 s49, s48, 0x7ffffe0
	s_lshl_b32 s48, s48, 1
	s_sub_i32 s45, s45, s49
	s_and_b32 s49, s48, 0xffffffc0
	v_or_b32_e32 v74, s49, v76
	s_lshl_b32 s48, s45, 5
	v_or_b32_e32 v2, 2, v74
	v_or_b32_e32 v4, 4, v74
	v_or_b32_e32 v6, 6, v74
	v_or_b32_e32 v8, 8, v74
	v_or_b32_e32 v10, 10, v74
	v_or_b32_e32 v12, 12, v74
	v_or_b32_e32 v14, 14, v74
	s_ashr_i32 s49, s48, 31
	v_ashrrev_i32_e32 v75, 31, v74
	v_ashrrev_i32_e32 v3, 31, v2
	v_ashrrev_i32_e32 v5, 31, v4
	v_ashrrev_i32_e32 v7, 31, v6
	v_ashrrev_i32_e32 v9, 31, v8
	v_ashrrev_i32_e32 v11, 31, v10
	v_ashrrev_i32_e32 v13, 31, v12
	v_ashrrev_i32_e32 v15, 31, v14
	v_lshl_add_u64 v[24:25], s[48:49], 2, v[26:27]
	v_lshlrev_b64 v[0:1], 12, v[74:75]
	v_lshlrev_b64 v[2:3], 12, v[2:3]
	v_lshlrev_b64 v[4:5], 12, v[4:5]
	v_lshlrev_b64 v[6:7], 12, v[6:7]
	v_lshlrev_b64 v[8:9], 12, v[8:9]
	v_lshlrev_b64 v[10:11], 12, v[10:11]
	v_lshlrev_b64 v[12:13], 12, v[12:13]
	v_lshlrev_b64 v[14:15], 12, v[14:15]
	v_lshl_add_u64 v[0:1], v[24:25], 0, v[0:1]
	v_lshl_add_u64 v[2:3], v[24:25], 0, v[2:3]
	v_lshl_add_u64 v[4:5], v[24:25], 0, v[4:5]
	v_lshl_add_u64 v[6:7], v[24:25], 0, v[6:7]
	v_lshl_add_u64 v[8:9], v[24:25], 0, v[8:9]
	v_lshl_add_u64 v[10:11], v[24:25], 0, v[10:11]
	v_lshl_add_u64 v[12:13], v[24:25], 0, v[12:13]
	v_lshl_add_u64 v[14:15], v[24:25], 0, v[14:15]
	global_load_dword v0, v[0:1], off nt
	s_nop 0
	global_load_dword v1, v[2:3], off nt
	s_nop 0
	global_load_dword v2, v[4:5], off nt
	global_load_dword v3, v[6:7], off nt
	s_nop 0
	global_load_dword v4, v[8:9], off nt
	global_load_dword v5, v[10:11], off nt
	global_load_dword v6, v[12:13], off nt
	global_load_dword v7, v[14:15], off nt
	v_or_b32_e32 v8, 16, v74
	v_or_b32_e32 v10, 18, v74
	v_or_b32_e32 v12, 20, v74
	v_or_b32_e32 v14, 22, v74
	v_or_b32_e32 v16, 24, v74
	v_or_b32_e32 v18, 26, v74
	v_or_b32_e32 v20, 28, v74
	v_or_b32_e32 v22, 30, v74
	v_ashrrev_i32_e32 v9, 31, v8
	v_ashrrev_i32_e32 v11, 31, v10
	v_ashrrev_i32_e32 v13, 31, v12
	v_ashrrev_i32_e32 v15, 31, v14
	v_ashrrev_i32_e32 v17, 31, v16
	v_ashrrev_i32_e32 v19, 31, v18
	v_ashrrev_i32_e32 v21, 31, v20
	v_ashrrev_i32_e32 v23, 31, v22
	v_lshlrev_b64 v[8:9], 12, v[8:9]
	v_lshlrev_b64 v[10:11], 12, v[10:11]
	v_lshlrev_b64 v[12:13], 12, v[12:13]
	v_lshlrev_b64 v[14:15], 12, v[14:15]
	v_lshlrev_b64 v[16:17], 12, v[16:17]
	v_lshlrev_b64 v[18:19], 12, v[18:19]
	v_lshlrev_b64 v[20:21], 12, v[20:21]
	v_lshlrev_b64 v[22:23], 12, v[22:23]
	v_lshl_add_u64 v[8:9], v[24:25], 0, v[8:9]
	v_lshl_add_u64 v[10:11], v[24:25], 0, v[10:11]
	v_lshl_add_u64 v[12:13], v[24:25], 0, v[12:13]
	v_lshl_add_u64 v[14:15], v[24:25], 0, v[14:15]
	v_lshl_add_u64 v[16:17], v[24:25], 0, v[16:17]
	v_lshl_add_u64 v[18:19], v[24:25], 0, v[18:19]
	v_lshl_add_u64 v[20:21], v[24:25], 0, v[20:21]
	v_lshl_add_u64 v[22:23], v[24:25], 0, v[22:23]
	global_load_dword v8, v[8:9], off nt
	s_nop 0
	global_load_dword v9, v[10:11], off nt
	s_nop 0
	global_load_dword v10, v[12:13], off nt
	global_load_dword v11, v[14:15], off nt
	s_nop 0
	global_load_dword v12, v[16:17], off nt
	global_load_dword v13, v[18:19], off nt
	global_load_dword v14, v[20:21], off nt
	global_load_dword v15, v[22:23], off nt
	v_or_b32_e32 v16, 32, v74
	v_or_b32_e32 v18, 34, v74
	v_or_b32_e32 v20, 36, v74
	v_or_b32_e32 v22, 38, v74
	v_or_b32_e32 v28, 40, v74
	v_or_b32_e32 v38, 42, v74
	v_or_b32_e32 v40, 44, v74
	v_ashrrev_i32_e32 v17, 31, v16
	v_ashrrev_i32_e32 v19, 31, v18
	v_ashrrev_i32_e32 v21, 31, v20
	v_ashrrev_i32_e32 v23, 31, v22
	v_ashrrev_i32_e32 v29, 31, v28
	v_ashrrev_i32_e32 v39, 31, v38
	v_ashrrev_i32_e32 v41, 31, v40
	v_or_b32_e32 v88, 46, v74
	v_lshlrev_b64 v[16:17], 12, v[16:17]
	v_lshlrev_b64 v[18:19], 12, v[18:19]
	v_lshlrev_b64 v[20:21], 12, v[20:21]
	v_lshlrev_b64 v[22:23], 12, v[22:23]
	v_lshlrev_b64 v[28:29], 12, v[28:29]
	v_lshlrev_b64 v[38:39], 12, v[38:39]
	v_lshlrev_b64 v[40:41], 12, v[40:41]
	v_ashrrev_i32_e32 v89, 31, v88
	v_lshl_add_u64 v[16:17], v[24:25], 0, v[16:17]
	v_lshl_add_u64 v[18:19], v[24:25], 0, v[18:19]
	v_lshl_add_u64 v[20:21], v[24:25], 0, v[20:21]
	v_lshl_add_u64 v[22:23], v[24:25], 0, v[22:23]
	v_lshl_add_u64 v[28:29], v[24:25], 0, v[28:29]
	v_lshl_add_u64 v[38:39], v[24:25], 0, v[38:39]
	v_lshl_add_u64 v[40:41], v[24:25], 0, v[40:41]
	v_lshlrev_b64 v[88:89], 12, v[88:89]
	v_lshl_add_u64 v[88:89], v[24:25], 0, v[88:89]
	global_load_dword v16, v[16:17], off nt
	s_nop 0
	global_load_dword v17, v[18:19], off nt
	s_nop 0
	global_load_dword v18, v[20:21], off nt
	global_load_dword v19, v[22:23], off nt
	s_nop 0
	global_load_dword v20, v[28:29], off nt
	global_load_dword v21, v[38:39], off nt
	global_load_dword v22, v[40:41], off nt
	global_load_dword v23, v[88:89], off nt
	v_or_b32_e32 v28, 48, v74
	v_or_b32_e32 v38, 50, v74
	v_or_b32_e32 v40, 52, v74
	v_ashrrev_i32_e32 v29, 31, v28
	v_ashrrev_i32_e32 v39, 31, v38
	v_ashrrev_i32_e32 v41, 31, v40
	v_or_b32_e32 v88, 54, v74
	v_or_b32_e32 v90, 56, v74
	v_or_b32_e32 v92, 58, v74
	v_or_b32_e32 v94, 60, v74
	v_or_b32_e32 v96, 62, v74
	v_lshlrev_b64 v[28:29], 12, v[28:29]
	v_lshlrev_b64 v[38:39], 12, v[38:39]
	v_lshlrev_b64 v[40:41], 12, v[40:41]
	v_ashrrev_i32_e32 v89, 31, v88
	v_ashrrev_i32_e32 v91, 31, v90
	v_ashrrev_i32_e32 v93, 31, v92
	v_ashrrev_i32_e32 v95, 31, v94
	v_ashrrev_i32_e32 v97, 31, v96
	v_lshl_add_u64 v[28:29], v[24:25], 0, v[28:29]
	v_lshl_add_u64 v[38:39], v[24:25], 0, v[38:39]
	v_lshl_add_u64 v[40:41], v[24:25], 0, v[40:41]
	v_lshlrev_b64 v[88:89], 12, v[88:89]
	v_lshlrev_b64 v[90:91], 12, v[90:91]
	v_lshlrev_b64 v[92:93], 12, v[92:93]
	v_lshlrev_b64 v[94:95], 12, v[94:95]
	v_lshlrev_b64 v[96:97], 12, v[96:97]
	v_lshl_add_u64 v[88:89], v[24:25], 0, v[88:89]
	v_lshl_add_u64 v[90:91], v[24:25], 0, v[90:91]
	v_lshl_add_u64 v[92:93], v[24:25], 0, v[92:93]
	v_lshl_add_u64 v[94:95], v[24:25], 0, v[94:95]
	v_lshl_add_u64 v[96:97], v[24:25], 0, v[96:97]
	global_load_dword v24, v[28:29], off nt
	global_load_dword v25, v[38:39], off nt
	s_nop 0
	global_load_dword v28, v[40:41], off nt
	global_load_dword v29, v[88:89], off nt
	global_load_dword v38, v[90:91], off nt
	global_load_dword v39, v[92:93], off nt
	s_nop 0
	global_load_dword v40, v[94:95], off nt
	global_load_dword v41, v[96:97], off nt
	s_andn2_b64 vcc, exec, s[46:47]
	s_cbranch_vccnz .LBB7_129
	v_lshl_add_u64 v[74:75], v[74:75], 2, s[12:13]
	global_load_dword v88, v[74:75], off
	global_load_dword v89, v[74:75], off offset:8
	global_load_dword v90, v[74:75], off offset:16
	global_load_dword v91, v[74:75], off offset:24
	global_load_dword v92, v[74:75], off offset:32
	global_load_dword v93, v[74:75], off offset:40
	global_load_dword v94, v[74:75], off offset:48
	global_load_dword v95, v[74:75], off offset:56
	global_load_dword v96, v[74:75], off offset:64
	global_load_dword v97, v[74:75], off offset:72
	global_load_dword v98, v[74:75], off offset:80
	global_load_dword v99, v[74:75], off offset:88
	global_load_dword v100, v[74:75], off offset:96
	global_load_dword v101, v[74:75], off offset:104
	global_load_dword v102, v[74:75], off offset:112
	global_load_dword v103, v[74:75], off offset:120
	global_load_dword v104, v[74:75], off offset:128
	global_load_dword v105, v[74:75], off offset:136
	global_load_dword v106, v[74:75], off offset:144
	global_load_dword v107, v[74:75], off offset:152
	global_load_dword v108, v[74:75], off offset:160
	global_load_dword v109, v[74:75], off offset:168
	global_load_dword v110, v[74:75], off offset:176
	global_load_dword v111, v[74:75], off offset:184
	global_load_dword v112, v[74:75], off offset:192
	global_load_dword v113, v[74:75], off offset:200
	global_load_dword v114, v[74:75], off offset:208
	global_load_dword v115, v[74:75], off offset:216
	global_load_dword v116, v[74:75], off offset:224
	global_load_dword v117, v[74:75], off offset:232
	global_load_dword v118, v[74:75], off offset:240
	global_load_dword v119, v[74:75], off offset:248
	s_waitcnt vmcnt(30)
	v_pk_mul_f32 v[0:1], v[0:1], v[88:89]
	s_waitcnt vmcnt(28)
	v_pk_mul_f32 v[2:3], v[2:3], v[90:91]
	s_waitcnt vmcnt(26)
	v_pk_mul_f32 v[4:5], v[4:5], v[92:93]
	s_waitcnt vmcnt(24)
	v_pk_mul_f32 v[6:7], v[6:7], v[94:95]
	s_waitcnt vmcnt(22)
	v_pk_mul_f32 v[8:9], v[8:9], v[96:97]
	s_waitcnt vmcnt(20)
	v_pk_mul_f32 v[10:11], v[10:11], v[98:99]
	s_waitcnt vmcnt(18)
	v_pk_mul_f32 v[12:13], v[12:13], v[100:101]
	s_waitcnt vmcnt(16)
	v_pk_mul_f32 v[14:15], v[14:15], v[102:103]
	s_waitcnt vmcnt(14)
	v_pk_mul_f32 v[16:17], v[16:17], v[104:105]
	s_waitcnt vmcnt(12)
	v_pk_mul_f32 v[18:19], v[18:19], v[106:107]
	s_waitcnt vmcnt(10)
	v_pk_mul_f32 v[20:21], v[20:21], v[108:109]
	s_waitcnt vmcnt(8)
	v_pk_mul_f32 v[22:23], v[22:23], v[110:111]
	s_waitcnt vmcnt(6)
	v_pk_mul_f32 v[24:25], v[24:25], v[112:113]
	s_waitcnt vmcnt(4)
	v_pk_mul_f32 v[28:29], v[28:29], v[114:115]
	s_waitcnt vmcnt(2)
	v_pk_mul_f32 v[38:39], v[38:39], v[116:117]
	s_waitcnt vmcnt(0)
	v_pk_mul_f32 v[40:41], v[40:41], v[118:119]
	s_branch .LBB7_129

.LBB7_142:
	ds_write2_b32 v77, v43, v42 offset1:66
	ds_write2_b32 v77, v45, v44 offset0:132 offset1:198
	ds_write2_b32 v32, v47, v46 offset0:8 offset1:74
	ds_write2_b32 v32, v49, v48 offset0:140 offset1:206
	ds_write2_b32 v35, v51, v50 offset0:16 offset1:82
	ds_write2_b32 v35, v53, v52 offset0:148 offset1:214
	ds_write2_b32 v37, v55, v54 offset0:24 offset1:90
	ds_write2_b32 v37, v57, v56 offset0:156 offset1:222
	ds_write2_b32 v84, v59, v58 offset0:32 offset1:98
	ds_write2_b32 v84, v61, v60 offset0:164 offset1:230
	ds_write2_b32 v85, v63, v62 offset0:40 offset1:106
	ds_write2_b32 v85, v65, v64 offset0:172 offset1:238
	ds_write2_b32 v86, v67, v66 offset0:48 offset1:114
	ds_write2_b32 v86, v69, v68 offset0:180 offset1:246
	ds_write2_b32 v87, v71, v70 offset0:56 offset1:122
	ds_write2_b32 v87, v73, v72 offset0:188 offset1:254
	s_waitcnt lgkmcnt(0)
	s_ashr_i32 s14, s48, 31
	s_lshr_b32 s14, s14, 27
	ds_read2_b32 v[74:75], v79 offset1:33
	s_add_i32 s14, s48, s14
	s_waitcnt lgkmcnt(0)
	v_cvt_pk_bf16_f32 v84, v74, v75
	ds_read2_b32 v[74:75], v79 offset0:66 offset1:99
	s_and_b32 s15, s14, 0x7ffffe0
	s_waitcnt lgkmcnt(0)
	v_cvt_pk_bf16_f32 v85, v74, v75
	ds_read2_b32 v[74:75], v79 offset0:132 offset1:165
	s_sub_i32 s15, s48, s15
	s_lshl_b32 s14, s14, 1
	s_waitcnt lgkmcnt(0)
	v_cvt_pk_bf16_f32 v86, v74, v75
	ds_read2_b32 v[74:75], v79 offset0:198 offset1:231
	s_lshl_b32 s49, s15, 5
	s_andn2_b32 s14, s14, 63
	s_waitcnt lgkmcnt(0)
	v_cvt_pk_bf16_f32 v87, v74, v75
	v_or_b32_e32 v74, s49, v78
	s_ashr_i32 s15, s14, 31
	v_ashrrev_i32_e32 v75, 31, v74
	v_lshl_add_u64 v[88:89], s[14:15], 1, v[30:31]
	v_lshlrev_b64 v[74:75], 11, v[74:75]
	v_lshl_add_u64 v[74:75], v[88:89], 0, v[74:75]
	ds_read2_b32 v[90:91], v79 offset0:8 offset1:41
	global_store_dwordx4 v[74:75], v[84:87], off nt
	s_add_i32 s45, s48, s72
	s_cmpk_gt_i32 s45, 0x1ff
	s_waitcnt lgkmcnt(0)
	v_cvt_pk_bf16_f32 v84, v90, v91
	ds_read2_b32 v[74:75], v79 offset0:74 offset1:107
	s_waitcnt lgkmcnt(0)
	v_cvt_pk_bf16_f32 v85, v74, v75
	ds_read2_b32 v[74:75], v79 offset0:140 offset1:173
	s_waitcnt lgkmcnt(0)
	v_cvt_pk_bf16_f32 v86, v74, v75
	ds_read2_b32 v[74:75], v79 offset0:206 offset1:239
	s_waitcnt lgkmcnt(0)
	v_cvt_pk_bf16_f32 v87, v74, v75
	v_or_b32_e32 v74, s49, v80
	v_ashrrev_i32_e32 v75, 31, v74
	v_lshlrev_b64 v[74:75], 11, v[74:75]
	ds_read2_b32 v[90:91], v79 offset0:16 offset1:49
	v_lshl_add_u64 v[74:75], v[88:89], 0, v[74:75]
	global_store_dwordx4 v[74:75], v[84:87], off nt
	s_cselect_b64 s[14:15], -1, 0
	s_waitcnt lgkmcnt(0)
	v_cvt_pk_bf16_f32 v84, v90, v91
	ds_read2_b32 v[74:75], v79 offset0:82 offset1:115
	v_or_b32_e32 v90, s49, v81
	s_waitcnt lgkmcnt(0)
	v_cvt_pk_bf16_f32 v85, v74, v75
	ds_read2_b32 v[74:75], v79 offset0:148 offset1:181
	v_ashrrev_i32_e32 v91, 31, v90
	s_waitcnt lgkmcnt(0)
	v_cvt_pk_bf16_f32 v86, v74, v75
	ds_read2_b32 v[74:75], v79 offset0:214 offset1:247
	v_lshlrev_b64 v[90:91], 11, v[90:91]
	s_waitcnt lgkmcnt(0)
	v_cvt_pk_bf16_f32 v87, v74, v75
	ds_read2_b32 v[74:75], v79 offset0:24 offset1:57
	v_lshl_add_u64 v[90:91], v[88:89], 0, v[90:91]
	global_store_dwordx4 v[90:91], v[84:87], off nt
	v_or_b32_e32 v90, s49, v82
	v_ashrrev_i32_e32 v91, 31, v90
	s_waitcnt lgkmcnt(0)
	v_cvt_pk_bf16_f32 v84, v74, v75
	ds_read2_b32 v[74:75], v79 offset0:90 offset1:123
	s_waitcnt lgkmcnt(0)
	v_cvt_pk_bf16_f32 v85, v74, v75
	ds_read2_b32 v[74:75], v79 offset0:156 offset1:189
	s_waitcnt lgkmcnt(0)
	v_cvt_pk_bf16_f32 v86, v74, v75
	ds_read2_b32 v[74:75], v79 offset0:222 offset1:255
	v_lshlrev_b64 v[90:91], 11, v[90:91]
	s_waitcnt lgkmcnt(0)
	v_cvt_pk_bf16_f32 v87, v74, v75
	v_lshl_add_u64 v[74:75], v[88:89], 0, v[90:91]
	global_store_dwordx4 v[74:75], v[84:87], off nt
	s_waitcnt lgkmcnt(0)

.LBB7_147:
	v_add_u32_e32 v32, 0x400, v77
	v_add_u32_e32 v35, 0x800, v77
	v_add_u32_e32 v37, 0xc00, v77
	v_add_u32_e32 v84, 0x1000, v77
	v_add_u32_e32 v85, 0x1400, v77
	v_add_u32_e32 v86, 0x1800, v77
	v_add_u32_e32 v87, 0x1c00, v77
	s_waitcnt vmcnt(30)
	ds_write2_b32 v77, v0, v1 offset1:66
	s_waitcnt vmcnt(28)
	ds_write2_b32 v77, v2, v3 offset0:132 offset1:198
	s_waitcnt vmcnt(26)
	ds_write2_b32 v32, v4, v5 offset0:8 offset1:74
	s_waitcnt vmcnt(24)
	ds_write2_b32 v32, v6, v7 offset0:140 offset1:206
	s_waitcnt vmcnt(22)
	ds_write2_b32 v35, v8, v9 offset0:16 offset1:82
	s_waitcnt vmcnt(20)
	ds_write2_b32 v35, v10, v11 offset0:148 offset1:214
	s_waitcnt vmcnt(18)
	ds_write2_b32 v37, v12, v13 offset0:24 offset1:90
	s_waitcnt vmcnt(16)
	ds_write2_b32 v37, v14, v15 offset0:156 offset1:222
	s_waitcnt vmcnt(14)
	ds_write2_b32 v84, v16, v17 offset0:32 offset1:98
	s_waitcnt vmcnt(12)
	ds_write2_b32 v84, v18, v19 offset0:164 offset1:230
	s_waitcnt vmcnt(10)
	ds_write2_b32 v85, v20, v21 offset0:40 offset1:106
	s_waitcnt vmcnt(8)
	ds_write2_b32 v85, v22, v23 offset0:172 offset1:238
	s_waitcnt vmcnt(6)
	ds_write2_b32 v86, v24, v25 offset0:48 offset1:114
	s_waitcnt vmcnt(4)
	ds_write2_b32 v86, v28, v29 offset0:180 offset1:246
	s_waitcnt vmcnt(2)
	ds_write2_b32 v87, v38, v39 offset0:56 offset1:122
	s_waitcnt vmcnt(0)
	ds_write2_b32 v87, v40, v41 offset0:188 offset1:254
	s_waitcnt lgkmcnt(0)
	s_ashr_i32 s49, s45, 31
	s_lshr_b32 s49, s49, 27
	ds_read2_b32 v[74:75], v79 offset1:33
	s_add_i32 s49, s45, s49
	s_waitcnt lgkmcnt(0)
	v_cvt_pk_bf16_f32 v88, v74, v75
	ds_read2_b32 v[74:75], v79 offset0:66 offset1:99
	s_and_b32 s50, s49, 0x7ffffe0
	s_waitcnt lgkmcnt(0)
	v_cvt_pk_bf16_f32 v89, v74, v75
	ds_read2_b32 v[74:75], v79 offset0:132 offset1:165
	s_sub_i32 s51, s45, s50
	s_lshl_b32 s49, s49, 1
	s_waitcnt lgkmcnt(0)
	v_cvt_pk_bf16_f32 v90, v74, v75
	ds_read2_b32 v[74:75], v79 offset0:198 offset1:231
	s_and_b32 s50, s49, 0xffffffc0
	s_lshl_b32 s49, s51, 5
	s_waitcnt lgkmcnt(0)
	v_cvt_pk_bf16_f32 v91, v74, v75
	v_or_b32_e32 v74, s49, v78
	s_ashr_i32 s51, s50, 31
	v_ashrrev_i32_e32 v75, 31, v74
	v_lshl_add_u64 v[92:93], s[50:51], 1, v[30:31]
	v_lshlrev_b64 v[74:75], 11, v[74:75]
	v_lshl_add_u64 v[74:75], v[92:93], 0, v[74:75]
	ds_read2_b32 v[94:95], v79 offset0:8 offset1:41
	global_store_dwordx4 v[74:75], v[88:91], off nt
	s_andn2_b64 vcc, exec, s[14:15]
	s_mov_b64 s[14:15], -1
	s_waitcnt lgkmcnt(0)
	v_cvt_pk_bf16_f32 v88, v94, v95
	ds_read2_b32 v[74:75], v79 offset0:74 offset1:107
	s_waitcnt lgkmcnt(0)
	v_cvt_pk_bf16_f32 v89, v74, v75
	ds_read2_b32 v[74:75], v79 offset0:140 offset1:173
	s_waitcnt lgkmcnt(0)
	v_cvt_pk_bf16_f32 v90, v74, v75
	ds_read2_b32 v[74:75], v79 offset0:206 offset1:239
	s_waitcnt lgkmcnt(0)
	v_cvt_pk_bf16_f32 v91, v74, v75
	v_or_b32_e32 v74, s49, v80
	v_ashrrev_i32_e32 v75, 31, v74
	v_lshlrev_b64 v[74:75], 11, v[74:75]
	v_lshl_add_u64 v[74:75], v[92:93], 0, v[74:75]
	ds_read2_b32 v[94:95], v79 offset0:16 offset1:49
	global_store_dwordx4 v[74:75], v[88:91], off nt
	s_waitcnt lgkmcnt(0)
	s_nop 0
	v_cvt_pk_bf16_f32 v88, v94, v95
	ds_read2_b32 v[74:75], v79 offset0:82 offset1:115
	s_waitcnt lgkmcnt(0)
	v_cvt_pk_bf16_f32 v89, v74, v75
	ds_read2_b32 v[74:75], v79 offset0:148 offset1:181
	s_waitcnt lgkmcnt(0)
	v_cvt_pk_bf16_f32 v90, v74, v75
	ds_read2_b32 v[74:75], v79 offset0:214 offset1:247
	s_waitcnt lgkmcnt(0)
	v_cvt_pk_bf16_f32 v91, v74, v75
	v_or_b32_e32 v74, s49, v81
	v_ashrrev_i32_e32 v75, 31, v74
	v_lshlrev_b64 v[74:75], 11, v[74:75]
	ds_read2_b32 v[94:95], v79 offset0:24 offset1:57
	v_lshl_add_u64 v[74:75], v[92:93], 0, v[74:75]
	global_store_dwordx4 v[74:75], v[88:91], off nt
	s_waitcnt lgkmcnt(0)
	s_nop 0
	v_cvt_pk_bf16_f32 v88, v94, v95
	ds_read2_b32 v[74:75], v79 offset0:90 offset1:123
	v_or_b32_e32 v94, s49, v82
	s_waitcnt lgkmcnt(0)
	v_cvt_pk_bf16_f32 v89, v74, v75
	ds_read2_b32 v[74:75], v79 offset0:156 offset1:189
	v_ashrrev_i32_e32 v95, 31, v94
	s_waitcnt lgkmcnt(0)
	v_cvt_pk_bf16_f32 v90, v74, v75
	ds_read2_b32 v[74:75], v79 offset0:222 offset1:255
	v_lshlrev_b64 v[94:95], 11, v[94:95]
	s_waitcnt lgkmcnt(0)
	v_cvt_pk_bf16_f32 v91, v74, v75
	v_lshl_add_u64 v[74:75], v[92:93], 0, v[94:95]
	global_store_dwordx4 v[74:75], v[88:91], off nt
	s_waitcnt lgkmcnt(0)
	s_cbranch_vccnz .LBB7_143
	s_add_i32 s14, s55, s45
	s_cmpk_gt_i32 s14, 0x1ff
	s_cbranch_scc1 .LBB7_142
	s_ashr_i32 s15, s14, 31
	s_lshr_b32 s15, s15, 27
	s_add_i32 s15, s14, s15
	s_and_b32 s45, s15, 0x7ffffe0
	s_lshl_b32 s15, s15, 1
	s_andn2_b32 s15, s15, 63
	s_sub_i32 s14, s14, s45
	v_or_b32_e32 v74, s15, v76
	s_lshl_b32 s14, s14, 5
	v_or_b32_e32 v2, 2, v74
	v_or_b32_e32 v4, 4, v74
	v_or_b32_e32 v6, 6, v74
	v_or_b32_e32 v8, 8, v74
	v_or_b32_e32 v10, 10, v74
	v_or_b32_e32 v12, 12, v74
	v_or_b32_e32 v14, 14, v74
	s_ashr_i32 s15, s14, 31
	v_ashrrev_i32_e32 v75, 31, v74
	v_ashrrev_i32_e32 v3, 31, v2
	v_ashrrev_i32_e32 v5, 31, v4
	v_ashrrev_i32_e32 v7, 31, v6
	v_ashrrev_i32_e32 v9, 31, v8
	v_ashrrev_i32_e32 v11, 31, v10
	v_ashrrev_i32_e32 v13, 31, v12
	v_ashrrev_i32_e32 v15, 31, v14
	v_lshl_add_u64 v[24:25], s[14:15], 2, v[26:27]
	v_lshlrev_b64 v[0:1], 12, v[74:75]
	v_lshlrev_b64 v[2:3], 12, v[2:3]
	v_lshlrev_b64 v[4:5], 12, v[4:5]
	v_lshlrev_b64 v[6:7], 12, v[6:7]
	v_lshlrev_b64 v[8:9], 12, v[8:9]
	v_lshlrev_b64 v[10:11], 12, v[10:11]
	v_lshlrev_b64 v[12:13], 12, v[12:13]
	v_lshlrev_b64 v[14:15], 12, v[14:15]
	v_lshl_add_u64 v[0:1], v[24:25], 0, v[0:1]
	v_lshl_add_u64 v[2:3], v[24:25], 0, v[2:3]
	v_lshl_add_u64 v[4:5], v[24:25], 0, v[4:5]
	v_lshl_add_u64 v[6:7], v[24:25], 0, v[6:7]
	v_lshl_add_u64 v[8:9], v[24:25], 0, v[8:9]
	v_lshl_add_u64 v[10:11], v[24:25], 0, v[10:11]
	v_lshl_add_u64 v[12:13], v[24:25], 0, v[12:13]
	v_lshl_add_u64 v[14:15], v[24:25], 0, v[14:15]
	global_load_dword v0, v[0:1], off nt
	s_nop 0
	global_load_dword v1, v[2:3], off nt
	s_nop 0
	global_load_dword v2, v[4:5], off nt
	global_load_dword v3, v[6:7], off nt
	s_nop 0
	global_load_dword v4, v[8:9], off nt
	global_load_dword v5, v[10:11], off nt
	global_load_dword v6, v[12:13], off nt
	global_load_dword v7, v[14:15], off nt
	v_or_b32_e32 v8, 16, v74
	v_or_b32_e32 v10, 18, v74
	v_or_b32_e32 v12, 20, v74
	v_or_b32_e32 v14, 22, v74
	v_or_b32_e32 v16, 24, v74
	v_or_b32_e32 v18, 26, v74
	v_or_b32_e32 v20, 28, v74
	v_or_b32_e32 v22, 30, v74
	v_ashrrev_i32_e32 v9, 31, v8
	v_ashrrev_i32_e32 v11, 31, v10
	v_ashrrev_i32_e32 v13, 31, v12
	v_ashrrev_i32_e32 v15, 31, v14
	v_ashrrev_i32_e32 v17, 31, v16
	v_ashrrev_i32_e32 v19, 31, v18
	v_ashrrev_i32_e32 v21, 31, v20
	v_ashrrev_i32_e32 v23, 31, v22
	v_lshlrev_b64 v[8:9], 12, v[8:9]
	v_lshlrev_b64 v[10:11], 12, v[10:11]
	v_lshlrev_b64 v[12:13], 12, v[12:13]
	v_lshlrev_b64 v[14:15], 12, v[14:15]
	v_lshlrev_b64 v[16:17], 12, v[16:17]
	v_lshlrev_b64 v[18:19], 12, v[18:19]
	v_lshlrev_b64 v[20:21], 12, v[20:21]
	v_lshlrev_b64 v[22:23], 12, v[22:23]
	v_lshl_add_u64 v[8:9], v[24:25], 0, v[8:9]
	v_lshl_add_u64 v[10:11], v[24:25], 0, v[10:11]
	v_lshl_add_u64 v[12:13], v[24:25], 0, v[12:13]
	v_lshl_add_u64 v[14:15], v[24:25], 0, v[14:15]
	v_lshl_add_u64 v[16:17], v[24:25], 0, v[16:17]
	v_lshl_add_u64 v[18:19], v[24:25], 0, v[18:19]
	v_lshl_add_u64 v[20:21], v[24:25], 0, v[20:21]
	v_lshl_add_u64 v[22:23], v[24:25], 0, v[22:23]
	global_load_dword v8, v[8:9], off nt
	s_nop 0
	global_load_dword v9, v[10:11], off nt
	s_nop 0
	global_load_dword v10, v[12:13], off nt
	global_load_dword v11, v[14:15], off nt
	s_nop 0
	global_load_dword v12, v[16:17], off nt
	global_load_dword v13, v[18:19], off nt
	global_load_dword v14, v[20:21], off nt
	global_load_dword v15, v[22:23], off nt
	v_or_b32_e32 v16, 32, v74
	v_or_b32_e32 v18, 34, v74
	v_or_b32_e32 v20, 36, v74
	v_or_b32_e32 v22, 38, v74
	v_or_b32_e32 v28, 40, v74
	v_or_b32_e32 v38, 42, v74
	v_or_b32_e32 v40, 44, v74
	v_ashrrev_i32_e32 v17, 31, v16
	v_ashrrev_i32_e32 v19, 31, v18
	v_ashrrev_i32_e32 v21, 31, v20
	v_ashrrev_i32_e32 v23, 31, v22
	v_ashrrev_i32_e32 v29, 31, v28
	v_ashrrev_i32_e32 v39, 31, v38
	v_ashrrev_i32_e32 v41, 31, v40
	v_or_b32_e32 v88, 46, v74
	v_lshlrev_b64 v[16:17], 12, v[16:17]
	v_lshlrev_b64 v[18:19], 12, v[18:19]
	v_lshlrev_b64 v[20:21], 12, v[20:21]
	v_lshlrev_b64 v[22:23], 12, v[22:23]
	v_lshlrev_b64 v[28:29], 12, v[28:29]
	v_lshlrev_b64 v[38:39], 12, v[38:39]
	v_lshlrev_b64 v[40:41], 12, v[40:41]
	v_ashrrev_i32_e32 v89, 31, v88
	v_lshl_add_u64 v[16:17], v[24:25], 0, v[16:17]
	v_lshl_add_u64 v[18:19], v[24:25], 0, v[18:19]
	v_lshl_add_u64 v[20:21], v[24:25], 0, v[20:21]
	v_lshl_add_u64 v[22:23], v[24:25], 0, v[22:23]
	v_lshl_add_u64 v[28:29], v[24:25], 0, v[28:29]
	v_lshl_add_u64 v[38:39], v[24:25], 0, v[38:39]
	v_lshl_add_u64 v[40:41], v[24:25], 0, v[40:41]
	v_lshlrev_b64 v[88:89], 12, v[88:89]
	v_lshl_add_u64 v[88:89], v[24:25], 0, v[88:89]
	global_load_dword v16, v[16:17], off nt
	s_nop 0
	global_load_dword v17, v[18:19], off nt
	s_nop 0
	global_load_dword v18, v[20:21], off nt
	global_load_dword v19, v[22:23], off nt
	s_nop 0
	global_load_dword v20, v[28:29], off nt
	global_load_dword v21, v[38:39], off nt
	global_load_dword v22, v[40:41], off nt
	global_load_dword v23, v[88:89], off nt
	v_or_b32_e32 v28, 48, v74
	v_or_b32_e32 v38, 50, v74
	v_or_b32_e32 v40, 52, v74
	v_ashrrev_i32_e32 v29, 31, v28
	v_ashrrev_i32_e32 v39, 31, v38
	v_ashrrev_i32_e32 v41, 31, v40
	v_or_b32_e32 v88, 54, v74
	v_or_b32_e32 v90, 56, v74
	v_or_b32_e32 v92, 58, v74
	v_or_b32_e32 v94, 60, v74
	v_or_b32_e32 v96, 62, v74
	v_lshlrev_b64 v[28:29], 12, v[28:29]
	v_lshlrev_b64 v[38:39], 12, v[38:39]
	v_lshlrev_b64 v[40:41], 12, v[40:41]
	v_ashrrev_i32_e32 v89, 31, v88
	v_ashrrev_i32_e32 v91, 31, v90
	v_ashrrev_i32_e32 v93, 31, v92
	v_ashrrev_i32_e32 v95, 31, v94
	v_ashrrev_i32_e32 v97, 31, v96
	v_lshl_add_u64 v[28:29], v[24:25], 0, v[28:29]
	v_lshl_add_u64 v[38:39], v[24:25], 0, v[38:39]
	v_lshl_add_u64 v[40:41], v[24:25], 0, v[40:41]
	v_lshlrev_b64 v[88:89], 12, v[88:89]
	v_lshlrev_b64 v[90:91], 12, v[90:91]
	v_lshlrev_b64 v[92:93], 12, v[92:93]
	v_lshlrev_b64 v[94:95], 12, v[94:95]
	v_lshlrev_b64 v[96:97], 12, v[96:97]
	v_lshl_add_u64 v[88:89], v[24:25], 0, v[88:89]
	v_lshl_add_u64 v[90:91], v[24:25], 0, v[90:91]
	v_lshl_add_u64 v[92:93], v[24:25], 0, v[92:93]
	v_lshl_add_u64 v[94:95], v[24:25], 0, v[94:95]
	v_lshl_add_u64 v[96:97], v[24:25], 0, v[96:97]
	global_load_dword v24, v[28:29], off nt
	global_load_dword v25, v[38:39], off nt
	s_nop 0
	global_load_dword v28, v[40:41], off nt
	global_load_dword v29, v[88:89], off nt
	global_load_dword v38, v[90:91], off nt
	global_load_dword v39, v[92:93], off nt
	s_nop 0
	global_load_dword v40, v[94:95], off nt
	global_load_dword v41, v[96:97], off nt
	s_andn2_b64 vcc, exec, s[46:47]
	s_cbranch_vccnz .LBB7_142
	v_lshl_add_u64 v[74:75], v[74:75], 2, s[12:13]
	global_load_dword v88, v[74:75], off
	global_load_dword v89, v[74:75], off offset:8
	global_load_dword v90, v[74:75], off offset:16
	global_load_dword v91, v[74:75], off offset:24
	global_load_dword v92, v[74:75], off offset:32
	global_load_dword v93, v[74:75], off offset:40
	global_load_dword v94, v[74:75], off offset:48
	global_load_dword v95, v[74:75], off offset:56
	global_load_dword v96, v[74:75], off offset:64
	global_load_dword v97, v[74:75], off offset:72
	global_load_dword v98, v[74:75], off offset:80
	global_load_dword v99, v[74:75], off offset:88
	global_load_dword v100, v[74:75], off offset:96
	global_load_dword v101, v[74:75], off offset:104
	global_load_dword v102, v[74:75], off offset:112
	global_load_dword v103, v[74:75], off offset:120
	global_load_dword v104, v[74:75], off offset:128
	global_load_dword v105, v[74:75], off offset:136
	global_load_dword v106, v[74:75], off offset:144
	global_load_dword v107, v[74:75], off offset:152
	global_load_dword v108, v[74:75], off offset:160
	global_load_dword v109, v[74:75], off offset:168
	global_load_dword v110, v[74:75], off offset:176
	global_load_dword v111, v[74:75], off offset:184
	global_load_dword v112, v[74:75], off offset:192
	global_load_dword v113, v[74:75], off offset:200
	global_load_dword v114, v[74:75], off offset:208
	global_load_dword v115, v[74:75], off offset:216
	global_load_dword v116, v[74:75], off offset:224
	global_load_dword v117, v[74:75], off offset:232
	global_load_dword v118, v[74:75], off offset:240
	global_load_dword v119, v[74:75], off offset:248
	s_waitcnt vmcnt(30)
	v_pk_mul_f32 v[0:1], v[0:1], v[88:89]
	s_waitcnt vmcnt(28)
	v_pk_mul_f32 v[2:3], v[2:3], v[90:91]
	s_waitcnt vmcnt(26)
	v_pk_mul_f32 v[4:5], v[4:5], v[92:93]
	s_waitcnt vmcnt(24)
	v_pk_mul_f32 v[6:7], v[6:7], v[94:95]
	s_waitcnt vmcnt(22)
	v_pk_mul_f32 v[8:9], v[8:9], v[96:97]
	s_waitcnt vmcnt(20)
	v_pk_mul_f32 v[10:11], v[10:11], v[98:99]
	s_waitcnt vmcnt(18)
	v_pk_mul_f32 v[12:13], v[12:13], v[100:101]
	s_waitcnt vmcnt(16)
	v_pk_mul_f32 v[14:15], v[14:15], v[102:103]
	s_waitcnt vmcnt(14)
	v_pk_mul_f32 v[16:17], v[16:17], v[104:105]
	s_waitcnt vmcnt(12)
	v_pk_mul_f32 v[18:19], v[18:19], v[106:107]
	s_waitcnt vmcnt(10)
	v_pk_mul_f32 v[20:21], v[20:21], v[108:109]
	s_waitcnt vmcnt(8)
	v_pk_mul_f32 v[22:23], v[22:23], v[110:111]
	s_waitcnt vmcnt(6)
	v_pk_mul_f32 v[24:25], v[24:25], v[112:113]
	s_waitcnt vmcnt(4)
	v_pk_mul_f32 v[28:29], v[28:29], v[114:115]
	s_waitcnt vmcnt(2)
	v_pk_mul_f32 v[38:39], v[38:39], v[116:117]
	s_waitcnt vmcnt(0)
	v_pk_mul_f32 v[40:41], v[40:41], v[118:119]
	s_branch .LBB7_142

.LBB7_153:
	ds_write2_b32 v77, v32, v35 offset1:66
	ds_write2_b32 v77, v37, v42 offset0:132 offset1:198
	ds_write2_b32 v71, v43, v44 offset0:8 offset1:74
	ds_write2_b32 v71, v45, v46 offset0:140 offset1:206
	ds_write2_b32 v72, v47, v48 offset0:16 offset1:82
	ds_write2_b32 v72, v49, v50 offset0:148 offset1:214
	ds_write2_b32 v73, v51, v52 offset0:24 offset1:90
	ds_write2_b32 v73, v53, v54 offset0:156 offset1:222
	ds_write2_b32 v74, v55, v56 offset0:32 offset1:98
	ds_write2_b32 v74, v57, v58 offset0:164 offset1:230
	ds_write2_b32 v75, v59, v60 offset0:40 offset1:106
	ds_write2_b32 v75, v61, v62 offset0:172 offset1:238
	ds_write2_b32 v84, v63, v64 offset0:48 offset1:114
	ds_write2_b32 v84, v65, v66 offset0:180 offset1:246
	ds_write2_b32 v85, v67, v68 offset0:56 offset1:122
	ds_write2_b32 v85, v69, v70 offset0:188 offset1:254
	s_waitcnt lgkmcnt(0)
	s_ashr_i32 s6, s14, 31
	s_lshr_b32 s6, s6, 27
	ds_read2_b32 v[72:73], v79 offset1:33
	s_add_i32 s6, s14, s6
	s_waitcnt lgkmcnt(0)
	v_cvt_pk_bf16_f32 v72, v72, v73
	ds_read2_b32 v[74:75], v79 offset0:66 offset1:99
	s_and_b32 s7, s6, 0x7ffffe0
	s_waitcnt lgkmcnt(0)
	v_cvt_pk_bf16_f32 v73, v74, v75
	ds_read2_b32 v[74:75], v79 offset0:132 offset1:165
	s_sub_i32 s7, s14, s7
	s_lshl_b32 s6, s6, 1
	s_waitcnt lgkmcnt(0)
	v_cvt_pk_bf16_f32 v74, v74, v75
	ds_read2_b32 v[84:85], v79 offset0:198 offset1:231
	s_lshl_b32 s15, s7, 5
	s_andn2_b32 s6, s6, 63
	s_waitcnt lgkmcnt(0)
	v_cvt_pk_bf16_f32 v75, v84, v85
	v_or_b32_e32 v84, s15, v78
	s_ashr_i32 s7, s6, 31
	v_ashrrev_i32_e32 v85, 31, v84
	v_lshl_add_u64 v[86:87], s[6:7], 1, v[40:41]
	v_lshlrev_b64 v[84:85], 11, v[84:85]
	v_lshl_add_u64 v[84:85], v[86:87], 0, v[84:85]
	ds_read2_b32 v[88:89], v79 offset0:8 offset1:41
	global_store_dwordx4 v[84:85], v[72:75], off nt
	s_add_i32 s13, s14, s72
	s_cmpk_gt_i32 s13, 0x1ff
	s_waitcnt lgkmcnt(0)
	v_cvt_pk_bf16_f32 v72, v88, v89
	ds_read2_b32 v[74:75], v79 offset0:74 offset1:107
	s_waitcnt lgkmcnt(0)
	v_cvt_pk_bf16_f32 v73, v74, v75
	ds_read2_b32 v[74:75], v79 offset0:140 offset1:173
	s_waitcnt lgkmcnt(0)
	v_cvt_pk_bf16_f32 v74, v74, v75
	ds_read2_b32 v[84:85], v79 offset0:206 offset1:239
	s_waitcnt lgkmcnt(0)
	v_cvt_pk_bf16_f32 v75, v84, v85
	v_or_b32_e32 v84, s15, v80
	v_ashrrev_i32_e32 v85, 31, v84
	v_lshlrev_b64 v[84:85], 11, v[84:85]
	ds_read2_b32 v[88:89], v79 offset0:16 offset1:49
	v_lshl_add_u64 v[84:85], v[86:87], 0, v[84:85]
	global_store_dwordx4 v[84:85], v[72:75], off nt
	s_cselect_b64 s[6:7], -1, 0
	s_waitcnt lgkmcnt(0)
	v_cvt_pk_bf16_f32 v72, v88, v89
	v_or_b32_e32 v88, s15, v81
	ds_read2_b32 v[74:75], v79 offset0:82 offset1:115
	v_ashrrev_i32_e32 v89, 31, v88
	s_waitcnt lgkmcnt(0)
	v_cvt_pk_bf16_f32 v73, v74, v75
	ds_read2_b32 v[74:75], v79 offset0:148 offset1:181
	v_lshlrev_b64 v[88:89], 11, v[88:89]
	s_waitcnt lgkmcnt(0)
	v_cvt_pk_bf16_f32 v74, v74, v75
	ds_read2_b32 v[84:85], v79 offset0:214 offset1:247
	s_waitcnt lgkmcnt(0)
	v_cvt_pk_bf16_f32 v75, v84, v85
	v_lshl_add_u64 v[88:89], v[86:87], 0, v[88:89]
	ds_read2_b32 v[84:85], v79 offset0:24 offset1:57
	global_store_dwordx4 v[88:89], v[72:75], off nt
	v_or_b32_e32 v88, s15, v82
	v_ashrrev_i32_e32 v89, 31, v88
	s_waitcnt lgkmcnt(0)
	v_cvt_pk_bf16_f32 v72, v84, v85
	ds_read2_b32 v[74:75], v79 offset0:90 offset1:123
	s_waitcnt lgkmcnt(0)
	v_cvt_pk_bf16_f32 v73, v74, v75
	ds_read2_b32 v[74:75], v79 offset0:156 offset1:189
	s_waitcnt lgkmcnt(0)
	v_cvt_pk_bf16_f32 v74, v74, v75
	ds_read2_b32 v[84:85], v79 offset0:222 offset1:255
	v_lshlrev_b64 v[88:89], 11, v[88:89]
	s_waitcnt lgkmcnt(0)
	v_cvt_pk_bf16_f32 v75, v84, v85
	v_lshl_add_u64 v[84:85], v[86:87], 0, v[88:89]
	global_store_dwordx4 v[84:85], v[72:75], off nt
	s_waitcnt lgkmcnt(0)

.LBB7_157:
	v_add_u32_e32 v71, 0x400, v77
	v_add_u32_e32 v72, 0x800, v77
	v_add_u32_e32 v73, 0xc00, v77
	v_add_u32_e32 v74, 0x1000, v77
	v_add_u32_e32 v75, 0x1400, v77
	v_add_u32_e32 v84, 0x1800, v77
	v_add_u32_e32 v85, 0x1c00, v77
	s_waitcnt vmcnt(30)
	ds_write2_b32 v77, v0, v1 offset1:66
	s_waitcnt vmcnt(28)
	ds_write2_b32 v77, v2, v3 offset0:132 offset1:198
	s_waitcnt vmcnt(26)
	ds_write2_b32 v71, v4, v5 offset0:8 offset1:74
	s_waitcnt vmcnt(24)
	ds_write2_b32 v71, v6, v7 offset0:140 offset1:206
	s_waitcnt vmcnt(22)
	ds_write2_b32 v72, v8, v9 offset0:16 offset1:82
	s_waitcnt vmcnt(20)
	ds_write2_b32 v72, v10, v11 offset0:148 offset1:214
	s_waitcnt vmcnt(18)
	ds_write2_b32 v73, v12, v13 offset0:24 offset1:90
	s_waitcnt vmcnt(16)
	ds_write2_b32 v73, v14, v15 offset0:156 offset1:222
	s_waitcnt vmcnt(14)
	ds_write2_b32 v74, v16, v17 offset0:32 offset1:98
	s_waitcnt vmcnt(12)
	ds_write2_b32 v74, v18, v19 offset0:164 offset1:230
	s_waitcnt vmcnt(10)
	ds_write2_b32 v75, v20, v21 offset0:40 offset1:106
	s_waitcnt vmcnt(8)
	ds_write2_b32 v75, v22, v23 offset0:172 offset1:238
	s_waitcnt vmcnt(6)
	ds_write2_b32 v84, v24, v25 offset0:48 offset1:114
	s_waitcnt vmcnt(4)
	ds_write2_b32 v84, v26, v27 offset0:180 offset1:246
	s_waitcnt vmcnt(2)
	ds_write2_b32 v85, v28, v29 offset0:56 offset1:122
	s_waitcnt vmcnt(0)
	ds_write2_b32 v85, v30, v31 offset0:188 offset1:254
	s_waitcnt lgkmcnt(0)
	s_ashr_i32 s15, s13, 31
	s_lshr_b32 s15, s15, 27
	ds_read2_b32 v[86:87], v79 offset1:33
	s_add_i32 s15, s13, s15
	s_waitcnt lgkmcnt(0)
	v_cvt_pk_bf16_f32 v86, v86, v87
	ds_read2_b32 v[88:89], v79 offset0:66 offset1:99
	s_and_b32 s16, s15, 0x7ffffe0
	s_waitcnt lgkmcnt(0)
	v_cvt_pk_bf16_f32 v87, v88, v89
	ds_read2_b32 v[88:89], v79 offset0:132 offset1:165
	s_sub_i32 s16, s13, s16
	s_lshl_b32 s15, s15, 1
	s_waitcnt lgkmcnt(0)
	v_cvt_pk_bf16_f32 v88, v88, v89
	ds_read2_b32 v[90:91], v79 offset0:198 offset1:231
	s_and_b32 s46, s15, 0xffffffc0
	s_lshl_b32 s15, s16, 5
	s_waitcnt lgkmcnt(0)
	v_cvt_pk_bf16_f32 v89, v90, v91
	v_or_b32_e32 v90, s15, v78
	s_ashr_i32 s47, s46, 31
	v_ashrrev_i32_e32 v91, 31, v90
	v_lshlrev_b64 v[90:91], 11, v[90:91]
	v_lshl_add_u64 v[92:93], s[46:47], 1, v[40:41]
	v_lshl_add_u64 v[90:91], v[92:93], 0, v[90:91]
	global_store_dwordx4 v[90:91], v[86:89], off nt
	ds_read2_b32 v[86:87], v79 offset0:8 offset1:41
	s_andn2_b64 vcc, exec, s[6:7]
	s_waitcnt lgkmcnt(0)
	v_cvt_pk_bf16_f32 v86, v86, v87
	ds_read2_b32 v[88:89], v79 offset0:74 offset1:107
	s_waitcnt lgkmcnt(0)
	v_cvt_pk_bf16_f32 v87, v88, v89
	ds_read2_b32 v[88:89], v79 offset0:140 offset1:173
	s_waitcnt lgkmcnt(0)
	v_cvt_pk_bf16_f32 v88, v88, v89
	ds_read2_b32 v[90:91], v79 offset0:206 offset1:239
	s_waitcnt lgkmcnt(0)
	v_cvt_pk_bf16_f32 v89, v90, v91
	v_or_b32_e32 v90, s15, v80
	v_ashrrev_i32_e32 v91, 31, v90
	v_lshlrev_b64 v[90:91], 11, v[90:91]
	v_lshl_add_u64 v[90:91], v[92:93], 0, v[90:91]
	global_store_dwordx4 v[90:91], v[86:89], off nt
	ds_read2_b32 v[86:87], v79 offset0:16 offset1:49
	s_mov_b64 s[6:7], -1
	s_waitcnt lgkmcnt(0)
	v_cvt_pk_bf16_f32 v86, v86, v87
	ds_read2_b32 v[88:89], v79 offset0:82 offset1:115
	s_waitcnt lgkmcnt(0)
	v_cvt_pk_bf16_f32 v87, v88, v89
	ds_read2_b32 v[88:89], v79 offset0:148 offset1:181
	s_waitcnt lgkmcnt(0)
	v_cvt_pk_bf16_f32 v88, v88, v89
	ds_read2_b32 v[90:91], v79 offset0:214 offset1:247
	s_waitcnt lgkmcnt(0)
	v_cvt_pk_bf16_f32 v89, v90, v91
	v_or_b32_e32 v90, s15, v81
	v_ashrrev_i32_e32 v91, 31, v90
	v_lshlrev_b64 v[90:91], 11, v[90:91]
	v_lshl_add_u64 v[90:91], v[92:93], 0, v[90:91]
	global_store_dwordx4 v[90:91], v[86:89], off nt
	ds_read2_b32 v[86:87], v79 offset0:24 offset1:57
	s_waitcnt lgkmcnt(0)
	v_cvt_pk_bf16_f32 v86, v86, v87
	ds_read2_b32 v[88:89], v79 offset0:90 offset1:123
	s_waitcnt lgkmcnt(0)
	v_cvt_pk_bf16_f32 v87, v88, v89
	ds_read2_b32 v[88:89], v79 offset0:156 offset1:189
	s_waitcnt lgkmcnt(0)
	v_cvt_pk_bf16_f32 v88, v88, v89
	ds_read2_b32 v[90:91], v79 offset0:222 offset1:255
	s_waitcnt lgkmcnt(0)
	v_cvt_pk_bf16_f32 v89, v90, v91
	v_or_b32_e32 v90, s15, v82
	v_ashrrev_i32_e32 v91, 31, v90
	v_lshlrev_b64 v[90:91], 11, v[90:91]
	v_lshl_add_u64 v[90:91], v[92:93], 0, v[90:91]
	global_store_dwordx4 v[90:91], v[86:89], off nt
	s_waitcnt lgkmcnt(0)
	s_cbranch_vccnz .LBB7_154
	s_add_i32 s6, s55, s13
	s_cmpk_gt_i32 s6, 0x1ff
	s_cbranch_scc1 .LBB7_153
	s_ashr_i32 s7, s6, 31
	s_lshr_b32 s7, s7, 27
	s_add_i32 s7, s6, s7
	s_and_b32 s13, s7, 0x7ffffe0
	s_lshl_b32 s7, s7, 1
	s_andn2_b32 s7, s7, 63
	s_sub_i32 s6, s6, s13
	v_or_b32_e32 v0, s7, v76
	s_lshl_b32 s6, s6, 5
	v_ashrrev_i32_e32 v1, 31, v0
	v_or_b32_e32 v6, 2, v0
	v_or_b32_e32 v8, 4, v0
	v_or_b32_e32 v10, 6, v0
	v_or_b32_e32 v12, 8, v0
	v_or_b32_e32 v14, 10, v0
	v_or_b32_e32 v16, 12, v0
	v_or_b32_e32 v18, 14, v0
	v_or_b32_e32 v20, 16, v0
	v_or_b32_e32 v22, 18, v0
	v_or_b32_e32 v24, 20, v0
	v_or_b32_e32 v26, 22, v0
	v_or_b32_e32 v28, 24, v0
	v_or_b32_e32 v30, 26, v0
	s_ashr_i32 s7, s6, 31
	v_lshlrev_b64 v[4:5], 12, v[0:1]
	v_ashrrev_i32_e32 v7, 31, v6
	v_ashrrev_i32_e32 v9, 31, v8
	v_ashrrev_i32_e32 v11, 31, v10
	v_ashrrev_i32_e32 v13, 31, v12
	v_ashrrev_i32_e32 v15, 31, v14
	v_ashrrev_i32_e32 v17, 31, v16
	v_ashrrev_i32_e32 v19, 31, v18
	v_ashrrev_i32_e32 v21, 31, v20
	v_ashrrev_i32_e32 v23, 31, v22
	v_ashrrev_i32_e32 v25, 31, v24
	v_ashrrev_i32_e32 v27, 31, v26
	v_ashrrev_i32_e32 v29, 31, v28
	v_ashrrev_i32_e32 v31, 31, v30
	v_or_b32_e32 v86, 28, v0
	v_or_b32_e32 v88, 30, v0
	v_or_b32_e32 v90, 32, v0
	v_or_b32_e32 v92, 34, v0
	v_or_b32_e32 v94, 36, v0
	v_or_b32_e32 v96, 38, v0
	v_or_b32_e32 v98, 40, v0
	v_or_b32_e32 v100, 42, v0
	v_or_b32_e32 v102, 44, v0
	v_or_b32_e32 v104, 46, v0
	v_or_b32_e32 v106, 48, v0
	v_or_b32_e32 v108, 50, v0
	v_or_b32_e32 v110, 52, v0
	v_or_b32_e32 v112, 54, v0
	v_or_b32_e32 v114, 56, v0
	v_or_b32_e32 v116, 58, v0
	v_or_b32_e32 v118, 60, v0
	v_or_b32_e32 v0, 62, v0
	v_lshl_add_u64 v[2:3], s[6:7], 2, v[38:39]
	v_lshlrev_b64 v[6:7], 12, v[6:7]
	v_lshlrev_b64 v[8:9], 12, v[8:9]
	v_lshlrev_b64 v[10:11], 12, v[10:11]
	v_lshlrev_b64 v[12:13], 12, v[12:13]
	v_lshlrev_b64 v[14:15], 12, v[14:15]
	v_lshlrev_b64 v[16:17], 12, v[16:17]
	v_lshlrev_b64 v[18:19], 12, v[18:19]
	v_lshlrev_b64 v[20:21], 12, v[20:21]
	v_lshlrev_b64 v[22:23], 12, v[22:23]
	v_lshlrev_b64 v[24:25], 12, v[24:25]
	v_lshlrev_b64 v[26:27], 12, v[26:27]
	v_lshlrev_b64 v[28:29], 12, v[28:29]
	v_lshlrev_b64 v[30:31], 12, v[30:31]
	v_ashrrev_i32_e32 v87, 31, v86
	v_ashrrev_i32_e32 v89, 31, v88
	v_ashrrev_i32_e32 v91, 31, v90
	v_ashrrev_i32_e32 v93, 31, v92
	v_ashrrev_i32_e32 v95, 31, v94
	v_ashrrev_i32_e32 v97, 31, v96
	v_ashrrev_i32_e32 v99, 31, v98
	v_ashrrev_i32_e32 v101, 31, v100
	v_ashrrev_i32_e32 v103, 31, v102
	v_ashrrev_i32_e32 v105, 31, v104
	v_ashrrev_i32_e32 v107, 31, v106
	v_ashrrev_i32_e32 v109, 31, v108
	v_ashrrev_i32_e32 v111, 31, v110
	v_ashrrev_i32_e32 v113, 31, v112
	v_ashrrev_i32_e32 v115, 31, v114
	v_ashrrev_i32_e32 v117, 31, v116
	v_ashrrev_i32_e32 v119, 31, v118
	v_ashrrev_i32_e32 v1, 31, v0
	v_lshl_add_u64 v[4:5], v[2:3], 0, v[4:5]
	v_lshl_add_u64 v[6:7], v[2:3], 0, v[6:7]
	v_lshl_add_u64 v[8:9], v[2:3], 0, v[8:9]
	v_lshl_add_u64 v[10:11], v[2:3], 0, v[10:11]
	v_lshl_add_u64 v[12:13], v[2:3], 0, v[12:13]
	v_lshl_add_u64 v[14:15], v[2:3], 0, v[14:15]
	v_lshl_add_u64 v[16:17], v[2:3], 0, v[16:17]
	v_lshl_add_u64 v[18:19], v[2:3], 0, v[18:19]
	v_lshl_add_u64 v[20:21], v[2:3], 0, v[20:21]
	v_lshl_add_u64 v[22:23], v[2:3], 0, v[22:23]
	v_lshl_add_u64 v[24:25], v[2:3], 0, v[24:25]
	v_lshl_add_u64 v[26:27], v[2:3], 0, v[26:27]
	v_lshl_add_u64 v[28:29], v[2:3], 0, v[28:29]
	v_lshl_add_u64 v[30:31], v[2:3], 0, v[30:31]
	v_lshlrev_b64 v[86:87], 12, v[86:87]
	v_lshlrev_b64 v[88:89], 12, v[88:89]
	v_lshlrev_b64 v[90:91], 12, v[90:91]
	v_lshlrev_b64 v[92:93], 12, v[92:93]
	v_lshlrev_b64 v[94:95], 12, v[94:95]
	v_lshlrev_b64 v[96:97], 12, v[96:97]
	v_lshlrev_b64 v[98:99], 12, v[98:99]
	v_lshlrev_b64 v[100:101], 12, v[100:101]
	v_lshlrev_b64 v[102:103], 12, v[102:103]
	v_lshlrev_b64 v[104:105], 12, v[104:105]
	v_lshlrev_b64 v[106:107], 12, v[106:107]
	v_lshlrev_b64 v[108:109], 12, v[108:109]
	v_lshlrev_b64 v[110:111], 12, v[110:111]
	v_lshlrev_b64 v[112:113], 12, v[112:113]
	v_lshlrev_b64 v[114:115], 12, v[114:115]
	v_lshlrev_b64 v[116:117], 12, v[116:117]
	v_lshlrev_b64 v[118:119], 12, v[118:119]
	v_lshlrev_b64 v[0:1], 12, v[0:1]
	v_lshl_add_u64 v[86:87], v[2:3], 0, v[86:87]
	v_lshl_add_u64 v[88:89], v[2:3], 0, v[88:89]
	v_lshl_add_u64 v[90:91], v[2:3], 0, v[90:91]
	v_lshl_add_u64 v[92:93], v[2:3], 0, v[92:93]
	v_lshl_add_u64 v[94:95], v[2:3], 0, v[94:95]
	v_lshl_add_u64 v[96:97], v[2:3], 0, v[96:97]
	v_lshl_add_u64 v[98:99], v[2:3], 0, v[98:99]
	v_lshl_add_u64 v[100:101], v[2:3], 0, v[100:101]
	v_lshl_add_u64 v[102:103], v[2:3], 0, v[102:103]
	v_lshl_add_u64 v[104:105], v[2:3], 0, v[104:105]
	v_lshl_add_u64 v[106:107], v[2:3], 0, v[106:107]
	v_lshl_add_u64 v[108:109], v[2:3], 0, v[108:109]
	v_lshl_add_u64 v[110:111], v[2:3], 0, v[110:111]
	v_lshl_add_u64 v[112:113], v[2:3], 0, v[112:113]
	v_lshl_add_u64 v[114:115], v[2:3], 0, v[114:115]
	v_lshl_add_u64 v[116:117], v[2:3], 0, v[116:117]
	v_lshl_add_u64 v[118:119], v[2:3], 0, v[118:119]
	v_lshl_add_u64 v[120:121], v[2:3], 0, v[0:1]
	global_load_dword v0, v[4:5], off nt
	global_load_dword v1, v[6:7], off nt
	global_load_dword v2, v[8:9], off nt
	global_load_dword v3, v[10:11], off nt
	s_nop 0
	global_load_dword v4, v[12:13], off nt
	global_load_dword v5, v[14:15], off nt
	global_load_dword v6, v[16:17], off nt
	global_load_dword v7, v[18:19], off nt
	global_load_dword v8, v[20:21], off nt
	global_load_dword v9, v[22:23], off nt
	global_load_dword v10, v[24:25], off nt
	global_load_dword v11, v[26:27], off nt
	global_load_dword v12, v[28:29], off nt
	global_load_dword v13, v[30:31], off nt
	global_load_dword v14, v[86:87], off nt
	global_load_dword v15, v[88:89], off nt
	global_load_dword v16, v[90:91], off nt
	global_load_dword v17, v[92:93], off nt
	global_load_dword v18, v[94:95], off nt
	global_load_dword v19, v[96:97], off nt
	global_load_dword v20, v[98:99], off nt
	global_load_dword v21, v[100:101], off nt
	global_load_dword v22, v[102:103], off nt
	global_load_dword v23, v[104:105], off nt
	global_load_dword v24, v[106:107], off nt
	global_load_dword v25, v[108:109], off nt
	global_load_dword v26, v[110:111], off nt
	global_load_dword v27, v[112:113], off nt
	global_load_dword v28, v[114:115], off nt
	global_load_dword v29, v[116:117], off nt
	global_load_dword v30, v[118:119], off nt
	global_load_dword v31, v[120:121], off nt
	s_branch .LBB7_153

.LBB7_162:
	s_mul_hi_i32 s6, s14, 0x2aaaaaab
	s_lshr_b32 s7, s6, 31
	s_ashr_i32 s6, s6, 1
	s_add_i32 s6, s6, s7
	ds_write2_b32 v77, v32, v35 offset1:66
	ds_write2_b32 v77, v37, v42 offset0:132 offset1:198
	ds_write2_b32 v71, v43, v44 offset0:8 offset1:74
	ds_write2_b32 v71, v45, v46 offset0:140 offset1:206
	ds_write2_b32 v72, v47, v48 offset0:16 offset1:82
	ds_write2_b32 v72, v49, v50 offset0:148 offset1:214
	ds_write2_b32 v73, v51, v52 offset0:24 offset1:90
	ds_write2_b32 v73, v53, v54 offset0:156 offset1:222
	ds_write2_b32 v74, v55, v56 offset0:32 offset1:98
	ds_write2_b32 v74, v57, v58 offset0:164 offset1:230
	ds_write2_b32 v75, v59, v60 offset0:40 offset1:106
	ds_write2_b32 v75, v61, v62 offset0:172 offset1:238
	ds_write2_b32 v84, v63, v64 offset0:48 offset1:114
	ds_write2_b32 v84, v65, v66 offset0:180 offset1:246
	ds_write2_b32 v85, v67, v68 offset0:56 offset1:122
	ds_write2_b32 v85, v69, v70 offset0:188 offset1:254
	s_mul_i32 s7, s6, 12
	s_waitcnt lgkmcnt(0)
	s_sub_i32 s7, s14, s7
	s_lshl_b32 s15, s7, 5
	ds_read2_b32 v[72:73], v79 offset1:33
	s_lshl_b32 s6, s6, 6
	v_or_b32_e32 v71, s15, v78
	s_waitcnt lgkmcnt(0)
	v_cvt_pk_bf16_f32 v72, v72, v73
	ds_read2_b32 v[74:75], v79 offset0:66 offset1:99
	s_ashr_i32 s7, s6, 31
	v_mul_lo_u32 v88, v71, s58
	s_waitcnt lgkmcnt(0)
	v_cvt_pk_bf16_f32 v73, v74, v75
	ds_read2_b32 v[74:75], v79 offset0:132 offset1:165
	v_lshl_add_u64 v[86:87], s[6:7], 1, v[40:41]
	v_ashrrev_i32_e32 v89, 31, v88
	s_waitcnt lgkmcnt(0)
	v_cvt_pk_bf16_f32 v74, v74, v75
	ds_read2_b32 v[84:85], v79 offset0:198 offset1:231
	s_waitcnt lgkmcnt(0)
	v_cvt_pk_bf16_f32 v75, v84, v85
	v_lshl_add_u64 v[88:89], v[88:89], 1, v[86:87]
	v_or_b32_e32 v71, s15, v80
	ds_read2_b32 v[84:85], v79 offset0:8 offset1:41
	global_store_dwordx4 v[88:89], v[72:75], off nt
	v_mul_lo_u32 v88, v71, s58
	v_ashrrev_i32_e32 v89, 31, v88
	s_waitcnt lgkmcnt(0)
	v_cvt_pk_bf16_f32 v72, v84, v85
	ds_read2_b32 v[74:75], v79 offset0:74 offset1:107
	s_waitcnt lgkmcnt(0)
	v_cvt_pk_bf16_f32 v73, v74, v75
	ds_read2_b32 v[74:75], v79 offset0:140 offset1:173
	s_waitcnt lgkmcnt(0)
	v_cvt_pk_bf16_f32 v74, v74, v75
	ds_read2_b32 v[84:85], v79 offset0:206 offset1:239
	s_waitcnt lgkmcnt(0)
	v_cvt_pk_bf16_f32 v75, v84, v85
	v_lshl_add_u64 v[88:89], v[88:89], 1, v[86:87]
	v_or_b32_e32 v71, s15, v81
	ds_read2_b32 v[84:85], v79 offset0:16 offset1:49
	global_store_dwordx4 v[88:89], v[72:75], off nt
	v_mul_lo_u32 v88, v71, s58
	v_ashrrev_i32_e32 v89, 31, v88
	s_waitcnt lgkmcnt(0)
	v_cvt_pk_bf16_f32 v72, v84, v85
	ds_read2_b32 v[74:75], v79 offset0:82 offset1:115
	s_waitcnt lgkmcnt(0)
	v_cvt_pk_bf16_f32 v73, v74, v75
	ds_read2_b32 v[74:75], v79 offset0:148 offset1:181
	s_waitcnt lgkmcnt(0)
	v_cvt_pk_bf16_f32 v74, v74, v75
	ds_read2_b32 v[84:85], v79 offset0:214 offset1:247
	s_waitcnt lgkmcnt(0)
	v_cvt_pk_bf16_f32 v75, v84, v85
	v_lshl_add_u64 v[88:89], v[88:89], 1, v[86:87]
	ds_read2_b32 v[84:85], v79 offset0:24 offset1:57
	global_store_dwordx4 v[88:89], v[72:75], off nt
	v_or_b32_e32 v71, s15, v82
	v_mul_lo_u32 v88, v71, s58
	s_waitcnt lgkmcnt(0)
	v_cvt_pk_bf16_f32 v72, v84, v85
	ds_read2_b32 v[74:75], v79 offset0:90 offset1:123
	s_waitcnt lgkmcnt(0)
	v_cvt_pk_bf16_f32 v73, v74, v75
	ds_read2_b32 v[74:75], v79 offset0:156 offset1:189
	s_waitcnt lgkmcnt(0)
	v_cvt_pk_bf16_f32 v74, v74, v75
	ds_read2_b32 v[84:85], v79 offset0:222 offset1:255
	v_ashrrev_i32_e32 v89, 31, v88
	s_waitcnt lgkmcnt(0)
	v_cvt_pk_bf16_f32 v75, v84, v85
	v_lshl_add_u64 v[84:85], v[88:89], 1, v[86:87]
	global_store_dwordx4 v[84:85], v[72:75], off nt
	s_waitcnt lgkmcnt(0)
	s_add_i32 s13, s14, s72
	s_cmpk_gt_i32 s13, 0x47
	s_cselect_b64 s[6:7], -1, 0

.LBB7_166:
	v_add_u32_e32 v71, 0x400, v77
	v_add_u32_e32 v72, 0x800, v77
	v_add_u32_e32 v73, 0xc00, v77
	v_add_u32_e32 v74, 0x1000, v77
	v_add_u32_e32 v75, 0x1400, v77
	v_add_u32_e32 v84, 0x1800, v77
	v_add_u32_e32 v85, 0x1c00, v77
	s_waitcnt vmcnt(30)
	ds_write2_b32 v77, v0, v1 offset1:66
	s_waitcnt vmcnt(28)
	ds_write2_b32 v77, v2, v3 offset0:132 offset1:198
	s_waitcnt vmcnt(26)
	ds_write2_b32 v71, v4, v5 offset0:8 offset1:74
	s_waitcnt vmcnt(24)
	ds_write2_b32 v71, v6, v7 offset0:140 offset1:206
	s_waitcnt vmcnt(22)
	ds_write2_b32 v72, v8, v9 offset0:16 offset1:82
	s_waitcnt vmcnt(20)
	ds_write2_b32 v72, v10, v11 offset0:148 offset1:214
	s_waitcnt vmcnt(18)
	ds_write2_b32 v73, v12, v13 offset0:24 offset1:90
	s_waitcnt vmcnt(16)
	ds_write2_b32 v73, v14, v15 offset0:156 offset1:222
	s_waitcnt vmcnt(14)
	ds_write2_b32 v74, v16, v17 offset0:32 offset1:98
	s_waitcnt vmcnt(12)
	ds_write2_b32 v74, v18, v19 offset0:164 offset1:230
	s_waitcnt vmcnt(10)
	ds_write2_b32 v75, v20, v21 offset0:40 offset1:106
	s_waitcnt vmcnt(8)
	ds_write2_b32 v75, v22, v23 offset0:172 offset1:238
	s_waitcnt vmcnt(6)
	ds_write2_b32 v84, v24, v25 offset0:48 offset1:114
	s_waitcnt vmcnt(4)
	ds_write2_b32 v84, v26, v27 offset0:180 offset1:246
	s_waitcnt vmcnt(2)
	ds_write2_b32 v85, v28, v29 offset0:56 offset1:122
	s_waitcnt vmcnt(0)
	ds_write2_b32 v85, v30, v31 offset0:188 offset1:254
	s_waitcnt lgkmcnt(0)
	s_mul_hi_i32 s15, s13, 0x2aaaaaab
	s_lshr_b32 s16, s15, 31
	s_ashr_i32 s15, s15, 1
	ds_read2_b32 v[86:87], v79 offset1:33
	s_add_i32 s15, s15, s16
	s_waitcnt lgkmcnt(0)
	v_cvt_pk_bf16_f32 v86, v86, v87
	ds_read2_b32 v[88:89], v79 offset0:66 offset1:99
	s_mul_i32 s16, s15, 12
	s_waitcnt lgkmcnt(0)
	v_cvt_pk_bf16_f32 v87, v88, v89
	ds_read2_b32 v[88:89], v79 offset0:132 offset1:165
	s_sub_i32 s16, s13, s16
	s_waitcnt lgkmcnt(0)
	v_cvt_pk_bf16_f32 v88, v88, v89
	ds_read2_b32 v[90:91], v79 offset0:198 offset1:231
	s_lshl_b32 s42, s15, 6
	s_lshl_b32 s15, s16, 5
	s_waitcnt lgkmcnt(0)
	v_cvt_pk_bf16_f32 v89, v90, v91
	v_or_b32_e32 v90, s15, v78
	s_ashr_i32 s43, s42, 31
	v_mul_lo_u32 v90, v90, s58
	v_ashrrev_i32_e32 v91, 31, v90
	v_lshl_add_u64 v[92:93], s[42:43], 1, v[40:41]
	v_lshl_add_u64 v[90:91], v[90:91], 1, v[92:93]
	global_store_dwordx4 v[90:91], v[86:89], off nt
	ds_read2_b32 v[86:87], v79 offset0:8 offset1:41
	s_andn2_b64 vcc, exec, s[6:7]
	s_waitcnt lgkmcnt(0)
	v_cvt_pk_bf16_f32 v86, v86, v87
	ds_read2_b32 v[88:89], v79 offset0:74 offset1:107
	s_waitcnt lgkmcnt(0)
	v_cvt_pk_bf16_f32 v87, v88, v89
	ds_read2_b32 v[88:89], v79 offset0:140 offset1:173
	s_waitcnt lgkmcnt(0)
	v_cvt_pk_bf16_f32 v88, v88, v89
	ds_read2_b32 v[90:91], v79 offset0:206 offset1:239
	s_waitcnt lgkmcnt(0)
	v_cvt_pk_bf16_f32 v89, v90, v91
	v_or_b32_e32 v90, s15, v80
	v_mul_lo_u32 v90, v90, s58
	v_ashrrev_i32_e32 v91, 31, v90
	v_lshl_add_u64 v[90:91], v[90:91], 1, v[92:93]
	global_store_dwordx4 v[90:91], v[86:89], off nt
	ds_read2_b32 v[86:87], v79 offset0:16 offset1:49
	s_mov_b64 s[6:7], -1
	s_waitcnt lgkmcnt(0)
	v_cvt_pk_bf16_f32 v86, v86, v87
	ds_read2_b32 v[88:89], v79 offset0:82 offset1:115
	s_waitcnt lgkmcnt(0)
	v_cvt_pk_bf16_f32 v87, v88, v89
	ds_read2_b32 v[88:89], v79 offset0:148 offset1:181
	s_waitcnt lgkmcnt(0)
	v_cvt_pk_bf16_f32 v88, v88, v89
	ds_read2_b32 v[90:91], v79 offset0:214 offset1:247
	s_waitcnt lgkmcnt(0)
	v_cvt_pk_bf16_f32 v89, v90, v91
	v_or_b32_e32 v90, s15, v81
	v_mul_lo_u32 v90, v90, s58
	v_ashrrev_i32_e32 v91, 31, v90
	v_lshl_add_u64 v[90:91], v[90:91], 1, v[92:93]
	global_store_dwordx4 v[90:91], v[86:89], off nt
	ds_read2_b32 v[86:87], v79 offset0:24 offset1:57
	s_waitcnt lgkmcnt(0)
	v_cvt_pk_bf16_f32 v86, v86, v87
	ds_read2_b32 v[88:89], v79 offset0:90 offset1:123
	s_waitcnt lgkmcnt(0)
	v_cvt_pk_bf16_f32 v87, v88, v89
	ds_read2_b32 v[88:89], v79 offset0:156 offset1:189
	s_waitcnt lgkmcnt(0)
	v_cvt_pk_bf16_f32 v88, v88, v89
	ds_read2_b32 v[90:91], v79 offset0:222 offset1:255
	s_waitcnt lgkmcnt(0)
	v_cvt_pk_bf16_f32 v89, v90, v91
	v_or_b32_e32 v90, s15, v82
	v_mul_lo_u32 v90, v90, s58
	v_ashrrev_i32_e32 v91, 31, v90
	v_lshl_add_u64 v[90:91], v[90:91], 1, v[92:93]
	global_store_dwordx4 v[90:91], v[86:89], off nt
	s_waitcnt lgkmcnt(0)
	s_cbranch_vccnz .LBB7_163
	s_add_i32 s6, s55, s13
	s_cmpk_gt_i32 s6, 0x47
	s_cbranch_scc1 .LBB7_162
	s_mul_hi_i32 s7, s6, 0x2aaaaaab
	s_lshr_b32 s13, s7, 31
	s_ashr_i32 s7, s7, 1
	s_add_i32 s7, s7, s13
	s_mul_i32 s13, s7, 12
	s_sub_i32 s6, s6, s13
	s_lshl_b32 s6, s6, 5
	v_lshl_or_b32 v118, s7, 6, v76
	s_ashr_i32 s7, s6, 31
	v_lshl_add_u64 v[0:1], s[6:7], 2, v[38:39]
	v_or_b32_e32 v4, 2, v118
	v_or_b32_e32 v6, 4, v118
	v_or_b32_e32 v8, 6, v118
	v_or_b32_e32 v10, 8, v118
	v_or_b32_e32 v12, 10, v118
	v_or_b32_e32 v14, 12, v118
	v_or_b32_e32 v16, 14, v118
	v_or_b32_e32 v18, 16, v118
	v_or_b32_e32 v20, 18, v118
	v_or_b32_e32 v22, 20, v118
	v_or_b32_e32 v24, 22, v118
	v_or_b32_e32 v26, 24, v118
	v_or_b32_e32 v28, 26, v118
	v_or_b32_e32 v30, 28, v118
	v_mad_i64_i32 v[2:3], s[6:7], v118, s59, v[0:1]
	v_mad_i64_i32 v[4:5], s[6:7], v4, s59, v[0:1]
	v_mad_i64_i32 v[6:7], s[6:7], v6, s59, v[0:1]
	v_mad_i64_i32 v[8:9], s[6:7], v8, s59, v[0:1]
	v_mad_i64_i32 v[10:11], s[6:7], v10, s59, v[0:1]
	v_mad_i64_i32 v[12:13], s[6:7], v12, s59, v[0:1]
	v_mad_i64_i32 v[14:15], s[6:7], v14, s59, v[0:1]
	v_mad_i64_i32 v[16:17], s[6:7], v16, s59, v[0:1]
	v_mad_i64_i32 v[18:19], s[6:7], v18, s59, v[0:1]
	v_mad_i64_i32 v[20:21], s[6:7], v20, s59, v[0:1]
	v_mad_i64_i32 v[22:23], s[6:7], v22, s59, v[0:1]
	v_mad_i64_i32 v[24:25], s[6:7], v24, s59, v[0:1]
	v_mad_i64_i32 v[26:27], s[6:7], v26, s59, v[0:1]
	v_mad_i64_i32 v[28:29], s[6:7], v28, s59, v[0:1]
	v_mad_i64_i32 v[30:31], s[6:7], v30, s59, v[0:1]
	v_or_b32_e32 v86, 30, v118
	v_or_b32_e32 v88, 32, v118
	v_or_b32_e32 v90, 34, v118
	v_or_b32_e32 v92, 36, v118
	v_or_b32_e32 v94, 38, v118
	v_or_b32_e32 v96, 40, v118
	v_or_b32_e32 v98, 42, v118
	v_or_b32_e32 v100, 44, v118
	v_or_b32_e32 v102, 46, v118
	v_or_b32_e32 v104, 48, v118
	v_or_b32_e32 v106, 50, v118
	v_or_b32_e32 v108, 52, v118
	v_or_b32_e32 v110, 54, v118
	v_or_b32_e32 v112, 56, v118
	v_or_b32_e32 v114, 58, v118
	v_or_b32_e32 v116, 60, v118
	v_or_b32_e32 v118, 62, v118
	v_mad_i64_i32 v[86:87], s[6:7], v86, s59, v[0:1]
	v_mad_i64_i32 v[88:89], s[6:7], v88, s59, v[0:1]
	v_mad_i64_i32 v[90:91], s[6:7], v90, s59, v[0:1]
	v_mad_i64_i32 v[92:93], s[6:7], v92, s59, v[0:1]
	v_mad_i64_i32 v[94:95], s[6:7], v94, s59, v[0:1]
	v_mad_i64_i32 v[96:97], s[6:7], v96, s59, v[0:1]
	v_mad_i64_i32 v[98:99], s[6:7], v98, s59, v[0:1]
	v_mad_i64_i32 v[100:101], s[6:7], v100, s59, v[0:1]
	v_mad_i64_i32 v[102:103], s[6:7], v102, s59, v[0:1]
	v_mad_i64_i32 v[104:105], s[6:7], v104, s59, v[0:1]
	v_mad_i64_i32 v[106:107], s[6:7], v106, s59, v[0:1]
	v_mad_i64_i32 v[108:109], s[6:7], v108, s59, v[0:1]
	v_mad_i64_i32 v[110:111], s[6:7], v110, s59, v[0:1]
	v_mad_i64_i32 v[112:113], s[6:7], v112, s59, v[0:1]
	v_mad_i64_i32 v[114:115], s[6:7], v114, s59, v[0:1]
	v_mad_i64_i32 v[116:117], s[6:7], v116, s59, v[0:1]
	v_mad_i64_i32 v[118:119], s[6:7], v118, s59, v[0:1]
	global_load_dword v0, v[2:3], off nt
	global_load_dword v1, v[4:5], off nt
	s_nop 0
	global_load_dword v2, v[6:7], off nt
	global_load_dword v3, v[8:9], off nt
	global_load_dword v4, v[10:11], off nt
	global_load_dword v5, v[12:13], off nt
	s_nop 0
	global_load_dword v6, v[14:15], off nt
	global_load_dword v7, v[16:17], off nt
	global_load_dword v8, v[18:19], off nt
	global_load_dword v9, v[20:21], off nt
	global_load_dword v10, v[22:23], off nt
	global_load_dword v11, v[24:25], off nt
	global_load_dword v12, v[26:27], off nt
	global_load_dword v13, v[28:29], off nt
	global_load_dword v14, v[30:31], off nt
	global_load_dword v15, v[86:87], off nt
	global_load_dword v16, v[88:89], off nt
	global_load_dword v17, v[90:91], off nt
	global_load_dword v18, v[92:93], off nt
	global_load_dword v19, v[94:95], off nt
	global_load_dword v20, v[96:97], off nt
	global_load_dword v21, v[98:99], off nt
	global_load_dword v22, v[100:101], off nt
	global_load_dword v23, v[102:103], off nt
	global_load_dword v24, v[104:105], off nt
	global_load_dword v25, v[106:107], off nt
	global_load_dword v26, v[108:109], off nt
	global_load_dword v27, v[110:111], off nt
	global_load_dword v28, v[112:113], off nt
	global_load_dword v29, v[114:115], off nt
	global_load_dword v30, v[116:117], off nt
	global_load_dword v31, v[118:119], off nt
	s_branch .LBB7_162

.LBB7_176:
	s_or_b64 exec, exec, s[6:7]
	v_mov_b64_e32 v[2:3], s[22:23]
	v_mad_i64_i32 v[2:3], s[6:7], v18, s54, v[2:3]
	v_lshl_or_b32 v18, v5, 7, v19
	v_ashrrev_i32_e32 v19, 31, v18
	v_lshlrev_b64 v[18:19], 10, v[18:19]
	v_ashrrev_i32_e32 v5, 31, v4
	v_lshl_add_u64 v[2:3], v[2:3], 0, v[18:19]
	v_lshl_add_u64 v[2:3], v[4:5], 1, v[2:3]
	v_add_co_u32_e32 v2, vcc, 0x2f80000, v2
	v_add_u32_e32 v12, s33, v12
	s_nop 0
	v_addc_co_u32_e32 v3, vcc, 0, v3, vcc
	v_cmp_lt_i32_e32 vcc, s55, v12
	s_or_b64 s[28:29], vcc, s[28:29]
	v_add_u32_e32 v10, s36, v10
	v_cvt_pk_bf16_f32 v6, v0, v20
	v_cvt_pk_bf16_f32 v7, v21, v22
	v_cvt_pk_bf16_f32 v8, v23, v24
	v_cvt_pk_bf16_f32 v9, v25, v26
	global_store_dwordx4 v[2:3], v[6:9], off nt
	s_andn2_b64 exec, exec, s[28:29]
	s_cbranch_execz .LBB7_217

.LBB7_223:
	s_waitcnt vmcnt(3)
	v_mul_f32_e32 v44, v29, v29
	v_mul_f32_e32 v45, v31, v31
	v_fmac_f32_e32 v44, v28, v28
	v_fmac_f32_e32 v45, v30, v30
	v_add_f32_e32 v44, v44, v45
	s_waitcnt vmcnt(2)
	v_mul_f32_e32 v45, v25, v25
	v_mul_f32_e32 v46, v27, v27
	v_fmac_f32_e32 v45, v24, v24
	v_fmac_f32_e32 v46, v26, v26
	v_add_f32_e32 v45, v45, v46
	v_add_f32_e32 v44, v44, v45
	s_waitcnt vmcnt(1)
	v_mul_f32_e32 v45, v21, v21
	v_mul_f32_e32 v46, v23, v23
	v_fmac_f32_e32 v45, v20, v20
	v_fmac_f32_e32 v46, v22, v22
	v_add_f32_e32 v45, v45, v46
	v_add_f32_e32 v44, v44, v45
	s_waitcnt vmcnt(0)
	v_mul_f32_e32 v45, v17, v17
	v_mul_f32_e32 v46, v19, v19
	v_fmac_f32_e32 v45, v16, v16
	v_fmac_f32_e32 v46, v18, v18
	v_add_f32_e32 v45, v45, v46
	v_cmp_lt_i32_e32 vcc, v39, v38
	v_add_f32_e32 v44, v44, v45
	s_and_b64 s[14:15], s[14:15], exec
	v_cndmask_b32_e32 v45, v37, v39, vcc
	v_lshlrev_b32_e32 v45, 2, v45
	s_nop 0
	v_cmp_lt_i32_e32 vcc, v40, v38
	s_cselect_b32 s14, s18, 0x1c580000
	s_add_u32 s25, s22, s14
	s_addc_u32 s26, s23, 0
	s_waitcnt lgkmcnt(0)
	s_nop 1
	v_add_f32_dpp v46, v44, v44 quad_perm:[1,0,3,2] row_mask:0xf bank_mask:0xf
	v_cndmask_b32_e32 v44, v37, v40, vcc
	v_lshlrev_b32_e32 v44, 2, v44
	s_nop 0
	v_cmp_lt_i32_e32 vcc, v42, v38
	s_lshl_b64 s[14:15], s[10:11], 11
	s_add_u32 s14, s25, s14
	s_addc_u32 s15, s26, s15
	s_waitcnt lgkmcnt(0)
	s_nop 1
	v_add_f32_dpp v47, v46, v46 quad_perm:[2,3,0,1] row_mask:0xf bank_mask:0xf
	v_cndmask_b32_e32 v46, v37, v42, vcc
	v_lshlrev_b32_e32 v46, 2, v46
	s_nop 0
	v_cmp_lt_i32_e32 vcc, v43, v38
	v_cvt_pk_bf16_f32 v28, v28, v29
	v_cvt_pk_bf16_f32 v29, v30, v31
	global_store_dwordx2 v32, v[28:29], s[14:15] nt
	s_waitcnt lgkmcnt(0)
	s_nop 1
	v_add_f32_dpp v48, v47, v47 row_half_mirror row_mask:0xf bank_mask:0xf
	v_cndmask_b32_e32 v47, v37, v43, vcc
	v_lshlrev_b32_e32 v47, 2, v47
	s_nop 0
	v_cvt_pk_bf16_f32 v28, v24, v25
	v_xor_b32_e32 v24, 16, v37
	v_cmp_lt_i32_e32 vcc, v24, v38
	v_cvt_pk_bf16_f32 v29, v26, v27
	s_waitcnt lgkmcnt(0)
	s_nop 1
	v_add_f32_dpp v25, v48, v48 row_mirror row_mask:0xf bank_mask:0xf
	global_store_dwordx2 v32, v[28:29], s[14:15] offset:512 nt
	v_cndmask_b32_e32 v24, v37, v24, vcc
	v_lshlrev_b32_e32 v24, 2, v24
	ds_bpermute_b32 v30, v24, v25
	v_cvt_pk_bf16_f32 v26, v20, v21
	v_xor_b32_e32 v20, 32, v37
	v_cmp_lt_i32_e32 vcc, v20, v38
	v_cvt_pk_bf16_f32 v27, v22, v23
	s_waitcnt lgkmcnt(0)
	v_add_f32_e32 v21, v25, v30
	global_store_dwordx2 v32, v[26:27], s[14:15] offset:1024 nt
	v_cndmask_b32_e32 v20, v37, v20, vcc
	v_lshlrev_b32_e32 v20, 2, v20
	ds_bpermute_b32 v22, v20, v21
	v_cvt_pk_bf16_f32 v16, v16, v17
	v_cvt_pk_bf16_f32 v17, v18, v19
	global_store_dwordx2 v32, v[16:17], s[14:15] offset:1536 nt
	s_mov_b64 s[14:15], -1
	s_waitcnt lgkmcnt(0)
	v_add_f32_e32 v16, v21, v22
	s_and_b64 vcc, exec, s[12:13]
	s_cbranch_vccz .LBB7_228
	s_and_saveexec_b64 s[12:13], s[6:7]
	s_cbranch_execz .LBB7_226
	v_fmamk_f32 v17, v16, 0x3a800000, v41
	v_mul_f32_e32 v18, 0x4b800000, v17
	v_cmp_gt_f32_e32 vcc, s19, v17
	s_lshl_b64 s[14:15], s[10:11], 2
	s_add_u32 s14, s16, s14
	v_cndmask_b32_e32 v17, v17, v18, vcc
	v_rsq_f32_e32 v17, v17
	s_addc_u32 s15, s17, s15
	v_mul_f32_e32 v18, 0x45800000, v17
	v_cndmask_b32_e32 v17, v17, v18, vcc
	global_store_dword v33, v17, s[14:15]

.LBB7_232:
	v_mul_f32_e32 v16, v13, v13
	v_mul_f32_e32 v17, v15, v15
	v_fmac_f32_e32 v16, v12, v12
	v_fmac_f32_e32 v17, v14, v14
	v_add_f32_e32 v16, v16, v17
	v_mul_f32_e32 v17, v9, v9
	v_mul_f32_e32 v18, v11, v11
	v_fmac_f32_e32 v17, v8, v8
	v_fmac_f32_e32 v18, v10, v10
	v_add_f32_e32 v17, v17, v18
	v_add_f32_e32 v16, v17, v16
	v_mul_f32_e32 v17, v5, v5
	v_mul_f32_e32 v18, v7, v7
	v_fmac_f32_e32 v17, v4, v4
	v_fmac_f32_e32 v18, v6, v6
	v_add_f32_e32 v17, v17, v18
	v_add_f32_e32 v16, v17, v16
	v_mul_f32_e32 v17, v1, v1
	v_mul_f32_e32 v18, v3, v3
	v_fmac_f32_e32 v17, v0, v0
	v_fmac_f32_e32 v18, v2, v2
	v_add_f32_e32 v17, v17, v18
	v_add_f32_e32 v16, v17, v16
	s_nop 0
	s_add_i32 s10, s24, 0xffff8000
	s_cmp_lt_i32 s24, 0x8000
	s_cselect_b64 s[8:9], -1, 0
	s_and_b64 vcc, s[8:9], exec
	s_waitcnt lgkmcnt(0)
	s_nop 1
	v_add_f32_dpp v16, v16, v16 quad_perm:[1,0,3,2] row_mask:0xf bank_mask:0xf
	s_nop 0
	s_cselect_b32 s9, s18, 0x1c580000
	s_cselect_b32 s8, s24, s10
	s_add_u32 s12, s22, s9
	s_addc_u32 s13, s23, 0
	s_waitcnt lgkmcnt(0)
	s_nop 1
	v_add_f32_dpp v16, v16, v16 quad_perm:[2,3,0,1] row_mask:0xf bank_mask:0xf
	s_nop 0
	s_ashr_i32 s9, s8, 31
	s_lshl_b64 s[10:11], s[8:9], 11
	s_add_u32 s10, s12, s10
	s_addc_u32 s11, s13, s11
	s_waitcnt lgkmcnt(0)
	s_nop 1
	v_add_f32_dpp v18, v16, v16 row_half_mirror row_mask:0xf bank_mask:0xf
	s_nop 0
	v_cvt_pk_bf16_f32 v16, v12, v13
	v_cvt_pk_bf16_f32 v17, v14, v15
	global_store_dwordx2 v32, v[16:17], s[10:11] nt
	v_cvt_pk_bf16_f32 v16, v8, v9
	s_waitcnt lgkmcnt(0)
	s_nop 1
	v_add_f32_dpp v18, v18, v18 row_mirror row_mask:0xf bank_mask:0xf
	v_mov_b32_e32 v19, v18
	s_nop 1
	v_permlane16_swap_b32_e32 v18, v19
	v_cvt_pk_bf16_f32 v17, v10, v11
	global_store_dwordx2 v32, v[16:17], s[10:11] offset:512 nt
	v_cvt_pk_bf16_f32 v16, v4, v5
	v_cvt_pk_bf16_f32 v17, v6, v7
	s_waitcnt lgkmcnt(0)
	v_add_f32_e32 v18, v18, v19
	v_mov_b32_e32 v19, v18
	s_nop 1
	v_permlane32_swap_b32_e32 v18, v19
	global_store_dwordx2 v32, v[16:17], s[10:11] offset:1024 nt
	v_cvt_pk_bf16_f32 v16, v0, v1
	v_cvt_pk_bf16_f32 v17, v2, v3
	global_store_dwordx2 v32, v[16:17], s[10:11] offset:1536 nt
	s_waitcnt lgkmcnt(0)
	v_add_f32_e32 v16, v18, v19
	s_mov_b64 s[10:11], -1
	s_cbranch_vccnz .LBB7_236
	s_and_saveexec_b64 s[10:11], s[6:7]
	s_cbranch_execz .LBB7_235
	v_fmamk_f32 v17, v16, 0x3a800000, v41
	v_mul_f32_e32 v18, 0x4b800000, v17
	v_cmp_gt_f32_e32 vcc, s19, v17
	s_lshl_b64 s[12:13], s[8:9], 2
	s_add_u32 s12, s16, s12
	v_cndmask_b32_e32 v17, v17, v18, vcc
	v_rsq_f32_e32 v17, v17
	s_addc_u32 s13, s17, s13
	v_mul_f32_e32 v18, 0x45800000, v17
	v_cndmask_b32_e32 v17, v17, v18, vcc
	global_store_dword v33, v17, s[12:13]

.LBB7_330:
	s_ashr_i32 s38, s78, 1
	v_lshl_add_u32 v168, s80, 8, v174
	s_bitcmp1_b32 s78, 0
	v_lshl_or_b32 v166, s79, 8, v176
	s_cselect_b64 s[42:43], -1, 0
	s_ashr_i32 s39, s38, 31
	v_or_b32_e32 v164, 16, v168
	v_or_b32_e32 v162, 32, v168
	v_or_b32_e32 v160, 48, v168
	s_lshl_b64 s[38:39], s[38:39], 23
	v_ashrrev_i32_e32 v167, 31, v166
	s_mov_b64 s[40:41], -1
	s_and_b64 vcc, exec, s[42:43]
	v_ashrrev_i32_e32 v169, 31, v168
	v_ashrrev_i32_e32 v165, 31, v164
	v_ashrrev_i32_e32 v163, 31, v162
	v_ashrrev_i32_e32 v161, 31, v160
	s_cbranch_vccz .LBB7_333
	v_lshl_add_u64 v[132:133], v[166:167], 2, s[8:9]
	global_load_dwordx4 v[136:139], v[132:133], off offset:16
	global_load_dwordx4 v[140:143], v[132:133], off
	global_load_dwordx4 v[128:131], v[132:133], off offset:528
	s_nop 0
	global_load_dwordx4 v[132:135], v[132:133], off offset:512
	s_add_u32 s40, s53, s38
	s_addc_u32 s41, s54, s39
	v_lshl_add_u64 v[172:173], v[166:167], 1, s[40:41]
	v_lshlrev_b64 v[170:171], 13, v[168:169]
	v_lshl_add_u64 v[170:171], v[172:173], 0, v[170:171]
	s_waitcnt vmcnt(0)
	v_pk_mul_f32 v[184:185], v[122:123], v[138:139]
	v_pk_mul_f32 v[180:181], v[124:125], v[140:141]
	v_pk_mul_f32 v[182:183], v[126:127], v[142:143]
	v_cvt_pk_bf16_f32 v180, v180, v181
	v_pk_mul_f32 v[186:187], v[120:121], v[136:137]
	v_cvt_pk_bf16_f32 v181, v182, v183
	v_pk_mul_f32 v[188:189], v[104:105], v[136:137]
	v_cvt_pk_bf16_f32 v182, v186, v187
	v_cvt_pk_bf16_f32 v183, v184, v185
	global_store_dwordx4 v[170:171], v[180:183], off nt
	v_pk_mul_f32 v[184:185], v[114:115], v[130:131]
	v_pk_mul_f32 v[186:187], v[112:113], v[128:129]
	v_pk_mul_f32 v[180:181], v[116:117], v[132:133]
	v_pk_mul_f32 v[182:183], v[118:119], v[134:135]
	v_cvt_pk_bf16_f32 v180, v180, v181
	s_nop 0
	v_cvt_pk_bf16_f32 v181, v182, v183
	v_cvt_pk_bf16_f32 v182, v186, v187
	v_cvt_pk_bf16_f32 v183, v184, v185
	global_store_dwordx4 v[170:171], v[180:183], off offset:256 nt
	v_pk_mul_f32 v[186:187], v[106:107], v[138:139]
	s_nop 0
	v_lshlrev_b64 v[180:181], 13, v[164:165]
	v_lshl_add_u64 v[184:185], v[172:173], 0, v[180:181]
	v_pk_mul_f32 v[180:181], v[108:109], v[140:141]
	v_pk_mul_f32 v[182:183], v[110:111], v[142:143]
	v_cvt_pk_bf16_f32 v180, v180, v181
	s_nop 0
	v_cvt_pk_bf16_f32 v181, v182, v183
	v_cvt_pk_bf16_f32 v182, v188, v189
	v_cvt_pk_bf16_f32 v183, v186, v187
	global_store_dwordx4 v[184:185], v[180:183], off nt
	v_pk_mul_f32 v[186:187], v[98:99], v[130:131]
	v_pk_mul_f32 v[188:189], v[96:97], v[128:129]
	v_pk_mul_f32 v[180:181], v[100:101], v[132:133]
	v_pk_mul_f32 v[182:183], v[102:103], v[134:135]
	v_cvt_pk_bf16_f32 v180, v180, v181
	s_nop 0
	v_cvt_pk_bf16_f32 v181, v182, v183
	v_cvt_pk_bf16_f32 v182, v188, v189
	v_cvt_pk_bf16_f32 v183, v186, v187
	global_store_dwordx4 v[184:185], v[180:183], off offset:256 nt
	v_pk_mul_f32 v[186:187], v[90:91], v[138:139]
	v_pk_mul_f32 v[188:189], v[88:89], v[136:137]
	v_lshlrev_b64 v[180:181], 13, v[162:163]
	v_lshl_add_u64 v[184:185], v[172:173], 0, v[180:181]
	v_pk_mul_f32 v[180:181], v[92:93], v[140:141]
	v_pk_mul_f32 v[182:183], v[94:95], v[142:143]
	v_cvt_pk_bf16_f32 v180, v180, v181
	s_nop 0
	v_cvt_pk_bf16_f32 v181, v182, v183
	v_cvt_pk_bf16_f32 v182, v188, v189
	v_cvt_pk_bf16_f32 v183, v186, v187
	global_store_dwordx4 v[184:185], v[180:183], off nt
	v_pk_mul_f32 v[186:187], v[82:83], v[130:131]
	v_pk_mul_f32 v[188:189], v[80:81], v[128:129]
	v_pk_mul_f32 v[180:181], v[84:85], v[132:133]
	v_pk_mul_f32 v[182:183], v[86:87], v[134:135]
	v_cvt_pk_bf16_f32 v180, v180, v181
	s_nop 0
	v_cvt_pk_bf16_f32 v181, v182, v183
	v_cvt_pk_bf16_f32 v182, v188, v189
	v_cvt_pk_bf16_f32 v183, v186, v187
	global_store_dwordx4 v[184:185], v[180:183], off offset:256 nt
	v_pk_mul_f32 v[184:185], v[74:75], v[138:139]
	v_pk_mul_f32 v[186:187], v[72:73], v[136:137]
	v_lshlrev_b64 v[180:181], 13, v[160:161]
	v_lshl_add_u64 v[172:173], v[172:173], 0, v[180:181]
	v_pk_mul_f32 v[182:183], v[78:79], v[142:143]
	v_pk_mul_f32 v[180:181], v[76:77], v[140:141]
	s_nop 0
	v_cvt_pk_bf16_f32 v180, v180, v181
	v_cvt_pk_bf16_f32 v181, v182, v183
	v_cvt_pk_bf16_f32 v182, v186, v187
	v_cvt_pk_bf16_f32 v183, v184, v185
	global_store_dwordx4 v[172:173], v[180:183], off nt
	v_pk_mul_f32 v[184:185], v[66:67], v[130:131]
	v_pk_mul_f32 v[186:187], v[64:65], v[128:129]
	v_pk_mul_f32 v[182:183], v[70:71], v[134:135]
	v_pk_mul_f32 v[180:181], v[68:69], v[132:133]
	s_nop 0
	v_cvt_pk_bf16_f32 v180, v180, v181
	v_cvt_pk_bf16_f32 v181, v182, v183
	v_cvt_pk_bf16_f32 v182, v186, v187
	v_cvt_pk_bf16_f32 v183, v184, v185
	global_store_dwordx4 v[172:173], v[180:183], off offset:256 nt
	v_pk_mul_f32 v[184:185], v[58:59], v[138:139]
	v_pk_mul_f32 v[186:187], v[56:57], v[136:137]
	v_pk_mul_f32 v[182:183], v[62:63], v[142:143]
	v_pk_mul_f32 v[180:181], v[60:61], v[140:141]
	v_lshl_add_u64 v[172:173], v[170:171], 0, s[16:17]
	v_cvt_pk_bf16_f32 v180, v180, v181
	v_cvt_pk_bf16_f32 v181, v182, v183
	v_cvt_pk_bf16_f32 v182, v186, v187
	v_cvt_pk_bf16_f32 v183, v184, v185
	v_add_co_u32_e32 v184, vcc, s65, v170
	v_pk_mul_f32 v[186:187], v[48:49], v[128:129]
	s_nop 0
	v_addc_co_u32_e32 v185, vcc, 0, v171, vcc
	global_store_dwordx4 v[184:185], v[180:183], off nt
	v_pk_mul_f32 v[184:185], v[50:51], v[130:131]
	s_nop 0
	v_pk_mul_f32 v[182:183], v[54:55], v[134:135]
	v_pk_mul_f32 v[180:181], v[52:53], v[132:133]
	s_nop 0
	v_cvt_pk_bf16_f32 v180, v180, v181
	v_cvt_pk_bf16_f32 v181, v182, v183
	v_cvt_pk_bf16_f32 v182, v186, v187
	v_cvt_pk_bf16_f32 v183, v184, v185
	global_store_dwordx4 v[172:173], v[180:183], off offset:256 nt
	v_pk_mul_f32 v[184:185], v[42:43], v[138:139]
	v_pk_mul_f32 v[186:187], v[40:41], v[136:137]
	v_pk_mul_f32 v[182:183], v[46:47], v[142:143]
	v_pk_mul_f32 v[180:181], v[44:45], v[140:141]
	v_lshl_add_u64 v[172:173], v[170:171], 0, s[18:19]
	v_cvt_pk_bf16_f32 v180, v180, v181
	v_cvt_pk_bf16_f32 v181, v182, v183
	v_cvt_pk_bf16_f32 v182, v186, v187
	v_cvt_pk_bf16_f32 v183, v184, v185
	v_add_co_u32_e32 v184, vcc, s66, v170
	v_pk_mul_f32 v[186:187], v[32:33], v[128:129]
	s_nop 0
	v_addc_co_u32_e32 v185, vcc, 0, v171, vcc
	global_store_dwordx4 v[184:185], v[180:183], off nt
	v_pk_mul_f32 v[184:185], v[34:35], v[130:131]
	s_nop 0
	v_pk_mul_f32 v[182:183], v[38:39], v[134:135]
	v_pk_mul_f32 v[180:181], v[36:37], v[132:133]
	s_nop 0
	v_cvt_pk_bf16_f32 v180, v180, v181
	v_cvt_pk_bf16_f32 v181, v182, v183
	v_cvt_pk_bf16_f32 v182, v186, v187
	v_cvt_pk_bf16_f32 v183, v184, v185
	global_store_dwordx4 v[172:173], v[180:183], off offset:256 nt
	v_pk_mul_f32 v[184:185], v[26:27], v[138:139]
	v_pk_mul_f32 v[186:187], v[24:25], v[136:137]
	v_pk_mul_f32 v[182:183], v[30:31], v[142:143]
	v_pk_mul_f32 v[180:181], v[28:29], v[140:141]
	v_lshl_add_u64 v[172:173], v[170:171], 0, s[20:21]
	v_cvt_pk_bf16_f32 v180, v180, v181
	v_cvt_pk_bf16_f32 v181, v182, v183
	v_cvt_pk_bf16_f32 v182, v186, v187
	v_cvt_pk_bf16_f32 v183, v184, v185
	v_add_co_u32_e32 v184, vcc, s67, v170
	v_pk_mul_f32 v[186:187], v[16:17], v[128:129]
	s_nop 0
	v_addc_co_u32_e32 v185, vcc, 0, v171, vcc
	global_store_dwordx4 v[184:185], v[180:183], off nt
	v_pk_mul_f32 v[184:185], v[18:19], v[130:131]
	v_pk_mul_f32 v[140:141], v[12:13], v[140:141]
	v_pk_mul_f32 v[182:183], v[22:23], v[134:135]
	v_pk_mul_f32 v[180:181], v[20:21], v[132:133]
	v_pk_mul_f32 v[142:143], v[14:15], v[142:143]
	v_cvt_pk_bf16_f32 v180, v180, v181
	v_cvt_pk_bf16_f32 v181, v182, v183
	v_cvt_pk_bf16_f32 v182, v186, v187
	v_cvt_pk_bf16_f32 v183, v184, v185
	global_store_dwordx4 v[172:173], v[180:183], off offset:256 nt
	v_lshl_add_u64 v[172:173], v[170:171], 0, s[22:23]
	v_pk_mul_f32 v[134:135], v[6:7], v[134:135]
	v_pk_mul_f32 v[180:181], v[10:11], v[138:139]
	v_pk_mul_f32 v[138:139], v[8:9], v[136:137]
	v_cvt_pk_bf16_f32 v136, v140, v141
	v_add_co_u32_e32 v140, vcc, s68, v170
	v_cvt_pk_bf16_f32 v137, v142, v143
	v_cvt_pk_bf16_f32 v138, v138, v139
	v_cvt_pk_bf16_f32 v139, v180, v181
	v_pk_mul_f32 v[132:133], v[4:5], v[132:133]
	s_nop 0
	v_addc_co_u32_e32 v141, vcc, 0, v171, vcc
	global_store_dwordx4 v[140:141], v[136:139], off nt
	s_nop 1
	v_pk_mul_f32 v[136:137], v[2:3], v[130:131]
	v_pk_mul_f32 v[130:131], v[0:1], v[128:129]
	v_cvt_pk_bf16_f32 v128, v132, v133
	v_cvt_pk_bf16_f32 v129, v134, v135
	s_nop 0
	v_cvt_pk_bf16_f32 v130, v130, v131
	v_cvt_pk_bf16_f32 v131, v136, v137
	global_store_dwordx4 v[172:173], v[128:131], off offset:256 nt
	s_cbranch_execz .LBB7_334

.LBB7_334:
	s_nop 0
	v_lshl_add_u64 v[128:129], v[168:169], 2, s[8:9]
	global_load_dword v132, v[128:129], off
	v_readlane_b32 s40, v251, 10
	s_add_u32 s38, s40, s38
	v_readlane_b32 s40, v251, 11
	s_addc_u32 s39, s40, s39
	v_lshlrev_b64 v[130:131], 11, v[168:169]
	v_lshl_add_u64 v[136:137], v[166:167], 1, s[38:39]
	v_lshl_add_u64 v[130:131], v[136:137], 0, v[130:131]
	v_lshl_add_u64 v[134:135], v[164:165], 2, s[8:9]
	s_mov_b64 s[38:39], 0x40000
	s_waitcnt vmcnt(0)
	v_pk_mul_f32 v[126:127], v[126:127], v[132:133] op_sel_hi:[1,0]
	v_pk_mul_f32 v[124:125], v[124:125], v[132:133] op_sel_hi:[1,0]
	v_pk_mul_f32 v[122:123], v[122:123], v[132:133] op_sel_hi:[1,0]
	v_pk_mul_f32 v[120:121], v[120:121], v[132:133] op_sel_hi:[1,0]
	v_pk_mul_f32 v[118:119], v[118:119], v[132:133] op_sel_hi:[1,0]
	v_pk_mul_f32 v[116:117], v[116:117], v[132:133] op_sel_hi:[1,0]
	v_pk_mul_f32 v[138:139], v[114:115], v[132:133] op_sel_hi:[1,0]
	v_pk_mul_f32 v[132:133], v[112:113], v[132:133] op_sel_hi:[1,0]
	v_cvt_pk_bf16_f32 v112, v124, v125
	v_cvt_pk_bf16_f32 v113, v126, v127
	v_cvt_pk_bf16_f32 v114, v120, v121
	v_cvt_pk_bf16_f32 v115, v122, v123
	global_store_dwordx4 v[130:131], v[112:115], off nt
	s_nop 1
	v_cvt_pk_bf16_f32 v112, v116, v117
	v_cvt_pk_bf16_f32 v113, v118, v119
	v_cvt_pk_bf16_f32 v114, v132, v133
	v_cvt_pk_bf16_f32 v115, v138, v139
	global_store_dwordx4 v[130:131], v[112:115], off offset:256 nt
	global_load_dword v112, v[134:135], off
	v_lshl_add_u64 v[116:117], v[162:163], 2, s[8:9]
	v_lshlrev_b64 v[114:115], 11, v[164:165]
	v_lshl_add_u64 v[114:115], v[136:137], 0, v[114:115]
	s_waitcnt vmcnt(0)
	v_pk_mul_f32 v[110:111], v[110:111], v[112:113] op_sel_hi:[1,0]
	v_pk_mul_f32 v[108:109], v[108:109], v[112:113] op_sel_hi:[1,0]
	v_pk_mul_f32 v[106:107], v[106:107], v[112:113] op_sel_hi:[1,0]
	v_pk_mul_f32 v[104:105], v[104:105], v[112:113] op_sel_hi:[1,0]
	v_pk_mul_f32 v[102:103], v[102:103], v[112:113] op_sel_hi:[1,0]
	v_pk_mul_f32 v[100:101], v[100:101], v[112:113] op_sel_hi:[1,0]
	v_pk_mul_f32 v[118:119], v[98:99], v[112:113] op_sel_hi:[1,0]
	v_pk_mul_f32 v[112:113], v[96:97], v[112:113] op_sel_hi:[1,0]
	v_cvt_pk_bf16_f32 v96, v108, v109
	v_cvt_pk_bf16_f32 v97, v110, v111
	v_cvt_pk_bf16_f32 v98, v104, v105
	v_cvt_pk_bf16_f32 v99, v106, v107
	global_store_dwordx4 v[114:115], v[96:99], off nt
	s_nop 1
	v_cvt_pk_bf16_f32 v96, v100, v101
	v_cvt_pk_bf16_f32 v97, v102, v103
	v_cvt_pk_bf16_f32 v98, v112, v113
	v_cvt_pk_bf16_f32 v99, v118, v119
	global_store_dwordx4 v[114:115], v[96:99], off offset:256 nt
	global_load_dword v96, v[116:117], off
	v_lshl_add_u64 v[100:101], v[160:161], 2, s[8:9]
	v_lshlrev_b64 v[98:99], 11, v[162:163]
	v_lshl_add_u64 v[98:99], v[136:137], 0, v[98:99]
	s_waitcnt vmcnt(0)
	v_pk_mul_f32 v[94:95], v[94:95], v[96:97] op_sel_hi:[1,0]
	v_pk_mul_f32 v[92:93], v[92:93], v[96:97] op_sel_hi:[1,0]
	v_pk_mul_f32 v[90:91], v[90:91], v[96:97] op_sel_hi:[1,0]
	v_pk_mul_f32 v[88:89], v[88:89], v[96:97] op_sel_hi:[1,0]
	v_pk_mul_f32 v[86:87], v[86:87], v[96:97] op_sel_hi:[1,0]
	v_pk_mul_f32 v[84:85], v[84:85], v[96:97] op_sel_hi:[1,0]
	v_pk_mul_f32 v[102:103], v[82:83], v[96:97] op_sel_hi:[1,0]
	v_pk_mul_f32 v[96:97], v[80:81], v[96:97] op_sel_hi:[1,0]
	v_cvt_pk_bf16_f32 v80, v92, v93
	v_cvt_pk_bf16_f32 v81, v94, v95
	v_cvt_pk_bf16_f32 v82, v88, v89
	v_cvt_pk_bf16_f32 v83, v90, v91
	global_store_dwordx4 v[98:99], v[80:83], off nt
	s_nop 1
	v_cvt_pk_bf16_f32 v80, v84, v85
	v_cvt_pk_bf16_f32 v81, v86, v87
	v_cvt_pk_bf16_f32 v82, v96, v97
	v_cvt_pk_bf16_f32 v83, v102, v103
	global_store_dwordx4 v[98:99], v[80:83], off offset:256 nt
	global_load_dword v80, v[100:101], off
	s_waitcnt vmcnt(0)
	v_pk_mul_f32 v[78:79], v[78:79], v[80:81] op_sel_hi:[1,0]
	v_lshlrev_b64 v[82:83], 11, v[160:161]
	v_lshl_add_u64 v[82:83], v[136:137], 0, v[82:83]
	v_pk_mul_f32 v[76:77], v[76:77], v[80:81] op_sel_hi:[1,0]
	v_pk_mul_f32 v[74:75], v[74:75], v[80:81] op_sel_hi:[1,0]
	v_pk_mul_f32 v[72:73], v[72:73], v[80:81] op_sel_hi:[1,0]
	v_pk_mul_f32 v[70:71], v[70:71], v[80:81] op_sel_hi:[1,0]
	v_pk_mul_f32 v[68:69], v[68:69], v[80:81] op_sel_hi:[1,0]
	v_pk_mul_f32 v[84:85], v[66:67], v[80:81] op_sel_hi:[1,0]
	v_pk_mul_f32 v[80:81], v[64:65], v[80:81] op_sel_hi:[1,0]
	v_cvt_pk_bf16_f32 v64, v76, v77
	v_cvt_pk_bf16_f32 v65, v78, v79
	v_cvt_pk_bf16_f32 v66, v72, v73
	v_cvt_pk_bf16_f32 v67, v74, v75
	global_store_dwordx4 v[82:83], v[64:67], off nt
	s_nop 1
	v_cvt_pk_bf16_f32 v64, v68, v69
	v_cvt_pk_bf16_f32 v65, v70, v71
	v_cvt_pk_bf16_f32 v66, v80, v81
	v_cvt_pk_bf16_f32 v67, v84, v85
	global_store_dwordx4 v[82:83], v[64:67], off offset:256 nt
	global_load_dword v64, v[128:129], off offset:512
	v_add_co_u32_e32 v68, vcc, s69, v130
	v_lshl_add_u64 v[66:67], v[130:131], 0, s[38:39]
	s_nop 0
	v_addc_co_u32_e32 v69, vcc, 0, v131, vcc
	s_waitcnt vmcnt(0)
	v_pk_mul_f32 v[62:63], v[62:63], v[64:65] op_sel_hi:[1,0]
	v_pk_mul_f32 v[60:61], v[60:61], v[64:65] op_sel_hi:[1,0]
	v_pk_mul_f32 v[58:59], v[58:59], v[64:65] op_sel_hi:[1,0]
	v_pk_mul_f32 v[56:57], v[56:57], v[64:65] op_sel_hi:[1,0]
	v_pk_mul_f32 v[54:55], v[54:55], v[64:65] op_sel_hi:[1,0]
	v_pk_mul_f32 v[52:53], v[52:53], v[64:65] op_sel_hi:[1,0]
	v_pk_mul_f32 v[70:71], v[50:51], v[64:65] op_sel_hi:[1,0]
	v_pk_mul_f32 v[64:65], v[48:49], v[64:65] op_sel_hi:[1,0]
	v_cvt_pk_bf16_f32 v48, v60, v61
	v_cvt_pk_bf16_f32 v49, v62, v63
	v_cvt_pk_bf16_f32 v50, v56, v57
	v_cvt_pk_bf16_f32 v51, v58, v59
	global_store_dwordx4 v[68:69], v[48:51], off nt
	s_nop 1
	v_cvt_pk_bf16_f32 v48, v52, v53
	v_cvt_pk_bf16_f32 v49, v54, v55
	v_cvt_pk_bf16_f32 v50, v64, v65
	v_cvt_pk_bf16_f32 v51, v70, v71
	global_store_dwordx4 v[66:67], v[48:51], off offset:256 nt
	global_load_dword v48, v[128:129], off offset:576
	v_add_co_u32_e32 v52, vcc, s70, v130
	v_lshl_add_u64 v[50:51], v[130:131], 0, s[24:25]
	s_nop 0
	v_addc_co_u32_e32 v53, vcc, 0, v131, vcc
	s_waitcnt vmcnt(0)
	v_pk_mul_f32 v[46:47], v[46:47], v[48:49] op_sel_hi:[1,0]
	v_pk_mul_f32 v[44:45], v[44:45], v[48:49] op_sel_hi:[1,0]
	v_pk_mul_f32 v[42:43], v[42:43], v[48:49] op_sel_hi:[1,0]
	v_pk_mul_f32 v[40:41], v[40:41], v[48:49] op_sel_hi:[1,0]
	v_pk_mul_f32 v[38:39], v[38:39], v[48:49] op_sel_hi:[1,0]
	v_pk_mul_f32 v[36:37], v[36:37], v[48:49] op_sel_hi:[1,0]
	v_pk_mul_f32 v[54:55], v[34:35], v[48:49] op_sel_hi:[1,0]
	v_pk_mul_f32 v[48:49], v[32:33], v[48:49] op_sel_hi:[1,0]
	v_cvt_pk_bf16_f32 v32, v44, v45
	v_cvt_pk_bf16_f32 v33, v46, v47
	v_cvt_pk_bf16_f32 v34, v40, v41
	v_cvt_pk_bf16_f32 v35, v42, v43
	global_store_dwordx4 v[52:53], v[32:35], off nt
	s_nop 1
	v_cvt_pk_bf16_f32 v32, v36, v37
	v_cvt_pk_bf16_f32 v33, v38, v39
	v_cvt_pk_bf16_f32 v34, v48, v49
	v_cvt_pk_bf16_f32 v35, v54, v55
	global_store_dwordx4 v[50:51], v[32:35], off offset:256 nt
	global_load_dword v32, v[128:129], off offset:640
	v_add_co_u32_e32 v36, vcc, s71, v130
	v_lshl_add_u64 v[34:35], v[130:131], 0, s[44:45]
	s_nop 0
	v_addc_co_u32_e32 v37, vcc, 0, v131, vcc
	s_waitcnt vmcnt(0)
	v_pk_mul_f32 v[30:31], v[30:31], v[32:33] op_sel_hi:[1,0]
	v_pk_mul_f32 v[28:29], v[28:29], v[32:33] op_sel_hi:[1,0]
	v_pk_mul_f32 v[26:27], v[26:27], v[32:33] op_sel_hi:[1,0]
	v_pk_mul_f32 v[24:25], v[24:25], v[32:33] op_sel_hi:[1,0]
	v_pk_mul_f32 v[22:23], v[22:23], v[32:33] op_sel_hi:[1,0]
	v_pk_mul_f32 v[20:21], v[20:21], v[32:33] op_sel_hi:[1,0]
	v_pk_mul_f32 v[38:39], v[18:19], v[32:33] op_sel_hi:[1,0]
	v_pk_mul_f32 v[32:33], v[16:17], v[32:33] op_sel_hi:[1,0]
	v_cvt_pk_bf16_f32 v16, v28, v29
	v_cvt_pk_bf16_f32 v17, v30, v31
	v_cvt_pk_bf16_f32 v18, v24, v25
	v_cvt_pk_bf16_f32 v19, v26, v27
	global_store_dwordx4 v[36:37], v[16:19], off nt
	s_nop 1
	v_cvt_pk_bf16_f32 v16, v20, v21
	v_cvt_pk_bf16_f32 v17, v22, v23
	v_cvt_pk_bf16_f32 v18, v32, v33
	v_cvt_pk_bf16_f32 v19, v38, v39
	global_store_dwordx4 v[34:35], v[16:19], off offset:256 nt
	global_load_dword v16, v[128:129], off offset:704
	v_add_co_u32_e32 v20, vcc, s72, v130
	v_lshl_add_u64 v[18:19], v[130:131], 0, s[28:29]
	s_nop 0
	v_addc_co_u32_e32 v21, vcc, 0, v131, vcc
	s_waitcnt vmcnt(0)
	v_pk_mul_f32 v[14:15], v[14:15], v[16:17] op_sel_hi:[1,0]
	v_pk_mul_f32 v[12:13], v[12:13], v[16:17] op_sel_hi:[1,0]
	v_pk_mul_f32 v[10:11], v[10:11], v[16:17] op_sel_hi:[1,0]
	v_pk_mul_f32 v[8:9], v[8:9], v[16:17] op_sel_hi:[1,0]
	v_pk_mul_f32 v[6:7], v[6:7], v[16:17] op_sel_hi:[1,0]
	v_pk_mul_f32 v[4:5], v[4:5], v[16:17] op_sel_hi:[1,0]
	v_pk_mul_f32 v[22:23], v[2:3], v[16:17] op_sel_hi:[1,0]
	v_pk_mul_f32 v[16:17], v[0:1], v[16:17] op_sel_hi:[1,0]
	v_cvt_pk_bf16_f32 v0, v12, v13
	v_cvt_pk_bf16_f32 v1, v14, v15
	v_cvt_pk_bf16_f32 v2, v8, v9
	v_cvt_pk_bf16_f32 v3, v10, v11
	global_store_dwordx4 v[20:21], v[0:3], off nt
	s_nop 1
	v_cvt_pk_bf16_f32 v0, v4, v5
	v_cvt_pk_bf16_f32 v1, v6, v7
	v_cvt_pk_bf16_f32 v2, v16, v17
	v_cvt_pk_bf16_f32 v3, v22, v23
	global_store_dwordx4 v[18:19], v[0:3], off offset:256 nt
	s_andn2_b64 vcc, exec, s[6:7]
	s_mov_b64 s[6:7], -1
	s_cbranch_vccnz .LBB7_319

.LBB7_437:
	s_waitcnt lgkmcnt(0)
	v_lshl_or_b32 v2, s10, 8, v206
	v_lshl_add_u32 v184, s89, 8, v204
	v_ashrrev_i32_e32 v3, 31, v2
	v_lshlrev_b64 v[132:133], 1, v[2:3]
	v_ashrrev_i32_e32 v185, 31, v184
	v_lshl_add_u64 v[190:191], s[68:69], 0, v[132:133]
	v_lshlrev_b64 v[134:135], 11, v[184:185]
	v_lshl_add_u64 v[136:137], v[190:191], 0, v[134:135]
	global_load_dwordx4 v[196:199], v[136:137], off
	global_load_dwordx4 v[208:211], v[136:137], off offset:256
	v_or_b32_e32 v192, 16, v184
	v_or_b32_e32 v186, 32, v184
	v_or_b32_e32 v156, 48, v184
	v_ashrrev_i32_e32 v193, 31, v192
	v_ashrrev_i32_e32 v187, 31, v186
	v_ashrrev_i32_e32 v157, 31, v156
	v_lshlrev_b64 v[194:195], 11, v[192:193]
	v_lshlrev_b64 v[188:189], 11, v[186:187]
	v_lshlrev_b64 v[158:159], 11, v[156:157]
	v_lshl_add_u64 v[134:135], s[68:69], 0, v[134:135]
	v_lshl_add_u64 v[136:137], v[190:191], 0, v[194:195]
	v_lshl_add_u64 v[138:139], v[190:191], 0, v[188:189]
	v_lshl_add_u64 v[170:171], v[190:191], 0, v[158:159]
	v_lshl_add_u64 v[172:173], v[134:135], 0, v[132:133]
	global_load_dwordx4 v[152:155], v[136:137], off
	global_load_dwordx4 v[148:151], v[136:137], off offset:256
	global_load_dwordx4 v[144:147], v[138:139], off
	global_load_dwordx4 v[140:143], v[138:139], off offset:256
	s_nop 0
	global_load_dwordx4 v[136:139], v[170:171], off
	global_load_dwordx4 v[132:135], v[170:171], off offset:256
	v_add_u32_e32 v248, 0x80, v184
	v_ashrrev_i32_e32 v249, 31, v248
	v_lshlrev_b64 v[248:249], 11, v[248:249]
	v_lshl_add_u64 v[248:249], v[190:191], 0, v[248:249]
	global_load_dwordx4 v[232:235], v[248:249], off
	global_load_dwordx4 v[236:239], v[248:249], off offset:256
	s_mov_b64 s[72:73], 0x8000
	v_lshl_add_u64 v[248:249], v[248:249], 0, s[72:73]
	global_load_dwordx4 v[240:243], v[248:249], off
	global_load_dwordx4 v[244:247], v[248:249], off offset:256
	s_lshl_b32 s16, s10, 2
	s_ashr_i32 s17, s16, 31
	s_waitcnt vmcnt(0)
	v_lshlrev_b32_e32 v212, 16, v198
	v_and_b32_e32 v213, 0xffff0000, v198
	v_lshlrev_b32_e32 v198, 16, v199
	v_and_b32_e32 v199, 0xffff0000, v199
	v_lshlrev_b32_e32 v170, 16, v196
	v_and_b32_e32 v171, 0xffff0000, v196
	v_lshlrev_b32_e32 v196, 16, v197
	v_and_b32_e32 v197, 0xffff0000, v197
	v_pk_fma_f32 v[220:221], v[126:127], 0.5, v[198:199] op_sel_hi:[1,0,1]
	v_pk_fma_f32 v[198:199], v[124:125], 0.5, v[212:213] op_sel_hi:[1,0,1]
	v_lshlrev_b32_e32 v214, 16, v208
	v_and_b32_e32 v215, 0xffff0000, v208
	v_lshlrev_b32_e32 v208, 16, v209
	v_and_b32_e32 v209, 0xffff0000, v209
	v_lshlrev_b32_e32 v216, 16, v210
	v_and_b32_e32 v217, 0xffff0000, v210
	v_lshlrev_b32_e32 v210, 16, v211
	v_and_b32_e32 v211, 0xffff0000, v211
	v_pk_fma_f32 v[218:219], v[130:131], 0.5, v[196:197] op_sel_hi:[1,0,1]
	v_pk_fma_f32 v[170:171], v[128:129], 0.5, v[170:171] op_sel_hi:[1,0,1]
	v_pk_fma_f32 v[208:209], v[98:99], 0.5, v[208:209] op_sel_hi:[1,0,1]
	v_cvt_pk_bf16_f32 v196, v170, v171
	v_cvt_pk_bf16_f32 v197, v218, v219
	v_cvt_pk_bf16_f32 v198, v198, v199
	v_cvt_pk_bf16_f32 v199, v220, v221
	v_pk_fma_f32 v[212:213], v[96:97], 0.5, v[214:215] op_sel_hi:[1,0,1]
	v_pk_fma_f32 v[214:215], v[94:95], 0.5, v[210:211] op_sel_hi:[1,0,1]
	global_store_dwordx4 v[172:173], v[196:199], off nt
	v_lshlrev_b32_e32 v0, 16, v196
	v_and_b32_e32 v170, 0xffff0000, v196
	v_lshlrev_b32_e32 v171, 16, v197
	v_and_b32_e32 v196, 0xffff0000, v197
	v_lshlrev_b32_e32 v197, 16, v198
	v_and_b32_e32 v198, 0xffff0000, v198
	v_lshlrev_b32_e32 v218, 16, v199
	v_and_b32_e32 v199, 0xffff0000, v199
	v_pk_fma_f32 v[216:217], v[92:93], 0.5, v[216:217] op_sel_hi:[1,0,1]
	v_cvt_pk_bf16_f32 v210, v212, v213
	v_cvt_pk_bf16_f32 v211, v208, v209
	v_mul_f32_e32 v170, v170, v170
	v_cvt_pk_bf16_f32 v212, v216, v217
	v_cvt_pk_bf16_f32 v213, v214, v215
	v_mul_f32_e32 v196, v196, v196
	v_mul_f32_e32 v198, v198, v198
	v_mul_f32_e32 v199, v199, v199
	v_and_b32_e32 v209, 0xffff0000, v210
	v_and_b32_e32 v215, 0xffff0000, v211
	v_lshlrev_b32_e32 v208, 16, v210
	v_lshlrev_b32_e32 v214, 16, v211
	v_fmac_f32_e32 v170, v0, v0
	v_fmac_f32_e32 v196, v171, v171
	v_fmac_f32_e32 v198, v197, v197
	v_fmac_f32_e32 v199, v218, v218
	v_mul_f32_e32 v0, v209, v209
	v_mul_f32_e32 v171, v215, v215
	v_and_b32_e32 v217, 0xffff0000, v212
	v_and_b32_e32 v220, 0xffff0000, v213
	v_add_f32_e32 v170, v170, v196
	v_add_f32_e32 v196, v198, v199
	v_fmac_f32_e32 v0, v208, v208
	v_fmac_f32_e32 v171, v214, v214
	v_lshlrev_b32_e32 v216, 16, v212
	v_lshlrev_b32_e32 v219, 16, v213
	v_add_f32_e32 v170, v170, v196
	v_add_f32_e32 v0, v0, v171
	v_mul_f32_e32 v171, v217, v217
	v_mul_f32_e32 v196, v220, v220
	v_fmac_f32_e32 v171, v216, v216
	v_fmac_f32_e32 v196, v219, v219
	v_add_f32_e32 v171, v171, v196
	v_add_f32_e32 v0, v0, v171
	v_and_b32_e32 v171, 64, v163
	v_add_f32_e32 v170, v170, v0
	v_xor_b32_e32 v0, 16, v163
	v_add_u32_e32 v171, 64, v171
	v_cmp_lt_i32_e32 vcc, v0, v171
	global_store_dwordx4 v[172:173], v[210:213], off offset:256 nt
	s_nop 0
	v_cndmask_b32_e32 v0, v163, v0, vcc
	v_lshlrev_b32_e32 v0, 2, v0
	v_mov_b32_e32 v196, v170
	s_nop 1
	v_permlane16_swap_b32_e32 v170, v196
	s_waitcnt lgkmcnt(0)
	v_add_f32_e32 v196, v170, v196
	v_xor_b32_e32 v170, 32, v163
	v_cmp_lt_i32_e32 vcc, v170, v171
	s_nop 1
	v_cndmask_b32_e32 v170, v163, v170, vcc
	v_lshlrev_b32_e32 v208, 2, v170
	v_mov_b32_e32 v197, v196
	s_nop 1
	v_permlane32_swap_b32_e32 v196, v197
	s_and_saveexec_b64 s[72:73], s[40:41]
	s_cbranch_execz .LBB7_439
	v_lshlrev_b64 v[170:171], 6, v[184:185]
	v_lshl_add_u64 v[170:171], s[66:67], 0, v[170:171]
	v_lshl_add_u64 v[170:171], s[16:17], 2, v[170:171]
	s_lshl_b32 s20, s96, 2
	v_lshl_add_u64 v[170:171], v[170:171], 0, s[20:21]
	s_waitcnt lgkmcnt(0)
	v_add_f32_e32 v172, v196, v197
	global_store_dword v[170:171], v172, off
.LBB7_439:
	s_or_b64 exec, exec, s[72:73]
	v_lshlrev_b32_e32 v170, 16, v152
	v_and_b32_e32 v171, 0xffff0000, v152
	v_lshlrev_b32_e32 v152, 16, v153
	v_and_b32_e32 v153, 0xffff0000, v153
	v_lshlrev_b32_e32 v172, 16, v154
	v_and_b32_e32 v173, 0xffff0000, v154
	v_lshlrev_b32_e32 v154, 16, v155
	v_and_b32_e32 v155, 0xffff0000, v155
	s_waitcnt lgkmcnt(0)
	v_pk_fma_f32 v[196:197], v[122:123], 0.5, v[152:153] op_sel_hi:[1,0,1]
	v_pk_fma_f32 v[152:153], v[120:121], 0.5, v[170:171] op_sel_hi:[1,0,1]
	v_pk_fma_f32 v[170:171], v[118:119], 0.5, v[154:155] op_sel_hi:[1,0,1]
	v_pk_fma_f32 v[154:155], v[116:117], 0.5, v[172:173] op_sel_hi:[1,0,1]
	v_cvt_pk_bf16_f32 v152, v152, v153
	v_cvt_pk_bf16_f32 v153, v196, v197
	s_nop 0
	v_cvt_pk_bf16_f32 v154, v154, v155
	v_cvt_pk_bf16_f32 v155, v170, v171
	v_lshl_add_u64 v[170:171], s[68:69], 0, v[194:195]
	v_lshl_add_u64 v[170:171], v[2:3], 1, v[170:171]
	global_store_dwordx4 v[170:171], v[152:155], off nt
	v_lshlrev_b32_e32 v172, 16, v152
	v_lshlrev_b32_e32 v173, 16, v153
	v_and_b32_e32 v152, 0xffff0000, v152
	v_and_b32_e32 v153, 0xffff0000, v153
	v_mul_f32_e32 v152, v152, v152
	v_mul_f32_e32 v153, v153, v153
	v_lshlrev_b32_e32 v185, 16, v154
	v_and_b32_e32 v154, 0xffff0000, v154
	v_lshlrev_b32_e32 v194, 16, v155
	v_and_b32_e32 v155, 0xffff0000, v155
	v_fmac_f32_e32 v152, v172, v172
	v_fmac_f32_e32 v153, v173, v173
	v_add_f32_e32 v152, v152, v153
	v_mul_f32_e32 v153, v154, v154
	v_mul_f32_e32 v154, v155, v155
	v_fmac_f32_e32 v153, v185, v185
	v_fmac_f32_e32 v154, v194, v194
	v_add_f32_e32 v153, v153, v154
	v_add_f32_e32 v185, v152, v153
	v_lshlrev_b32_e32 v152, 16, v148
	v_and_b32_e32 v153, 0xffff0000, v148
	v_lshlrev_b32_e32 v148, 16, v149
	v_and_b32_e32 v149, 0xffff0000, v149
	v_lshlrev_b32_e32 v154, 16, v150
	v_and_b32_e32 v155, 0xffff0000, v150
	v_lshlrev_b32_e32 v150, 16, v151
	v_and_b32_e32 v151, 0xffff0000, v151
	v_pk_fma_f32 v[148:149], v[90:91], 0.5, v[148:149] op_sel_hi:[1,0,1]
	v_pk_fma_f32 v[152:153], v[88:89], 0.5, v[152:153] op_sel_hi:[1,0,1]
	v_pk_fma_f32 v[172:173], v[86:87], 0.5, v[150:151] op_sel_hi:[1,0,1]
	v_pk_fma_f32 v[154:155], v[84:85], 0.5, v[154:155] op_sel_hi:[1,0,1]
	v_cvt_pk_bf16_f32 v150, v152, v153
	v_cvt_pk_bf16_f32 v151, v148, v149
	s_nop 0
	v_and_b32_e32 v149, 0xffff0000, v150
	v_cvt_pk_bf16_f32 v152, v154, v155
	v_lshlrev_b32_e32 v148, 16, v150
	v_and_b32_e32 v155, 0xffff0000, v151
	v_mul_f32_e32 v149, v149, v149
	v_lshlrev_b32_e32 v154, 16, v151
	v_fmac_f32_e32 v149, v148, v148
	v_mul_f32_e32 v148, v155, v155
	v_cvt_pk_bf16_f32 v153, v172, v173
	v_and_b32_e32 v173, 0xffff0000, v152
	v_and_b32_e32 v195, 0xffff0000, v153
	v_fmac_f32_e32 v148, v154, v154
	v_lshlrev_b32_e32 v172, 16, v152
	v_lshlrev_b32_e32 v194, 16, v153
	v_add_f32_e32 v148, v149, v148
	v_mul_f32_e32 v149, v173, v173
	v_mul_f32_e32 v154, v195, v195
	v_fmac_f32_e32 v149, v172, v172
	v_fmac_f32_e32 v154, v194, v194
	v_add_f32_e32 v149, v149, v154
	v_add_f32_e32 v148, v148, v149
	v_add_f32_e32 v148, v185, v148
	v_mov_b32_e32 v149, v148
	s_nop 1
	v_permlane16_swap_b32_e32 v148, v149
	global_store_dwordx4 v[170:171], v[150:153], off offset:256 nt
	s_waitcnt lgkmcnt(0)
	v_add_f32_e32 v148, v148, v149
	v_mov_b32_e32 v149, v148
	s_nop 1
	v_permlane32_swap_b32_e32 v148, v149
	s_and_saveexec_b64 s[72:73], s[40:41]
	s_cbranch_execz .LBB7_441
	v_lshlrev_b64 v[150:151], 6, v[192:193]
	v_lshl_add_u64 v[150:151], s[66:67], 0, v[150:151]
	v_lshl_add_u64 v[150:151], s[16:17], 2, v[150:151]
	s_lshl_b32 s20, s96, 2
	v_lshl_add_u64 v[150:151], v[150:151], 0, s[20:21]
	s_waitcnt lgkmcnt(0)
	v_add_f32_e32 v148, v148, v149
	global_store_dword v[150:151], v148, off
.LBB7_441:
	s_or_b64 exec, exec, s[72:73]
	v_lshlrev_b32_e32 v148, 16, v144
	s_waitcnt lgkmcnt(0)
	v_and_b32_e32 v149, 0xffff0000, v144
	v_lshlrev_b32_e32 v144, 16, v145
	v_and_b32_e32 v145, 0xffff0000, v145
	v_lshlrev_b32_e32 v150, 16, v146
	v_and_b32_e32 v151, 0xffff0000, v146
	v_lshlrev_b32_e32 v146, 16, v147
	v_and_b32_e32 v147, 0xffff0000, v147
	v_pk_fma_f32 v[152:153], v[114:115], 0.5, v[144:145] op_sel_hi:[1,0,1]
	v_pk_fma_f32 v[144:145], v[112:113], 0.5, v[148:149] op_sel_hi:[1,0,1]
	v_pk_fma_f32 v[148:149], v[110:111], 0.5, v[146:147] op_sel_hi:[1,0,1]
	v_pk_fma_f32 v[146:147], v[108:109], 0.5, v[150:151] op_sel_hi:[1,0,1]
	v_cvt_pk_bf16_f32 v144, v144, v145
	v_cvt_pk_bf16_f32 v145, v152, v153
	s_nop 0
	v_cvt_pk_bf16_f32 v146, v146, v147
	v_cvt_pk_bf16_f32 v147, v148, v149
	v_lshl_add_u64 v[148:149], s[68:69], 0, v[188:189]
	v_lshl_add_u64 v[148:149], v[2:3], 1, v[148:149]
	global_store_dwordx4 v[148:149], v[144:147], off nt
	v_lshlrev_b32_e32 v150, 16, v144
	v_lshlrev_b32_e32 v151, 16, v145
	v_and_b32_e32 v144, 0xffff0000, v144
	v_and_b32_e32 v145, 0xffff0000, v145
	v_mul_f32_e32 v144, v144, v144
	v_mul_f32_e32 v145, v145, v145
	v_lshlrev_b32_e32 v152, 16, v146
	v_and_b32_e32 v146, 0xffff0000, v146
	v_lshlrev_b32_e32 v153, 16, v147
	v_and_b32_e32 v147, 0xffff0000, v147
	v_fmac_f32_e32 v144, v150, v150
	v_fmac_f32_e32 v145, v151, v151
	v_add_f32_e32 v144, v144, v145
	v_mul_f32_e32 v145, v146, v146
	v_mul_f32_e32 v146, v147, v147
	v_fmac_f32_e32 v145, v152, v152
	v_fmac_f32_e32 v146, v153, v153
	v_add_f32_e32 v145, v145, v146
	v_add_f32_e32 v152, v144, v145
	v_lshlrev_b32_e32 v144, 16, v140
	v_and_b32_e32 v145, 0xffff0000, v140
	v_lshlrev_b32_e32 v140, 16, v141
	v_and_b32_e32 v141, 0xffff0000, v141
	v_lshlrev_b32_e32 v146, 16, v142
	v_and_b32_e32 v147, 0xffff0000, v142
	v_lshlrev_b32_e32 v142, 16, v143
	v_and_b32_e32 v143, 0xffff0000, v143
	v_pk_fma_f32 v[140:141], v[82:83], 0.5, v[140:141] op_sel_hi:[1,0,1]
	v_pk_fma_f32 v[144:145], v[80:81], 0.5, v[144:145] op_sel_hi:[1,0,1]
	v_pk_fma_f32 v[150:151], v[78:79], 0.5, v[142:143] op_sel_hi:[1,0,1]
	v_pk_fma_f32 v[146:147], v[76:77], 0.5, v[146:147] op_sel_hi:[1,0,1]
	v_cvt_pk_bf16_f32 v142, v144, v145
	v_cvt_pk_bf16_f32 v143, v140, v141
	s_nop 0
	v_and_b32_e32 v141, 0xffff0000, v142
	v_cvt_pk_bf16_f32 v144, v146, v147
	v_lshlrev_b32_e32 v140, 16, v142
	v_and_b32_e32 v147, 0xffff0000, v143
	v_mul_f32_e32 v141, v141, v141
	v_lshlrev_b32_e32 v146, 16, v143
	v_fmac_f32_e32 v141, v140, v140
	v_mul_f32_e32 v140, v147, v147
	v_cvt_pk_bf16_f32 v145, v150, v151
	v_and_b32_e32 v151, 0xffff0000, v144
	v_and_b32_e32 v154, 0xffff0000, v145
	v_fmac_f32_e32 v140, v146, v146
	v_lshlrev_b32_e32 v150, 16, v144
	v_lshlrev_b32_e32 v153, 16, v145
	v_add_f32_e32 v140, v141, v140
	v_mul_f32_e32 v141, v151, v151
	v_mul_f32_e32 v146, v154, v154
	v_fmac_f32_e32 v141, v150, v150
	v_fmac_f32_e32 v146, v153, v153
	v_add_f32_e32 v141, v141, v146
	v_add_f32_e32 v140, v140, v141
	v_add_f32_e32 v140, v152, v140
	v_mov_b32_e32 v141, v140
	s_nop 1
	v_permlane16_swap_b32_e32 v140, v141
	global_store_dwordx4 v[148:149], v[142:145], off offset:256 nt
	s_waitcnt lgkmcnt(0)
	v_add_f32_e32 v140, v140, v141
	v_mov_b32_e32 v141, v140
	s_nop 1
	v_permlane32_swap_b32_e32 v140, v141
	s_and_saveexec_b64 s[72:73], s[40:41]
	s_cbranch_execz .LBB7_443
	v_lshlrev_b64 v[142:143], 6, v[186:187]
	v_lshl_add_u64 v[142:143], s[66:67], 0, v[142:143]
	v_lshl_add_u64 v[142:143], s[16:17], 2, v[142:143]
	s_lshl_b32 s20, s96, 2
	v_lshl_add_u64 v[142:143], v[142:143], 0, s[20:21]
	s_waitcnt lgkmcnt(0)
	v_add_f32_e32 v140, v140, v141
	global_store_dword v[142:143], v140, off
.LBB7_443:
	s_or_b64 exec, exec, s[72:73]
	v_lshlrev_b32_e32 v140, 16, v136
	s_waitcnt lgkmcnt(0)
	v_and_b32_e32 v141, 0xffff0000, v136
	v_lshlrev_b32_e32 v136, 16, v137
	v_and_b32_e32 v137, 0xffff0000, v137
	v_lshlrev_b32_e32 v142, 16, v138
	v_and_b32_e32 v143, 0xffff0000, v138
	v_lshlrev_b32_e32 v138, 16, v139
	v_and_b32_e32 v139, 0xffff0000, v139
	v_pk_fma_f32 v[144:145], v[106:107], 0.5, v[136:137] op_sel_hi:[1,0,1]
	v_pk_fma_f32 v[136:137], v[104:105], 0.5, v[140:141] op_sel_hi:[1,0,1]
	v_pk_fma_f32 v[140:141], v[102:103], 0.5, v[138:139] op_sel_hi:[1,0,1]
	v_pk_fma_f32 v[138:139], v[100:101], 0.5, v[142:143] op_sel_hi:[1,0,1]
	v_cvt_pk_bf16_f32 v136, v136, v137
	v_cvt_pk_bf16_f32 v137, v144, v145
	s_nop 0
	v_cvt_pk_bf16_f32 v138, v138, v139
	v_cvt_pk_bf16_f32 v139, v140, v141
	v_lshl_add_u64 v[140:141], s[68:69], 0, v[158:159]
	v_lshl_add_u64 v[140:141], v[2:3], 1, v[140:141]
	global_store_dwordx4 v[140:141], v[136:139], off nt
	v_lshlrev_b32_e32 v142, 16, v136
	v_lshlrev_b32_e32 v143, 16, v137
	v_and_b32_e32 v136, 0xffff0000, v136
	v_and_b32_e32 v137, 0xffff0000, v137
	v_mul_f32_e32 v136, v136, v136
	v_mul_f32_e32 v137, v137, v137
	v_lshlrev_b32_e32 v144, 16, v138
	v_and_b32_e32 v138, 0xffff0000, v138
	v_lshlrev_b32_e32 v145, 16, v139
	v_and_b32_e32 v139, 0xffff0000, v139
	v_fmac_f32_e32 v136, v142, v142
	v_fmac_f32_e32 v137, v143, v143
	v_add_f32_e32 v136, v136, v137
	v_mul_f32_e32 v137, v138, v138
	v_mul_f32_e32 v138, v139, v139
	v_fmac_f32_e32 v137, v144, v144
	v_fmac_f32_e32 v138, v145, v145
	v_add_f32_e32 v137, v137, v138
	v_add_f32_e32 v144, v136, v137
	v_lshlrev_b32_e32 v136, 16, v132
	v_and_b32_e32 v137, 0xffff0000, v132
	v_lshlrev_b32_e32 v132, 16, v133
	v_and_b32_e32 v133, 0xffff0000, v133
	v_lshlrev_b32_e32 v138, 16, v134
	v_and_b32_e32 v139, 0xffff0000, v134
	v_lshlrev_b32_e32 v134, 16, v135
	v_and_b32_e32 v135, 0xffff0000, v135
	v_pk_fma_f32 v[132:133], v[74:75], 0.5, v[132:133] op_sel_hi:[1,0,1]
	v_pk_fma_f32 v[136:137], v[72:73], 0.5, v[136:137] op_sel_hi:[1,0,1]
	v_pk_fma_f32 v[142:143], v[66:67], 0.5, v[134:135] op_sel_hi:[1,0,1]
	v_pk_fma_f32 v[138:139], v[64:65], 0.5, v[138:139] op_sel_hi:[1,0,1]
	v_cvt_pk_bf16_f32 v134, v136, v137
	v_cvt_pk_bf16_f32 v135, v132, v133
	s_nop 0
	v_and_b32_e32 v133, 0xffff0000, v134
	v_cvt_pk_bf16_f32 v136, v138, v139
	v_lshlrev_b32_e32 v132, 16, v134
	v_and_b32_e32 v139, 0xffff0000, v135
	v_mul_f32_e32 v133, v133, v133
	v_lshlrev_b32_e32 v138, 16, v135
	v_fmac_f32_e32 v133, v132, v132
	v_mul_f32_e32 v132, v139, v139
	v_cvt_pk_bf16_f32 v137, v142, v143
	v_and_b32_e32 v143, 0xffff0000, v136
	v_and_b32_e32 v146, 0xffff0000, v137
	v_fmac_f32_e32 v132, v138, v138
	v_lshlrev_b32_e32 v142, 16, v136
	v_lshlrev_b32_e32 v145, 16, v137
	v_add_f32_e32 v132, v133, v132
	v_mul_f32_e32 v133, v143, v143
	v_mul_f32_e32 v138, v146, v146
	v_fmac_f32_e32 v133, v142, v142
	v_fmac_f32_e32 v138, v145, v145
	v_add_f32_e32 v133, v133, v138
	v_add_f32_e32 v132, v132, v133
	v_add_f32_e32 v132, v144, v132
	v_mov_b32_e32 v133, v132
	s_nop 1
	v_permlane16_swap_b32_e32 v132, v133
	global_store_dwordx4 v[140:141], v[134:137], off offset:256 nt
	s_waitcnt lgkmcnt(0)
	v_add_f32_e32 v132, v132, v133
	v_mov_b32_e32 v133, v132
	s_nop 1
	v_permlane32_swap_b32_e32 v132, v133
	s_and_saveexec_b64 s[72:73], s[40:41]
	s_cbranch_execz .LBB7_445
	v_lshlrev_b64 v[134:135], 6, v[156:157]
	v_lshl_add_u64 v[134:135], s[66:67], 0, v[134:135]
	v_lshl_add_u64 v[134:135], s[16:17], 2, v[134:135]
	s_lshl_b32 s20, s96, 2
	v_lshl_add_u64 v[134:135], v[134:135], 0, s[20:21]
	s_waitcnt lgkmcnt(0)
	v_add_f32_e32 v132, v132, v133
	global_store_dword v[134:135], v132, off
.LBB7_445:
	s_or_b64 exec, exec, s[72:73]
	v_add_u32_e32 v198, 0x80, v184
	v_ashrrev_i32_e32 v199, 31, v198
	v_lshlrev_b64 v[170:171], 11, v[198:199]
	s_waitcnt lgkmcnt(0)
	v_lshl_add_u64 v[132:133], v[190:191], 0, v[170:171]
	v_mov_b64_e32 v[210:211], v[232:233]
	v_mov_b64_e32 v[212:213], v[234:235]
	v_mov_b64_e32 v[156:157], v[236:237]
	v_mov_b64_e32 v[158:159], v[238:239]
	v_add_u32_e32 v194, 0x90, v184
	v_ashrrev_i32_e32 v195, 31, v194
	v_add_u32_e32 v188, 0xa0, v184
	v_lshlrev_b64 v[196:197], 11, v[194:195]
	v_ashrrev_i32_e32 v189, 31, v188
	v_add_u32_e32 v184, 0xb0, v184
	v_lshl_add_u64 v[132:133], v[190:191], 0, v[196:197]
	v_lshlrev_b64 v[192:193], 11, v[188:189]
	v_ashrrev_i32_e32 v185, 31, v184
	v_mov_b64_e32 v[152:153], v[240:241]
	v_mov_b64_e32 v[154:155], v[242:243]
	v_mov_b64_e32 v[148:149], v[244:245]
	v_mov_b64_e32 v[150:151], v[246:247]
	v_lshl_add_u64 v[132:133], v[190:191], 0, v[192:193]
	v_lshlrev_b64 v[186:187], 11, v[184:185]
	global_load_dwordx4 v[144:147], v[132:133], off
	global_load_dwordx4 v[140:143], v[132:133], off offset:256
	v_lshl_add_u64 v[132:133], v[190:191], 0, v[186:187]
	global_load_dwordx4 v[136:139], v[132:133], off
	s_nop 0
	global_load_dwordx4 v[132:135], v[132:133], off offset:256
	v_lshl_add_u64 v[170:171], s[68:69], 0, v[170:171]
	v_lshl_add_u64 v[170:171], v[2:3], 1, v[170:171]
	s_waitcnt vmcnt(7)
	v_lshlrev_b32_e32 v172, 16, v210
	v_and_b32_e32 v173, 0xffff0000, v210
	v_lshlrev_b32_e32 v190, 16, v211
	v_and_b32_e32 v191, 0xffff0000, v211
	v_lshlrev_b32_e32 v210, 16, v212
	v_and_b32_e32 v211, 0xffff0000, v212
	v_lshlrev_b32_e32 v212, 16, v213
	v_and_b32_e32 v213, 0xffff0000, v213
	v_pk_fma_f32 v[172:173], v[68:69], 0.5, v[172:173] op_sel_hi:[1,0,1]
	v_pk_fma_f32 v[190:191], v[70:71], 0.5, v[190:191] op_sel_hi:[1,0,1]
	v_pk_fma_f32 v[214:215], v[62:63], 0.5, v[212:213] op_sel_hi:[1,0,1]
	v_pk_fma_f32 v[212:213], v[60:61], 0.5, v[210:211] op_sel_hi:[1,0,1]
	v_cvt_pk_bf16_f32 v210, v172, v173
	v_cvt_pk_bf16_f32 v211, v190, v191
	s_nop 0
	v_and_b32_e32 v173, 0xffff0000, v210
	v_lshlrev_b32_e32 v172, 16, v210
	v_and_b32_e32 v191, 0xffff0000, v211
	v_mul_f32_e32 v173, v173, v173
	v_cvt_pk_bf16_f32 v212, v212, v213
	v_lshlrev_b32_e32 v190, 16, v211
	v_fmac_f32_e32 v173, v172, v172
	v_mul_f32_e32 v172, v191, v191
	v_cvt_pk_bf16_f32 v213, v214, v215
	global_store_dwordx4 v[170:171], v[210:213], off nt
	v_lshlrev_b32_e32 v209, 16, v212
	v_fmac_f32_e32 v172, v190, v190
	v_and_b32_e32 v210, 0xffff0000, v212
	v_and_b32_e32 v212, 0xffff0000, v213
	v_lshlrev_b32_e32 v211, 16, v213
	v_add_f32_e32 v172, v173, v172
	v_mul_f32_e32 v173, v210, v210
	v_mul_f32_e32 v190, v212, v212
	v_fmac_f32_e32 v173, v209, v209
	v_fmac_f32_e32 v190, v211, v211
	v_add_f32_e32 v173, v173, v190
	v_add_f32_e32 v209, v172, v173
	s_waitcnt vmcnt(7)
	v_lshlrev_b32_e32 v172, 16, v156
	v_and_b32_e32 v173, 0xffff0000, v156
	v_lshlrev_b32_e32 v156, 16, v157
	v_and_b32_e32 v157, 0xffff0000, v157
	v_lshlrev_b32_e32 v190, 16, v158
	v_and_b32_e32 v191, 0xffff0000, v158
	v_lshlrev_b32_e32 v158, 16, v159
	v_and_b32_e32 v159, 0xffff0000, v159
	v_pk_fma_f32 v[210:211], v[34:35], 0.5, v[156:157] op_sel_hi:[1,0,1]
	v_pk_fma_f32 v[156:157], v[32:33], 0.5, v[172:173] op_sel_hi:[1,0,1]
	v_pk_fma_f32 v[172:173], v[30:31], 0.5, v[158:159] op_sel_hi:[1,0,1]
	v_pk_fma_f32 v[158:159], v[28:29], 0.5, v[190:191] op_sel_hi:[1,0,1]
	v_cvt_pk_bf16_f32 v156, v156, v157
	v_cvt_pk_bf16_f32 v157, v210, v211
	s_nop 0
	v_cvt_pk_bf16_f32 v158, v158, v159
	v_cvt_pk_bf16_f32 v159, v172, v173
	global_store_dwordx4 v[170:171], v[156:159], off offset:256 nt
	v_lshlrev_b32_e32 v170, 16, v156
	v_lshlrev_b32_e32 v171, 16, v157
	v_and_b32_e32 v156, 0xffff0000, v156
	v_and_b32_e32 v157, 0xffff0000, v157
	v_mul_f32_e32 v156, v156, v156
	v_mul_f32_e32 v157, v157, v157
	v_lshlrev_b32_e32 v172, 16, v158
	v_and_b32_e32 v158, 0xffff0000, v158
	v_lshlrev_b32_e32 v173, 16, v159
	v_and_b32_e32 v159, 0xffff0000, v159
	v_fmac_f32_e32 v156, v170, v170
	v_fmac_f32_e32 v157, v171, v171
	v_add_f32_e32 v156, v156, v157
	v_mul_f32_e32 v157, v158, v158
	v_mul_f32_e32 v158, v159, v159
	v_fmac_f32_e32 v157, v172, v172
	v_fmac_f32_e32 v158, v173, v173
	v_add_f32_e32 v157, v157, v158
	v_add_f32_e32 v156, v156, v157
	v_add_f32_e32 v156, v209, v156
	v_mov_b32_e32 v157, v156
	s_nop 1
	v_permlane16_swap_b32_e32 v156, v157
	s_waitcnt lgkmcnt(0)
	v_add_f32_e32 v156, v156, v157
	v_mov_b32_e32 v157, v156
	s_nop 1
	v_permlane32_swap_b32_e32 v156, v157
	s_and_saveexec_b64 s[72:73], s[40:41]
	s_cbranch_execz .LBB7_447
	v_lshlrev_b64 v[158:159], 6, v[198:199]
	v_lshl_add_u64 v[158:159], s[66:67], 0, v[158:159]
	v_lshl_add_u64 v[158:159], s[16:17], 2, v[158:159]
	s_lshl_b32 s20, s96, 2
	v_lshl_add_u64 v[158:159], v[158:159], 0, s[20:21]
	s_waitcnt lgkmcnt(0)
	v_add_f32_e32 v156, v156, v157
	global_store_dword v[158:159], v156, off
.LBB7_447:
	s_or_b64 exec, exec, s[72:73]
	s_waitcnt vmcnt(7)
	v_lshlrev_b32_e32 v156, 16, v152
	s_waitcnt lgkmcnt(0)
	v_and_b32_e32 v157, 0xffff0000, v152
	v_lshlrev_b32_e32 v152, 16, v153
	v_and_b32_e32 v153, 0xffff0000, v153
	v_lshlrev_b32_e32 v158, 16, v154
	v_and_b32_e32 v159, 0xffff0000, v154
	v_lshlrev_b32_e32 v154, 16, v155
	v_and_b32_e32 v155, 0xffff0000, v155
	v_pk_fma_f32 v[170:171], v[58:59], 0.5, v[152:153] op_sel_hi:[1,0,1]
	v_pk_fma_f32 v[152:153], v[56:57], 0.5, v[156:157] op_sel_hi:[1,0,1]
	v_pk_fma_f32 v[156:157], v[54:55], 0.5, v[154:155] op_sel_hi:[1,0,1]
	v_pk_fma_f32 v[154:155], v[52:53], 0.5, v[158:159] op_sel_hi:[1,0,1]
	v_cvt_pk_bf16_f32 v152, v152, v153
	v_cvt_pk_bf16_f32 v153, v170, v171
	s_nop 0
	v_cvt_pk_bf16_f32 v154, v154, v155
	v_cvt_pk_bf16_f32 v155, v156, v157
	v_lshl_add_u64 v[156:157], s[68:69], 0, v[196:197]
	v_lshl_add_u64 v[156:157], v[2:3], 1, v[156:157]
	global_store_dwordx4 v[156:157], v[152:155], off nt
	v_lshlrev_b32_e32 v158, 16, v152
	v_lshlrev_b32_e32 v159, 16, v153
	v_and_b32_e32 v152, 0xffff0000, v152
	v_and_b32_e32 v153, 0xffff0000, v153
	v_mul_f32_e32 v152, v152, v152
	v_mul_f32_e32 v153, v153, v153
	v_lshlrev_b32_e32 v170, 16, v154
	v_and_b32_e32 v154, 0xffff0000, v154
	v_lshlrev_b32_e32 v171, 16, v155
	v_and_b32_e32 v155, 0xffff0000, v155
	v_fmac_f32_e32 v152, v158, v158
	v_fmac_f32_e32 v153, v159, v159
	v_add_f32_e32 v152, v152, v153
	v_mul_f32_e32 v153, v154, v154
	v_mul_f32_e32 v154, v155, v155
	v_fmac_f32_e32 v153, v170, v170
	v_fmac_f32_e32 v154, v171, v171
	v_add_f32_e32 v153, v153, v154
	v_add_f32_e32 v170, v152, v153
	s_waitcnt vmcnt(7)
	v_lshlrev_b32_e32 v152, 16, v148
	v_and_b32_e32 v153, 0xffff0000, v148
	v_lshlrev_b32_e32 v148, 16, v149
	v_and_b32_e32 v149, 0xffff0000, v149
	v_lshlrev_b32_e32 v154, 16, v150
	v_and_b32_e32 v155, 0xffff0000, v150
	v_lshlrev_b32_e32 v150, 16, v151
	v_and_b32_e32 v151, 0xffff0000, v151
	v_pk_fma_f32 v[148:149], v[26:27], 0.5, v[148:149] op_sel_hi:[1,0,1]
	v_pk_fma_f32 v[152:153], v[24:25], 0.5, v[152:153] op_sel_hi:[1,0,1]
	v_pk_fma_f32 v[158:159], v[22:23], 0.5, v[150:151] op_sel_hi:[1,0,1]
	v_pk_fma_f32 v[154:155], v[20:21], 0.5, v[154:155] op_sel_hi:[1,0,1]
	v_cvt_pk_bf16_f32 v150, v152, v153
	v_cvt_pk_bf16_f32 v151, v148, v149
	s_nop 0
	v_and_b32_e32 v149, 0xffff0000, v150
	v_cvt_pk_bf16_f32 v152, v154, v155
	v_lshlrev_b32_e32 v148, 16, v150
	v_and_b32_e32 v155, 0xffff0000, v151
	v_mul_f32_e32 v149, v149, v149
	v_lshlrev_b32_e32 v154, 16, v151
	v_fmac_f32_e32 v149, v148, v148
	v_mul_f32_e32 v148, v155, v155
	v_cvt_pk_bf16_f32 v153, v158, v159
	v_and_b32_e32 v159, 0xffff0000, v152
	v_and_b32_e32 v172, 0xffff0000, v153
	v_fmac_f32_e32 v148, v154, v154
	v_lshlrev_b32_e32 v158, 16, v152
	v_lshlrev_b32_e32 v171, 16, v153
	v_add_f32_e32 v148, v149, v148
	v_mul_f32_e32 v149, v159, v159
	v_mul_f32_e32 v154, v172, v172
	v_fmac_f32_e32 v149, v158, v158
	v_fmac_f32_e32 v154, v171, v171
	v_add_f32_e32 v149, v149, v154
	v_add_f32_e32 v148, v148, v149
	v_add_f32_e32 v148, v170, v148
	v_mov_b32_e32 v149, v148
	s_nop 1
	v_permlane16_swap_b32_e32 v148, v149
	global_store_dwordx4 v[156:157], v[150:153], off offset:256 nt
	s_waitcnt lgkmcnt(0)
	v_add_f32_e32 v148, v148, v149
	v_mov_b32_e32 v149, v148
	s_nop 1
	v_permlane32_swap_b32_e32 v148, v149
	s_and_saveexec_b64 s[72:73], s[40:41]
	s_cbranch_execz .LBB7_449
	v_lshlrev_b64 v[150:151], 6, v[194:195]
	v_lshl_add_u64 v[150:151], s[66:67], 0, v[150:151]
	v_lshl_add_u64 v[150:151], s[16:17], 2, v[150:151]
	s_lshl_b32 s20, s96, 2
	v_lshl_add_u64 v[150:151], v[150:151], 0, s[20:21]
	s_waitcnt lgkmcnt(0)
	v_add_f32_e32 v148, v148, v149
	global_store_dword v[150:151], v148, off
.LBB7_449:
	s_or_b64 exec, exec, s[72:73]
	s_waitcnt vmcnt(7)
	v_lshlrev_b32_e32 v148, 16, v144
	s_waitcnt lgkmcnt(0)
	v_and_b32_e32 v149, 0xffff0000, v144
	v_lshlrev_b32_e32 v144, 16, v145
	v_and_b32_e32 v145, 0xffff0000, v145
	v_lshlrev_b32_e32 v150, 16, v146
	v_and_b32_e32 v151, 0xffff0000, v146
	v_lshlrev_b32_e32 v146, 16, v147
	v_and_b32_e32 v147, 0xffff0000, v147
	v_pk_fma_f32 v[152:153], v[50:51], 0.5, v[144:145] op_sel_hi:[1,0,1]
	v_pk_fma_f32 v[144:145], v[48:49], 0.5, v[148:149] op_sel_hi:[1,0,1]
	v_pk_fma_f32 v[148:149], v[46:47], 0.5, v[146:147] op_sel_hi:[1,0,1]
	v_pk_fma_f32 v[146:147], v[44:45], 0.5, v[150:151] op_sel_hi:[1,0,1]
	v_cvt_pk_bf16_f32 v144, v144, v145
	v_cvt_pk_bf16_f32 v145, v152, v153
	s_nop 0
	v_cvt_pk_bf16_f32 v146, v146, v147
	v_cvt_pk_bf16_f32 v147, v148, v149
	v_lshl_add_u64 v[148:149], s[68:69], 0, v[192:193]
	v_lshl_add_u64 v[148:149], v[2:3], 1, v[148:149]
	global_store_dwordx4 v[148:149], v[144:147], off nt
	v_lshlrev_b32_e32 v150, 16, v144
	v_lshlrev_b32_e32 v151, 16, v145
	v_and_b32_e32 v144, 0xffff0000, v144
	v_and_b32_e32 v145, 0xffff0000, v145
	v_mul_f32_e32 v144, v144, v144
	v_mul_f32_e32 v145, v145, v145
	v_lshlrev_b32_e32 v152, 16, v146
	v_and_b32_e32 v146, 0xffff0000, v146
	v_lshlrev_b32_e32 v153, 16, v147
	v_and_b32_e32 v147, 0xffff0000, v147
	v_fmac_f32_e32 v144, v150, v150
	v_fmac_f32_e32 v145, v151, v151
	v_add_f32_e32 v144, v144, v145
	v_mul_f32_e32 v145, v146, v146
	v_mul_f32_e32 v146, v147, v147
	v_fmac_f32_e32 v145, v152, v152
	v_fmac_f32_e32 v146, v153, v153
	v_add_f32_e32 v145, v145, v146
	v_add_f32_e32 v152, v144, v145
	s_waitcnt vmcnt(7)
	v_lshlrev_b32_e32 v144, 16, v140
	v_and_b32_e32 v145, 0xffff0000, v140
	v_lshlrev_b32_e32 v140, 16, v141
	v_and_b32_e32 v141, 0xffff0000, v141
	v_lshlrev_b32_e32 v146, 16, v142
	v_and_b32_e32 v147, 0xffff0000, v142
	v_lshlrev_b32_e32 v142, 16, v143
	v_and_b32_e32 v143, 0xffff0000, v143
	v_pk_fma_f32 v[140:141], v[18:19], 0.5, v[140:141] op_sel_hi:[1,0,1]
	v_pk_fma_f32 v[144:145], v[16:17], 0.5, v[144:145] op_sel_hi:[1,0,1]
	v_pk_fma_f32 v[150:151], v[14:15], 0.5, v[142:143] op_sel_hi:[1,0,1]
	v_pk_fma_f32 v[146:147], v[12:13], 0.5, v[146:147] op_sel_hi:[1,0,1]
	v_cvt_pk_bf16_f32 v142, v144, v145
	v_cvt_pk_bf16_f32 v143, v140, v141
	s_nop 0
	v_and_b32_e32 v141, 0xffff0000, v142
	v_cvt_pk_bf16_f32 v144, v146, v147
	v_lshlrev_b32_e32 v140, 16, v142
	v_and_b32_e32 v147, 0xffff0000, v143
	v_mul_f32_e32 v141, v141, v141
	v_lshlrev_b32_e32 v146, 16, v143
	v_fmac_f32_e32 v141, v140, v140
	v_mul_f32_e32 v140, v147, v147
	v_cvt_pk_bf16_f32 v145, v150, v151
	v_and_b32_e32 v151, 0xffff0000, v144
	v_and_b32_e32 v154, 0xffff0000, v145
	v_fmac_f32_e32 v140, v146, v146
	v_lshlrev_b32_e32 v150, 16, v144
	v_lshlrev_b32_e32 v153, 16, v145
	v_add_f32_e32 v140, v141, v140
	v_mul_f32_e32 v141, v151, v151
	v_mul_f32_e32 v146, v154, v154
	v_fmac_f32_e32 v141, v150, v150
	v_fmac_f32_e32 v146, v153, v153
	v_add_f32_e32 v141, v141, v146
	v_add_f32_e32 v140, v140, v141
	v_add_f32_e32 v140, v152, v140
	v_mov_b32_e32 v141, v140
	s_nop 1
	v_permlane16_swap_b32_e32 v140, v141
	global_store_dwordx4 v[148:149], v[142:145], off offset:256 nt
	s_waitcnt lgkmcnt(0)
	v_add_f32_e32 v140, v140, v141
	v_mov_b32_e32 v141, v140
	s_nop 1
	v_permlane32_swap_b32_e32 v140, v141
	s_and_saveexec_b64 s[72:73], s[40:41]
	s_cbranch_execz .LBB7_451
	v_lshlrev_b64 v[142:143], 6, v[188:189]
	v_lshl_add_u64 v[142:143], s[66:67], 0, v[142:143]
	v_lshl_add_u64 v[142:143], s[16:17], 2, v[142:143]
	s_lshl_b32 s20, s96, 2
	v_lshl_add_u64 v[142:143], v[142:143], 0, s[20:21]
	s_waitcnt lgkmcnt(0)
	v_add_f32_e32 v140, v140, v141
	global_store_dword v[142:143], v140, off
.LBB7_451:
	s_or_b64 exec, exec, s[72:73]
	s_waitcnt vmcnt(7)
	v_lshlrev_b32_e32 v140, 16, v136
	s_waitcnt lgkmcnt(0)
	v_and_b32_e32 v141, 0xffff0000, v136
	v_lshlrev_b32_e32 v136, 16, v137
	v_and_b32_e32 v137, 0xffff0000, v137
	v_lshlrev_b32_e32 v142, 16, v138
	v_and_b32_e32 v143, 0xffff0000, v138
	v_lshlrev_b32_e32 v138, 16, v139
	v_and_b32_e32 v139, 0xffff0000, v139
	v_pk_fma_f32 v[144:145], v[42:43], 0.5, v[136:137] op_sel_hi:[1,0,1]
	v_pk_fma_f32 v[136:137], v[40:41], 0.5, v[140:141] op_sel_hi:[1,0,1]
	v_pk_fma_f32 v[140:141], v[38:39], 0.5, v[138:139] op_sel_hi:[1,0,1]
	v_pk_fma_f32 v[138:139], v[36:37], 0.5, v[142:143] op_sel_hi:[1,0,1]
	v_cvt_pk_bf16_f32 v136, v136, v137
	v_cvt_pk_bf16_f32 v137, v144, v145
	s_nop 0
	v_cvt_pk_bf16_f32 v138, v138, v139
	v_cvt_pk_bf16_f32 v139, v140, v141
	v_lshl_add_u64 v[140:141], s[68:69], 0, v[186:187]
	v_lshl_add_u64 v[140:141], v[2:3], 1, v[140:141]
	v_and_b32_e32 v3, 0xffff0000, v136
	global_store_dwordx4 v[140:141], v[136:139], off nt
	v_lshlrev_b32_e32 v2, 16, v136
	v_mul_f32_e32 v3, v3, v3
	v_lshlrev_b32_e32 v136, 16, v137
	v_and_b32_e32 v137, 0xffff0000, v137
	v_fmac_f32_e32 v3, v2, v2
	v_mul_f32_e32 v2, v137, v137
	v_lshlrev_b32_e32 v142, 16, v138
	v_and_b32_e32 v138, 0xffff0000, v138
	v_lshlrev_b32_e32 v143, 16, v139
	v_and_b32_e32 v139, 0xffff0000, v139
	v_fmac_f32_e32 v2, v136, v136
	v_add_f32_e32 v2, v3, v2
	v_mul_f32_e32 v3, v138, v138
	v_mul_f32_e32 v136, v139, v139
	v_fmac_f32_e32 v3, v142, v142
	v_fmac_f32_e32 v136, v143, v143
	v_add_f32_e32 v3, v3, v136
	v_add_f32_e32 v144, v2, v3
	s_waitcnt vmcnt(7)
	v_lshlrev_b32_e32 v2, 16, v132
	v_and_b32_e32 v3, 0xffff0000, v132
	v_lshlrev_b32_e32 v132, 16, v133
	v_and_b32_e32 v133, 0xffff0000, v133
	v_pk_fma_f32 v[2:3], v[8:9], 0.5, v[2:3] op_sel_hi:[1,0,1]
	v_lshlrev_b32_e32 v136, 16, v134
	v_and_b32_e32 v137, 0xffff0000, v134
	v_lshlrev_b32_e32 v134, 16, v135
	v_and_b32_e32 v135, 0xffff0000, v135
	v_pk_fma_f32 v[138:139], v[10:11], 0.5, v[132:133] op_sel_hi:[1,0,1]
	v_cvt_pk_bf16_f32 v132, v2, v3
	v_pk_fma_f32 v[142:143], v[6:7], 0.5, v[134:135] op_sel_hi:[1,0,1]
	v_and_b32_e32 v3, 0xffff0000, v132
	v_pk_fma_f32 v[134:135], v[4:5], 0.5, v[136:137] op_sel_hi:[1,0,1]
	v_cvt_pk_bf16_f32 v133, v138, v139
	v_lshlrev_b32_e32 v2, 16, v132
	v_and_b32_e32 v137, 0xffff0000, v133
	v_mul_f32_e32 v3, v3, v3
	v_lshlrev_b32_e32 v136, 16, v133
	v_fmac_f32_e32 v3, v2, v2
	v_mul_f32_e32 v2, v137, v137
	v_cvt_pk_bf16_f32 v134, v134, v135
	v_cvt_pk_bf16_f32 v135, v142, v143
	v_fmac_f32_e32 v2, v136, v136
	v_and_b32_e32 v139, 0xffff0000, v134
	v_and_b32_e32 v143, 0xffff0000, v135
	v_lshlrev_b32_e32 v138, 16, v134
	v_lshlrev_b32_e32 v142, 16, v135
	v_add_f32_e32 v2, v3, v2
	v_mul_f32_e32 v3, v139, v139
	v_mul_f32_e32 v136, v143, v143
	v_fmac_f32_e32 v3, v138, v138
	v_fmac_f32_e32 v136, v142, v142
	v_add_f32_e32 v3, v3, v136
	v_add_f32_e32 v2, v2, v3
	v_add_f32_e32 v2, v144, v2
	v_mov_b32_e32 v0, v2
	s_nop 1
	v_permlane16_swap_b32_e32 v2, v0
	global_store_dwordx4 v[140:141], v[132:135], off offset:256 nt
	s_waitcnt lgkmcnt(0)
	v_add_f32_e32 v0, v2, v0
	v_mov_b32_e32 v2, v0
	s_nop 1
	v_permlane32_swap_b32_e32 v0, v2
	s_and_saveexec_b64 s[72:73], s[40:41]
	s_cbranch_execz .LBB7_453
	v_lshlrev_b64 v[132:133], 6, v[184:185]
	v_lshl_add_u64 v[132:133], s[66:67], 0, v[132:133]
	v_lshl_add_u64 v[132:133], s[16:17], 2, v[132:133]
	s_lshl_b32 s20, s96, 2
	v_lshl_add_u64 v[132:133], v[132:133], 0, s[20:21]
	s_waitcnt lgkmcnt(0)
	v_add_f32_e32 v0, v0, v2
	global_store_dword v[132:133], v0, off

.LBB7_526:
	v_and_b32_e32 v192, 0x30, v163
	v_lshl_add_u32 v192, v143, 6, v192
	v_add_u32_e32 v192, 0x20000, v192
	ds_read_b128 v[204:207], v192 offset:1024
	ds_read_b128 v[208:211], v192 offset:2048
	ds_read_b128 v[212:215], v192 offset:3072
	ds_read_b128 v[216:219], v192 offset:8192
	ds_read_b128 v[220:223], v192 offset:9216
	ds_read_b128 v[224:227], v192 offset:10240
	ds_read_b128 v[228:231], v192 offset:11264
	v_and_b32_e32 v130, 64, v163
	v_xor_b32_e32 v0, 16, v163
	v_add_u32_e32 v130, 64, v130
	v_cmp_lt_i32_e32 vcc, v0, v130
	v_lshl_add_u32 v184, s28, 8, v143
	v_ashrrev_i32_e32 v185, 31, v184
	v_cndmask_b32_e32 v0, v163, v0, vcc
	v_lshlrev_b32_e32 v191, 2, v0
	v_xor_b32_e32 v0, 32, v163
	v_cmp_lt_i32_e32 vcc, v0, v130
	v_lshlrev_b64 v[130:131], 6, v[184:185]
	v_lshl_add_u64 v[130:131], v[144:145], 0, v[130:131]
	ds_read_b128 v[130:133], v192
	v_or_b32_e32 v180, 16, v184
	v_ashrrev_i32_e32 v181, 31, v180
	v_cndmask_b32_e32 v0, v163, v0, vcc
	v_lshlrev_b32_e32 v0, 2, v0
	v_or_b32_e32 v178, 32, v184
	v_ashrrev_i32_e32 v179, 31, v178
	v_or_b32_e32 v158, 48, v184
	v_ashrrev_i32_e32 v159, 31, v158
	v_add_u32_e32 v156, 0x80, v184
	v_ashrrev_i32_e32 v157, 31, v156
	v_add_u32_e32 v154, 0x90, v184
	v_ashrrev_i32_e32 v155, 31, v154
	s_lshl_b32 s13, s10, 8
	s_or_b32 s10, s13, s31
	s_movk_i32 s15, 0x17f
	v_lshlrev_b64 v[192:193], 11, v[184:185]
	s_waitcnt lgkmcnt(0)
	v_mov_b32_e32 v150, v131
	v_mov_b32_e32 v151, v132
	v_mov_b32_e32 v131, v133
	v_pk_add_f32 v[150:151], v[150:151], v[130:131]
	v_lshlrev_b64 v[130:131], 6, v[180:181]
	v_lshl_add_u64 v[130:131], v[144:145], 0, v[130:131]
	v_mov_b64_e32 v[130:131], v[204:205]
	v_mov_b64_e32 v[132:133], v[206:207]
	v_mov_b32_e32 v152, v131
	v_mov_b32_e32 v153, v132
	v_mov_b32_e32 v131, v133
	v_pk_add_f32 v[130:131], v[152:153], v[130:131]
	v_mov_b32_e32 v133, v150
	v_mov_b32_e32 v132, v130
	v_mov_b32_e32 v150, v131
	v_pk_add_f32 v[130:131], v[132:133], v[150:151]
	v_mov_b32_e32 v133, v131
	s_nop 1
	v_permlane16_swap_b32_e32 v131, v133
	v_mov_b32_e32 v132, v130
	s_nop 1
	v_permlane16_swap_b32_e32 v130, v132
	s_waitcnt lgkmcnt(0)
	v_pk_add_f32 v[130:131], v[130:131], v[132:133]
	v_mov_b32_e32 v133, v131
	s_nop 1
	v_permlane32_swap_b32_e32 v131, v133
	v_mov_b32_e32 v132, v130
	s_nop 1
	v_permlane32_swap_b32_e32 v130, v132
	s_waitcnt lgkmcnt(0)
	v_pk_add_f32 v[130:131], v[130:131], v[132:133]
	s_nop 0
	v_pk_fma_f32 v[188:189], v[130:131], s[26:27], v[162:163] op_sel_hi:[1,0,0]
	s_nop 0
	v_mul_f32_e32 v130, 0x4b800000, v189
	v_cmp_gt_f32_e32 vcc, s11, v189
	v_cmp_gt_f32_e64 s[44:45], s11, v188
	s_nop 0
	v_cndmask_b32_e32 v130, v189, v130, vcc
	v_rsq_f32_e32 v130, v130
	s_nop 0
	v_mul_f32_e32 v131, 0x45800000, v130
	v_cndmask_b32_e32 v190, v130, v131, vcc
	v_lshlrev_b64 v[130:131], 6, v[178:179]
	v_lshl_add_u64 v[130:131], v[144:145], 0, v[130:131]
	v_pk_mul_f32 v[128:129], v[128:129], v[190:191] op_sel_hi:[1,0]
	v_pk_mul_f32 v[126:127], v[126:127], v[190:191] op_sel_hi:[1,0]
	v_mov_b64_e32 v[130:131], v[208:209]
	v_mov_b64_e32 v[132:133], v[210:211]
	v_mov_b32_e32 v150, v131
	v_mov_b32_e32 v151, v132
	v_mov_b32_e32 v131, v133
	v_pk_add_f32 v[150:151], v[150:151], v[130:131]
	v_lshlrev_b64 v[130:131], 6, v[158:159]
	v_lshl_add_u64 v[130:131], v[144:145], 0, v[130:131]
	v_mov_b64_e32 v[130:131], v[212:213]
	v_mov_b64_e32 v[132:133], v[214:215]
	v_mov_b32_e32 v152, v131
	v_mov_b32_e32 v153, v132
	v_mov_b32_e32 v131, v133
	v_pk_add_f32 v[130:131], v[152:153], v[130:131]
	v_mov_b32_e32 v133, v150
	v_mov_b32_e32 v132, v130
	v_mov_b32_e32 v150, v131
	v_pk_add_f32 v[130:131], v[132:133], v[150:151]
	v_mov_b32_e32 v133, v131
	s_nop 1
	v_permlane16_swap_b32_e32 v131, v133
	v_mov_b32_e32 v132, v130
	s_nop 1
	v_permlane16_swap_b32_e32 v130, v132
	s_waitcnt lgkmcnt(0)
	v_pk_add_f32 v[182:183], v[130:131], v[132:133]
	v_lshlrev_b64 v[130:131], 6, v[156:157]
	v_lshl_add_u64 v[130:131], v[144:145], 0, v[130:131]
	ds_bpermute_b32 v187, v0, v183
	ds_bpermute_b32 v186, v0, v182
	v_mov_b64_e32 v[130:131], v[216:217]
	v_mov_b64_e32 v[132:133], v[218:219]
	v_mov_b32_e32 v150, v131
	v_mov_b32_e32 v151, v132
	v_mov_b32_e32 v131, v133
	v_pk_add_f32 v[150:151], v[150:151], v[130:131]
	v_lshlrev_b64 v[130:131], 6, v[154:155]
	v_lshl_add_u64 v[130:131], v[144:145], 0, v[130:131]
	v_mov_b64_e32 v[130:131], v[220:221]
	v_mov_b64_e32 v[132:133], v[222:223]
	v_mov_b32_e32 v152, v131
	v_mov_b32_e32 v153, v132
	v_mov_b32_e32 v131, v133
	v_pk_add_f32 v[130:131], v[152:153], v[130:131]
	v_mov_b32_e32 v133, v150
	v_mov_b32_e32 v132, v130
	v_mov_b32_e32 v150, v131
	v_pk_add_f32 v[130:131], v[132:133], v[150:151]
	v_mov_b32_e32 v133, v131
	s_nop 1
	v_permlane16_swap_b32_e32 v131, v133
	v_mov_b32_e32 v132, v130
	s_nop 1
	v_permlane16_swap_b32_e32 v130, v132
	v_add_u32_e32 v152, 0xa0, v184
	v_ashrrev_i32_e32 v153, 31, v152
	s_waitcnt lgkmcnt(0)
	v_pk_add_f32 v[160:161], v[130:131], v[132:133]
	v_lshlrev_b64 v[130:131], 6, v[152:153]
	v_lshl_add_u64 v[130:131], v[144:145], 0, v[130:131]
	ds_bpermute_b32 v175, v0, v161
	ds_bpermute_b32 v174, v0, v160
	v_mov_b64_e32 v[130:131], v[224:225]
	v_mov_b64_e32 v[132:133], v[226:227]
	v_mov_b32_e32 v150, v131
	v_mov_b32_e32 v151, v132
	v_mov_b32_e32 v131, v133
	v_pk_add_f32 v[176:177], v[150:151], v[130:131]
	v_add_u32_e32 v150, 0xb0, v184
	v_ashrrev_i32_e32 v151, 31, v150
	v_lshlrev_b64 v[130:131], 6, v[150:151]
	v_lshl_add_u64 v[130:131], v[144:145], 0, v[130:131]
	v_mov_b64_e32 v[130:131], v[228:229]
	v_mov_b64_e32 v[132:133], v[230:231]
	v_mov_b32_e32 v170, v131
	v_mov_b32_e32 v171, v132
	v_mov_b32_e32 v131, v133
	v_pk_add_f32 v[130:131], v[170:171], v[130:131]
	v_mov_b32_e32 v133, v176
	v_mov_b32_e32 v132, v130
	v_mov_b32_e32 v176, v131
	v_pk_add_f32 v[130:131], v[132:133], v[176:177]
	v_mov_b32_e32 v133, v131
	s_nop 1
	v_permlane16_swap_b32_e32 v131, v133
	v_mov_b32_e32 v132, v130
	s_nop 1
	v_permlane16_swap_b32_e32 v130, v132
	v_pk_mul_f32 v[170:171], v[124:125], v[190:191] op_sel_hi:[1,0]
	v_pk_mul_f32 v[124:125], v[122:123], v[190:191] op_sel_hi:[1,0]
	v_cvt_pk_bf16_f32 v122, v126, v127
	v_cvt_pk_bf16_f32 v123, v128, v129
	s_waitcnt lgkmcnt(0)
	v_pk_add_f32 v[132:133], v[130:131], v[132:133]
	ds_bpermute_b32 v177, v0, v133
	ds_bpermute_b32 v176, v0, v132
	v_or_b32_e32 v130, s10, v194
	v_cmp_lt_i32_e64 s[42:43], s15, v130
	v_cvt_pk_bf16_f32 v124, v124, v125
	v_cvt_pk_bf16_f32 v125, v170, v171
	s_and_saveexec_b64 s[16:17], s[42:43]
	s_xor_b64 s[16:17], exec, s[16:17]
	s_cbranch_execz .LBB7_529
	s_cmpk_gt_u32 s13, 0x57f
	s_cbranch_scc1 .LBB7_529
	v_lshl_add_u64 v[126:127], s[94:95], 0, v[192:193]
	v_mov_b32_e32 v131, v1
	v_lshl_add_u64 v[126:127], v[130:131], 1, v[126:127]
	global_store_dwordx4 v[126:127], v[122:125], off offset:-768 nt
.LBB7_529:
	s_or_saveexec_b64 s[16:17], s[16:17]
	v_lshrrev_b32_e32 v0, 27, v185
	v_add_u32_e32 v0, v184, v0
	v_ashrrev_i32_e32 v128, 5, v0
	v_and_b32_e32 v0, 0xfffffe0, v0
	v_sub_u32_e32 v0, v184, v0
	v_lshlrev_b32_e32 v126, 4, v0
	v_ashrrev_i32_e32 v127, 31, v126
	s_xor_b64 exec, exec, s[16:17]
	s_cbranch_execz .LBB7_531
	v_lshlrev_b32_e32 v0, 6, v130
	v_and_b32_e32 v0, 0xffffdc00, v0
	v_add_u32_e32 v0, v0, v128
	v_mov_b64_e32 v[170:171], s[70:71]
	v_mad_i64_i32 v[170:171], s[28:29], v0, s58, v[170:171]
	v_lshl_add_u64 v[170:171], v[126:127], 1, v[170:171]
	v_lshlrev_b32_e32 v0, 1, v142
	v_lshl_add_u64 v[170:171], v[170:171], 0, v[0:1]
	global_store_dwordx4 v[170:171], v[122:125], off offset:256 nt
.LBB7_531:
	s_or_b64 exec, exec, s[16:17]
	s_or_b32 s15, s10, 0x80
	v_mov_b32_e32 v191, v190
	v_or_b32_e32 v122, s15, v194
	v_mov_b32_e32 v124, v190
	v_mov_b32_e32 v125, v190
	s_movk_i32 s16, 0x17f
	v_pk_mul_f32 v[120:121], v[120:121], v[124:125]
	v_pk_mul_f32 v[124:125], v[116:117], v[124:125]
	v_pk_mul_f32 v[116:117], v[114:115], v[190:191]
	v_cmp_lt_i32_e32 vcc, s16, v122
	v_pk_mul_f32 v[118:119], v[118:119], v[190:191]
	s_nop 0
	v_cvt_pk_bf16_f32 v114, v118, v119
	v_cvt_pk_bf16_f32 v115, v120, v121
	v_cvt_pk_bf16_f32 v116, v116, v117
	v_cvt_pk_bf16_f32 v117, v124, v125
	s_and_saveexec_b64 s[16:17], vcc
	s_xor_b64 s[16:17], exec, s[16:17]
	s_cbranch_execz .LBB7_534
	s_cmpk_gt_u32 s15, 0x57f
	s_cbranch_scc1 .LBB7_534
	v_lshl_add_u64 v[118:119], s[94:95], 0, v[192:193]
	v_add_u32_e32 v0, s10, v194
	v_lshl_add_u64 v[118:119], v[0:1], 1, v[118:119]
	global_store_dwordx4 v[118:119], v[114:117], off offset:-512 nt
.LBB7_534:
	s_andn2_saveexec_b64 s[16:17], s[16:17]
	s_cbranch_execz .LBB7_536
	v_lshlrev_b32_e32 v0, 6, v122
	v_and_b32_e32 v0, 0xfffffc00, v0
	v_add_u32_e32 v0, v0, v128
	v_mov_b64_e32 v[118:119], s[70:71]
	v_mad_i64_i32 v[118:119], s[28:29], v0, s58, v[118:119]
	v_lshl_add_u64 v[118:119], v[126:127], 1, v[118:119]
	v_lshlrev_b32_e32 v0, 1, v142
	v_lshl_add_u64 v[118:119], v[118:119], 0, v[0:1]
	global_store_dwordx4 v[118:119], v[114:117], off offset:256 nt
.LBB7_536:
	s_or_b64 exec, exec, s[16:17]
	v_mul_f32_e32 v0, 0x4b800000, v188
	v_cndmask_b32_e64 v0, v188, v0, s[44:45]
	v_rsq_f32_e32 v0, v0
	v_lshlrev_b64 v[114:115], 11, v[180:181]
	v_mul_f32_e32 v116, 0x45800000, v0
	v_cndmask_b32_e64 v116, v0, v116, s[44:45]
	v_pk_mul_f32 v[118:119], v[108:109], v[116:117] op_sel_hi:[1,0]
	v_pk_mul_f32 v[108:109], v[106:107], v[116:117] op_sel_hi:[1,0]
	v_pk_mul_f32 v[112:113], v[112:113], v[116:117] op_sel_hi:[1,0]
	v_pk_mul_f32 v[110:111], v[110:111], v[116:117] op_sel_hi:[1,0]
	s_nop 0
	v_cvt_pk_bf16_f32 v106, v110, v111
	v_cvt_pk_bf16_f32 v107, v112, v113
	v_cvt_pk_bf16_f32 v108, v108, v109
	v_cvt_pk_bf16_f32 v109, v118, v119
	s_and_saveexec_b64 s[16:17], s[42:43]
	s_xor_b64 s[16:17], exec, s[16:17]
	s_cbranch_execz .LBB7_539
	s_cmpk_gt_u32 s13, 0x57f
	s_cbranch_scc1 .LBB7_539
	v_lshl_add_u64 v[110:111], s[94:95], 0, v[114:115]
	v_mov_b32_e32 v131, v1
	v_lshl_add_u64 v[110:111], v[130:131], 1, v[110:111]
	global_store_dwordx4 v[110:111], v[106:109], off offset:-768 nt
.LBB7_539:
	s_or_saveexec_b64 s[16:17], s[16:17]
	v_ashrrev_i32_e32 v0, 31, v180
	v_lshrrev_b32_e32 v0, 27, v0
	v_add_u32_e32 v0, v180, v0
	v_ashrrev_i32_e32 v112, 5, v0
	v_and_b32_e32 v0, 0xfffffe0, v0
	v_sub_u32_e32 v0, v180, v0
	v_lshlrev_b32_e32 v110, 4, v0
	v_ashrrev_i32_e32 v111, 31, v110
	s_xor_b64 exec, exec, s[16:17]
	s_cbranch_execz .LBB7_541
	v_lshlrev_b32_e32 v0, 6, v130
	v_and_b32_e32 v0, 0xffffdc00, v0
	v_add_u32_e32 v0, v112, v0
	v_mov_b64_e32 v[118:119], s[70:71]
	v_mad_i64_i32 v[118:119], s[28:29], v0, s58, v[118:119]
	v_lshl_add_u64 v[118:119], v[110:111], 1, v[118:119]
	v_lshlrev_b32_e32 v0, 1, v142
	v_lshl_add_u64 v[118:119], v[118:119], 0, v[0:1]
	global_store_dwordx4 v[118:119], v[106:109], off offset:256 nt
.LBB7_541:
	s_or_b64 exec, exec, s[16:17]
	v_mov_b32_e32 v117, v116
	v_mov_b32_e32 v106, v116
	v_mov_b32_e32 v107, v116
	v_pk_mul_f32 v[104:105], v[104:105], v[106:107]
	v_pk_mul_f32 v[106:107], v[100:101], v[106:107]
	v_pk_mul_f32 v[100:101], v[98:99], v[116:117]
	v_pk_mul_f32 v[102:103], v[102:103], v[116:117]
	s_nop 0
	v_cvt_pk_bf16_f32 v98, v102, v103
	v_cvt_pk_bf16_f32 v99, v104, v105
	v_cvt_pk_bf16_f32 v100, v100, v101
	v_cvt_pk_bf16_f32 v101, v106, v107
	s_and_saveexec_b64 s[16:17], vcc
	s_xor_b64 s[16:17], exec, s[16:17]
	s_cbranch_execz .LBB7_544
	s_cmpk_gt_u32 s15, 0x57f
	s_cbranch_scc1 .LBB7_544
	v_lshl_add_u64 v[102:103], s[94:95], 0, v[114:115]
	v_add_u32_e32 v0, s10, v194
	v_lshl_add_u64 v[102:103], v[0:1], 1, v[102:103]
	global_store_dwordx4 v[102:103], v[98:101], off offset:-512 nt
.LBB7_544:
	s_andn2_saveexec_b64 s[16:17], s[16:17]
	s_cbranch_execz .LBB7_546
	v_lshlrev_b32_e32 v0, 6, v122
	v_and_b32_e32 v0, 0xfffffc00, v0
	v_add_u32_e32 v0, v0, v112
	v_mov_b64_e32 v[102:103], s[70:71]
	v_mad_i64_i32 v[102:103], s[28:29], v0, s58, v[102:103]
	v_lshl_add_u64 v[102:103], v[110:111], 1, v[102:103]
	v_lshlrev_b32_e32 v0, 1, v142
	v_lshl_add_u64 v[102:103], v[102:103], 0, v[0:1]
	global_store_dwordx4 v[102:103], v[98:101], off offset:256 nt
.LBB7_546:
	s_or_b64 exec, exec, s[16:17]
	s_nop 0
	v_pk_add_f32 v[98:99], v[182:183], v[186:187]
	v_lshlrev_b64 v[100:101], 11, v[178:179]
	v_pk_fma_f32 v[98:99], v[98:99], s[26:27], v[162:163] op_sel_hi:[1,0,0]
	s_nop 0
	v_mul_f32_e32 v0, 0x4b800000, v99
	v_cmp_gt_f32_e64 s[48:49], s11, v99
	v_cmp_gt_f32_e64 s[44:45], s11, v98
	s_nop 0
	v_cndmask_b32_e64 v0, v99, v0, s[48:49]
	v_rsq_f32_e32 v0, v0
	s_nop 0
	v_mul_f32_e32 v99, 0x45800000, v0
	v_cndmask_b32_e64 v102, v0, v99, s[48:49]
	v_pk_mul_f32 v[104:105], v[92:93], v[102:103] op_sel_hi:[1,0]
	v_pk_mul_f32 v[92:93], v[90:91], v[102:103] op_sel_hi:[1,0]
	v_pk_mul_f32 v[96:97], v[96:97], v[102:103] op_sel_hi:[1,0]
	v_pk_mul_f32 v[94:95], v[94:95], v[102:103] op_sel_hi:[1,0]
	s_nop 0
	v_cvt_pk_bf16_f32 v90, v94, v95
	v_cvt_pk_bf16_f32 v91, v96, v97
	v_cvt_pk_bf16_f32 v92, v92, v93
	v_cvt_pk_bf16_f32 v93, v104, v105
	s_and_saveexec_b64 s[16:17], s[42:43]
	s_xor_b64 s[16:17], exec, s[16:17]
	s_cbranch_execz .LBB7_549
	s_cmpk_gt_u32 s13, 0x57f
	s_cbranch_scc1 .LBB7_549
	v_lshl_add_u64 v[94:95], s[94:95], 0, v[100:101]
	v_mov_b32_e32 v131, v1
	v_lshl_add_u64 v[94:95], v[130:131], 1, v[94:95]
	global_store_dwordx4 v[94:95], v[90:93], off offset:-768 nt
.LBB7_549:
	s_or_saveexec_b64 s[16:17], s[16:17]
	v_ashrrev_i32_e32 v0, 31, v178
	v_lshrrev_b32_e32 v0, 27, v0
	v_add_u32_e32 v0, v178, v0
	v_ashrrev_i32_e32 v94, 5, v0
	s_xor_b64 exec, exec, s[16:17]
	s_cbranch_execz .LBB7_551
	v_lshlrev_b32_e32 v0, 6, v130
	v_and_b32_e32 v0, 0xffffdc00, v0
	v_add_u32_e32 v0, v94, v0
	v_mov_b64_e32 v[96:97], s[70:71]
	v_mad_i64_i32 v[96:97], s[28:29], v0, s58, v[96:97]
	v_lshl_add_u64 v[96:97], v[126:127], 1, v[96:97]
	v_lshlrev_b32_e32 v0, 1, v142
	v_lshl_add_u64 v[96:97], v[96:97], 0, v[0:1]
	global_store_dwordx4 v[96:97], v[90:93], off offset:256 nt
.LBB7_551:
	s_or_b64 exec, exec, s[16:17]
	v_mov_b32_e32 v103, v102
	v_mov_b32_e32 v90, v102
	v_mov_b32_e32 v91, v102
	v_pk_mul_f32 v[88:89], v[88:89], v[90:91]
	v_pk_mul_f32 v[90:91], v[84:85], v[90:91]
	v_pk_mul_f32 v[84:85], v[82:83], v[102:103]
	v_pk_mul_f32 v[86:87], v[86:87], v[102:103]
	s_nop 0
	v_cvt_pk_bf16_f32 v82, v86, v87
	v_cvt_pk_bf16_f32 v83, v88, v89
	v_cvt_pk_bf16_f32 v84, v84, v85
	v_cvt_pk_bf16_f32 v85, v90, v91
	s_and_saveexec_b64 s[16:17], vcc
	s_xor_b64 s[16:17], exec, s[16:17]
	s_cbranch_execz .LBB7_554
	s_cmpk_gt_u32 s15, 0x57f
	s_cbranch_scc1 .LBB7_554
	v_lshl_add_u64 v[86:87], s[94:95], 0, v[100:101]
	v_add_u32_e32 v0, s10, v194
	v_lshl_add_u64 v[86:87], v[0:1], 1, v[86:87]
	global_store_dwordx4 v[86:87], v[82:85], off offset:-512 nt
.LBB7_554:
	s_andn2_saveexec_b64 s[16:17], s[16:17]
	s_cbranch_execz .LBB7_556
	v_lshlrev_b32_e32 v0, 6, v122
	v_and_b32_e32 v0, 0xfffffc00, v0
	v_add_u32_e32 v0, v0, v94
	v_mov_b64_e32 v[86:87], s[70:71]
	v_mad_i64_i32 v[86:87], s[28:29], v0, s58, v[86:87]
	v_lshl_add_u64 v[86:87], v[126:127], 1, v[86:87]
	v_lshlrev_b32_e32 v0, 1, v142
	v_lshl_add_u64 v[86:87], v[86:87], 0, v[0:1]
	global_store_dwordx4 v[86:87], v[82:85], off offset:256 nt
.LBB7_556:
	s_or_b64 exec, exec, s[16:17]
	v_mul_f32_e32 v0, 0x4b800000, v98
	v_cndmask_b32_e64 v0, v98, v0, s[44:45]
	v_rsq_f32_e32 v0, v0
	v_lshlrev_b64 v[82:83], 11, v[158:159]
	v_mul_f32_e32 v84, 0x45800000, v0
	v_cndmask_b32_e64 v84, v0, v84, s[44:45]
	v_pk_mul_f32 v[86:87], v[76:77], v[84:85] op_sel_hi:[1,0]
	v_pk_mul_f32 v[76:77], v[74:75], v[84:85] op_sel_hi:[1,0]
	v_pk_mul_f32 v[80:81], v[80:81], v[84:85] op_sel_hi:[1,0]
	v_pk_mul_f32 v[78:79], v[78:79], v[84:85] op_sel_hi:[1,0]
	s_nop 0
	v_cvt_pk_bf16_f32 v74, v78, v79
	v_cvt_pk_bf16_f32 v75, v80, v81
	v_cvt_pk_bf16_f32 v76, v76, v77
	v_cvt_pk_bf16_f32 v77, v86, v87
	s_and_saveexec_b64 s[16:17], s[42:43]
	s_xor_b64 s[16:17], exec, s[16:17]
	s_cbranch_execz .LBB7_559
	s_cmpk_gt_u32 s13, 0x57f
	s_cbranch_scc1 .LBB7_559
	v_lshl_add_u64 v[78:79], s[94:95], 0, v[82:83]
	v_mov_b32_e32 v131, v1
	v_lshl_add_u64 v[78:79], v[130:131], 1, v[78:79]
	global_store_dwordx4 v[78:79], v[74:77], off offset:-768 nt
.LBB7_559:
	s_or_saveexec_b64 s[16:17], s[16:17]
	v_ashrrev_i32_e32 v0, 31, v158
	v_lshrrev_b32_e32 v0, 27, v0
	v_add_u32_e32 v0, v158, v0
	v_ashrrev_i32_e32 v80, 5, v0
	v_and_b32_e32 v0, 0xfffffe0, v0
	v_sub_u32_e32 v0, v158, v0
	v_lshlrev_b32_e32 v78, 4, v0
	v_ashrrev_i32_e32 v79, 31, v78
	s_xor_b64 exec, exec, s[16:17]
	s_cbranch_execz .LBB7_561
	v_lshlrev_b32_e32 v0, 6, v130
	v_and_b32_e32 v0, 0xffffdc00, v0
	v_add_u32_e32 v0, v80, v0
	v_mov_b64_e32 v[86:87], s[70:71]
	v_mad_i64_i32 v[86:87], s[28:29], v0, s58, v[86:87]
	v_lshl_add_u64 v[86:87], v[78:79], 1, v[86:87]
	v_lshlrev_b32_e32 v0, 1, v142
	v_lshl_add_u64 v[86:87], v[86:87], 0, v[0:1]
	global_store_dwordx4 v[86:87], v[74:77], off offset:256 nt
.LBB7_561:
	s_or_b64 exec, exec, s[16:17]
	v_mov_b32_e32 v85, v84
	v_mov_b32_e32 v74, v84
	v_mov_b32_e32 v75, v84
	v_pk_mul_f32 v[72:73], v[72:73], v[74:75]
	v_pk_mul_f32 v[74:75], v[68:69], v[74:75]
	v_pk_mul_f32 v[68:69], v[66:67], v[84:85]
	v_pk_mul_f32 v[70:71], v[70:71], v[84:85]
	s_nop 0
	v_cvt_pk_bf16_f32 v66, v70, v71
	v_cvt_pk_bf16_f32 v67, v72, v73
	v_cvt_pk_bf16_f32 v68, v68, v69
	v_cvt_pk_bf16_f32 v69, v74, v75
	s_and_saveexec_b64 s[16:17], vcc
	s_xor_b64 s[16:17], exec, s[16:17]
	s_cbranch_execz .LBB7_564
	s_cmpk_gt_u32 s15, 0x57f
	s_cbranch_scc1 .LBB7_564
	v_lshl_add_u64 v[70:71], s[94:95], 0, v[82:83]
	v_add_u32_e32 v0, s10, v194
	v_lshl_add_u64 v[70:71], v[0:1], 1, v[70:71]
	global_store_dwordx4 v[70:71], v[66:69], off offset:-512 nt
.LBB7_564:
	s_andn2_saveexec_b64 s[16:17], s[16:17]
	s_cbranch_execz .LBB7_566
	v_lshlrev_b32_e32 v0, 6, v122
	v_and_b32_e32 v0, 0xfffffc00, v0
	v_add_u32_e32 v0, v0, v80
	v_mov_b64_e32 v[70:71], s[70:71]
	v_mad_i64_i32 v[70:71], s[28:29], v0, s58, v[70:71]
	v_lshl_add_u64 v[70:71], v[78:79], 1, v[70:71]
	v_lshlrev_b32_e32 v0, 1, v142
	v_lshl_add_u64 v[70:71], v[70:71], 0, v[0:1]
	global_store_dwordx4 v[70:71], v[66:69], off offset:256 nt
.LBB7_566:
	s_or_b64 exec, exec, s[16:17]
	s_nop 0
	v_pk_add_f32 v[66:67], v[160:161], v[174:175]
	v_lshlrev_b64 v[68:69], 11, v[156:157]
	v_pk_fma_f32 v[66:67], v[66:67], s[26:27], v[162:163] op_sel_hi:[1,0,0]
	s_nop 0
	v_mul_f32_e32 v0, 0x4b800000, v67
	v_cmp_gt_f32_e64 s[48:49], s11, v67
	v_cmp_gt_f32_e64 s[44:45], s11, v66
	s_nop 0
	v_cndmask_b32_e64 v0, v67, v0, s[48:49]
	v_rsq_f32_e32 v0, v0
	s_nop 0
	v_mul_f32_e32 v67, 0x45800000, v0
	v_cndmask_b32_e64 v70, v0, v67, s[48:49]
	v_pk_mul_f32 v[72:73], v[60:61], v[70:71] op_sel_hi:[1,0]
	v_pk_mul_f32 v[60:61], v[58:59], v[70:71] op_sel_hi:[1,0]
	v_pk_mul_f32 v[64:65], v[64:65], v[70:71] op_sel_hi:[1,0]
	v_pk_mul_f32 v[62:63], v[62:63], v[70:71] op_sel_hi:[1,0]
	s_nop 0
	v_cvt_pk_bf16_f32 v58, v62, v63
	v_cvt_pk_bf16_f32 v59, v64, v65
	v_cvt_pk_bf16_f32 v60, v60, v61
	v_cvt_pk_bf16_f32 v61, v72, v73
	s_and_saveexec_b64 s[16:17], s[42:43]
	s_xor_b64 s[16:17], exec, s[16:17]
	s_cbranch_execz .LBB7_569
	s_cmpk_gt_u32 s13, 0x57f
	s_cbranch_scc1 .LBB7_569
	v_lshl_add_u64 v[62:63], s[94:95], 0, v[68:69]
	v_mov_b32_e32 v131, v1
	v_lshl_add_u64 v[62:63], v[130:131], 1, v[62:63]
	global_store_dwordx4 v[62:63], v[58:61], off offset:-768 nt
.LBB7_569:
	s_or_saveexec_b64 s[16:17], s[16:17]
	v_ashrrev_i32_e32 v0, 31, v156
	v_lshrrev_b32_e32 v0, 27, v0
	v_add_u32_e32 v0, v156, v0
	v_ashrrev_i32_e32 v64, 5, v0
	v_and_b32_e32 v0, 0xfffffe0, v0
	v_sub_u32_e32 v0, v156, v0
	v_lshlrev_b32_e32 v62, 4, v0
	v_ashrrev_i32_e32 v63, 31, v62
	s_xor_b64 exec, exec, s[16:17]
	s_cbranch_execz .LBB7_571
	v_lshlrev_b32_e32 v0, 6, v130
	v_and_b32_e32 v0, 0xffffdc00, v0
	v_add_u32_e32 v0, v64, v0
	v_mov_b64_e32 v[72:73], s[70:71]
	v_mad_i64_i32 v[72:73], s[28:29], v0, s58, v[72:73]
	v_lshl_add_u64 v[72:73], v[62:63], 1, v[72:73]
	v_lshlrev_b32_e32 v0, 1, v142
	v_lshl_add_u64 v[72:73], v[72:73], 0, v[0:1]
	global_store_dwordx4 v[72:73], v[58:61], off offset:256 nt
.LBB7_571:
	s_or_b64 exec, exec, s[16:17]
	v_mov_b32_e32 v71, v70
	v_mov_b32_e32 v58, v70
	v_mov_b32_e32 v59, v70
	v_pk_mul_f32 v[56:57], v[56:57], v[58:59]
	v_pk_mul_f32 v[58:59], v[52:53], v[58:59]
	v_pk_mul_f32 v[52:53], v[50:51], v[70:71]
	v_pk_mul_f32 v[54:55], v[54:55], v[70:71]
	s_nop 0
	v_cvt_pk_bf16_f32 v50, v54, v55
	v_cvt_pk_bf16_f32 v51, v56, v57
	v_cvt_pk_bf16_f32 v52, v52, v53
	v_cvt_pk_bf16_f32 v53, v58, v59
	s_and_saveexec_b64 s[16:17], vcc
	s_xor_b64 s[16:17], exec, s[16:17]
	s_cbranch_execz .LBB7_574
	s_cmpk_gt_u32 s15, 0x57f
	s_cbranch_scc1 .LBB7_574
	v_lshl_add_u64 v[54:55], s[94:95], 0, v[68:69]
	v_add_u32_e32 v0, s10, v194
	v_lshl_add_u64 v[54:55], v[0:1], 1, v[54:55]
	global_store_dwordx4 v[54:55], v[50:53], off offset:-512 nt
.LBB7_574:
	s_andn2_saveexec_b64 s[16:17], s[16:17]
	s_cbranch_execz .LBB7_576
	v_lshlrev_b32_e32 v0, 6, v122
	v_and_b32_e32 v0, 0xfffffc00, v0
	v_add_u32_e32 v0, v0, v64
	v_mov_b64_e32 v[54:55], s[70:71]
	v_mad_i64_i32 v[54:55], s[28:29], v0, s58, v[54:55]
	v_lshl_add_u64 v[54:55], v[62:63], 1, v[54:55]
	v_lshlrev_b32_e32 v0, 1, v142
	v_lshl_add_u64 v[54:55], v[54:55], 0, v[0:1]
	global_store_dwordx4 v[54:55], v[50:53], off offset:256 nt
.LBB7_576:
	s_or_b64 exec, exec, s[16:17]
	v_mul_f32_e32 v0, 0x4b800000, v66
	v_cndmask_b32_e64 v0, v66, v0, s[44:45]
	v_rsq_f32_e32 v0, v0
	v_lshlrev_b64 v[50:51], 11, v[154:155]
	v_mul_f32_e32 v52, 0x45800000, v0
	v_cndmask_b32_e64 v52, v0, v52, s[44:45]
	v_pk_mul_f32 v[54:55], v[44:45], v[52:53] op_sel_hi:[1,0]
	v_pk_mul_f32 v[44:45], v[42:43], v[52:53] op_sel_hi:[1,0]
	v_pk_mul_f32 v[48:49], v[48:49], v[52:53] op_sel_hi:[1,0]
	v_pk_mul_f32 v[46:47], v[46:47], v[52:53] op_sel_hi:[1,0]
	s_nop 0
	v_cvt_pk_bf16_f32 v42, v46, v47
	v_cvt_pk_bf16_f32 v43, v48, v49
	v_cvt_pk_bf16_f32 v44, v44, v45
	v_cvt_pk_bf16_f32 v45, v54, v55
	s_and_saveexec_b64 s[16:17], s[42:43]
	s_xor_b64 s[16:17], exec, s[16:17]
	s_cbranch_execz .LBB7_579
	s_cmpk_gt_u32 s13, 0x57f
	s_cbranch_scc1 .LBB7_579
	v_lshl_add_u64 v[46:47], s[94:95], 0, v[50:51]
	v_mov_b32_e32 v131, v1
	v_lshl_add_u64 v[46:47], v[130:131], 1, v[46:47]
	global_store_dwordx4 v[46:47], v[42:45], off offset:-768 nt

.LBB7_679:
	v_lshl_add_u32 v82, s55, 8, v78
	v_ashrrev_i32_e32 v83, 31, v82
	v_lshlrev_b64 v[84:85], 9, v[82:83]
	v_lshl_add_u64 v[84:85], v[72:73], 0, v[84:85]
	global_store_dwordx4 v[84:85], v[62:65], off nt
	global_store_dwordx4 v[84:85], v[58:61], off offset:64 nt
	s_mov_b32 s29, 0x10000
	s_mov_b64 s[42:43], 0x10000
	v_or_b32_e32 v58, 16, v82
	v_ashrrev_i32_e32 v59, 31, v58
	v_lshlrev_b64 v[58:59], 9, v[58:59]
	v_lshl_add_u64 v[58:59], v[72:73], 0, v[58:59]
	global_store_dwordx4 v[58:59], v[54:57], off nt
	global_store_dwordx4 v[58:59], v[50:53], off offset:64 nt
	s_nop 1
	v_or_b32_e32 v50, 32, v82
	v_ashrrev_i32_e32 v51, 31, v50
	v_lshlrev_b64 v[50:51], 9, v[50:51]
	v_lshl_add_u64 v[50:51], v[72:73], 0, v[50:51]
	global_store_dwordx4 v[50:51], v[46:49], off nt
	global_store_dwordx4 v[50:51], v[42:45], off offset:64 nt
	s_nop 1
	v_or_b32_e32 v42, 48, v82
	v_ashrrev_i32_e32 v43, 31, v42
	v_lshlrev_b64 v[42:43], 9, v[42:43]
	v_lshl_add_u64 v[42:43], v[72:73], 0, v[42:43]
	global_store_dwordx4 v[42:43], v[38:41], off nt
	global_store_dwordx4 v[42:43], v[34:37], off offset:64 nt
	s_nop 1
	v_add_co_u32_e32 v36, vcc, s29, v84
	s_mov_b32 s29, 0x12000
	s_nop 0
	v_addc_co_u32_e32 v37, vcc, 0, v85, vcc
	v_lshl_add_u64 v[34:35], v[84:85], 0, s[42:43]
	global_store_dwordx4 v[36:37], v[30:33], off nt
	global_store_dwordx4 v[34:35], v[26:29], off offset:64 nt
	s_mov_b64 s[42:43], 0x12000
	s_nop 0
	v_add_co_u32_e32 v28, vcc, s29, v84
	s_mov_b32 s29, 0x14000
	s_nop 0
	v_addc_co_u32_e32 v29, vcc, 0, v85, vcc
	v_lshl_add_u64 v[26:27], v[84:85], 0, s[42:43]
	global_store_dwordx4 v[28:29], v[22:25], off nt
	global_store_dwordx4 v[26:27], v[18:21], off offset:64 nt
	s_mov_b64 s[42:43], 0x14000
	s_nop 0
	v_add_co_u32_e32 v20, vcc, s29, v84
	v_lshl_add_u64 v[18:19], v[84:85], 0, s[42:43]
	s_nop 0
	v_addc_co_u32_e32 v21, vcc, 0, v85, vcc
	global_store_dwordx4 v[20:21], v[14:17], off nt
	global_store_dwordx4 v[18:19], v[10:13], off offset:64 nt
	s_mov_b64 s[42:43], 0x16000
	s_nop 0
	v_add_co_u32_e32 v12, vcc, 0x16000, v84
	v_lshl_add_u64 v[10:11], v[84:85], 0, s[42:43]
	s_nop 0
	v_addc_co_u32_e32 v13, vcc, 0, v85, vcc
	s_andn2_b64 vcc, exec, s[40:41]
	s_mov_b64 s[40:41], -1
	global_store_dwordx4 v[12:13], v[6:9], off nt
	global_store_dwordx4 v[10:11], v[2:5], off offset:64 nt
	s_cbranch_vccnz .LBB7_671
	s_andn2_b64 vcc, exec, s[0:1]
	s_cbranch_vccnz .LBB7_670
	s_barrier
	s_branch .LBB7_670

.LBB7_687:
	s_or_b64 exec, exec, s[18:19]
	v_lshl_add_u32 v0, v10, 9, v7
	v_mov_b64_e32 v[10:11], s[8:9]
	v_mad_i64_i32 v[10:11], s[4:5], v0, s58, v[10:11]
	v_ashrrev_i32_e32 v7, 31, v6
	v_lshl_add_u64 v[6:7], v[6:7], 1, v[10:11]
	global_store_dwordx4 v[6:7], v[2:5], off offset:256 nt

.LBB7_694:
	v_ashrrev_i32_e32 v6, 31, v0
	v_lshrrev_b32_e32 v7, 23, v6
	v_lshrrev_b32_e32 v6, 19, v6
	s_load_dwordx2 s[4:5], s[42:43], 0x58
	v_ashrrev_i32_e32 v3, 4, v0
	v_add_u32_e32 v6, v0, v6
	v_add_u32_e32 v7, v3, v7
	v_ashrrev_i32_e32 v33, 13, v6
	v_and_b32_e32 v7, 0xfffffe00, v7
	v_add_u32_e32 v6, s56, v33
	v_sub_u32_e32 v3, v3, v7
	v_ashrrev_i32_e32 v7, 31, v6
	s_waitcnt lgkmcnt(0)
	v_lshl_add_u64 v[8:9], v[6:7], 2, s[4:5]
	global_load_dword v8, v[8:9], off
	v_lshlrev_b32_e32 v28, 6, v6
	v_ashrrev_i32_e32 v10, 4, v3
	v_lshlrev_b64 v[6:7], 10, v[6:7]
	s_movk_i32 s3, 0x3c0
	v_or_b32_e32 v22, v28, v2
	v_ashrrev_i32_e32 v23, 31, v22
	v_add_u32_e32 v0, s88, v0
	s_waitcnt vmcnt(0)
	v_mul_f32_e32 v9, 0x3fb8aa3b, v8
	v_fma_f32 v11, v8, s33, -v9
	v_rndne_f32_e32 v12, v9
	v_fmac_f32_e32 v11, 0x32a5705f, v8
	v_sub_f32_e32 v9, v9, v12
	v_add_f32_e32 v9, v9, v11
	v_exp_f32_e32 v9, v9
	v_cvt_i32_f32_e32 v11, v12
	v_cmp_ngt_f32_e64 s[40:41], s10, v8
	v_ldexp_f32 v9, v9, v11
	s_nop 0
	v_cndmask_b32_e64 v9, 0, v9, s[40:41]
	v_cmp_nlt_f32_e64 s[40:41], s20, v8
	v_lshlrev_b32_e32 v8, 6, v3
	v_and_or_b32 v6, v8, s3, v6
	v_add_u32_e32 v8, 1, v10
	v_cndmask_b32_e64 v37, v203, v9, s[40:41]
	v_cvt_f32_i32_e32 v42, v8
	v_lshlrev_b64 v[8:9], 2, v[22:23]
	v_lshl_add_u64 v[10:11], s[48:49], 0, v[8:9]
	global_load_dword v23, v[10:11], off
	v_lshl_add_u64 v[8:9], s[50:51], 0, v[8:9]
	global_load_dword v25, v[8:9], off
	v_or_b32_e32 v6, v6, v2
	v_lshlrev_b64 v[14:15], 2, v[6:7]
	v_lshl_add_u64 v[10:11], s[52:53], 0, v[14:15]
	v_lshl_add_u64 v[18:19], s[54:55], 0, v[14:15]
	global_load_dwordx4 v[6:9], v[10:11], off offset:16
	s_nop 0
	global_load_dwordx4 v[10:13], v[10:11], off
	s_nop 0
	global_load_dwordx4 v[14:17], v[18:19], off offset:16
	s_nop 0
	global_load_dwordx4 v[18:21], v[18:19], off
	s_mov_b32 s3, 0x2ffff
	v_lshl_add_u32 v3, v33, 9, v3
	v_cmp_lt_i32_e64 s[40:41], s3, v0
	s_or_b64 s[8:9], s[40:41], s[8:9]
	s_waitcnt vmcnt(5)
	v_mul_f32_e32 v23, v37, v23
	v_mul_f32_e32 v23, v23, v42
	v_mul_f32_e32 v23, 0x3fb8aa3b, v23
	v_exp_f32_e32 v24, v23
	s_waitcnt vmcnt(4)
	v_mul_f32_e32 v23, v37, v25
	v_mul_f32_e32 v23, 0.15915494, v23
	v_mul_f32_e32 v23, v23, v42
	v_fract_f32_e32 v23, v23
	v_cos_f32_e32 v26, v23
	v_sin_f32_e32 v27, v23
	s_nop 0
	v_pk_mul_f32 v[24:25], v[24:25], v[26:27] op_sel_hi:[0,1]
	s_waitcnt vmcnt(0)
	v_mov_b32_e32 v26, v18
	v_mov_b32_e32 v27, v10
	v_pk_mul_f32 v[26:27], v[26:27], v[24:25]
	s_nop 0
	v_add_f32_e32 v23, v27, v26
	v_mov_b32_e32 v26, v10
	v_mov_b32_e32 v27, v18
	v_pk_mul_f32 v[24:25], v[26:27], v[24:25]
	s_nop 0
	v_sub_f32_e32 v10, v24, v25
	v_cndmask_b32_e64 v43, v10, -v23, vcc
	v_ashrrev_i32_e32 v23, 31, v28
	v_lshlrev_b64 v[26:27], 2, v[22:23]
	v_lshl_add_u64 v[22:23], s[48:49], 0, v[26:27]
	v_lshl_add_u64 v[26:27], s[50:51], 0, v[26:27]
	global_load_dwordx3 v[30:32], v[22:23], off offset:20
	s_nop 0
	global_load_dwordx4 v[22:25], v[22:23], off offset:4
	s_nop 0
	global_load_dwordx3 v[34:36], v[26:27], off offset:20
	s_nop 0
	global_load_dwordx4 v[26:29], v[26:27], off offset:4
	s_waitcnt vmcnt(2)
	v_mul_f32_e32 v10, v37, v22
	s_waitcnt vmcnt(0)
	v_mul_f32_e32 v18, v37, v26
	v_mul_f32_e32 v18, 0.15915494, v18
	v_mul_f32_e32 v10, v10, v42
	v_mul_f32_e32 v18, v18, v42
	v_mul_f32_e32 v10, 0x3fb8aa3b, v10
	v_fract_f32_e32 v18, v18
	v_exp_f32_e32 v10, v10
	v_cos_f32_e32 v38, v18
	v_sin_f32_e32 v39, v18
	v_mov_b32_e32 v18, v11
	v_pk_mul_f32 v[38:39], v[10:11], v[38:39] op_sel_hi:[0,1]
	v_mov_b32_e32 v10, v19
	v_pk_mul_f32 v[40:41], v[10:11], v[38:39]
	v_pk_mul_f32 v[10:11], v[18:19], v[38:39]
	v_add_f32_e32 v22, v41, v40
	v_sub_f32_e32 v10, v10, v11
	v_mul_f32_e32 v11, v37, v27
	v_cndmask_b32_e64 v22, v10, -v22, vcc
	v_mul_f32_e32 v10, v37, v23
	v_mul_f32_e32 v11, 0.15915494, v11
	v_mul_f32_e32 v10, v10, v42
	v_mul_f32_e32 v11, v11, v42
	v_mul_f32_e32 v10, 0x3fb8aa3b, v10
	v_fract_f32_e32 v11, v11
	v_exp_f32_e32 v10, v10
	v_cos_f32_e32 v18, v11
	v_sin_f32_e32 v19, v11
	s_nop 0
	v_pk_mul_f32 v[10:11], v[10:11], v[18:19] op_sel_hi:[0,1]
	v_mov_b32_e32 v18, v20
	v_mov_b32_e32 v19, v12
	v_pk_mul_f32 v[18:19], v[18:19], v[10:11]
	s_nop 0
	v_add_f32_e32 v23, v19, v18
	v_mov_b32_e32 v18, v12
	v_mov_b32_e32 v19, v20
	v_pk_mul_f32 v[10:11], v[18:19], v[10:11]
	v_mov_b32_e32 v12, v21
	v_sub_f32_e32 v10, v10, v11
	v_mul_f32_e32 v11, v37, v28
	v_cndmask_b32_e64 v23, v10, -v23, vcc
	v_mul_f32_e32 v10, v37, v24
	v_mul_f32_e32 v11, 0.15915494, v11
	v_mul_f32_e32 v10, v10, v42
	v_mul_f32_e32 v11, v11, v42
	v_mul_f32_e32 v10, 0x3fb8aa3b, v10
	v_fract_f32_e32 v11, v11
	v_exp_f32_e32 v10, v10
	v_cos_f32_e32 v18, v11
	v_sin_f32_e32 v19, v11
	v_mov_b32_e32 v20, v13
	v_pk_mul_f32 v[10:11], v[10:11], v[18:19] op_sel_hi:[0,1]
	v_pk_mul_f32 v[18:19], v[12:13], v[10:11]
	v_pk_mul_f32 v[10:11], v[20:21], v[10:11]
	v_add_f32_e32 v12, v19, v18
	v_sub_f32_e32 v10, v10, v11
	v_mul_f32_e32 v11, v37, v29
	v_cndmask_b32_e64 v18, v10, -v12, vcc
	v_mul_f32_e32 v10, v37, v25
	v_mul_f32_e32 v11, 0.15915494, v11
	v_mul_f32_e32 v10, v10, v42
	v_mul_f32_e32 v11, v11, v42
	v_mul_f32_e32 v10, 0x3fb8aa3b, v10
	v_fract_f32_e32 v11, v11
	v_exp_f32_e32 v10, v10
	v_cos_f32_e32 v12, v11
	v_sin_f32_e32 v13, v11
	s_nop 0
	v_pk_mul_f32 v[10:11], v[10:11], v[12:13] op_sel_hi:[0,1]
	v_mov_b32_e32 v12, v14
	v_mov_b32_e32 v13, v6
	v_pk_mul_f32 v[12:13], v[12:13], v[10:11]
	s_nop 0
	v_add_f32_e32 v19, v13, v12
	v_mov_b32_e32 v12, v6
	v_mov_b32_e32 v13, v14
	v_pk_mul_f32 v[10:11], v[12:13], v[10:11]
	v_mov_b32_e32 v14, v7
	v_sub_f32_e32 v6, v10, v11
	v_mul_f32_e32 v10, v37, v34
	v_cndmask_b32_e64 v19, v6, -v19, vcc
	v_mul_f32_e32 v6, v37, v30
	v_mul_f32_e32 v10, 0.15915494, v10
	v_mul_f32_e32 v6, v6, v42
	v_mul_f32_e32 v10, v10, v42
	v_mul_f32_e32 v6, 0x3fb8aa3b, v6
	v_fract_f32_e32 v11, v10
	v_exp_f32_e32 v6, v6
	v_cos_f32_e32 v10, v11
	v_sin_f32_e32 v11, v11
	s_nop 0
	v_pk_mul_f32 v[10:11], v[6:7], v[10:11] op_sel_hi:[0,1]
	v_mov_b32_e32 v6, v15
	v_pk_mul_f32 v[12:13], v[6:7], v[10:11]
	v_pk_mul_f32 v[6:7], v[14:15], v[10:11]
	v_add_f32_e32 v12, v13, v12
	v_sub_f32_e32 v6, v6, v7
	v_mul_f32_e32 v7, v37, v35
	v_cndmask_b32_e64 v12, v6, -v12, vcc
	v_mul_f32_e32 v6, v37, v31
	v_mul_f32_e32 v7, 0.15915494, v7
	v_mul_f32_e32 v6, v6, v42
	v_mul_f32_e32 v7, v7, v42
	v_mul_f32_e32 v6, 0x3fb8aa3b, v6
	v_fract_f32_e32 v7, v7
	v_exp_f32_e32 v6, v6
	v_cos_f32_e32 v10, v7
	v_sin_f32_e32 v11, v7
	s_nop 0
	v_pk_mul_f32 v[6:7], v[6:7], v[10:11] op_sel_hi:[0,1]
	v_mov_b32_e32 v10, v16
	v_mov_b32_e32 v11, v8
	v_pk_mul_f32 v[10:11], v[10:11], v[6:7]
	s_nop 0
	v_add_f32_e32 v13, v11, v10
	v_mov_b32_e32 v10, v8
	v_mov_b32_e32 v11, v16
	v_pk_mul_f32 v[6:7], v[10:11], v[6:7]
	v_mov_b32_e32 v8, v17
	v_sub_f32_e32 v6, v6, v7
	v_mul_f32_e32 v7, v37, v36
	v_cndmask_b32_e64 v13, v6, -v13, vcc
	v_mul_f32_e32 v6, v37, v32
	v_mul_f32_e32 v7, 0.15915494, v7
	v_mul_f32_e32 v6, v6, v42
	v_mul_f32_e32 v7, v7, v42
	v_mul_f32_e32 v6, 0x3fb8aa3b, v6
	v_fract_f32_e32 v7, v7
	v_exp_f32_e32 v6, v6
	v_cos_f32_e32 v10, v7
	v_sin_f32_e32 v11, v7
	v_mov_b32_e32 v16, v9
	v_pk_mul_f32 v[6:7], v[6:7], v[10:11] op_sel_hi:[0,1]
	v_pk_mul_f32 v[10:11], v[8:9], v[6:7]
	v_pk_mul_f32 v[6:7], v[16:17], v[6:7]
	v_add_f32_e32 v8, v11, v10
	v_sub_f32_e32 v6, v6, v7
	v_cndmask_b32_e64 v9, v6, -v8, vcc
	v_mad_i64_i32 v[10:11], s[4:5], v3, s58, v[4:5]
	v_cvt_pk_bf16_f32 v6, v43, v22
	v_cvt_pk_bf16_f32 v7, v23, v18
	v_cvt_pk_bf16_f32 v8, v19, v12
	v_cvt_pk_bf16_f32 v9, v13, v9
	global_store_dwordx4 v[10:11], v[6:9], off nt
	s_andn2_b64 exec, exec, s[8:9]
	s_cbranch_execnz .LBB7_694

.LBB7_699:
	s_or_b64 exec, exec, s[12:13]
	v_add_u32_e32 v10, 8, v206
	v_min_u32_e32 v10, v10, v180
	v_cvt_f32_ubyte0_e32 v10, v10
	v_div_scale_f32 v11, s[4:5], v10, v10, 1.0
	v_rcp_f32_e32 v12, v11
	v_div_scale_f32 v13, vcc, 1.0, v10, 1.0
	v_lshlrev_b32_e32 v16, 16, v20
	v_fma_f32 v14, -v11, v12, 1.0
	v_fmac_f32_e32 v12, v14, v12
	v_mul_f32_e32 v14, v13, v12
	v_fma_f32 v15, -v11, v14, v13
	v_fmac_f32_e32 v14, v15, v12
	v_fma_f32 v11, -v11, v14, v13
	v_div_fmas_f32 v11, v11, v12, v14
	v_lshlrev_b32_e32 v12, 16, v18
	v_and_b32_e32 v13, 0xffff0000, v18
	v_lshlrev_b32_e32 v14, 16, v19
	v_and_b32_e32 v15, 0xffff0000, v19
	v_pk_add_f32 v[14:15], v[24:25], v[14:15]
	v_pk_add_f32 v[12:13], v[22:23], v[12:13]
	v_div_fixup_f32 v10, v11, v10, 1.0
	v_and_b32_e32 v17, 0xffff0000, v20
	v_lshlrev_b32_e32 v18, 16, v21
	v_and_b32_e32 v19, 0xffff0000, v21
	v_sub_f32_e32 v11, v12, v22
	v_sub_f32_e32 v21, v14, v24
	v_sub_f32_e32 v22, v15, v25
	v_pk_add_f32 v[18:19], v[28:29], v[18:19]
	v_pk_add_f32 v[16:17], v[26:27], v[16:17]
	v_sub_f32_e32 v20, v13, v23
	v_sub_f32_e32 v7, v13, v7
	v_sub_f32_e32 v6, v12, v6
	v_sub_f32_e32 v9, v15, v9
	v_sub_f32_e32 v8, v14, v8
	v_xor_b32_e32 v13, 0x80000000, v22
	v_xor_b32_e32 v12, 0x80000000, v21
	v_sub_f32_e32 v23, v16, v26
	v_sub_f32_e32 v25, v18, v28
	v_sub_f32_e32 v26, v19, v29
	v_pk_fma_f32 v[8:9], v[10:11], v[8:9], v[12:13] op_sel_hi:[0,1,1]
	v_xor_b32_e32 v13, 0x80000000, v20
	v_xor_b32_e32 v12, 0x80000000, v11
	v_sub_f32_e32 v24, v17, v27
	v_pk_fma_f32 v[6:7], v[10:11], v[6:7], v[12:13] op_sel_hi:[0,1,1]
	v_sub_f32_e32 v5, v19, v5
	v_sub_f32_e32 v4, v18, v4
	v_xor_b32_e32 v13, 0x80000000, v26
	v_xor_b32_e32 v12, 0x80000000, v25
	v_sub_f32_e32 v3, v17, v3
	v_sub_f32_e32 v2, v16, v2
	v_pk_fma_f32 v[12:13], v[10:11], v[4:5], v[12:13] op_sel_hi:[0,1,1]
	v_xor_b32_e32 v5, 0x80000000, v24
	v_xor_b32_e32 v4, 0x80000000, v23
	v_add_u32_e32 v151, s88, v151
	s_mov_b32 s3, 0x1ffff
	v_pk_fma_f32 v[4:5], v[10:11], v[2:3], v[4:5] op_sel_hi:[0,1,1]
	v_cvt_pk_bf16_f32 v2, v6, v7
	v_lshl_add_u64 v[6:7], s[0:1], 0, v[152:153]
	v_cmp_lt_i32_e32 vcc, s3, v151
	v_lshl_add_u64 v[6:7], v[6:7], 0, v[0:1]
	s_or_b64 s[8:9], vcc, s[8:9]
	v_add_u32_e32 v205, s29, v205
	v_cvt_pk_bf16_f32 v3, v8, v9
	v_cvt_pk_bf16_f32 v4, v4, v5
	v_cvt_pk_bf16_f32 v5, v12, v13
	global_store_dwordx4 v[6:7], v[2:5], off offset:768 nt
	s_andn2_b64 exec, exec, s[8:9]
	s_cbranch_execz .LBB7_803

.LBB7_740:
	s_or_b64 exec, exec, s[12:13]
	v_pk_add_f32 v[64:65], v[72:73], v[178:179]
	v_pk_add_f32 v[68:69], v[76:77], v[138:139]
	s_waitcnt vmcnt(0)
	v_lshlrev_b32_e32 v138, 16, v126
	v_and_b32_e32 v139, 0xffff0000, v126
	v_lshlrev_b32_e32 v126, 16, v127
	v_and_b32_e32 v127, 0xffff0000, v127
	v_lshlrev_b32_e64 v180, v207, 2
	v_pk_add_f32 v[62:63], v[70:71], v[140:141]
	v_lshlrev_b32_e32 v170, 16, v128
	v_and_b32_e32 v171, 0xffff0000, v128
	v_lshlrev_b32_e32 v140, 16, v129
	v_and_b32_e32 v141, 0xffff0000, v129
	v_pk_add_f32 v[128:129], v[64:65], v[126:127]
	v_or_b32_e32 v126, 1, v206
	v_min_u32_e32 v126, v126, v180
	v_cvt_f32_ubyte0_e32 v172, v126
	v_div_scale_f32 v173, s[4:5], v172, v172, 1.0
	v_rcp_f32_e32 v178, v173
	v_pk_add_f32 v[66:67], v[74:75], v[66:67]
	v_pk_add_f32 v[126:127], v[62:63], v[138:139]
	v_pk_add_f32 v[138:139], v[66:67], v[170:171]
	v_fma_f32 v170, -v173, v178, 1.0
	v_fmac_f32_e32 v178, v170, v178
	v_div_scale_f32 v170, vcc, 1.0, v172, 1.0
	v_mul_f32_e32 v171, v170, v178
	v_fma_f32 v179, -v173, v171, v170
	v_fmac_f32_e32 v171, v179, v178
	v_fma_f32 v170, -v173, v171, v170
	v_div_fmas_f32 v170, v170, v178, v171
	v_sub_f32_e32 v171, v128, v64
	v_sub_f32_e32 v181, v129, v65
	v_pk_add_f32 v[140:141], v[68:69], v[140:141]
	v_div_fixup_f32 v170, v170, v172, 1.0
	v_sub_f32_e32 v184, v126, v62
	v_sub_f32_e32 v185, v127, v63
	v_sub_f32_e32 v173, v129, v209
	v_sub_f32_e32 v172, v128, v211
	v_xor_b32_e32 v183, 0x80000000, v181
	v_xor_b32_e32 v182, 0x80000000, v171
	v_sub_f32_e32 v188, v140, v68
	v_sub_f32_e32 v189, v141, v69
	v_sub_f32_e32 v179, v127, v213
	v_sub_f32_e32 v178, v126, v215
	v_pk_fma_f32 v[172:173], v[170:171], v[172:173], v[182:183] op_sel_hi:[0,1,1]
	v_xor_b32_e32 v183, 0x80000000, v185
	v_xor_b32_e32 v182, 0x80000000, v184
	v_sub_f32_e32 v190, v138, v66
	v_sub_f32_e32 v191, v139, v67
	v_pk_fma_f32 v[178:179], v[170:171], v[178:179], v[182:183] op_sel_hi:[0,1,1]
	v_sub_f32_e32 v183, v141, v210
	v_sub_f32_e32 v182, v140, v212
	v_xor_b32_e32 v189, 0x80000000, v189
	v_xor_b32_e32 v188, 0x80000000, v188
	v_sub_f32_e32 v185, v139, v214
	v_sub_f32_e32 v184, v138, v208
	v_pk_fma_f32 v[188:189], v[170:171], v[182:183], v[188:189] op_sel_hi:[0,1,1]
	v_xor_b32_e32 v183, 0x80000000, v191
	v_xor_b32_e32 v182, 0x80000000, v190
	v_pk_fma_f32 v[170:171], v[170:171], v[184:185], v[182:183] op_sel_hi:[0,1,1]
	v_cvt_pk_bf16_f32 v182, v178, v179
	v_cvt_pk_bf16_f32 v183, v172, v173
	v_cvt_pk_bf16_f32 v184, v170, v171
	v_lshl_add_u64 v[170:171], s[0:1], 0, v[186:187]
	v_lshl_add_u64 v[170:171], v[170:171], 0, v[0:1]
	v_cmp_lt_i32_e32 vcc, 1, v207
	v_cvt_pk_bf16_f32 v185, v188, v189
	global_store_dwordx4 v[170:171], v[182:185], off offset:768 nt
	s_and_saveexec_b64 s[4:5], vcc
	s_xor_b64 s[12:13], exec, s[4:5]
	s_cbranch_execz .LBB7_744
	v_cmp_gt_i32_e32 vcc, 3, v207
	s_and_saveexec_b64 s[14:15], vcc
	v_mov_b64_e32 v[34:35], v[130:131]
	v_mov_b64_e32 v[30:31], v[134:135]
	v_mov_b64_e32 v[36:37], v[132:133]
	v_mov_b64_e32 v[32:33], v[136:137]
	s_or_b64 exec, exec, s[14:15]

.LBB7_748:
	s_or_b64 exec, exec, s[12:13]
	v_or_b32_e32 v130, 2, v206
	v_min_u32_e32 v130, v130, v180
	v_cvt_f32_ubyte0_e32 v130, v130
	v_div_scale_f32 v131, s[4:5], v130, v130, 1.0
	v_rcp_f32_e32 v132, v131
	v_div_scale_f32 v133, vcc, 1.0, v130, 1.0
	v_fma_f32 v134, -v131, v132, 1.0
	v_fmac_f32_e32 v132, v134, v132
	v_mul_f32_e32 v134, v133, v132
	v_fma_f32 v135, -v131, v134, v133
	v_fmac_f32_e32 v134, v135, v132
	v_fma_f32 v131, -v131, v134, v133
	v_div_fmas_f32 v131, v131, v132, v134
	v_div_fixup_f32 v170, v131, v130, 1.0
	v_lshlrev_b32_e32 v130, 16, v122
	v_and_b32_e32 v131, 0xffff0000, v122
	v_lshlrev_b32_e32 v122, 16, v123
	v_and_b32_e32 v123, 0xffff0000, v123
	v_lshlrev_b32_e32 v134, 16, v124
	v_and_b32_e32 v135, 0xffff0000, v124
	v_pk_add_f32 v[132:133], v[128:129], v[122:123]
	v_lshlrev_b32_e32 v124, 16, v125
	v_and_b32_e32 v125, 0xffff0000, v125
	v_pk_add_f32 v[130:131], v[126:127], v[130:131]
	v_pk_add_f32 v[134:135], v[138:139], v[134:135]
	v_sub_f32_e32 v122, v132, v128
	v_sub_f32_e32 v123, v133, v129
	v_pk_add_f32 v[136:137], v[140:141], v[124:125]
	v_sub_f32_e32 v124, v130, v126
	v_sub_f32_e32 v125, v131, v127
	v_sub_f32_e32 v171, v134, v138
	v_sub_f32_e32 v37, v133, v37
	v_sub_f32_e32 v36, v132, v36
	v_xor_b32_e32 v123, 0x80000000, v123
	v_xor_b32_e32 v122, 0x80000000, v122
	v_sub_f32_e32 v173, v136, v140
	v_sub_f32_e32 v178, v137, v141
	v_sub_f32_e32 v35, v131, v35
	v_sub_f32_e32 v34, v130, v34
	v_pk_fma_f32 v[36:37], v[170:171], v[36:37], v[122:123] op_sel_hi:[0,1,1]
	v_xor_b32_e32 v123, 0x80000000, v125
	v_xor_b32_e32 v122, 0x80000000, v124
	v_sub_f32_e32 v172, v135, v139
	v_pk_fma_f32 v[34:35], v[170:171], v[34:35], v[122:123] op_sel_hi:[0,1,1]
	v_sub_f32_e32 v33, v137, v33
	v_sub_f32_e32 v32, v136, v32
	v_xor_b32_e32 v123, 0x80000000, v178
	v_xor_b32_e32 v122, 0x80000000, v173
	v_sub_f32_e32 v31, v135, v31
	v_sub_f32_e32 v30, v134, v30
	v_pk_fma_f32 v[122:123], v[170:171], v[32:33], v[122:123] op_sel_hi:[0,1,1]
	v_xor_b32_e32 v33, 0x80000000, v172
	v_xor_b32_e32 v32, 0x80000000, v171
	v_pk_fma_f32 v[32:33], v[170:171], v[30:31], v[32:33] op_sel_hi:[0,1,1]
	v_cvt_pk_bf16_f32 v30, v34, v35
	v_lshl_add_u64 v[34:35], s[0:1], 0, v[176:177]
	v_lshl_add_u64 v[34:35], v[34:35], 0, v[0:1]
	v_cmp_lt_i32_e32 vcc, 1, v207
	v_cvt_pk_bf16_f32 v31, v36, v37
	v_cvt_pk_bf16_f32 v32, v32, v33
	v_cvt_pk_bf16_f32 v33, v122, v123
	global_store_dwordx4 v[34:35], v[30:33], off offset:768 nt
	s_and_saveexec_b64 s[4:5], vcc
	s_xor_b64 s[12:13], exec, s[4:5]
	s_cbranch_execz .LBB7_752
	v_cmp_gt_i32_e32 vcc, 3, v207
	s_and_saveexec_b64 s[14:15], vcc
	v_mov_b64_e32 v[86:87], v[142:143]
	v_mov_b64_e32 v[82:83], v[146:147]
	v_mov_b64_e32 v[88:89], v[144:145]
	v_mov_b64_e32 v[84:85], v[148:149]
	s_or_b64 exec, exec, s[14:15]

.LBB7_756:
	s_or_b64 exec, exec, s[12:13]
	v_or_b32_e32 v30, 3, v206
	v_min_u32_e32 v30, v30, v180
	v_cvt_f32_ubyte0_e32 v30, v30
	v_div_scale_f32 v31, s[4:5], v30, v30, 1.0
	v_rcp_f32_e32 v32, v31
	v_div_scale_f32 v33, vcc, 1.0, v30, 1.0
	v_lshlrev_b32_e32 v36, 16, v112
	v_fma_f32 v34, -v31, v32, 1.0
	v_fmac_f32_e32 v32, v34, v32
	v_mul_f32_e32 v34, v33, v32
	v_fma_f32 v35, -v31, v34, v33
	v_fmac_f32_e32 v34, v35, v32
	v_fma_f32 v31, -v31, v34, v33
	v_div_fmas_f32 v31, v31, v32, v34
	v_lshlrev_b32_e32 v34, 16, v111
	v_and_b32_e32 v35, 0xffff0000, v111
	v_lshlrev_b32_e32 v32, 16, v110
	v_and_b32_e32 v33, 0xffff0000, v110
	v_and_b32_e32 v37, 0xffff0000, v112
	v_lshlrev_b32_e32 v124, 16, v113
	v_and_b32_e32 v125, 0xffff0000, v113
	v_pk_add_f32 v[112:113], v[132:133], v[34:35]
	v_pk_add_f32 v[110:111], v[130:131], v[32:33]
	v_pk_add_f32 v[122:123], v[134:135], v[36:37]
	v_sub_f32_e32 v36, v112, v132
	v_sub_f32_e32 v37, v113, v133
	v_div_fixup_f32 v30, v31, v30, 1.0
	v_pk_add_f32 v[124:125], v[136:137], v[124:125]
	v_sub_f32_e32 v31, v110, v130
	v_sub_f32_e32 v142, v111, v131
	v_sub_f32_e32 v35, v113, v89
	v_sub_f32_e32 v34, v112, v88
	v_xor_b32_e32 v37, 0x80000000, v37
	v_xor_b32_e32 v36, 0x80000000, v36
	v_sub_f32_e32 v145, v124, v136
	v_sub_f32_e32 v146, v125, v137
	v_sub_f32_e32 v33, v111, v87
	v_sub_f32_e32 v32, v110, v86
	v_pk_fma_f32 v[34:35], v[30:31], v[34:35], v[36:37] op_sel_hi:[0,1,1]
	v_xor_b32_e32 v37, 0x80000000, v142
	v_xor_b32_e32 v36, 0x80000000, v31
	v_sub_f32_e32 v143, v122, v134
	v_sub_f32_e32 v144, v123, v135
	v_pk_fma_f32 v[32:33], v[30:31], v[32:33], v[36:37] op_sel_hi:[0,1,1]
	v_sub_f32_e32 v37, v123, v83
	v_sub_f32_e32 v36, v122, v82
	v_sub_f32_e32 v83, v125, v85
	v_sub_f32_e32 v82, v124, v84
	v_xor_b32_e32 v85, 0x80000000, v146
	v_xor_b32_e32 v84, 0x80000000, v145
	v_pk_fma_f32 v[82:83], v[30:31], v[82:83], v[84:85] op_sel_hi:[0,1,1]
	v_xor_b32_e32 v85, 0x80000000, v144
	v_xor_b32_e32 v84, 0x80000000, v143
	v_pk_fma_f32 v[36:37], v[30:31], v[36:37], v[84:85] op_sel_hi:[0,1,1]
	v_cvt_pk_bf16_f32 v30, v32, v33
	v_cvt_pk_bf16_f32 v31, v34, v35
	v_lshl_add_u64 v[34:35], s[0:1], 0, v[174:175]
	v_lshl_add_u64 v[34:35], v[34:35], 0, v[0:1]
	v_cmp_lt_i32_e32 vcc, 1, v207
	v_cvt_pk_bf16_f32 v32, v36, v37
	v_cvt_pk_bf16_f32 v33, v82, v83
	global_store_dwordx4 v[34:35], v[30:33], off offset:768 nt
	s_and_saveexec_b64 s[4:5], vcc
	s_xor_b64 s[12:13], exec, s[4:5]
	s_cbranch_execz .LBB7_760
	v_cmp_gt_i32_e32 vcc, 3, v207
	s_and_saveexec_b64 s[14:15], vcc
	v_mov_b64_e32 v[58:59], v[114:115]
	v_mov_b64_e32 v[54:55], v[118:119]
	v_mov_b64_e32 v[60:61], v[116:117]
	v_mov_b64_e32 v[56:57], v[120:121]
	s_or_b64 exec, exec, s[14:15]

.LBB7_764:
	s_or_b64 exec, exec, s[12:13]
	v_or_b32_e32 v30, 4, v206
	v_min_u32_e32 v30, v30, v180
	v_cvt_f32_ubyte0_e32 v30, v30
	v_div_scale_f32 v31, s[4:5], v30, v30, 1.0
	v_rcp_f32_e32 v32, v31
	v_div_scale_f32 v33, vcc, 1.0, v30, 1.0
	v_lshlrev_b32_e32 v36, 16, v101
	v_fma_f32 v34, -v31, v32, 1.0
	v_fmac_f32_e32 v32, v34, v32
	v_mul_f32_e32 v34, v33, v32
	v_fma_f32 v35, -v31, v34, v33
	v_fmac_f32_e32 v34, v35, v32
	v_fma_f32 v31, -v31, v34, v33
	v_div_fmas_f32 v31, v31, v32, v34
	v_lshlrev_b32_e32 v32, 16, v99
	v_and_b32_e32 v33, 0xffff0000, v99
	v_div_fixup_f32 v82, v31, v30, 1.0
	v_lshlrev_b32_e32 v30, 16, v98
	v_and_b32_e32 v31, 0xffff0000, v98
	v_pk_add_f32 v[32:33], v[112:113], v[32:33]
	v_and_b32_e32 v37, 0xffff0000, v101
	v_pk_add_f32 v[30:31], v[110:111], v[30:31]
	v_sub_f32_e32 v84, v32, v112
	v_sub_f32_e32 v85, v33, v113
	v_lshlrev_b32_e32 v34, 16, v100
	v_and_b32_e32 v35, 0xffff0000, v100
	v_pk_add_f32 v[36:37], v[124:125], v[36:37]
	v_sub_f32_e32 v83, v30, v110
	v_sub_f32_e32 v86, v31, v111
	v_sub_f32_e32 v61, v33, v61
	v_sub_f32_e32 v60, v32, v60
	v_xor_b32_e32 v85, 0x80000000, v85
	v_xor_b32_e32 v84, 0x80000000, v84
	v_pk_add_f32 v[34:35], v[122:123], v[34:35]
	v_sub_f32_e32 v89, v36, v124
	v_sub_f32_e32 v98, v37, v125
	v_sub_f32_e32 v59, v31, v59
	v_sub_f32_e32 v58, v30, v58
	v_pk_fma_f32 v[60:61], v[82:83], v[60:61], v[84:85] op_sel_hi:[0,1,1]
	v_xor_b32_e32 v85, 0x80000000, v86
	v_xor_b32_e32 v84, 0x80000000, v83
	v_sub_f32_e32 v87, v34, v122
	v_sub_f32_e32 v88, v35, v123
	v_pk_fma_f32 v[58:59], v[82:83], v[58:59], v[84:85] op_sel_hi:[0,1,1]
	v_sub_f32_e32 v57, v37, v57
	v_sub_f32_e32 v56, v36, v56
	v_xor_b32_e32 v85, 0x80000000, v98
	v_xor_b32_e32 v84, 0x80000000, v89
	v_sub_f32_e32 v55, v35, v55
	v_sub_f32_e32 v54, v34, v54
	v_pk_fma_f32 v[84:85], v[82:83], v[56:57], v[84:85] op_sel_hi:[0,1,1]
	v_xor_b32_e32 v57, 0x80000000, v88
	v_xor_b32_e32 v56, 0x80000000, v87
	v_pk_fma_f32 v[56:57], v[82:83], v[54:55], v[56:57] op_sel_hi:[0,1,1]
	v_cvt_pk_bf16_f32 v54, v58, v59
	v_lshl_add_u64 v[58:59], s[0:1], 0, v[160:161]
	v_lshl_add_u64 v[58:59], v[58:59], 0, v[0:1]
	v_cmp_lt_i32_e32 vcc, 1, v207
	v_cvt_pk_bf16_f32 v55, v60, v61
	v_cvt_pk_bf16_f32 v56, v56, v57
	v_cvt_pk_bf16_f32 v57, v84, v85
	global_store_dwordx4 v[58:59], v[54:57], off offset:768 nt
	s_and_saveexec_b64 s[4:5], vcc
	s_xor_b64 s[12:13], exec, s[4:5]
	s_cbranch_execz .LBB7_768
	v_cmp_gt_i32_e32 vcc, 3, v207
	s_and_saveexec_b64 s[14:15], vcc
	v_mov_b64_e32 v[46:47], v[102:103]
	v_mov_b64_e32 v[42:43], v[106:107]
	v_mov_b64_e32 v[48:49], v[104:105]
	v_mov_b64_e32 v[44:45], v[108:109]
	s_or_b64 exec, exec, s[14:15]

.LBB7_774:
	s_or_b64 exec, exec, s[12:13]
	v_or_b32_e32 v54, 5, v206
	v_min_u32_e32 v54, v54, v180
	v_cvt_f32_ubyte0_e32 v54, v54
	v_div_scale_f32 v55, s[4:5], v54, v54, 1.0
	v_rcp_f32_e32 v56, v55
	v_div_scale_f32 v57, vcc, 1.0, v54, 1.0
	v_lshlrev_b32_e32 v60, 16, v81
	v_fma_f32 v58, -v55, v56, 1.0
	v_fmac_f32_e32 v56, v58, v56
	v_mul_f32_e32 v58, v57, v56
	v_fma_f32 v59, -v55, v58, v57
	v_fmac_f32_e32 v58, v59, v56
	v_fma_f32 v55, -v55, v58, v57
	v_div_fmas_f32 v55, v55, v56, v58
	v_lshlrev_b32_e32 v56, 16, v79
	v_and_b32_e32 v57, 0xffff0000, v79
	v_div_fixup_f32 v82, v55, v54, 1.0
	v_lshlrev_b32_e32 v54, 16, v78
	v_and_b32_e32 v55, 0xffff0000, v78
	v_lshlrev_b32_e32 v58, 16, v80
	v_and_b32_e32 v59, 0xffff0000, v80
	v_pk_add_f32 v[56:57], v[32:33], v[56:57]
	v_and_b32_e32 v61, 0xffff0000, v81
	v_pk_add_f32 v[54:55], v[30:31], v[54:55]
	v_pk_add_f32 v[58:59], v[34:35], v[58:59]
	v_sub_f32_e32 v78, v56, v32
	v_sub_f32_e32 v79, v57, v33
	v_pk_add_f32 v[60:61], v[36:37], v[60:61]
	v_sub_f32_e32 v80, v54, v30
	v_sub_f32_e32 v81, v55, v31
	v_sub_f32_e32 v83, v58, v34
	v_sub_f32_e32 v49, v57, v49
	v_sub_f32_e32 v48, v56, v48
	v_xor_b32_e32 v79, 0x80000000, v79
	v_xor_b32_e32 v78, 0x80000000, v78
	v_sub_f32_e32 v85, v60, v36
	v_sub_f32_e32 v86, v61, v37
	v_sub_f32_e32 v47, v55, v47
	v_sub_f32_e32 v46, v54, v46
	v_pk_fma_f32 v[48:49], v[82:83], v[48:49], v[78:79] op_sel_hi:[0,1,1]
	v_xor_b32_e32 v79, 0x80000000, v81
	v_xor_b32_e32 v78, 0x80000000, v80
	v_sub_f32_e32 v84, v59, v35
	v_pk_fma_f32 v[46:47], v[82:83], v[46:47], v[78:79] op_sel_hi:[0,1,1]
	v_sub_f32_e32 v45, v61, v45
	v_sub_f32_e32 v44, v60, v44
	v_xor_b32_e32 v79, 0x80000000, v86
	v_xor_b32_e32 v78, 0x80000000, v85
	v_sub_f32_e32 v43, v59, v43
	v_sub_f32_e32 v42, v58, v42
	v_pk_fma_f32 v[78:79], v[82:83], v[44:45], v[78:79] op_sel_hi:[0,1,1]
	v_xor_b32_e32 v45, 0x80000000, v84
	v_xor_b32_e32 v44, 0x80000000, v83
	v_pk_fma_f32 v[44:45], v[82:83], v[42:43], v[44:45] op_sel_hi:[0,1,1]
	v_cvt_pk_bf16_f32 v42, v46, v47
	v_lshl_add_u64 v[46:47], s[0:1], 0, v[158:159]
	v_lshl_add_u64 v[46:47], v[46:47], 0, v[0:1]
	v_cmp_lt_i32_e32 vcc, 1, v207
	v_cvt_pk_bf16_f32 v43, v48, v49
	v_cvt_pk_bf16_f32 v44, v44, v45
	v_cvt_pk_bf16_f32 v45, v78, v79
	global_store_dwordx4 v[46:47], v[42:45], off offset:768 nt
	s_and_saveexec_b64 s[4:5], vcc
	s_xor_b64 s[12:13], exec, s[4:5]
	s_cbranch_execz .LBB7_778
	v_cmp_gt_i32_e32 vcc, 3, v207
	s_and_saveexec_b64 s[14:15], vcc
	v_mov_b64_e32 v[26:27], v[90:91]
	v_mov_b64_e32 v[22:23], v[94:95]
	v_mov_b64_e32 v[28:29], v[92:93]
	v_mov_b64_e32 v[24:25], v[96:97]
	s_or_b64 exec, exec, s[14:15]

.LBB7_784:
	s_or_b64 exec, exec, s[12:13]
	v_or_b32_e32 v42, 6, v206
	v_min_u32_e32 v42, v42, v180
	v_cvt_f32_ubyte0_e32 v42, v42
	v_div_scale_f32 v43, s[4:5], v42, v42, 1.0
	v_rcp_f32_e32 v44, v43
	v_div_scale_f32 v45, vcc, 1.0, v42, 1.0
	v_lshlrev_b32_e32 v48, 16, v53
	v_fma_f32 v46, -v43, v44, 1.0
	v_fmac_f32_e32 v44, v46, v44
	v_mul_f32_e32 v46, v45, v44
	v_fma_f32 v47, -v43, v46, v45
	v_fmac_f32_e32 v46, v47, v44
	v_fma_f32 v43, -v43, v46, v45
	v_div_fmas_f32 v43, v43, v44, v46
	v_lshlrev_b32_e32 v44, 16, v51
	v_and_b32_e32 v45, 0xffff0000, v51
	v_div_fixup_f32 v78, v43, v42, 1.0
	v_lshlrev_b32_e32 v42, 16, v50
	v_and_b32_e32 v43, 0xffff0000, v50
	v_lshlrev_b32_e32 v46, 16, v52
	v_and_b32_e32 v47, 0xffff0000, v52
	v_pk_add_f32 v[44:45], v[56:57], v[44:45]
	v_and_b32_e32 v49, 0xffff0000, v53
	v_pk_add_f32 v[42:43], v[54:55], v[42:43]
	v_pk_add_f32 v[46:47], v[58:59], v[46:47]
	v_sub_f32_e32 v50, v44, v56
	v_sub_f32_e32 v51, v45, v57
	v_pk_add_f32 v[48:49], v[60:61], v[48:49]
	v_sub_f32_e32 v52, v42, v54
	v_sub_f32_e32 v53, v43, v55
	v_sub_f32_e32 v79, v46, v58
	v_sub_f32_e32 v29, v45, v29
	v_sub_f32_e32 v28, v44, v28
	v_xor_b32_e32 v51, 0x80000000, v51
	v_xor_b32_e32 v50, 0x80000000, v50
	v_sub_f32_e32 v81, v48, v60
	v_sub_f32_e32 v82, v49, v61
	v_sub_f32_e32 v27, v43, v27
	v_sub_f32_e32 v26, v42, v26
	v_pk_fma_f32 v[28:29], v[78:79], v[28:29], v[50:51] op_sel_hi:[0,1,1]
	v_xor_b32_e32 v51, 0x80000000, v53
	v_xor_b32_e32 v50, 0x80000000, v52
	v_sub_f32_e32 v80, v47, v59
	v_pk_fma_f32 v[26:27], v[78:79], v[26:27], v[50:51] op_sel_hi:[0,1,1]
	v_sub_f32_e32 v25, v49, v25
	v_sub_f32_e32 v24, v48, v24
	v_xor_b32_e32 v51, 0x80000000, v82
	v_xor_b32_e32 v50, 0x80000000, v81
	v_sub_f32_e32 v23, v47, v23
	v_sub_f32_e32 v22, v46, v22
	v_pk_fma_f32 v[50:51], v[78:79], v[24:25], v[50:51] op_sel_hi:[0,1,1]
	v_xor_b32_e32 v25, 0x80000000, v80
	v_xor_b32_e32 v24, 0x80000000, v79
	v_pk_fma_f32 v[24:25], v[78:79], v[22:23], v[24:25] op_sel_hi:[0,1,1]
	v_cvt_pk_bf16_f32 v22, v26, v27
	v_lshl_add_u64 v[26:27], s[0:1], 0, v[156:157]
	v_lshl_add_u64 v[26:27], v[26:27], 0, v[0:1]
	v_cmp_lt_i32_e32 vcc, 1, v207
	v_cvt_pk_bf16_f32 v23, v28, v29
	v_cvt_pk_bf16_f32 v24, v24, v25
	v_cvt_pk_bf16_f32 v25, v50, v51
	global_store_dwordx4 v[26:27], v[22:25], off offset:768 nt
	s_and_saveexec_b64 s[4:5], vcc
	s_xor_b64 s[12:13], exec, s[4:5]
	s_cbranch_execz .LBB7_788
	v_cmp_gt_i32_e32 vcc, 3, v207
	s_and_saveexec_b64 s[14:15], vcc
	v_mov_b64_e32 v[14:15], v[70:71]
	v_mov_b64_e32 v[10:11], v[74:75]
	v_mov_b64_e32 v[16:17], v[72:73]
	v_mov_b64_e32 v[12:13], v[76:77]
	s_or_b64 exec, exec, s[14:15]

.LBB7_794:
	s_or_b64 exec, exec, s[12:13]
	v_or_b32_e32 v22, 7, v206
	v_min_u32_e32 v22, v22, v180
	v_cvt_f32_ubyte0_e32 v22, v22
	v_div_scale_f32 v23, s[4:5], v22, v22, 1.0
	v_rcp_f32_e32 v24, v23
	v_div_scale_f32 v25, vcc, 1.0, v22, 1.0
	v_lshlrev_b32_e32 v28, 16, v41
	v_fma_f32 v26, -v23, v24, 1.0
	v_fmac_f32_e32 v24, v26, v24
	v_mul_f32_e32 v26, v25, v24
	v_fma_f32 v27, -v23, v26, v25
	v_fmac_f32_e32 v26, v27, v24
	v_fma_f32 v23, -v23, v26, v25
	v_div_fmas_f32 v23, v23, v24, v26
	v_lshlrev_b32_e32 v24, 16, v39
	v_and_b32_e32 v25, 0xffff0000, v39
	v_div_fixup_f32 v50, v23, v22, 1.0
	v_lshlrev_b32_e32 v22, 16, v38
	v_and_b32_e32 v23, 0xffff0000, v38
	v_lshlrev_b32_e32 v26, 16, v40
	v_and_b32_e32 v27, 0xffff0000, v40
	v_pk_add_f32 v[24:25], v[44:45], v[24:25]
	v_and_b32_e32 v29, 0xffff0000, v41
	v_pk_add_f32 v[22:23], v[42:43], v[22:23]
	v_pk_add_f32 v[26:27], v[46:47], v[26:27]
	v_sub_f32_e32 v38, v24, v44
	v_sub_f32_e32 v39, v25, v45
	v_pk_add_f32 v[28:29], v[48:49], v[28:29]
	v_sub_f32_e32 v40, v22, v42
	v_sub_f32_e32 v41, v23, v43
	v_sub_f32_e32 v51, v26, v46
	v_sub_f32_e32 v17, v25, v17
	v_sub_f32_e32 v16, v24, v16
	v_xor_b32_e32 v39, 0x80000000, v39
	v_xor_b32_e32 v38, 0x80000000, v38
	v_sub_f32_e32 v53, v28, v48
	v_sub_f32_e32 v54, v29, v49
	v_sub_f32_e32 v15, v23, v15
	v_sub_f32_e32 v14, v22, v14
	v_pk_fma_f32 v[16:17], v[50:51], v[16:17], v[38:39] op_sel_hi:[0,1,1]
	v_xor_b32_e32 v39, 0x80000000, v41
	v_xor_b32_e32 v38, 0x80000000, v40
	v_sub_f32_e32 v52, v27, v47
	v_pk_fma_f32 v[14:15], v[50:51], v[14:15], v[38:39] op_sel_hi:[0,1,1]
	v_sub_f32_e32 v13, v29, v13
	v_sub_f32_e32 v12, v28, v12
	v_xor_b32_e32 v39, 0x80000000, v54
	v_xor_b32_e32 v38, 0x80000000, v53
	v_sub_f32_e32 v11, v27, v11
	v_sub_f32_e32 v10, v26, v10
	v_pk_fma_f32 v[38:39], v[50:51], v[12:13], v[38:39] op_sel_hi:[0,1,1]
	v_xor_b32_e32 v13, 0x80000000, v52
	v_xor_b32_e32 v12, 0x80000000, v51
	v_pk_fma_f32 v[12:13], v[50:51], v[10:11], v[12:13] op_sel_hi:[0,1,1]
	v_cvt_pk_bf16_f32 v10, v14, v15
	v_lshl_add_u64 v[14:15], s[0:1], 0, v[154:155]
	v_lshl_add_u64 v[14:15], v[14:15], 0, v[0:1]
	v_cmp_lt_i32_e32 vcc, 1, v207
	v_cvt_pk_bf16_f32 v11, v16, v17
	v_cvt_pk_bf16_f32 v12, v12, v13
	v_cvt_pk_bf16_f32 v13, v38, v39
	global_store_dwordx4 v[14:15], v[10:13], off offset:768 nt
	s_and_saveexec_b64 s[4:5], vcc
	s_xor_b64 s[12:13], exec, s[4:5]
	s_cbranch_execz .LBB7_798
	v_cmp_gt_i32_e32 vcc, 3, v207
	s_and_saveexec_b64 s[14:15], vcc
	v_mov_b64_e32 v[6:7], v[62:63]
	v_mov_b64_e32 v[2:3], v[66:67]
	v_mov_b64_e32 v[8:9], v[64:65]
	v_mov_b64_e32 v[4:5], v[68:69]
	s_or_b64 exec, exec, s[14:15]

.LBB7_889:
	v_lshl_add_u32 v196, s10, 8, v192
	v_mov_b64_e32 v[188:189], s[70:71]
	v_mad_i64_i32 v[74:75], s[16:17], v196, s58, v[188:189]
	s_ashr_i32 s16, s10, 31
	s_lshr_b32 s16, s16, 30
	v_lshl_or_b32 v170, s28, 8, v194
	s_add_i32 s10, s10, s16
	v_ashrrev_i32_e32 v171, 31, v170
	s_lshl_b32 s10, s10, 2
	v_lshlrev_b64 v[190:191], 1, v[170:171]
	s_and_b32 s16, s10, -16
	v_lshl_add_u64 v[138:139], v[74:75], 0, v[190:191]
	s_ashr_i32 s17, s16, 31
	global_load_dwordx4 v[204:207], v[138:139], off offset:256
	v_lshl_add_u64 v[74:75], s[16:17], 2, v[182:183]
	global_load_dwordx4 v[78:81], v[74:75], off
	s_nop 0
	global_load_dwordx4 v[74:77], v[74:75], off offset:16
	v_or_b32_e32 v140, 16, v196
	v_or_b32_e32 v142, 32, v196
	v_or_b32_e32 v144, 48, v196
	v_mad_i64_i32 v[140:141], s[28:29], v140, s58, v[188:189]
	v_mad_i64_i32 v[142:143], s[28:29], v142, s58, v[188:189]
	v_mad_i64_i32 v[144:145], s[28:29], v144, s58, v[188:189]
	v_lshl_add_u64 v[140:141], v[140:141], 0, v[190:191]
	v_lshl_add_u64 v[142:143], v[142:143], 0, v[190:191]
	v_lshl_add_u64 v[172:173], v[144:145], 0, v[190:191]
	global_load_dwordx4 v[208:211], v[138:139], off offset:512
	global_load_dwordx4 v[158:161], v[140:141], off offset:256
	global_load_dwordx4 v[154:157], v[140:141], off offset:512
	global_load_dwordx4 v[150:153], v[142:143], off offset:256
	global_load_dwordx4 v[146:149], v[142:143], off offset:512
	s_nop 0
	global_load_dwordx4 v[142:145], v[172:173], off offset:256
	global_load_dwordx4 v[138:141], v[172:173], off offset:512
	v_lshlrev_b32_e32 v197, 5, v196
	v_and_b32_e32 v198, 0x79e0, v197
	s_lshl_b64 s[16:17], s[16:17], 1
	s_andn2_b64 vcc, exec, s[40:41]
	s_waitcnt vmcnt(0)
	v_lshlrev_b32_e32 v212, 16, v206
	v_and_b32_e32 v213, 0xffff0000, v206
	v_lshlrev_b32_e32 v172, 16, v204
	v_and_b32_e32 v173, 0xffff0000, v204
	v_pk_fma_f32 v[130:131], v[74:75], v[212:213], v[130:131]
	v_pk_fma_f32 v[134:135], v[78:79], v[172:173], v[134:135]
	v_mul_f32_e32 v172, 0x3d372713, v130
	v_mul_f32_e32 v171, 0x3d372713, v134
	v_mul_f32_e32 v172, v130, v172
	v_mul_f32_e32 v171, v134, v171
	v_fma_f32 v172, v130, v172, v130
	v_fma_f32 v171, v134, v171, v134
	v_mul_f32_e32 v172, 0x3fcc422a, v172
	v_mul_f32_e32 v171, 0x3fcc422a, v171
	v_mul_f32_e32 v172, 0xbfb8aa3b, v172
	v_mul_f32_e32 v171, 0xbfb8aa3b, v171
	v_exp_f32_e32 v172, v172
	v_exp_f32_e32 v171, v171
	v_mul_f32_e32 v173, 0x3d372713, v135
	v_mul_f32_e32 v173, v135, v173
	v_add_f32_e32 v172, 1.0, v172
	v_add_f32_e32 v171, 1.0, v171
	v_rcp_f32_e32 v172, v172
	v_rcp_f32_e32 v171, v171
	v_lshlrev_b32_e32 v204, 16, v205
	v_and_b32_e32 v205, 0xffff0000, v205
	v_lshlrev_b32_e32 v206, 16, v207
	v_and_b32_e32 v207, 0xffff0000, v207
	v_fma_f32 v173, v135, v173, v135
	v_pk_fma_f32 v[136:137], v[80:81], v[204:205], v[136:137]
	v_pk_fma_f32 v[132:133], v[76:77], v[206:207], v[132:133]
	v_mul_f32_e32 v173, 0x3fcc422a, v173
	v_mul_f32_e32 v199, 0x3d372713, v131
	v_mul_f32_e32 v204, 0x3d372713, v136
	v_mul_f32_e32 v205, 0x3d372713, v132
	v_mul_f32_e32 v206, 0x3d372713, v137
	v_mul_f32_e32 v173, 0xbfb8aa3b, v173
	v_mul_f32_e32 v130, v130, v172
	v_mul_f32_e32 v172, 0x3d372713, v133
	v_mul_f32_e32 v199, v131, v199
	v_mul_f32_e32 v204, v136, v204
	v_mul_f32_e32 v205, v132, v205
	v_exp_f32_e32 v173, v173
	v_mul_f32_e32 v134, v134, v171
	v_mul_f32_e32 v171, v137, v206
	v_mul_f32_e32 v172, v133, v172
	v_fma_f32 v199, v131, v199, v131
	v_fma_f32 v204, v136, v204, v136
	v_fma_f32 v205, v132, v205, v132
	v_fma_f32 v171, v137, v171, v137
	v_fma_f32 v172, v133, v172, v133
	v_mul_f32_e32 v199, 0x3fcc422a, v199
	v_mul_f32_e32 v204, 0x3fcc422a, v204
	v_mul_f32_e32 v205, 0x3fcc422a, v205
	v_mul_f32_e32 v171, 0x3fcc422a, v171
	v_mul_f32_e32 v172, 0x3fcc422a, v172
	v_mul_f32_e32 v199, 0xbfb8aa3b, v199
	v_mul_f32_e32 v204, 0xbfb8aa3b, v204
	v_mul_f32_e32 v205, 0xbfb8aa3b, v205
	v_mul_f32_e32 v171, 0xbfb8aa3b, v171
	v_mul_f32_e32 v172, 0xbfb8aa3b, v172
	v_exp_f32_e32 v199, v199
	v_exp_f32_e32 v204, v204
	v_exp_f32_e32 v205, v205
	v_add_f32_e32 v173, 1.0, v173
	v_exp_f32_e32 v171, v171
	v_exp_f32_e32 v172, v172
	v_rcp_f32_e32 v173, v173
	v_add_f32_e32 v199, 1.0, v199
	v_add_f32_e32 v204, 1.0, v204
	v_add_f32_e32 v205, 1.0, v205
	v_add_f32_e32 v171, 1.0, v171
	v_add_f32_e32 v172, 1.0, v172
	v_rcp_f32_e32 v199, v199
	v_rcp_f32_e32 v204, v204
	v_mul_f32_e32 v135, v135, v173
	v_rcp_f32_e32 v173, v205
	v_rcp_f32_e32 v171, v171
	v_rcp_f32_e32 v172, v172
	v_mul_f32_e32 v131, v131, v199
	v_mul_f32_e32 v136, v136, v204
	v_mul_f32_e32 v173, v132, v173
	v_mul_f32_e32 v137, v137, v171
	v_mul_f32_e32 v133, v133, v172
	v_ashrrev_i32_e32 v132, 4, v170
	v_cvt_pk_bf16_f32 v134, v134, v135
	v_cvt_pk_bf16_f32 v135, v136, v137
	v_cvt_pk_bf16_f32 v136, v130, v131
	v_cvt_pk_bf16_f32 v137, v173, v133
	v_add_u32_e32 v133, v198, v132
	v_mov_b64_e32 v[130:131], s[46:47]
	v_mad_i64_i32 v[170:171], s[28:29], v133, s90, v[130:131]
	v_lshl_add_u64 v[170:171], v[170:171], 0, s[16:17]
	v_lshl_add_u64 v[170:171], v[170:171], 0, v[0:1]
	global_store_dwordx4 v[170:171], v[134:137], off nt
	v_lshlrev_b32_e32 v170, 16, v210
	v_and_b32_e32 v171, 0xffff0000, v210
	v_lshlrev_b32_e32 v134, 16, v208
	v_and_b32_e32 v135, 0xffff0000, v208
	v_pk_fma_f32 v[126:127], v[78:79], v[134:135], v[126:127]
	v_pk_fma_f32 v[122:123], v[74:75], v[170:171], v[122:123]
	v_mul_f32_e32 v133, 0x3d372713, v126
	v_mul_f32_e32 v134, 0x3d372713, v122
	v_mul_f32_e32 v135, 0x3d372713, v127
	v_mul_f32_e32 v133, v126, v133
	v_mul_f32_e32 v134, v122, v134
	v_mul_f32_e32 v135, v127, v135
	v_fma_f32 v133, v126, v133, v126
	v_fma_f32 v134, v122, v134, v122
	v_fma_f32 v135, v127, v135, v127
	v_mul_f32_e32 v133, 0x3fcc422a, v133
	v_mul_f32_e32 v134, 0x3fcc422a, v134
	v_mul_f32_e32 v135, 0x3fcc422a, v135
	v_mul_f32_e32 v133, 0xbfb8aa3b, v133
	v_mul_f32_e32 v134, 0xbfb8aa3b, v134
	v_mul_f32_e32 v135, 0xbfb8aa3b, v135
	v_exp_f32_e32 v133, v133
	v_exp_f32_e32 v134, v134
	v_exp_f32_e32 v135, v135
	v_lshlrev_b32_e32 v136, 16, v209
	v_and_b32_e32 v137, 0xffff0000, v209
	v_pk_fma_f32 v[128:129], v[80:81], v[136:137], v[128:129]
	v_add_f32_e32 v133, 1.0, v133
	v_add_f32_e32 v134, 1.0, v134
	v_add_f32_e32 v135, 1.0, v135
	v_mul_f32_e32 v136, 0x3d372713, v123
	v_rcp_f32_e32 v133, v133
	v_rcp_f32_e32 v134, v134
	v_rcp_f32_e32 v135, v135
	v_mul_f32_e32 v136, v123, v136
	v_fma_f32 v136, v123, v136, v123
	v_lshlrev_b32_e32 v172, 16, v211
	v_and_b32_e32 v173, 0xffff0000, v211
	v_mul_f32_e32 v136, 0x3fcc422a, v136
	v_pk_fma_f32 v[124:125], v[76:77], v[172:173], v[124:125]
	v_mul_f32_e32 v136, 0xbfb8aa3b, v136
	v_exp_f32_e32 v136, v136
	v_mul_f32_e32 v126, v126, v133
	v_mul_f32_e32 v133, v122, v134
	v_mul_f32_e32 v127, v127, v135
	v_mul_f32_e32 v134, 0x3d372713, v128
	v_mul_f32_e32 v135, 0x3d372713, v124
	v_mul_f32_e32 v134, v128, v134
	v_mul_f32_e32 v135, v124, v135
	v_fma_f32 v134, v128, v134, v128
	v_fma_f32 v135, v124, v135, v124
	v_mul_f32_e32 v134, 0x3fcc422a, v134
	v_mul_f32_e32 v135, 0x3fcc422a, v135
	v_add_f32_e32 v122, 1.0, v136
	v_mul_f32_e32 v134, 0xbfb8aa3b, v134
	v_mul_f32_e32 v135, 0xbfb8aa3b, v135
	v_rcp_f32_e32 v122, v122
	v_exp_f32_e32 v134, v134
	v_exp_f32_e32 v135, v135
	v_mul_f32_e32 v136, 0x3d372713, v125
	v_mul_f32_e32 v123, v123, v122
	v_add_f32_e32 v122, 1.0, v134
	v_add_f32_e32 v134, 1.0, v135
	v_mul_f32_e32 v135, 0x3d372713, v129
	v_mul_f32_e32 v135, v129, v135
	v_mul_f32_e32 v136, v125, v136
	v_fma_f32 v135, v129, v135, v129
	v_fma_f32 v136, v125, v136, v125
	v_mul_f32_e32 v135, 0x3fcc422a, v135
	v_mul_f32_e32 v136, 0x3fcc422a, v136
	v_mul_f32_e32 v135, 0xbfb8aa3b, v135
	v_mul_f32_e32 v136, 0xbfb8aa3b, v136
	v_exp_f32_e32 v135, v135
	v_exp_f32_e32 v136, v136
	v_rcp_f32_e32 v122, v122
	v_rcp_f32_e32 v134, v134
	v_add_f32_e32 v135, 1.0, v135
	v_add_f32_e32 v136, 1.0, v136
	v_rcp_f32_e32 v135, v135
	v_rcp_f32_e32 v136, v136
	v_mul_f32_e32 v128, v128, v122
	v_or_b32_e32 v122, 8, v132
	v_mul_f32_e32 v134, v124, v134
	v_mul_f32_e32 v129, v129, v135
	v_mul_f32_e32 v135, v125, v136
	v_cvt_pk_bf16_f32 v124, v126, v127
	v_cvt_pk_bf16_f32 v125, v128, v129
	v_cvt_pk_bf16_f32 v126, v133, v123
	v_add_u32_e32 v123, v198, v122
	v_mad_i64_i32 v[128:129], s[28:29], v123, s90, v[130:131]
	v_lshl_add_u64 v[128:129], v[128:129], 0, s[16:17]
	v_lshl_add_u64 v[128:129], v[128:129], 0, v[0:1]
	v_cvt_pk_bf16_f32 v127, v134, v135
	global_store_dwordx4 v[128:129], v[124:127], off nt
	v_lshlrev_b32_e32 v128, 16, v160
	v_and_b32_e32 v129, 0xffff0000, v160
	v_lshlrev_b32_e32 v124, 16, v158
	v_and_b32_e32 v125, 0xffff0000, v158
	v_lshlrev_b32_e32 v126, 16, v159
	v_and_b32_e32 v127, 0xffff0000, v159
	v_pk_fma_f32 v[118:119], v[78:79], v[124:125], v[118:119]
	v_pk_fma_f32 v[114:115], v[74:75], v[128:129], v[114:115]
	v_mul_f32_e32 v124, 0x3d372713, v118
	v_pk_fma_f32 v[120:121], v[80:81], v[126:127], v[120:121]
	v_mul_f32_e32 v125, 0x3d372713, v114
	v_mul_f32_e32 v126, 0x3d372713, v119
	v_mul_f32_e32 v124, v118, v124
	v_mul_f32_e32 v125, v114, v125
	v_mul_f32_e32 v126, v119, v126
	v_fma_f32 v124, v118, v124, v118
	v_fma_f32 v125, v114, v125, v114
	v_fma_f32 v126, v119, v126, v119
	v_mul_f32_e32 v124, 0x3fcc422a, v124
	v_mul_f32_e32 v125, 0x3fcc422a, v125
	v_mul_f32_e32 v126, 0x3fcc422a, v126
	v_mul_f32_e32 v124, 0xbfb8aa3b, v124
	v_mul_f32_e32 v125, 0xbfb8aa3b, v125
	v_mul_f32_e32 v126, 0xbfb8aa3b, v126
	v_exp_f32_e32 v124, v124
	v_exp_f32_e32 v125, v125
	v_exp_f32_e32 v126, v126
	v_mul_f32_e32 v127, 0x3d372713, v115
	v_add_f32_e32 v124, 1.0, v124
	v_add_f32_e32 v125, 1.0, v125
	v_add_f32_e32 v126, 1.0, v126
	v_rcp_f32_e32 v124, v124
	v_rcp_f32_e32 v125, v125
	v_rcp_f32_e32 v126, v126
	v_mul_f32_e32 v127, v115, v127
	v_fma_f32 v127, v115, v127, v115
	v_lshlrev_b32_e32 v134, 16, v161
	v_and_b32_e32 v135, 0xffff0000, v161
	v_mul_f32_e32 v127, 0x3fcc422a, v127
	v_pk_fma_f32 v[116:117], v[76:77], v[134:135], v[116:117]
	v_mul_f32_e32 v127, 0xbfb8aa3b, v127
	v_exp_f32_e32 v127, v127
	v_mul_f32_e32 v118, v118, v124
	v_mul_f32_e32 v124, v114, v125
	v_mul_f32_e32 v114, v119, v126
	v_mul_f32_e32 v125, 0x3d372713, v120
	v_mul_f32_e32 v126, 0x3d372713, v116
	v_mul_f32_e32 v125, v120, v125
	v_mul_f32_e32 v126, v116, v126
	v_fma_f32 v125, v120, v125, v120
	v_fma_f32 v126, v116, v126, v116
	v_mul_f32_e32 v125, 0x3fcc422a, v125
	v_mul_f32_e32 v126, 0x3fcc422a, v126
	v_add_f32_e32 v119, 1.0, v127
	v_mul_f32_e32 v125, 0xbfb8aa3b, v125
	v_mul_f32_e32 v126, 0xbfb8aa3b, v126
	v_rcp_f32_e32 v119, v119
	v_exp_f32_e32 v125, v125
	v_exp_f32_e32 v126, v126
	v_mul_f32_e32 v127, 0x3d372713, v117
	v_mul_f32_e32 v119, v115, v119
	v_add_f32_e32 v115, 1.0, v125
	v_add_f32_e32 v125, 1.0, v126
	v_mul_f32_e32 v126, 0x3d372713, v121
	v_mul_f32_e32 v126, v121, v126
	v_fma_f32 v126, v121, v126, v121
	v_mul_f32_e32 v126, 0x3fcc422a, v126
	v_mul_f32_e32 v126, 0xbfb8aa3b, v126
	v_mul_f32_e32 v127, v117, v127
	v_exp_f32_e32 v126, v126
	v_fma_f32 v127, v117, v127, v117
	v_mul_f32_e32 v127, 0x3fcc422a, v127
	v_mul_f32_e32 v127, 0xbfb8aa3b, v127
	v_exp_f32_e32 v127, v127
	v_add_f32_e32 v126, 1.0, v126
	v_rcp_f32_e32 v115, v115
	v_rcp_f32_e32 v125, v125
	v_rcp_f32_e32 v126, v126
	v_add_f32_e32 v127, 1.0, v127
	v_or_b32_e32 v123, 0x200, v198
	v_rcp_f32_e32 v127, v127
	v_mul_f32_e32 v115, v120, v115
	v_mul_f32_e32 v120, v116, v125
	v_mul_f32_e32 v116, v121, v126
	v_cvt_pk_bf16_f32 v114, v118, v114
	v_add_u32_e32 v118, v123, v132
	v_cvt_pk_bf16_f32 v115, v115, v116
	v_cvt_pk_bf16_f32 v116, v124, v119
	v_mad_i64_i32 v[118:119], s[28:29], v118, s90, v[130:131]
	v_lshl_add_u64 v[118:119], v[118:119], 0, s[16:17]
	v_mul_f32_e32 v117, v117, v127
	v_lshl_add_u64 v[118:119], v[118:119], 0, v[0:1]
	v_cvt_pk_bf16_f32 v117, v120, v117
	global_store_dwordx4 v[118:119], v[114:117], off nt
	v_lshlrev_b32_e32 v118, 16, v156
	v_and_b32_e32 v119, 0xffff0000, v156
	v_lshlrev_b32_e32 v114, 16, v154
	v_and_b32_e32 v115, 0xffff0000, v154
	v_lshlrev_b32_e32 v116, 16, v155
	v_and_b32_e32 v117, 0xffff0000, v155
	v_pk_fma_f32 v[110:111], v[78:79], v[114:115], v[110:111]
	v_pk_fma_f32 v[106:107], v[74:75], v[118:119], v[106:107]
	v_mul_f32_e32 v114, 0x3d372713, v110
	v_pk_fma_f32 v[112:113], v[80:81], v[116:117], v[112:113]
	v_mul_f32_e32 v115, 0x3d372713, v106
	v_mul_f32_e32 v116, 0x3d372713, v111
	v_mul_f32_e32 v114, v110, v114
	v_mul_f32_e32 v115, v106, v115
	v_mul_f32_e32 v116, v111, v116
	v_fma_f32 v114, v110, v114, v110
	v_fma_f32 v115, v106, v115, v106
	v_fma_f32 v116, v111, v116, v111
	v_mul_f32_e32 v114, 0x3fcc422a, v114
	v_mul_f32_e32 v115, 0x3fcc422a, v115
	v_mul_f32_e32 v116, 0x3fcc422a, v116
	v_mul_f32_e32 v114, 0xbfb8aa3b, v114
	v_mul_f32_e32 v115, 0xbfb8aa3b, v115
	v_mul_f32_e32 v116, 0xbfb8aa3b, v116
	v_exp_f32_e32 v114, v114
	v_exp_f32_e32 v115, v115
	v_exp_f32_e32 v116, v116
	v_mul_f32_e32 v117, 0x3d372713, v107
	v_add_f32_e32 v114, 1.0, v114
	v_add_f32_e32 v115, 1.0, v115
	v_add_f32_e32 v116, 1.0, v116
	v_rcp_f32_e32 v114, v114
	v_rcp_f32_e32 v115, v115
	v_rcp_f32_e32 v116, v116
	v_mul_f32_e32 v117, v107, v117
	v_fma_f32 v117, v107, v117, v107
	v_lshlrev_b32_e32 v120, 16, v157
	v_and_b32_e32 v121, 0xffff0000, v157
	v_mul_f32_e32 v117, 0x3fcc422a, v117
	v_pk_fma_f32 v[108:109], v[76:77], v[120:121], v[108:109]
	v_mul_f32_e32 v117, 0xbfb8aa3b, v117
	v_exp_f32_e32 v117, v117
	v_mul_f32_e32 v110, v110, v114
	v_mul_f32_e32 v114, v106, v115
	v_mul_f32_e32 v106, v111, v116
	v_mul_f32_e32 v115, 0x3d372713, v112
	v_mul_f32_e32 v116, 0x3d372713, v108
	v_mul_f32_e32 v115, v112, v115
	v_mul_f32_e32 v116, v108, v116
	v_fma_f32 v115, v112, v115, v112
	v_fma_f32 v116, v108, v116, v108
	v_mul_f32_e32 v115, 0x3fcc422a, v115
	v_mul_f32_e32 v116, 0x3fcc422a, v116
	v_add_f32_e32 v111, 1.0, v117
	v_mul_f32_e32 v115, 0xbfb8aa3b, v115
	v_mul_f32_e32 v116, 0xbfb8aa3b, v116
	v_rcp_f32_e32 v111, v111
	v_exp_f32_e32 v115, v115
	v_exp_f32_e32 v116, v116
	v_mul_f32_e32 v117, 0x3d372713, v109
	v_mul_f32_e32 v111, v107, v111
	v_add_f32_e32 v107, 1.0, v115
	v_add_f32_e32 v115, 1.0, v116
	v_mul_f32_e32 v116, 0x3d372713, v113
	v_mul_f32_e32 v116, v113, v116
	v_fma_f32 v116, v113, v116, v113
	v_mul_f32_e32 v116, 0x3fcc422a, v116
	v_mul_f32_e32 v116, 0xbfb8aa3b, v116
	v_mul_f32_e32 v117, v109, v117
	v_exp_f32_e32 v116, v116
	v_fma_f32 v117, v109, v117, v109
	v_mul_f32_e32 v117, 0x3fcc422a, v117
	v_mul_f32_e32 v117, 0xbfb8aa3b, v117
	v_exp_f32_e32 v117, v117
	v_add_f32_e32 v116, 1.0, v116
	v_rcp_f32_e32 v107, v107
	v_rcp_f32_e32 v115, v115
	v_rcp_f32_e32 v116, v116
	v_add_f32_e32 v117, 1.0, v117
	v_rcp_f32_e32 v117, v117
	v_mul_f32_e32 v107, v112, v107
	v_mul_f32_e32 v112, v108, v115
	v_mul_f32_e32 v108, v113, v116
	v_cvt_pk_bf16_f32 v106, v110, v106
	v_add_u32_e32 v110, v123, v122
	v_cvt_pk_bf16_f32 v107, v107, v108
	v_cvt_pk_bf16_f32 v108, v114, v111
	v_mad_i64_i32 v[110:111], s[28:29], v110, s90, v[130:131]
	v_lshl_add_u64 v[110:111], v[110:111], 0, s[16:17]
	v_mul_f32_e32 v109, v109, v117
	v_lshl_add_u64 v[110:111], v[110:111], 0, v[0:1]
	v_cvt_pk_bf16_f32 v109, v112, v109
	global_store_dwordx4 v[110:111], v[106:109], off nt
	v_lshlrev_b32_e32 v110, 16, v152
	v_and_b32_e32 v111, 0xffff0000, v152
	v_lshlrev_b32_e32 v106, 16, v150
	v_and_b32_e32 v107, 0xffff0000, v150
	v_lshlrev_b32_e32 v108, 16, v151
	v_and_b32_e32 v109, 0xffff0000, v151
	v_pk_fma_f32 v[102:103], v[78:79], v[106:107], v[102:103]
	v_pk_fma_f32 v[98:99], v[74:75], v[110:111], v[98:99]
	v_mul_f32_e32 v106, 0x3d372713, v102
	v_pk_fma_f32 v[104:105], v[80:81], v[108:109], v[104:105]
	v_mul_f32_e32 v107, 0x3d372713, v98
	v_mul_f32_e32 v108, 0x3d372713, v103
	v_mul_f32_e32 v106, v102, v106
	v_mul_f32_e32 v107, v98, v107
	v_mul_f32_e32 v108, v103, v108
	v_fma_f32 v106, v102, v106, v102
	v_fma_f32 v107, v98, v107, v98
	v_fma_f32 v108, v103, v108, v103
	v_mul_f32_e32 v106, 0x3fcc422a, v106
	v_mul_f32_e32 v107, 0x3fcc422a, v107
	v_mul_f32_e32 v108, 0x3fcc422a, v108
	v_mul_f32_e32 v106, 0xbfb8aa3b, v106
	v_mul_f32_e32 v107, 0xbfb8aa3b, v107
	v_mul_f32_e32 v108, 0xbfb8aa3b, v108
	v_exp_f32_e32 v106, v106
	v_exp_f32_e32 v107, v107
	v_exp_f32_e32 v108, v108
	v_mul_f32_e32 v109, 0x3d372713, v99
	v_add_f32_e32 v106, 1.0, v106
	v_add_f32_e32 v107, 1.0, v107
	v_add_f32_e32 v108, 1.0, v108
	v_rcp_f32_e32 v106, v106
	v_rcp_f32_e32 v107, v107
	v_rcp_f32_e32 v108, v108
	v_mul_f32_e32 v109, v99, v109
	v_fma_f32 v109, v99, v109, v99
	v_lshlrev_b32_e32 v112, 16, v153
	v_and_b32_e32 v113, 0xffff0000, v153
	v_mul_f32_e32 v109, 0x3fcc422a, v109
	v_pk_fma_f32 v[100:101], v[76:77], v[112:113], v[100:101]
	v_mul_f32_e32 v109, 0xbfb8aa3b, v109
	v_exp_f32_e32 v109, v109
	v_mul_f32_e32 v102, v102, v106
	v_mul_f32_e32 v106, v98, v107
	v_mul_f32_e32 v98, v103, v108
	v_mul_f32_e32 v107, 0x3d372713, v104
	v_mul_f32_e32 v108, 0x3d372713, v100
	v_mul_f32_e32 v107, v104, v107
	v_mul_f32_e32 v108, v100, v108
	v_fma_f32 v107, v104, v107, v104
	v_fma_f32 v108, v100, v108, v100
	v_mul_f32_e32 v107, 0x3fcc422a, v107
	v_mul_f32_e32 v108, 0x3fcc422a, v108
	v_add_f32_e32 v103, 1.0, v109
	v_mul_f32_e32 v107, 0xbfb8aa3b, v107
	v_mul_f32_e32 v108, 0xbfb8aa3b, v108
	v_rcp_f32_e32 v103, v103
	v_exp_f32_e32 v107, v107
	v_exp_f32_e32 v108, v108
	v_mul_f32_e32 v109, 0x3d372713, v101
	v_mul_f32_e32 v103, v99, v103
	v_add_f32_e32 v99, 1.0, v107
	v_add_f32_e32 v107, 1.0, v108
	v_mul_f32_e32 v108, 0x3d372713, v105
	v_mul_f32_e32 v108, v105, v108
	v_fma_f32 v108, v105, v108, v105
	v_mul_f32_e32 v108, 0x3fcc422a, v108
	v_mul_f32_e32 v108, 0xbfb8aa3b, v108
	v_mul_f32_e32 v109, v101, v109
	v_exp_f32_e32 v108, v108
	v_fma_f32 v109, v101, v109, v101
	v_mul_f32_e32 v109, 0x3fcc422a, v109
	v_mul_f32_e32 v109, 0xbfb8aa3b, v109
	v_exp_f32_e32 v109, v109
	v_add_f32_e32 v108, 1.0, v108
	v_rcp_f32_e32 v99, v99
	v_rcp_f32_e32 v107, v107
	v_rcp_f32_e32 v108, v108
	v_add_f32_e32 v109, 1.0, v109
	v_or_b32_e32 v114, 0x400, v198
	v_rcp_f32_e32 v109, v109
	v_mul_f32_e32 v99, v104, v99
	v_mul_f32_e32 v104, v100, v107
	v_mul_f32_e32 v100, v105, v108
	v_cvt_pk_bf16_f32 v98, v102, v98
	v_add_u32_e32 v102, v114, v132
	v_cvt_pk_bf16_f32 v99, v99, v100
	v_cvt_pk_bf16_f32 v100, v106, v103
	v_mad_i64_i32 v[102:103], s[28:29], v102, s90, v[130:131]
	v_lshl_add_u64 v[102:103], v[102:103], 0, s[16:17]
	v_mul_f32_e32 v101, v101, v109
	v_lshl_add_u64 v[102:103], v[102:103], 0, v[0:1]
	v_cvt_pk_bf16_f32 v101, v104, v101
	global_store_dwordx4 v[102:103], v[98:101], off nt
	v_lshlrev_b32_e32 v102, 16, v148
	v_and_b32_e32 v103, 0xffff0000, v148
	v_lshlrev_b32_e32 v98, 16, v146
	v_and_b32_e32 v99, 0xffff0000, v146
	v_lshlrev_b32_e32 v100, 16, v147
	v_and_b32_e32 v101, 0xffff0000, v147
	v_pk_fma_f32 v[94:95], v[78:79], v[98:99], v[94:95]
	v_pk_fma_f32 v[90:91], v[74:75], v[102:103], v[90:91]
	v_mul_f32_e32 v98, 0x3d372713, v94
	v_pk_fma_f32 v[96:97], v[80:81], v[100:101], v[96:97]
	v_mul_f32_e32 v99, 0x3d372713, v90
	v_mul_f32_e32 v100, 0x3d372713, v95
	v_mul_f32_e32 v98, v94, v98
	v_mul_f32_e32 v99, v90, v99
	v_mul_f32_e32 v100, v95, v100
	v_fma_f32 v98, v94, v98, v94
	v_fma_f32 v99, v90, v99, v90
	v_fma_f32 v100, v95, v100, v95
	v_mul_f32_e32 v98, 0x3fcc422a, v98
	v_mul_f32_e32 v99, 0x3fcc422a, v99
	v_mul_f32_e32 v100, 0x3fcc422a, v100
	v_mul_f32_e32 v98, 0xbfb8aa3b, v98
	v_mul_f32_e32 v99, 0xbfb8aa3b, v99
	v_mul_f32_e32 v100, 0xbfb8aa3b, v100
	v_exp_f32_e32 v98, v98
	v_exp_f32_e32 v99, v99
	v_exp_f32_e32 v100, v100
	v_mul_f32_e32 v101, 0x3d372713, v91
	v_add_f32_e32 v98, 1.0, v98
	v_add_f32_e32 v99, 1.0, v99
	v_add_f32_e32 v100, 1.0, v100
	v_rcp_f32_e32 v98, v98
	v_rcp_f32_e32 v99, v99
	v_rcp_f32_e32 v100, v100
	v_mul_f32_e32 v101, v91, v101
	v_fma_f32 v101, v91, v101, v91
	v_lshlrev_b32_e32 v104, 16, v149
	v_and_b32_e32 v105, 0xffff0000, v149
	v_mul_f32_e32 v101, 0x3fcc422a, v101
	v_pk_fma_f32 v[92:93], v[76:77], v[104:105], v[92:93]
	v_mul_f32_e32 v101, 0xbfb8aa3b, v101
	v_exp_f32_e32 v101, v101
	v_mul_f32_e32 v94, v94, v98
	v_mul_f32_e32 v98, v90, v99
	v_mul_f32_e32 v90, v95, v100
	v_mul_f32_e32 v99, 0x3d372713, v96
	v_mul_f32_e32 v100, 0x3d372713, v92
	v_mul_f32_e32 v99, v96, v99
	v_mul_f32_e32 v100, v92, v100
	v_fma_f32 v99, v96, v99, v96
	v_fma_f32 v100, v92, v100, v92
	v_mul_f32_e32 v99, 0x3fcc422a, v99
	v_mul_f32_e32 v100, 0x3fcc422a, v100
	v_add_f32_e32 v95, 1.0, v101
	v_mul_f32_e32 v99, 0xbfb8aa3b, v99
	v_mul_f32_e32 v100, 0xbfb8aa3b, v100
	v_rcp_f32_e32 v95, v95
	v_exp_f32_e32 v99, v99
	v_exp_f32_e32 v100, v100
	v_mul_f32_e32 v101, 0x3d372713, v93
	v_mul_f32_e32 v95, v91, v95
	v_add_f32_e32 v91, 1.0, v99
	v_add_f32_e32 v99, 1.0, v100
	v_mul_f32_e32 v100, 0x3d372713, v97
	v_mul_f32_e32 v100, v97, v100
	v_fma_f32 v100, v97, v100, v97
	v_mul_f32_e32 v100, 0x3fcc422a, v100
	v_mul_f32_e32 v100, 0xbfb8aa3b, v100
	v_mul_f32_e32 v101, v93, v101
	v_exp_f32_e32 v100, v100
	v_fma_f32 v101, v93, v101, v93
	v_mul_f32_e32 v101, 0x3fcc422a, v101
	v_mul_f32_e32 v101, 0xbfb8aa3b, v101
	v_exp_f32_e32 v101, v101
	v_add_f32_e32 v100, 1.0, v100
	v_rcp_f32_e32 v91, v91
	v_rcp_f32_e32 v99, v99
	v_rcp_f32_e32 v100, v100
	v_add_f32_e32 v101, 1.0, v101
	v_rcp_f32_e32 v101, v101
	v_mul_f32_e32 v91, v96, v91
	v_mul_f32_e32 v96, v92, v99
	v_mul_f32_e32 v92, v97, v100
	v_cvt_pk_bf16_f32 v90, v94, v90
	v_add_u32_e32 v94, v114, v122
	v_cvt_pk_bf16_f32 v91, v91, v92
	v_cvt_pk_bf16_f32 v92, v98, v95
	v_mad_i64_i32 v[94:95], s[28:29], v94, s90, v[130:131]
	v_lshl_add_u64 v[94:95], v[94:95], 0, s[16:17]
	v_mul_f32_e32 v93, v93, v101
	v_lshl_add_u64 v[94:95], v[94:95], 0, v[0:1]
	v_cvt_pk_bf16_f32 v93, v96, v93
	global_store_dwordx4 v[94:95], v[90:93], off nt
	v_lshlrev_b32_e32 v94, 16, v144
	v_and_b32_e32 v95, 0xffff0000, v144
	v_lshlrev_b32_e32 v90, 16, v142
	v_and_b32_e32 v91, 0xffff0000, v142
	v_lshlrev_b32_e32 v92, 16, v143
	v_and_b32_e32 v93, 0xffff0000, v143
	v_pk_fma_f32 v[86:87], v[78:79], v[90:91], v[86:87]
	v_pk_fma_f32 v[82:83], v[74:75], v[94:95], v[82:83]
	v_mul_f32_e32 v90, 0x3d372713, v86
	v_pk_fma_f32 v[88:89], v[80:81], v[92:93], v[88:89]
	v_mul_f32_e32 v91, 0x3d372713, v82
	v_mul_f32_e32 v92, 0x3d372713, v87
	v_mul_f32_e32 v90, v86, v90
	v_mul_f32_e32 v91, v82, v91
	v_mul_f32_e32 v92, v87, v92
	v_fma_f32 v90, v86, v90, v86
	v_fma_f32 v91, v82, v91, v82
	v_fma_f32 v92, v87, v92, v87
	v_mul_f32_e32 v90, 0x3fcc422a, v90
	v_mul_f32_e32 v91, 0x3fcc422a, v91
	v_mul_f32_e32 v92, 0x3fcc422a, v92
	v_mul_f32_e32 v90, 0xbfb8aa3b, v90
	v_mul_f32_e32 v91, 0xbfb8aa3b, v91
	v_mul_f32_e32 v92, 0xbfb8aa3b, v92
	v_exp_f32_e32 v90, v90
	v_exp_f32_e32 v91, v91
	v_exp_f32_e32 v92, v92
	v_mul_f32_e32 v93, 0x3d372713, v83
	v_add_f32_e32 v90, 1.0, v90
	v_add_f32_e32 v91, 1.0, v91
	v_add_f32_e32 v92, 1.0, v92
	v_rcp_f32_e32 v90, v90
	v_rcp_f32_e32 v91, v91
	v_rcp_f32_e32 v92, v92
	v_mul_f32_e32 v93, v83, v93
	v_fma_f32 v93, v83, v93, v83
	v_lshlrev_b32_e32 v96, 16, v145
	v_and_b32_e32 v97, 0xffff0000, v145
	v_mul_f32_e32 v93, 0x3fcc422a, v93
	v_pk_fma_f32 v[84:85], v[76:77], v[96:97], v[84:85]
	v_mul_f32_e32 v93, 0xbfb8aa3b, v93
	v_exp_f32_e32 v93, v93
	v_mul_f32_e32 v86, v86, v90
	v_mul_f32_e32 v90, v82, v91
	v_mul_f32_e32 v82, v87, v92
	v_mul_f32_e32 v91, 0x3d372713, v88
	v_mul_f32_e32 v92, 0x3d372713, v84
	v_mul_f32_e32 v91, v88, v91
	v_mul_f32_e32 v92, v84, v92
	v_fma_f32 v91, v88, v91, v88
	v_fma_f32 v92, v84, v92, v84
	v_mul_f32_e32 v91, 0x3fcc422a, v91
	v_mul_f32_e32 v92, 0x3fcc422a, v92
	v_add_f32_e32 v87, 1.0, v93
	v_mul_f32_e32 v91, 0xbfb8aa3b, v91
	v_mul_f32_e32 v92, 0xbfb8aa3b, v92
	v_rcp_f32_e32 v87, v87
	v_exp_f32_e32 v91, v91
	v_exp_f32_e32 v92, v92
	v_mul_f32_e32 v93, 0x3d372713, v85
	v_mul_f32_e32 v87, v83, v87
	v_add_f32_e32 v83, 1.0, v91
	v_add_f32_e32 v91, 1.0, v92
	v_mul_f32_e32 v92, 0x3d372713, v89
	v_mul_f32_e32 v92, v89, v92
	v_fma_f32 v92, v89, v92, v89
	v_mul_f32_e32 v92, 0x3fcc422a, v92
	v_mul_f32_e32 v92, 0xbfb8aa3b, v92
	v_mul_f32_e32 v93, v85, v93
	v_exp_f32_e32 v92, v92
	v_fma_f32 v93, v85, v93, v85
	v_mul_f32_e32 v93, 0x3fcc422a, v93
	v_mul_f32_e32 v93, 0xbfb8aa3b, v93
	v_exp_f32_e32 v93, v93
	v_add_f32_e32 v92, 1.0, v92
	v_rcp_f32_e32 v83, v83
	v_rcp_f32_e32 v91, v91
	v_rcp_f32_e32 v92, v92
	v_add_f32_e32 v93, 1.0, v93
	v_or_b32_e32 v98, 0x600, v198
	v_rcp_f32_e32 v93, v93
	v_mul_f32_e32 v83, v88, v83
	v_mul_f32_e32 v88, v84, v91
	v_mul_f32_e32 v84, v89, v92
	v_cvt_pk_bf16_f32 v82, v86, v82
	v_add_u32_e32 v86, v98, v132
	v_cvt_pk_bf16_f32 v83, v83, v84
	v_cvt_pk_bf16_f32 v84, v90, v87
	v_mad_i64_i32 v[86:87], s[28:29], v86, s90, v[130:131]
	v_lshl_add_u64 v[86:87], v[86:87], 0, s[16:17]
	v_mul_f32_e32 v85, v85, v93
	v_lshl_add_u64 v[86:87], v[86:87], 0, v[0:1]
	v_cvt_pk_bf16_f32 v85, v88, v85
	global_store_dwordx4 v[86:87], v[82:85], off nt
	v_lshlrev_b32_e32 v86, 16, v140
	v_and_b32_e32 v87, 0xffff0000, v140
	v_lshlrev_b32_e32 v82, 16, v138
	v_and_b32_e32 v83, 0xffff0000, v138
	v_lshlrev_b32_e32 v84, 16, v139
	v_and_b32_e32 v85, 0xffff0000, v139
	v_pk_fma_f32 v[70:71], v[78:79], v[82:83], v[70:71]
	v_pk_fma_f32 v[66:67], v[74:75], v[86:87], v[66:67]
	v_mul_f32_e32 v82, 0x3d372713, v70
	v_pk_fma_f32 v[72:73], v[80:81], v[84:85], v[72:73]
	v_mul_f32_e32 v83, 0x3d372713, v66
	v_mul_f32_e32 v84, 0x3d372713, v71
	v_mul_f32_e32 v82, v70, v82
	v_mul_f32_e32 v83, v66, v83
	v_mul_f32_e32 v84, v71, v84
	v_fma_f32 v82, v70, v82, v70
	v_fma_f32 v83, v66, v83, v66
	v_fma_f32 v84, v71, v84, v71
	v_mul_f32_e32 v82, 0x3fcc422a, v82
	v_mul_f32_e32 v83, 0x3fcc422a, v83
	v_mul_f32_e32 v84, 0x3fcc422a, v84
	v_mul_f32_e32 v82, 0xbfb8aa3b, v82
	v_mul_f32_e32 v83, 0xbfb8aa3b, v83
	v_mul_f32_e32 v84, 0xbfb8aa3b, v84
	v_exp_f32_e32 v82, v82
	v_exp_f32_e32 v83, v83
	v_exp_f32_e32 v84, v84
	v_mul_f32_e32 v85, 0x3d372713, v67
	v_add_f32_e32 v82, 1.0, v82
	v_add_f32_e32 v83, 1.0, v83
	v_add_f32_e32 v84, 1.0, v84
	v_rcp_f32_e32 v82, v82
	v_rcp_f32_e32 v83, v83
	v_rcp_f32_e32 v84, v84
	v_mul_f32_e32 v85, v67, v85
	v_fma_f32 v85, v67, v85, v67
	v_lshlrev_b32_e32 v88, 16, v141
	v_and_b32_e32 v89, 0xffff0000, v141
	v_mul_f32_e32 v85, 0x3fcc422a, v85
	v_pk_fma_f32 v[68:69], v[76:77], v[88:89], v[68:69]
	v_mul_f32_e32 v85, 0xbfb8aa3b, v85
	v_exp_f32_e32 v85, v85
	v_mul_f32_e32 v70, v70, v82
	v_mul_f32_e32 v82, v66, v83
	v_mul_f32_e32 v66, v71, v84
	v_mul_f32_e32 v83, 0x3d372713, v72
	v_mul_f32_e32 v84, 0x3d372713, v68
	v_mul_f32_e32 v83, v72, v83
	v_mul_f32_e32 v84, v68, v84
	v_fma_f32 v83, v72, v83, v72
	v_fma_f32 v84, v68, v84, v68
	v_mul_f32_e32 v83, 0x3fcc422a, v83
	v_mul_f32_e32 v84, 0x3fcc422a, v84
	v_add_f32_e32 v71, 1.0, v85
	v_mul_f32_e32 v83, 0xbfb8aa3b, v83
	v_mul_f32_e32 v84, 0xbfb8aa3b, v84
	v_rcp_f32_e32 v71, v71
	v_exp_f32_e32 v83, v83
	v_exp_f32_e32 v84, v84
	v_mul_f32_e32 v85, 0x3d372713, v69
	v_mul_f32_e32 v71, v67, v71
	v_add_f32_e32 v67, 1.0, v83
	v_add_f32_e32 v83, 1.0, v84
	v_mul_f32_e32 v84, 0x3d372713, v73
	v_mul_f32_e32 v84, v73, v84
	v_fma_f32 v84, v73, v84, v73
	v_mul_f32_e32 v84, 0x3fcc422a, v84
	v_mul_f32_e32 v84, 0xbfb8aa3b, v84
	v_mul_f32_e32 v85, v69, v85
	v_exp_f32_e32 v84, v84
	v_fma_f32 v85, v69, v85, v69
	v_mul_f32_e32 v85, 0x3fcc422a, v85
	v_mul_f32_e32 v85, 0xbfb8aa3b, v85
	v_exp_f32_e32 v85, v85
	v_add_f32_e32 v84, 1.0, v84
	v_rcp_f32_e32 v67, v67
	v_rcp_f32_e32 v83, v83
	v_rcp_f32_e32 v84, v84
	v_add_f32_e32 v85, 1.0, v85
	v_rcp_f32_e32 v85, v85
	v_mul_f32_e32 v67, v72, v67
	v_mul_f32_e32 v72, v68, v83
	v_mul_f32_e32 v68, v73, v84
	v_cvt_pk_bf16_f32 v66, v70, v66
	v_add_u32_e32 v70, v98, v122
	v_cvt_pk_bf16_f32 v67, v67, v68
	v_cvt_pk_bf16_f32 v68, v82, v71
	v_mad_i64_i32 v[70:71], s[28:29], v70, s90, v[130:131]
	v_lshl_add_u64 v[70:71], v[70:71], 0, s[16:17]
	v_mul_f32_e32 v69, v69, v85
	v_lshl_add_u64 v[70:71], v[70:71], 0, v[0:1]
	v_cvt_pk_bf16_f32 v69, v72, v69
	global_store_dwordx4 v[70:71], v[66:69], off nt
	v_add_u32_e32 v98, 0x1000, v197
	v_and_b32_e32 v98, 0x79e0, v98
	v_add_u32_e32 v66, 0x80, v196
	v_mad_i64_i32 v[66:67], s[28:29], v66, s58, v[188:189]
	v_lshl_add_u64 v[66:67], v[66:67], 0, v[190:191]
	global_load_dwordx4 v[100:103], v[66:67], off offset:256
	global_load_dwordx4 v[104:107], v[66:67], off offset:512
	v_add_u32_e32 v66, 0x90, v196
	v_mad_i64_i32 v[66:67], s[28:29], v66, s58, v[188:189]
	v_lshl_add_u64 v[66:67], v[66:67], 0, v[190:191]
	global_load_dwordx4 v[94:97], v[66:67], off offset:256
	global_load_dwordx4 v[90:93], v[66:67], off offset:512
	v_add_u32_e32 v66, 0xa0, v196
	v_mad_i64_i32 v[66:67], s[28:29], v66, s58, v[188:189]
	v_lshl_add_u64 v[66:67], v[66:67], 0, v[190:191]
	global_load_dwordx4 v[86:89], v[66:67], off offset:256
	global_load_dwordx4 v[82:85], v[66:67], off offset:512
	v_add_u32_e32 v66, 0xb0, v196
	v_mad_i64_i32 v[66:67], s[28:29], v66, s58, v[188:189]
	v_lshl_add_u64 v[66:67], v[66:67], 0, v[190:191]
	global_load_dwordx4 v[70:73], v[66:67], off offset:256
	s_nop 0
	global_load_dwordx4 v[66:69], v[66:67], off offset:512
	s_waitcnt vmcnt(0)
	v_lshlrev_b32_e32 v108, 16, v100
	v_and_b32_e32 v109, 0xffff0000, v100
	v_lshlrev_b32_e32 v110, 16, v102
	v_and_b32_e32 v111, 0xffff0000, v102
	v_lshlrev_b32_e32 v100, 16, v101
	v_and_b32_e32 v101, 0xffff0000, v101
	v_pk_fma_f32 v[62:63], v[78:79], v[108:109], v[62:63]
	v_pk_fma_f32 v[58:59], v[74:75], v[110:111], v[58:59]
	v_mul_f32_e32 v99, 0x3d372713, v62
	v_pk_fma_f32 v[64:65], v[80:81], v[100:101], v[64:65]
	v_mul_f32_e32 v100, 0x3d372713, v58
	v_mul_f32_e32 v101, 0x3d372713, v63
	v_mul_f32_e32 v99, v62, v99
	v_mul_f32_e32 v100, v58, v100
	v_mul_f32_e32 v101, v63, v101
	v_fma_f32 v99, v62, v99, v62
	v_fma_f32 v100, v58, v100, v58
	v_fma_f32 v101, v63, v101, v63
	v_mul_f32_e32 v99, 0x3fcc422a, v99
	v_mul_f32_e32 v100, 0x3fcc422a, v100
	v_mul_f32_e32 v101, 0x3fcc422a, v101
	v_mul_f32_e32 v99, 0xbfb8aa3b, v99
	v_mul_f32_e32 v100, 0xbfb8aa3b, v100
	v_mul_f32_e32 v101, 0xbfb8aa3b, v101
	v_exp_f32_e32 v99, v99
	v_exp_f32_e32 v100, v100
	v_exp_f32_e32 v101, v101
	v_lshlrev_b32_e32 v102, 16, v103
	v_and_b32_e32 v103, 0xffff0000, v103
	v_pk_fma_f32 v[60:61], v[76:77], v[102:103], v[60:61]
	v_add_f32_e32 v99, 1.0, v99
	v_add_f32_e32 v100, 1.0, v100
	v_add_f32_e32 v101, 1.0, v101
	v_mul_f32_e32 v102, 0x3d372713, v59
	v_rcp_f32_e32 v99, v99
	v_rcp_f32_e32 v100, v100
	v_rcp_f32_e32 v101, v101
	v_mul_f32_e32 v102, v59, v102
	v_fma_f32 v102, v59, v102, v59
	v_mul_f32_e32 v102, 0x3fcc422a, v102
	v_mul_f32_e32 v102, 0xbfb8aa3b, v102
	v_exp_f32_e32 v102, v102
	v_mul_f32_e32 v62, v62, v99
	v_mul_f32_e32 v99, v58, v100
	v_mul_f32_e32 v58, v63, v101
	v_mul_f32_e32 v100, 0x3d372713, v64
	v_mul_f32_e32 v101, 0x3d372713, v60
	v_mul_f32_e32 v100, v64, v100
	v_mul_f32_e32 v101, v60, v101
	v_fma_f32 v100, v64, v100, v64
	v_fma_f32 v101, v60, v101, v60
	v_mul_f32_e32 v100, 0x3fcc422a, v100
	v_mul_f32_e32 v101, 0x3fcc422a, v101
	v_add_f32_e32 v63, 1.0, v102
	v_mul_f32_e32 v100, 0xbfb8aa3b, v100
	v_mul_f32_e32 v101, 0xbfb8aa3b, v101
	v_rcp_f32_e32 v63, v63
	v_exp_f32_e32 v100, v100
	v_exp_f32_e32 v101, v101
	v_mul_f32_e32 v102, 0x3d372713, v61
	v_mul_f32_e32 v63, v59, v63
	v_add_f32_e32 v59, 1.0, v100
	v_add_f32_e32 v100, 1.0, v101
	v_mul_f32_e32 v101, 0x3d372713, v65
	v_mul_f32_e32 v101, v65, v101
	v_fma_f32 v101, v65, v101, v65
	v_mul_f32_e32 v101, 0x3fcc422a, v101
	v_mul_f32_e32 v101, 0xbfb8aa3b, v101
	v_mul_f32_e32 v102, v61, v102
	v_exp_f32_e32 v101, v101
	v_fma_f32 v102, v61, v102, v61
	v_mul_f32_e32 v102, 0x3fcc422a, v102
	v_mul_f32_e32 v102, 0xbfb8aa3b, v102
	v_exp_f32_e32 v102, v102
	v_add_f32_e32 v101, 1.0, v101
	v_rcp_f32_e32 v59, v59
	v_rcp_f32_e32 v100, v100
	v_rcp_f32_e32 v101, v101
	v_add_f32_e32 v102, 1.0, v102
	v_rcp_f32_e32 v102, v102
	v_mul_f32_e32 v59, v64, v59
	v_mul_f32_e32 v64, v60, v100
	v_mul_f32_e32 v60, v65, v101
	v_cvt_pk_bf16_f32 v58, v62, v58
	v_add_u32_e32 v62, v98, v132
	v_cvt_pk_bf16_f32 v59, v59, v60
	v_cvt_pk_bf16_f32 v60, v99, v63
	v_mad_i64_i32 v[62:63], s[28:29], v62, s90, v[130:131]
	v_lshl_add_u64 v[62:63], v[62:63], 0, s[16:17]
	v_mul_f32_e32 v61, v61, v102
	v_lshl_add_u64 v[62:63], v[62:63], 0, v[0:1]
	v_cvt_pk_bf16_f32 v61, v64, v61
	global_store_dwordx4 v[62:63], v[58:61], off nt
	v_lshlrev_b32_e32 v62, 16, v106
	v_and_b32_e32 v63, 0xffff0000, v106
	v_lshlrev_b32_e32 v58, 16, v104
	v_and_b32_e32 v59, 0xffff0000, v104
	v_lshlrev_b32_e32 v60, 16, v105
	v_and_b32_e32 v61, 0xffff0000, v105
	v_pk_fma_f32 v[54:55], v[78:79], v[58:59], v[54:55]
	v_pk_fma_f32 v[50:51], v[74:75], v[62:63], v[50:51]
	v_mul_f32_e32 v58, 0x3d372713, v54
	v_pk_fma_f32 v[56:57], v[80:81], v[60:61], v[56:57]
	v_mul_f32_e32 v59, 0x3d372713, v50
	v_mul_f32_e32 v60, 0x3d372713, v55
	v_mul_f32_e32 v58, v54, v58
	v_mul_f32_e32 v59, v50, v59
	v_mul_f32_e32 v60, v55, v60
	v_fma_f32 v58, v54, v58, v54
	v_fma_f32 v59, v50, v59, v50
	v_fma_f32 v60, v55, v60, v55
	v_mul_f32_e32 v58, 0x3fcc422a, v58
	v_mul_f32_e32 v59, 0x3fcc422a, v59
	v_mul_f32_e32 v60, 0x3fcc422a, v60
	v_mul_f32_e32 v58, 0xbfb8aa3b, v58
	v_mul_f32_e32 v59, 0xbfb8aa3b, v59
	v_mul_f32_e32 v60, 0xbfb8aa3b, v60
	v_exp_f32_e32 v58, v58
	v_exp_f32_e32 v59, v59
	v_exp_f32_e32 v60, v60
	v_mul_f32_e32 v61, 0x3d372713, v51
	v_add_f32_e32 v58, 1.0, v58
	v_add_f32_e32 v59, 1.0, v59
	v_add_f32_e32 v60, 1.0, v60
	v_rcp_f32_e32 v58, v58
	v_rcp_f32_e32 v59, v59
	v_rcp_f32_e32 v60, v60
	v_mul_f32_e32 v61, v51, v61
	v_fma_f32 v61, v51, v61, v51
	v_lshlrev_b32_e32 v64, 16, v107
	v_and_b32_e32 v65, 0xffff0000, v107
	v_mul_f32_e32 v61, 0x3fcc422a, v61
	v_pk_fma_f32 v[52:53], v[76:77], v[64:65], v[52:53]
	v_mul_f32_e32 v61, 0xbfb8aa3b, v61
	v_exp_f32_e32 v61, v61
	v_mul_f32_e32 v54, v54, v58
	v_mul_f32_e32 v58, v50, v59
	v_mul_f32_e32 v50, v55, v60
	v_mul_f32_e32 v59, 0x3d372713, v56
	v_mul_f32_e32 v60, 0x3d372713, v52
	v_mul_f32_e32 v59, v56, v59
	v_mul_f32_e32 v60, v52, v60
	v_fma_f32 v59, v56, v59, v56
	v_fma_f32 v60, v52, v60, v52
	v_mul_f32_e32 v59, 0x3fcc422a, v59
	v_mul_f32_e32 v60, 0x3fcc422a, v60
	v_add_f32_e32 v55, 1.0, v61
	v_mul_f32_e32 v59, 0xbfb8aa3b, v59
	v_mul_f32_e32 v60, 0xbfb8aa3b, v60
	v_rcp_f32_e32 v55, v55
	v_exp_f32_e32 v59, v59
	v_exp_f32_e32 v60, v60
	v_mul_f32_e32 v61, 0x3d372713, v53
	v_mul_f32_e32 v55, v51, v55
	v_add_f32_e32 v51, 1.0, v59
	v_add_f32_e32 v59, 1.0, v60
	v_mul_f32_e32 v60, 0x3d372713, v57
	v_mul_f32_e32 v60, v57, v60
	v_fma_f32 v60, v57, v60, v57
	v_mul_f32_e32 v60, 0x3fcc422a, v60
	v_mul_f32_e32 v60, 0xbfb8aa3b, v60
	v_mul_f32_e32 v61, v53, v61
	v_exp_f32_e32 v60, v60
	v_fma_f32 v61, v53, v61, v53
	v_mul_f32_e32 v61, 0x3fcc422a, v61
	v_mul_f32_e32 v61, 0xbfb8aa3b, v61
	v_exp_f32_e32 v61, v61
	v_add_f32_e32 v60, 1.0, v60
	v_rcp_f32_e32 v51, v51
	v_rcp_f32_e32 v59, v59
	v_rcp_f32_e32 v60, v60
	v_add_f32_e32 v61, 1.0, v61
	v_rcp_f32_e32 v61, v61
	v_mul_f32_e32 v51, v56, v51
	v_mul_f32_e32 v56, v52, v59
	v_mul_f32_e32 v52, v57, v60
	v_cvt_pk_bf16_f32 v50, v54, v50
	v_add_u32_e32 v54, v98, v122
	v_cvt_pk_bf16_f32 v51, v51, v52
	v_cvt_pk_bf16_f32 v52, v58, v55
	v_mad_i64_i32 v[54:55], s[28:29], v54, s90, v[130:131]
	v_lshl_add_u64 v[54:55], v[54:55], 0, s[16:17]
	v_mul_f32_e32 v53, v53, v61
	v_lshl_add_u64 v[54:55], v[54:55], 0, v[0:1]
	v_cvt_pk_bf16_f32 v53, v56, v53
	global_store_dwordx4 v[54:55], v[50:53], off
	v_lshlrev_b32_e32 v54, 16, v96
	v_and_b32_e32 v55, 0xffff0000, v96
	v_lshlrev_b32_e32 v50, 16, v94
	v_and_b32_e32 v51, 0xffff0000, v94
	v_lshlrev_b32_e32 v52, 16, v95
	v_and_b32_e32 v53, 0xffff0000, v95
	v_pk_fma_f32 v[46:47], v[78:79], v[50:51], v[46:47]
	v_pk_fma_f32 v[42:43], v[74:75], v[54:55], v[42:43]
	v_mul_f32_e32 v50, 0x3d372713, v46
	v_pk_fma_f32 v[48:49], v[80:81], v[52:53], v[48:49]
	v_mul_f32_e32 v51, 0x3d372713, v42
	v_mul_f32_e32 v52, 0x3d372713, v47
	v_mul_f32_e32 v50, v46, v50
	v_mul_f32_e32 v51, v42, v51
	v_mul_f32_e32 v52, v47, v52
	v_fma_f32 v50, v46, v50, v46
	v_fma_f32 v51, v42, v51, v42
	v_fma_f32 v52, v47, v52, v47
	v_mul_f32_e32 v50, 0x3fcc422a, v50
	v_mul_f32_e32 v51, 0x3fcc422a, v51
	v_mul_f32_e32 v52, 0x3fcc422a, v52
	v_mul_f32_e32 v50, 0xbfb8aa3b, v50
	v_mul_f32_e32 v51, 0xbfb8aa3b, v51
	v_mul_f32_e32 v52, 0xbfb8aa3b, v52
	v_exp_f32_e32 v50, v50
	v_exp_f32_e32 v51, v51
	v_exp_f32_e32 v52, v52
	v_mul_f32_e32 v53, 0x3d372713, v43
	v_add_f32_e32 v50, 1.0, v50
	v_add_f32_e32 v51, 1.0, v51
	v_add_f32_e32 v52, 1.0, v52
	v_rcp_f32_e32 v50, v50
	v_rcp_f32_e32 v51, v51
	v_rcp_f32_e32 v52, v52
	v_mul_f32_e32 v53, v43, v53
	v_fma_f32 v53, v43, v53, v43
	v_lshlrev_b32_e32 v56, 16, v97
	v_and_b32_e32 v57, 0xffff0000, v97
	v_mul_f32_e32 v53, 0x3fcc422a, v53
	v_pk_fma_f32 v[44:45], v[76:77], v[56:57], v[44:45]
	v_mul_f32_e32 v53, 0xbfb8aa3b, v53
	v_exp_f32_e32 v53, v53
	v_mul_f32_e32 v46, v46, v50
	v_mul_f32_e32 v50, v42, v51
	v_mul_f32_e32 v42, v47, v52
	v_mul_f32_e32 v51, 0x3d372713, v48
	v_mul_f32_e32 v52, 0x3d372713, v44
	v_mul_f32_e32 v51, v48, v51
	v_mul_f32_e32 v52, v44, v52
	v_fma_f32 v51, v48, v51, v48
	v_fma_f32 v52, v44, v52, v44
	v_mul_f32_e32 v51, 0x3fcc422a, v51
	v_mul_f32_e32 v52, 0x3fcc422a, v52
	v_add_f32_e32 v47, 1.0, v53
	v_mul_f32_e32 v51, 0xbfb8aa3b, v51
	v_mul_f32_e32 v52, 0xbfb8aa3b, v52
	v_rcp_f32_e32 v47, v47
	v_exp_f32_e32 v51, v51
	v_exp_f32_e32 v52, v52
	v_mul_f32_e32 v53, 0x3d372713, v45
	v_mul_f32_e32 v47, v43, v47
	v_add_f32_e32 v43, 1.0, v51
	v_add_f32_e32 v51, 1.0, v52
	v_mul_f32_e32 v52, 0x3d372713, v49
	v_mul_f32_e32 v52, v49, v52
	v_fma_f32 v52, v49, v52, v49
	v_mul_f32_e32 v52, 0x3fcc422a, v52
	v_mul_f32_e32 v52, 0xbfb8aa3b, v52
	v_mul_f32_e32 v53, v45, v53
	v_exp_f32_e32 v52, v52
	v_fma_f32 v53, v45, v53, v45
	v_mul_f32_e32 v53, 0x3fcc422a, v53
	v_mul_f32_e32 v53, 0xbfb8aa3b, v53
	v_exp_f32_e32 v53, v53
	v_add_f32_e32 v52, 1.0, v52
	v_rcp_f32_e32 v43, v43
	v_rcp_f32_e32 v51, v51
	v_rcp_f32_e32 v52, v52
	v_add_f32_e32 v53, 1.0, v53
	v_or_b32_e32 v58, 0x200, v98
	v_rcp_f32_e32 v53, v53
	v_mul_f32_e32 v43, v48, v43
	v_mul_f32_e32 v48, v44, v51
	v_mul_f32_e32 v44, v49, v52
	v_cvt_pk_bf16_f32 v42, v46, v42
	v_add_u32_e32 v46, v58, v132
	v_cvt_pk_bf16_f32 v43, v43, v44
	v_cvt_pk_bf16_f32 v44, v50, v47
	v_mad_i64_i32 v[46:47], s[28:29], v46, s90, v[130:131]
	v_lshl_add_u64 v[46:47], v[46:47], 0, s[16:17]
	v_mul_f32_e32 v45, v45, v53
	v_lshl_add_u64 v[46:47], v[46:47], 0, v[0:1]
	v_cvt_pk_bf16_f32 v45, v48, v45
	global_store_dwordx4 v[46:47], v[42:45], off
	v_lshlrev_b32_e32 v46, 16, v92
	v_and_b32_e32 v47, 0xffff0000, v92
	v_lshlrev_b32_e32 v42, 16, v90
	v_and_b32_e32 v43, 0xffff0000, v90
	v_lshlrev_b32_e32 v44, 16, v91
	v_and_b32_e32 v45, 0xffff0000, v91
	v_pk_fma_f32 v[38:39], v[78:79], v[42:43], v[38:39]
	v_pk_fma_f32 v[34:35], v[74:75], v[46:47], v[34:35]
	v_mul_f32_e32 v42, 0x3d372713, v38
	v_pk_fma_f32 v[40:41], v[80:81], v[44:45], v[40:41]
	v_mul_f32_e32 v43, 0x3d372713, v34
	v_mul_f32_e32 v44, 0x3d372713, v39
	v_mul_f32_e32 v42, v38, v42
	v_mul_f32_e32 v43, v34, v43
	v_mul_f32_e32 v44, v39, v44
	v_fma_f32 v42, v38, v42, v38
	v_fma_f32 v43, v34, v43, v34
	v_fma_f32 v44, v39, v44, v39
	v_mul_f32_e32 v42, 0x3fcc422a, v42
	v_mul_f32_e32 v43, 0x3fcc422a, v43
	v_mul_f32_e32 v44, 0x3fcc422a, v44
	v_mul_f32_e32 v42, 0xbfb8aa3b, v42
	v_mul_f32_e32 v43, 0xbfb8aa3b, v43
	v_mul_f32_e32 v44, 0xbfb8aa3b, v44
	v_exp_f32_e32 v42, v42
	v_exp_f32_e32 v43, v43
	v_exp_f32_e32 v44, v44
	v_mul_f32_e32 v45, 0x3d372713, v35
	v_add_f32_e32 v42, 1.0, v42
	v_add_f32_e32 v43, 1.0, v43
	v_add_f32_e32 v44, 1.0, v44
	v_rcp_f32_e32 v42, v42
	v_rcp_f32_e32 v43, v43
	v_rcp_f32_e32 v44, v44
	v_mul_f32_e32 v45, v35, v45
	v_fma_f32 v45, v35, v45, v35
	v_lshlrev_b32_e32 v48, 16, v93
	v_and_b32_e32 v49, 0xffff0000, v93
	v_mul_f32_e32 v45, 0x3fcc422a, v45
	v_pk_fma_f32 v[36:37], v[76:77], v[48:49], v[36:37]
	v_mul_f32_e32 v45, 0xbfb8aa3b, v45
	v_exp_f32_e32 v45, v45
	v_mul_f32_e32 v38, v38, v42
	v_mul_f32_e32 v42, v34, v43
	v_mul_f32_e32 v34, v39, v44
	v_mul_f32_e32 v43, 0x3d372713, v40
	v_mul_f32_e32 v44, 0x3d372713, v36
	v_mul_f32_e32 v43, v40, v43
	v_mul_f32_e32 v44, v36, v44
	v_fma_f32 v43, v40, v43, v40
	v_fma_f32 v44, v36, v44, v36
	v_mul_f32_e32 v43, 0x3fcc422a, v43
	v_mul_f32_e32 v44, 0x3fcc422a, v44
	v_add_f32_e32 v39, 1.0, v45
	v_mul_f32_e32 v43, 0xbfb8aa3b, v43
	v_mul_f32_e32 v44, 0xbfb8aa3b, v44
	v_rcp_f32_e32 v39, v39
	v_exp_f32_e32 v43, v43
	v_exp_f32_e32 v44, v44
	v_mul_f32_e32 v45, 0x3d372713, v37
	v_mul_f32_e32 v39, v35, v39
	v_add_f32_e32 v35, 1.0, v43
	v_add_f32_e32 v43, 1.0, v44
	v_mul_f32_e32 v44, 0x3d372713, v41
	v_mul_f32_e32 v44, v41, v44
	v_fma_f32 v44, v41, v44, v41
	v_mul_f32_e32 v44, 0x3fcc422a, v44
	v_mul_f32_e32 v44, 0xbfb8aa3b, v44
	v_mul_f32_e32 v45, v37, v45
	v_exp_f32_e32 v44, v44
	v_fma_f32 v45, v37, v45, v37
	v_mul_f32_e32 v45, 0x3fcc422a, v45
	v_mul_f32_e32 v45, 0xbfb8aa3b, v45
	v_exp_f32_e32 v45, v45
	v_add_f32_e32 v44, 1.0, v44
	v_rcp_f32_e32 v35, v35
	v_rcp_f32_e32 v43, v43
	v_rcp_f32_e32 v44, v44
	v_add_f32_e32 v45, 1.0, v45
	v_rcp_f32_e32 v45, v45
	v_mul_f32_e32 v35, v40, v35
	v_mul_f32_e32 v40, v36, v43
	v_mul_f32_e32 v36, v41, v44
	v_cvt_pk_bf16_f32 v34, v38, v34
	v_add_u32_e32 v38, v58, v122
	v_cvt_pk_bf16_f32 v35, v35, v36
	v_cvt_pk_bf16_f32 v36, v42, v39
	v_mad_i64_i32 v[38:39], s[28:29], v38, s90, v[130:131]
	v_lshl_add_u64 v[38:39], v[38:39], 0, s[16:17]
	v_mul_f32_e32 v37, v37, v45
	v_lshl_add_u64 v[38:39], v[38:39], 0, v[0:1]
	v_cvt_pk_bf16_f32 v37, v40, v37
	global_store_dwordx4 v[38:39], v[34:37], off
	v_lshlrev_b32_e32 v38, 16, v88
	v_and_b32_e32 v39, 0xffff0000, v88
	v_lshlrev_b32_e32 v34, 16, v86
	v_and_b32_e32 v35, 0xffff0000, v86
	v_lshlrev_b32_e32 v36, 16, v87
	v_and_b32_e32 v37, 0xffff0000, v87
	v_pk_fma_f32 v[30:31], v[78:79], v[34:35], v[30:31]
	v_pk_fma_f32 v[26:27], v[74:75], v[38:39], v[26:27]
	v_mul_f32_e32 v34, 0x3d372713, v30
	v_pk_fma_f32 v[32:33], v[80:81], v[36:37], v[32:33]
	v_mul_f32_e32 v35, 0x3d372713, v26
	v_mul_f32_e32 v36, 0x3d372713, v31
	v_mul_f32_e32 v34, v30, v34
	v_mul_f32_e32 v35, v26, v35
	v_mul_f32_e32 v36, v31, v36
	v_fma_f32 v34, v30, v34, v30
	v_fma_f32 v35, v26, v35, v26
	v_fma_f32 v36, v31, v36, v31
	v_mul_f32_e32 v34, 0x3fcc422a, v34
	v_mul_f32_e32 v35, 0x3fcc422a, v35
	v_mul_f32_e32 v36, 0x3fcc422a, v36
	v_mul_f32_e32 v34, 0xbfb8aa3b, v34
	v_mul_f32_e32 v35, 0xbfb8aa3b, v35
	v_mul_f32_e32 v36, 0xbfb8aa3b, v36
	v_exp_f32_e32 v34, v34
	v_exp_f32_e32 v35, v35
	v_exp_f32_e32 v36, v36
	v_mul_f32_e32 v37, 0x3d372713, v27
	v_add_f32_e32 v34, 1.0, v34
	v_add_f32_e32 v35, 1.0, v35
	v_add_f32_e32 v36, 1.0, v36
	v_rcp_f32_e32 v34, v34
	v_rcp_f32_e32 v35, v35
	v_rcp_f32_e32 v36, v36
	v_mul_f32_e32 v37, v27, v37
	v_fma_f32 v37, v27, v37, v27
	v_lshlrev_b32_e32 v40, 16, v89
	v_and_b32_e32 v41, 0xffff0000, v89
	v_mul_f32_e32 v37, 0x3fcc422a, v37
	v_pk_fma_f32 v[28:29], v[76:77], v[40:41], v[28:29]
	v_mul_f32_e32 v37, 0xbfb8aa3b, v37
	v_exp_f32_e32 v37, v37
	v_mul_f32_e32 v30, v30, v34
	v_mul_f32_e32 v34, v26, v35
	v_mul_f32_e32 v26, v31, v36
	v_mul_f32_e32 v35, 0x3d372713, v32
	v_mul_f32_e32 v36, 0x3d372713, v28
	v_mul_f32_e32 v35, v32, v35
	v_mul_f32_e32 v36, v28, v36
	v_fma_f32 v35, v32, v35, v32
	v_fma_f32 v36, v28, v36, v28
	v_mul_f32_e32 v35, 0x3fcc422a, v35
	v_mul_f32_e32 v36, 0x3fcc422a, v36
	v_add_f32_e32 v31, 1.0, v37
	v_mul_f32_e32 v35, 0xbfb8aa3b, v35
	v_mul_f32_e32 v36, 0xbfb8aa3b, v36
	v_rcp_f32_e32 v31, v31
	v_exp_f32_e32 v35, v35
	v_exp_f32_e32 v36, v36
	v_mul_f32_e32 v37, 0x3d372713, v29
	v_mul_f32_e32 v31, v27, v31
	v_add_f32_e32 v27, 1.0, v35
	v_add_f32_e32 v35, 1.0, v36
	v_mul_f32_e32 v36, 0x3d372713, v33
	v_mul_f32_e32 v36, v33, v36
	v_fma_f32 v36, v33, v36, v33
	v_mul_f32_e32 v36, 0x3fcc422a, v36
	v_mul_f32_e32 v36, 0xbfb8aa3b, v36
	v_mul_f32_e32 v37, v29, v37
	v_exp_f32_e32 v36, v36
	v_fma_f32 v37, v29, v37, v29
	v_mul_f32_e32 v37, 0x3fcc422a, v37
	v_mul_f32_e32 v37, 0xbfb8aa3b, v37
	v_exp_f32_e32 v37, v37
	v_add_f32_e32 v36, 1.0, v36
	v_rcp_f32_e32 v27, v27
	v_rcp_f32_e32 v35, v35
	v_rcp_f32_e32 v36, v36
	v_add_f32_e32 v37, 1.0, v37
	v_or_b32_e32 v42, 0x400, v98
	v_rcp_f32_e32 v37, v37
	v_mul_f32_e32 v27, v32, v27
	v_mul_f32_e32 v32, v28, v35
	v_mul_f32_e32 v28, v33, v36
	v_cvt_pk_bf16_f32 v26, v30, v26
	v_add_u32_e32 v30, v42, v132
	v_cvt_pk_bf16_f32 v27, v27, v28
	v_cvt_pk_bf16_f32 v28, v34, v31
	v_mad_i64_i32 v[30:31], s[28:29], v30, s90, v[130:131]
	v_lshl_add_u64 v[30:31], v[30:31], 0, s[16:17]
	v_mul_f32_e32 v29, v29, v37
	v_lshl_add_u64 v[30:31], v[30:31], 0, v[0:1]
	v_cvt_pk_bf16_f32 v29, v32, v29
	global_store_dwordx4 v[30:31], v[26:29], off
	v_lshlrev_b32_e32 v30, 16, v84
	v_and_b32_e32 v31, 0xffff0000, v84
	v_lshlrev_b32_e32 v26, 16, v82
	v_and_b32_e32 v27, 0xffff0000, v82
	v_lshlrev_b32_e32 v28, 16, v83
	v_and_b32_e32 v29, 0xffff0000, v83
	v_pk_fma_f32 v[22:23], v[78:79], v[26:27], v[22:23]
	v_pk_fma_f32 v[18:19], v[74:75], v[30:31], v[18:19]
	v_mul_f32_e32 v26, 0x3d372713, v22
	v_pk_fma_f32 v[24:25], v[80:81], v[28:29], v[24:25]
	v_mul_f32_e32 v27, 0x3d372713, v18
	v_mul_f32_e32 v28, 0x3d372713, v23
	v_mul_f32_e32 v26, v22, v26
	v_mul_f32_e32 v27, v18, v27
	v_mul_f32_e32 v28, v23, v28
	v_fma_f32 v26, v22, v26, v22
	v_fma_f32 v27, v18, v27, v18
	v_fma_f32 v28, v23, v28, v23
	v_mul_f32_e32 v26, 0x3fcc422a, v26
	v_mul_f32_e32 v27, 0x3fcc422a, v27
	v_mul_f32_e32 v28, 0x3fcc422a, v28
	v_mul_f32_e32 v26, 0xbfb8aa3b, v26
	v_mul_f32_e32 v27, 0xbfb8aa3b, v27
	v_mul_f32_e32 v28, 0xbfb8aa3b, v28
	v_exp_f32_e32 v26, v26
	v_exp_f32_e32 v27, v27
	v_exp_f32_e32 v28, v28
	v_mul_f32_e32 v29, 0x3d372713, v19
	v_add_f32_e32 v26, 1.0, v26
	v_add_f32_e32 v27, 1.0, v27
	v_add_f32_e32 v28, 1.0, v28
	v_rcp_f32_e32 v26, v26
	v_rcp_f32_e32 v27, v27
	v_rcp_f32_e32 v28, v28
	v_mul_f32_e32 v29, v19, v29
	v_fma_f32 v29, v19, v29, v19
	v_lshlrev_b32_e32 v32, 16, v85
	v_and_b32_e32 v33, 0xffff0000, v85
	v_mul_f32_e32 v29, 0x3fcc422a, v29
	v_pk_fma_f32 v[20:21], v[76:77], v[32:33], v[20:21]
	v_mul_f32_e32 v29, 0xbfb8aa3b, v29
	v_exp_f32_e32 v29, v29
	v_mul_f32_e32 v22, v22, v26
	v_mul_f32_e32 v26, v18, v27
	v_mul_f32_e32 v18, v23, v28
	v_mul_f32_e32 v27, 0x3d372713, v24
	v_mul_f32_e32 v28, 0x3d372713, v20
	v_mul_f32_e32 v27, v24, v27
	v_mul_f32_e32 v28, v20, v28
	v_fma_f32 v27, v24, v27, v24
	v_fma_f32 v28, v20, v28, v20
	v_mul_f32_e32 v27, 0x3fcc422a, v27
	v_mul_f32_e32 v28, 0x3fcc422a, v28
	v_add_f32_e32 v23, 1.0, v29
	v_mul_f32_e32 v27, 0xbfb8aa3b, v27
	v_mul_f32_e32 v28, 0xbfb8aa3b, v28
	v_rcp_f32_e32 v23, v23
	v_exp_f32_e32 v27, v27
	v_exp_f32_e32 v28, v28
	v_mul_f32_e32 v29, 0x3d372713, v21
	v_mul_f32_e32 v23, v19, v23
	v_add_f32_e32 v19, 1.0, v27
	v_add_f32_e32 v27, 1.0, v28
	v_mul_f32_e32 v28, 0x3d372713, v25
	v_mul_f32_e32 v28, v25, v28
	v_fma_f32 v28, v25, v28, v25
	v_mul_f32_e32 v28, 0x3fcc422a, v28
	v_mul_f32_e32 v28, 0xbfb8aa3b, v28
	v_mul_f32_e32 v29, v21, v29
	v_exp_f32_e32 v28, v28
	v_fma_f32 v29, v21, v29, v21
	v_mul_f32_e32 v29, 0x3fcc422a, v29
	v_mul_f32_e32 v29, 0xbfb8aa3b, v29
	v_exp_f32_e32 v29, v29
	v_add_f32_e32 v28, 1.0, v28
	v_rcp_f32_e32 v19, v19
	v_rcp_f32_e32 v27, v27
	v_rcp_f32_e32 v28, v28
	v_add_f32_e32 v29, 1.0, v29
	v_rcp_f32_e32 v29, v29
	v_mul_f32_e32 v19, v24, v19
	v_mul_f32_e32 v24, v20, v27
	v_mul_f32_e32 v20, v25, v28
	v_cvt_pk_bf16_f32 v18, v22, v18
	v_add_u32_e32 v22, v42, v122
	v_cvt_pk_bf16_f32 v19, v19, v20
	v_cvt_pk_bf16_f32 v20, v26, v23
	v_mad_i64_i32 v[22:23], s[28:29], v22, s90, v[130:131]
	v_lshl_add_u64 v[22:23], v[22:23], 0, s[16:17]
	v_mul_f32_e32 v21, v21, v29
	v_lshl_add_u64 v[22:23], v[22:23], 0, v[0:1]
	v_cvt_pk_bf16_f32 v21, v24, v21
	global_store_dwordx4 v[22:23], v[18:21], off
	v_lshlrev_b32_e32 v22, 16, v72
	v_and_b32_e32 v23, 0xffff0000, v72
	v_lshlrev_b32_e32 v18, 16, v70
	v_and_b32_e32 v19, 0xffff0000, v70
	v_lshlrev_b32_e32 v20, 16, v71
	v_and_b32_e32 v21, 0xffff0000, v71
	v_pk_fma_f32 v[14:15], v[78:79], v[18:19], v[14:15]
	v_pk_fma_f32 v[10:11], v[74:75], v[22:23], v[10:11]
	v_mul_f32_e32 v18, 0x3d372713, v14
	v_pk_fma_f32 v[16:17], v[80:81], v[20:21], v[16:17]
	v_mul_f32_e32 v19, 0x3d372713, v10
	v_mul_f32_e32 v20, 0x3d372713, v15
	v_mul_f32_e32 v18, v14, v18
	v_mul_f32_e32 v19, v10, v19
	v_mul_f32_e32 v20, v15, v20
	v_fma_f32 v18, v14, v18, v14
	v_fma_f32 v19, v10, v19, v10
	v_fma_f32 v20, v15, v20, v15
	v_mul_f32_e32 v18, 0x3fcc422a, v18
	v_mul_f32_e32 v19, 0x3fcc422a, v19
	v_mul_f32_e32 v20, 0x3fcc422a, v20
	v_mul_f32_e32 v18, 0xbfb8aa3b, v18
	v_mul_f32_e32 v19, 0xbfb8aa3b, v19
	v_mul_f32_e32 v20, 0xbfb8aa3b, v20
	v_exp_f32_e32 v18, v18
	v_exp_f32_e32 v19, v19
	v_exp_f32_e32 v20, v20
	v_mul_f32_e32 v21, 0x3d372713, v11
	v_add_f32_e32 v18, 1.0, v18
	v_add_f32_e32 v19, 1.0, v19
	v_add_f32_e32 v20, 1.0, v20
	v_rcp_f32_e32 v18, v18
	v_rcp_f32_e32 v19, v19
	v_rcp_f32_e32 v20, v20
	v_mul_f32_e32 v21, v11, v21
	v_fma_f32 v21, v11, v21, v11
	v_lshlrev_b32_e32 v24, 16, v73
	v_and_b32_e32 v25, 0xffff0000, v73
	v_mul_f32_e32 v21, 0x3fcc422a, v21
	v_pk_fma_f32 v[12:13], v[76:77], v[24:25], v[12:13]
	v_mul_f32_e32 v21, 0xbfb8aa3b, v21
	v_exp_f32_e32 v21, v21
	v_mul_f32_e32 v14, v14, v18
	v_mul_f32_e32 v18, v10, v19
	v_mul_f32_e32 v10, v15, v20
	v_mul_f32_e32 v19, 0x3d372713, v16
	v_mul_f32_e32 v20, 0x3d372713, v12
	v_mul_f32_e32 v19, v16, v19
	v_mul_f32_e32 v20, v12, v20
	v_fma_f32 v19, v16, v19, v16
	v_fma_f32 v20, v12, v20, v12
	v_mul_f32_e32 v19, 0x3fcc422a, v19
	v_mul_f32_e32 v20, 0x3fcc422a, v20
	v_add_f32_e32 v15, 1.0, v21
	v_mul_f32_e32 v19, 0xbfb8aa3b, v19
	v_mul_f32_e32 v20, 0xbfb8aa3b, v20
	v_rcp_f32_e32 v15, v15
	v_exp_f32_e32 v19, v19
	v_exp_f32_e32 v20, v20
	v_mul_f32_e32 v21, 0x3d372713, v13
	v_mul_f32_e32 v15, v11, v15
	v_add_f32_e32 v11, 1.0, v19
	v_add_f32_e32 v19, 1.0, v20
	v_mul_f32_e32 v20, 0x3d372713, v17
	v_mul_f32_e32 v20, v17, v20
	v_fma_f32 v20, v17, v20, v17
	v_mul_f32_e32 v20, 0x3fcc422a, v20
	v_mul_f32_e32 v20, 0xbfb8aa3b, v20
	v_mul_f32_e32 v21, v13, v21
	v_exp_f32_e32 v20, v20
	v_fma_f32 v21, v13, v21, v13
	v_mul_f32_e32 v21, 0x3fcc422a, v21
	v_mul_f32_e32 v21, 0xbfb8aa3b, v21
	v_exp_f32_e32 v21, v21
	v_add_f32_e32 v20, 1.0, v20
	v_rcp_f32_e32 v11, v11
	v_rcp_f32_e32 v19, v19
	v_rcp_f32_e32 v20, v20
	v_add_f32_e32 v21, 1.0, v21
	v_or_b32_e32 v26, 0x600, v98
	v_rcp_f32_e32 v21, v21
	v_mul_f32_e32 v11, v16, v11
	v_mul_f32_e32 v16, v12, v19
	v_mul_f32_e32 v12, v17, v20
	v_cvt_pk_bf16_f32 v10, v14, v10
	v_add_u32_e32 v14, v26, v132
	v_cvt_pk_bf16_f32 v11, v11, v12
	v_cvt_pk_bf16_f32 v12, v18, v15
	v_mad_i64_i32 v[14:15], s[28:29], v14, s90, v[130:131]
	v_lshl_add_u64 v[14:15], v[14:15], 0, s[16:17]
	v_mul_f32_e32 v13, v13, v21
	v_lshl_add_u64 v[14:15], v[14:15], 0, v[0:1]
	v_cvt_pk_bf16_f32 v13, v16, v13
	global_store_dwordx4 v[14:15], v[10:13], off
	v_lshlrev_b32_e32 v14, 16, v68
	v_and_b32_e32 v15, 0xffff0000, v68
	v_lshlrev_b32_e32 v10, 16, v66
	v_and_b32_e32 v11, 0xffff0000, v66
	v_lshlrev_b32_e32 v12, 16, v67
	v_and_b32_e32 v13, 0xffff0000, v67
	v_pk_fma_f32 v[6:7], v[78:79], v[10:11], v[6:7]
	v_pk_fma_f32 v[2:3], v[74:75], v[14:15], v[2:3]
	v_mul_f32_e32 v10, 0x3d372713, v6
	v_pk_fma_f32 v[8:9], v[80:81], v[12:13], v[8:9]
	v_mul_f32_e32 v11, 0x3d372713, v2
	v_mul_f32_e32 v12, 0x3d372713, v7
	v_mul_f32_e32 v10, v6, v10
	v_mul_f32_e32 v11, v2, v11
	v_mul_f32_e32 v12, v7, v12
	v_fma_f32 v10, v6, v10, v6
	v_fma_f32 v11, v2, v11, v2
	v_fma_f32 v12, v7, v12, v7
	v_mul_f32_e32 v10, 0x3fcc422a, v10
	v_mul_f32_e32 v11, 0x3fcc422a, v11
	v_mul_f32_e32 v12, 0x3fcc422a, v12
	v_mul_f32_e32 v10, 0xbfb8aa3b, v10
	v_mul_f32_e32 v11, 0xbfb8aa3b, v11
	v_mul_f32_e32 v12, 0xbfb8aa3b, v12
	v_exp_f32_e32 v10, v10
	v_exp_f32_e32 v11, v11
	v_exp_f32_e32 v12, v12
	v_mul_f32_e32 v13, 0x3d372713, v3
	v_add_f32_e32 v10, 1.0, v10
	v_add_f32_e32 v11, 1.0, v11
	v_add_f32_e32 v12, 1.0, v12
	v_rcp_f32_e32 v10, v10
	v_rcp_f32_e32 v11, v11
	v_rcp_f32_e32 v12, v12
	v_mul_f32_e32 v13, v3, v13
	v_fma_f32 v13, v3, v13, v3
	v_lshlrev_b32_e32 v16, 16, v69
	v_and_b32_e32 v17, 0xffff0000, v69
	v_mul_f32_e32 v13, 0x3fcc422a, v13
	v_pk_fma_f32 v[4:5], v[76:77], v[16:17], v[4:5]
	v_mul_f32_e32 v13, 0xbfb8aa3b, v13
	v_exp_f32_e32 v13, v13
	v_mul_f32_e32 v6, v6, v10
	v_mul_f32_e32 v10, v2, v11
	v_mul_f32_e32 v2, v7, v12
	v_mul_f32_e32 v11, 0x3d372713, v8
	v_mul_f32_e32 v12, 0x3d372713, v4
	v_mul_f32_e32 v11, v8, v11
	v_mul_f32_e32 v12, v4, v12
	v_fma_f32 v11, v8, v11, v8
	v_fma_f32 v12, v4, v12, v4
	v_mul_f32_e32 v11, 0x3fcc422a, v11
	v_mul_f32_e32 v12, 0x3fcc422a, v12
	v_add_f32_e32 v7, 1.0, v13
	v_mul_f32_e32 v11, 0xbfb8aa3b, v11
	v_mul_f32_e32 v12, 0xbfb8aa3b, v12
	v_rcp_f32_e32 v7, v7
	v_exp_f32_e32 v11, v11
	v_exp_f32_e32 v12, v12
	v_mul_f32_e32 v13, 0x3d372713, v5
	v_mul_f32_e32 v7, v3, v7
	v_add_f32_e32 v3, 1.0, v11
	v_add_f32_e32 v11, 1.0, v12
	v_mul_f32_e32 v12, 0x3d372713, v9
	v_mul_f32_e32 v12, v9, v12
	v_fma_f32 v12, v9, v12, v9
	v_mul_f32_e32 v12, 0x3fcc422a, v12
	v_mul_f32_e32 v12, 0xbfb8aa3b, v12
	v_mul_f32_e32 v13, v5, v13
	v_exp_f32_e32 v12, v12
	v_fma_f32 v13, v5, v13, v5
	v_mul_f32_e32 v13, 0x3fcc422a, v13
	v_mul_f32_e32 v13, 0xbfb8aa3b, v13
	v_exp_f32_e32 v13, v13
	v_add_f32_e32 v12, 1.0, v12
	v_rcp_f32_e32 v3, v3
	v_rcp_f32_e32 v11, v11
	v_rcp_f32_e32 v12, v12
	v_add_f32_e32 v13, 1.0, v13
	v_rcp_f32_e32 v13, v13
	v_mul_f32_e32 v3, v8, v3
	v_mul_f32_e32 v8, v4, v11
	v_mul_f32_e32 v4, v9, v12
	v_cvt_pk_bf16_f32 v2, v6, v2
	v_add_u32_e32 v6, v26, v122
	v_cvt_pk_bf16_f32 v3, v3, v4
	v_cvt_pk_bf16_f32 v4, v10, v7
	v_mad_i64_i32 v[6:7], s[28:29], v6, s90, v[130:131]
	v_lshl_add_u64 v[6:7], v[6:7], 0, s[16:17]
	v_mul_f32_e32 v5, v5, v13
	v_lshl_add_u64 v[6:7], v[6:7], 0, v[0:1]
	v_cvt_pk_bf16_f32 v5, v8, v5
	global_store_dwordx4 v[6:7], v[2:5], off
	s_mov_b64 s[16:17], -1
	s_cbranch_vccnz .LBB7_881
	s_andn2_b64 vcc, exec, s[0:1]
	s_cbranch_vccnz .LBB7_880
	s_barrier
	s_branch .LBB7_880

.LBB7_983:
	v_mul_f32_e32 v118, 0xbfb8aa3b, v118
	v_mul_f32_e32 v114, 0xbfb8aa3b, v114
	v_mul_f32_e32 v119, 0xbfb8aa3b, v119
	v_exp_f32_e32 v118, v118
	v_exp_f32_e32 v114, v114
	v_exp_f32_e32 v119, v119
	v_mul_f32_e32 v115, 0xbfb8aa3b, v115
	v_add_f32_e32 v118, 1.0, v118
	v_add_f32_e32 v114, 1.0, v114
	v_add_f32_e32 v119, 1.0, v119
	v_rcp_f32_e32 v118, v118
	v_rcp_f32_e32 v114, v114
	v_rcp_f32_e32 v119, v119
	v_exp_f32_e32 v115, v115
	s_waitcnt vmcnt(0)
	v_lshlrev_b32_e32 v122, 16, v154
	v_and_b32_e32 v123, 0xffff0000, v154
	v_lshlrev_b32_e32 v126, 16, v156
	v_mul_f32_e32 v118, v118, v122
	v_mul_f32_e32 v122, v114, v126
	v_mul_f32_e32 v114, v119, v123
	v_add_f32_e32 v115, 1.0, v115
	v_mul_f32_e32 v119, 0xbfb8aa3b, v120
	v_rcp_f32_e32 v115, v115
	v_exp_f32_e32 v119, v119
	v_and_b32_e32 v127, 0xffff0000, v156
	v_mul_f32_e32 v116, 0xbfb8aa3b, v116
	v_mul_f32_e32 v120, v115, v127
	v_add_f32_e32 v115, 1.0, v119
	v_mul_f32_e32 v119, 0xbfb8aa3b, v121
	v_exp_f32_e32 v116, v116
	v_exp_f32_e32 v119, v119
	v_mul_f32_e32 v117, 0xbfb8aa3b, v117
	v_exp_f32_e32 v117, v117
	v_add_f32_e32 v116, 1.0, v116
	v_add_f32_e32 v119, 1.0, v119
	v_rcp_f32_e32 v116, v116
	v_rcp_f32_e32 v119, v119
	v_add_f32_e32 v117, 1.0, v117
	v_rcp_f32_e32 v115, v115
	v_rcp_f32_e32 v117, v117
	v_and_b32_e32 v125, 0xffff0000, v155
	v_lshlrev_b32_e32 v128, 16, v157
	v_lshlrev_b32_e32 v124, 16, v155
	v_and_b32_e32 v129, 0xffff0000, v157
	v_mul_f32_e32 v121, v116, v128
	v_mul_f32_e32 v116, v119, v125
	v_cvt_pk_bf16_f32 v114, v118, v114
	v_lshl_add_u64 v[118:119], s[64:65], 0, v[194:195]
	v_ashrrev_i32_e32 v185, 31, v184
	v_mul_f32_e32 v115, v115, v124
	v_mul_f32_e32 v117, v117, v129
	v_lshl_add_u64 v[118:119], v[184:185], 1, v[118:119]
	v_cvt_pk_bf16_f32 v115, v115, v116
	v_cvt_pk_bf16_f32 v116, v122, v120
	v_cvt_pk_bf16_f32 v117, v121, v117
	global_store_dwordx4 v[118:119], v[114:117], off offset:256 nt
.LBB7_984:
	s_or_b64 exec, exec, s[16:17]
	v_ashrrev_i32_e32 v193, 31, v192
	v_lshlrev_b64 v[114:115], 11, v[192:193]
	s_and_saveexec_b64 s[16:17], s[42:43]
	s_cbranch_execz .LBB7_986
	v_mul_f32_e32 v110, 0xbfb8aa3b, v110
	v_mul_f32_e32 v106, 0xbfb8aa3b, v106
	v_mul_f32_e32 v111, 0xbfb8aa3b, v111
	v_exp_f32_e32 v110, v110
	v_exp_f32_e32 v106, v106
	v_exp_f32_e32 v111, v111
	v_mul_f32_e32 v107, 0xbfb8aa3b, v107
	v_add_f32_e32 v110, 1.0, v110
	v_add_f32_e32 v106, 1.0, v106
	v_add_f32_e32 v111, 1.0, v111
	v_rcp_f32_e32 v110, v110
	v_rcp_f32_e32 v106, v106
	v_rcp_f32_e32 v111, v111
	v_exp_f32_e32 v107, v107
	s_waitcnt vmcnt(0)
	v_lshlrev_b32_e32 v116, 16, v150
	v_and_b32_e32 v117, 0xffff0000, v150
	v_lshlrev_b32_e32 v120, 16, v152
	v_mul_f32_e32 v110, v110, v116
	v_mul_f32_e32 v116, v106, v120
	v_mul_f32_e32 v106, v111, v117
	v_add_f32_e32 v107, 1.0, v107
	v_mul_f32_e32 v111, 0xbfb8aa3b, v112
	v_rcp_f32_e32 v107, v107
	v_exp_f32_e32 v111, v111
	v_and_b32_e32 v121, 0xffff0000, v152
	v_mul_f32_e32 v108, 0xbfb8aa3b, v108
	v_mul_f32_e32 v112, v107, v121
	v_add_f32_e32 v107, 1.0, v111
	v_mul_f32_e32 v111, 0xbfb8aa3b, v113
	v_exp_f32_e32 v108, v108
	v_exp_f32_e32 v111, v111
	v_mul_f32_e32 v109, 0xbfb8aa3b, v109
	v_exp_f32_e32 v109, v109
	v_add_f32_e32 v108, 1.0, v108
	v_add_f32_e32 v111, 1.0, v111
	v_rcp_f32_e32 v108, v108
	v_rcp_f32_e32 v111, v111
	v_add_f32_e32 v109, 1.0, v109
	v_rcp_f32_e32 v107, v107
	v_rcp_f32_e32 v109, v109
	v_and_b32_e32 v119, 0xffff0000, v151
	v_lshlrev_b32_e32 v122, 16, v153
	v_lshlrev_b32_e32 v118, 16, v151
	v_and_b32_e32 v123, 0xffff0000, v153
	v_mul_f32_e32 v113, v108, v122
	v_mul_f32_e32 v108, v111, v119
	v_cvt_pk_bf16_f32 v106, v110, v106
	v_lshl_add_u64 v[110:111], s[64:65], 0, v[114:115]
	v_ashrrev_i32_e32 v185, 31, v184
	v_mul_f32_e32 v107, v107, v118
	v_mul_f32_e32 v109, v109, v123
	v_lshl_add_u64 v[110:111], v[184:185], 1, v[110:111]
	v_cvt_pk_bf16_f32 v107, v107, v108
	v_cvt_pk_bf16_f32 v108, v116, v112
	v_cvt_pk_bf16_f32 v109, v113, v109
	global_store_dwordx4 v[110:111], v[106:109], off nt
.LBB7_986:
	s_or_b64 exec, exec, s[16:17]
	s_and_saveexec_b64 s[16:17], vcc
	s_cbranch_execz .LBB7_988
	v_mul_f32_e32 v102, 0xbfb8aa3b, v102
	v_mul_f32_e32 v98, 0xbfb8aa3b, v98
	v_mul_f32_e32 v103, 0xbfb8aa3b, v103
	v_exp_f32_e32 v102, v102
	v_exp_f32_e32 v98, v98
	v_exp_f32_e32 v103, v103
	v_mul_f32_e32 v99, 0xbfb8aa3b, v99
	v_add_f32_e32 v102, 1.0, v102
	v_add_f32_e32 v98, 1.0, v98
	v_add_f32_e32 v103, 1.0, v103
	v_rcp_f32_e32 v102, v102
	v_rcp_f32_e32 v98, v98
	v_rcp_f32_e32 v103, v103
	v_exp_f32_e32 v99, v99
	s_waitcnt vmcnt(0)
	v_lshlrev_b32_e32 v106, 16, v146
	v_and_b32_e32 v107, 0xffff0000, v146
	v_lshlrev_b32_e32 v110, 16, v148
	v_mul_f32_e32 v102, v102, v106
	v_mul_f32_e32 v106, v98, v110
	v_mul_f32_e32 v98, v103, v107
	v_add_f32_e32 v99, 1.0, v99
	v_mul_f32_e32 v103, 0xbfb8aa3b, v104
	v_rcp_f32_e32 v99, v99
	v_exp_f32_e32 v103, v103
	v_and_b32_e32 v111, 0xffff0000, v148
	v_mul_f32_e32 v100, 0xbfb8aa3b, v100
	v_mul_f32_e32 v104, v99, v111
	v_add_f32_e32 v99, 1.0, v103
	v_mul_f32_e32 v103, 0xbfb8aa3b, v105
	v_exp_f32_e32 v100, v100
	v_exp_f32_e32 v103, v103
	v_mul_f32_e32 v101, 0xbfb8aa3b, v101
	v_exp_f32_e32 v101, v101
	v_add_f32_e32 v100, 1.0, v100
	v_add_f32_e32 v103, 1.0, v103
	v_rcp_f32_e32 v100, v100
	v_rcp_f32_e32 v103, v103
	v_add_f32_e32 v101, 1.0, v101
	v_rcp_f32_e32 v99, v99
	v_rcp_f32_e32 v101, v101
	v_and_b32_e32 v109, 0xffff0000, v147
	v_lshlrev_b32_e32 v112, 16, v149
	v_lshlrev_b32_e32 v108, 16, v147
	v_and_b32_e32 v113, 0xffff0000, v149
	v_mul_f32_e32 v105, v100, v112
	v_mul_f32_e32 v100, v103, v109
	v_cvt_pk_bf16_f32 v98, v102, v98
	v_lshl_add_u64 v[102:103], s[64:65], 0, v[114:115]
	v_ashrrev_i32_e32 v185, 31, v184
	v_mul_f32_e32 v99, v99, v108
	v_mul_f32_e32 v101, v101, v113
	v_lshl_add_u64 v[102:103], v[184:185], 1, v[102:103]
	v_cvt_pk_bf16_f32 v99, v99, v100
	v_cvt_pk_bf16_f32 v100, v106, v104
	v_cvt_pk_bf16_f32 v101, v105, v101
	global_store_dwordx4 v[102:103], v[98:101], off offset:256 nt
.LBB7_988:
	s_or_b64 exec, exec, s[16:17]
	v_ashrrev_i32_e32 v191, 31, v190
	v_lshlrev_b64 v[98:99], 11, v[190:191]
	s_and_saveexec_b64 s[16:17], s[42:43]
	s_cbranch_execz .LBB7_990
	v_mul_f32_e32 v94, 0xbfb8aa3b, v94
	v_mul_f32_e32 v90, 0xbfb8aa3b, v90
	v_mul_f32_e32 v95, 0xbfb8aa3b, v95
	v_exp_f32_e32 v94, v94
	v_exp_f32_e32 v90, v90
	v_exp_f32_e32 v95, v95
	v_mul_f32_e32 v91, 0xbfb8aa3b, v91
	v_add_f32_e32 v94, 1.0, v94
	v_add_f32_e32 v90, 1.0, v90
	v_add_f32_e32 v95, 1.0, v95
	v_rcp_f32_e32 v94, v94
	v_rcp_f32_e32 v90, v90
	v_rcp_f32_e32 v95, v95
	v_exp_f32_e32 v91, v91
	s_waitcnt vmcnt(0)
	v_lshlrev_b32_e32 v100, 16, v142
	v_and_b32_e32 v101, 0xffff0000, v142
	v_lshlrev_b32_e32 v104, 16, v144
	v_mul_f32_e32 v94, v94, v100
	v_mul_f32_e32 v100, v90, v104
	v_mul_f32_e32 v90, v95, v101
	v_add_f32_e32 v91, 1.0, v91
	v_mul_f32_e32 v95, 0xbfb8aa3b, v96
	v_rcp_f32_e32 v91, v91
	v_exp_f32_e32 v95, v95
	v_and_b32_e32 v105, 0xffff0000, v144
	v_mul_f32_e32 v92, 0xbfb8aa3b, v92
	v_mul_f32_e32 v96, v91, v105
	v_add_f32_e32 v91, 1.0, v95
	v_mul_f32_e32 v95, 0xbfb8aa3b, v97
	v_exp_f32_e32 v92, v92
	v_exp_f32_e32 v95, v95
	v_mul_f32_e32 v93, 0xbfb8aa3b, v93
	v_exp_f32_e32 v93, v93
	v_add_f32_e32 v92, 1.0, v92
	v_add_f32_e32 v95, 1.0, v95
	v_rcp_f32_e32 v92, v92
	v_rcp_f32_e32 v95, v95
	v_add_f32_e32 v93, 1.0, v93
	v_rcp_f32_e32 v91, v91
	v_rcp_f32_e32 v93, v93
	v_and_b32_e32 v103, 0xffff0000, v143
	v_lshlrev_b32_e32 v106, 16, v145
	v_lshlrev_b32_e32 v102, 16, v143
	v_and_b32_e32 v107, 0xffff0000, v145
	v_mul_f32_e32 v97, v92, v106
	v_mul_f32_e32 v92, v95, v103
	v_cvt_pk_bf16_f32 v90, v94, v90
	v_lshl_add_u64 v[94:95], s[64:65], 0, v[98:99]
	v_ashrrev_i32_e32 v185, 31, v184
	v_mul_f32_e32 v91, v91, v102
	v_mul_f32_e32 v93, v93, v107
	v_lshl_add_u64 v[94:95], v[184:185], 1, v[94:95]
	v_cvt_pk_bf16_f32 v91, v91, v92
	v_cvt_pk_bf16_f32 v92, v100, v96
	v_cvt_pk_bf16_f32 v93, v97, v93
	global_store_dwordx4 v[94:95], v[90:93], off nt
.LBB7_990:
	s_or_b64 exec, exec, s[16:17]
	s_and_saveexec_b64 s[16:17], vcc
	s_cbranch_execz .LBB7_992
	v_mul_f32_e32 v86, 0xbfb8aa3b, v86
	v_mul_f32_e32 v82, 0xbfb8aa3b, v82
	v_mul_f32_e32 v87, 0xbfb8aa3b, v87
	v_exp_f32_e32 v86, v86
	v_exp_f32_e32 v82, v82
	v_exp_f32_e32 v87, v87
	v_mul_f32_e32 v83, 0xbfb8aa3b, v83
	v_add_f32_e32 v86, 1.0, v86
	v_add_f32_e32 v82, 1.0, v82
	v_add_f32_e32 v87, 1.0, v87
	v_rcp_f32_e32 v86, v86
	v_rcp_f32_e32 v82, v82
	v_rcp_f32_e32 v87, v87
	v_exp_f32_e32 v83, v83
	s_waitcnt vmcnt(0)
	v_lshlrev_b32_e32 v90, 16, v138
	v_and_b32_e32 v91, 0xffff0000, v138
	v_lshlrev_b32_e32 v94, 16, v140
	v_mul_f32_e32 v86, v86, v90
	v_mul_f32_e32 v90, v82, v94
	v_mul_f32_e32 v82, v87, v91
	v_add_f32_e32 v83, 1.0, v83
	v_mul_f32_e32 v87, 0xbfb8aa3b, v88
	v_rcp_f32_e32 v83, v83
	v_exp_f32_e32 v87, v87
	v_and_b32_e32 v95, 0xffff0000, v140
	v_mul_f32_e32 v84, 0xbfb8aa3b, v84
	v_mul_f32_e32 v88, v83, v95
	v_add_f32_e32 v83, 1.0, v87
	v_mul_f32_e32 v87, 0xbfb8aa3b, v89
	v_exp_f32_e32 v84, v84
	v_exp_f32_e32 v87, v87
	v_mul_f32_e32 v85, 0xbfb8aa3b, v85
	v_exp_f32_e32 v85, v85
	v_add_f32_e32 v84, 1.0, v84
	v_add_f32_e32 v87, 1.0, v87
	v_rcp_f32_e32 v84, v84
	v_rcp_f32_e32 v87, v87
	v_add_f32_e32 v85, 1.0, v85
	v_rcp_f32_e32 v83, v83
	v_rcp_f32_e32 v85, v85
	v_and_b32_e32 v93, 0xffff0000, v139
	v_lshlrev_b32_e32 v96, 16, v141
	v_lshlrev_b32_e32 v92, 16, v139
	v_and_b32_e32 v97, 0xffff0000, v141
	v_mul_f32_e32 v89, v84, v96
	v_mul_f32_e32 v84, v87, v93
	v_cvt_pk_bf16_f32 v82, v86, v82
	v_lshl_add_u64 v[86:87], s[64:65], 0, v[98:99]
	v_ashrrev_i32_e32 v185, 31, v184
	v_mul_f32_e32 v83, v83, v92
	v_mul_f32_e32 v85, v85, v97
	v_lshl_add_u64 v[86:87], v[184:185], 1, v[86:87]
	v_cvt_pk_bf16_f32 v83, v83, v84
	v_cvt_pk_bf16_f32 v84, v90, v88
	v_cvt_pk_bf16_f32 v85, v89, v85
	global_store_dwordx4 v[86:87], v[82:85], off offset:256 nt
.LBB7_992:
	s_or_b64 exec, exec, s[16:17]
	v_ashrrev_i32_e32 v189, 31, v188
	v_lshlrev_b64 v[82:83], 11, v[188:189]
	s_and_saveexec_b64 s[16:17], s[42:43]
	s_cbranch_execz .LBB7_994
	v_mul_f32_e32 v78, 0xbfb8aa3b, v78
	v_mul_f32_e32 v74, 0xbfb8aa3b, v74
	v_mul_f32_e32 v79, 0xbfb8aa3b, v79
	v_exp_f32_e32 v78, v78
	v_exp_f32_e32 v74, v74
	v_exp_f32_e32 v79, v79
	v_mul_f32_e32 v75, 0xbfb8aa3b, v75
	v_add_f32_e32 v78, 1.0, v78
	v_add_f32_e32 v74, 1.0, v74
	v_add_f32_e32 v79, 1.0, v79
	v_rcp_f32_e32 v78, v78
	v_rcp_f32_e32 v74, v74
	v_rcp_f32_e32 v79, v79
	v_exp_f32_e32 v75, v75
	s_waitcnt vmcnt(0)
	v_lshlrev_b32_e32 v84, 16, v134
	v_and_b32_e32 v85, 0xffff0000, v134
	v_lshlrev_b32_e32 v88, 16, v136
	v_mul_f32_e32 v78, v78, v84
	v_mul_f32_e32 v84, v74, v88
	v_mul_f32_e32 v74, v79, v85
	v_add_f32_e32 v75, 1.0, v75
	v_mul_f32_e32 v79, 0xbfb8aa3b, v80
	v_rcp_f32_e32 v75, v75
	v_exp_f32_e32 v79, v79
	v_and_b32_e32 v89, 0xffff0000, v136
	v_mul_f32_e32 v76, 0xbfb8aa3b, v76
	v_mul_f32_e32 v80, v75, v89
	v_add_f32_e32 v75, 1.0, v79
	v_mul_f32_e32 v79, 0xbfb8aa3b, v81
	v_exp_f32_e32 v76, v76
	v_exp_f32_e32 v79, v79
	v_mul_f32_e32 v77, 0xbfb8aa3b, v77
	v_exp_f32_e32 v77, v77
	v_add_f32_e32 v76, 1.0, v76
	v_add_f32_e32 v79, 1.0, v79
	v_rcp_f32_e32 v76, v76
	v_rcp_f32_e32 v79, v79
	v_add_f32_e32 v77, 1.0, v77
	v_rcp_f32_e32 v75, v75
	v_rcp_f32_e32 v77, v77
	v_and_b32_e32 v87, 0xffff0000, v135
	v_lshlrev_b32_e32 v90, 16, v137
	v_lshlrev_b32_e32 v86, 16, v135
	v_and_b32_e32 v91, 0xffff0000, v137
	v_mul_f32_e32 v81, v76, v90
	v_mul_f32_e32 v76, v79, v87
	v_cvt_pk_bf16_f32 v74, v78, v74
	v_lshl_add_u64 v[78:79], s[64:65], 0, v[82:83]
	v_ashrrev_i32_e32 v185, 31, v184
	v_mul_f32_e32 v75, v75, v86
	v_mul_f32_e32 v77, v77, v91
	v_lshl_add_u64 v[78:79], v[184:185], 1, v[78:79]
	v_cvt_pk_bf16_f32 v75, v75, v76
	v_cvt_pk_bf16_f32 v76, v84, v80
	v_cvt_pk_bf16_f32 v77, v81, v77
	global_store_dwordx4 v[78:79], v[74:77], off nt
.LBB7_994:
	s_or_b64 exec, exec, s[16:17]
	s_and_saveexec_b64 s[16:17], vcc
	s_cbranch_execz .LBB7_996
	v_mul_f32_e32 v70, 0xbfb8aa3b, v70
	v_mul_f32_e32 v66, 0xbfb8aa3b, v66
	v_mul_f32_e32 v71, 0xbfb8aa3b, v71
	v_exp_f32_e32 v70, v70
	v_exp_f32_e32 v66, v66
	v_exp_f32_e32 v71, v71
	v_mul_f32_e32 v67, 0xbfb8aa3b, v67
	v_add_f32_e32 v70, 1.0, v70
	v_add_f32_e32 v66, 1.0, v66
	v_add_f32_e32 v71, 1.0, v71
	v_rcp_f32_e32 v70, v70
	v_rcp_f32_e32 v66, v66
	v_rcp_f32_e32 v71, v71
	v_exp_f32_e32 v67, v67
	s_waitcnt vmcnt(0)
	v_lshlrev_b32_e32 v74, 16, v130
	v_and_b32_e32 v75, 0xffff0000, v130
	v_lshlrev_b32_e32 v78, 16, v132
	v_mul_f32_e32 v70, v70, v74
	v_mul_f32_e32 v74, v66, v78
	v_mul_f32_e32 v66, v71, v75
	v_add_f32_e32 v67, 1.0, v67
	v_mul_f32_e32 v71, 0xbfb8aa3b, v72
	v_rcp_f32_e32 v67, v67
	v_exp_f32_e32 v71, v71
	v_and_b32_e32 v79, 0xffff0000, v132
	v_mul_f32_e32 v68, 0xbfb8aa3b, v68
	v_mul_f32_e32 v72, v67, v79
	v_add_f32_e32 v67, 1.0, v71
	v_mul_f32_e32 v71, 0xbfb8aa3b, v73
	v_exp_f32_e32 v68, v68
	v_exp_f32_e32 v71, v71
	v_mul_f32_e32 v69, 0xbfb8aa3b, v69
	v_exp_f32_e32 v69, v69
	v_add_f32_e32 v68, 1.0, v68
	v_add_f32_e32 v71, 1.0, v71
	v_rcp_f32_e32 v68, v68
	v_rcp_f32_e32 v71, v71
	v_add_f32_e32 v69, 1.0, v69
	v_rcp_f32_e32 v67, v67
	v_rcp_f32_e32 v69, v69
	v_and_b32_e32 v77, 0xffff0000, v131
	v_lshlrev_b32_e32 v80, 16, v133
	v_lshlrev_b32_e32 v76, 16, v131
	v_and_b32_e32 v81, 0xffff0000, v133
	v_mul_f32_e32 v73, v68, v80
	v_mul_f32_e32 v68, v71, v77
	v_cvt_pk_bf16_f32 v66, v70, v66
	v_lshl_add_u64 v[70:71], s[64:65], 0, v[82:83]
	v_ashrrev_i32_e32 v185, 31, v184
	v_mul_f32_e32 v67, v67, v76
	v_mul_f32_e32 v69, v69, v81
	v_lshl_add_u64 v[70:71], v[184:185], 1, v[70:71]
	v_cvt_pk_bf16_f32 v67, v67, v68
	v_cvt_pk_bf16_f32 v68, v74, v72
	v_cvt_pk_bf16_f32 v69, v73, v69
	global_store_dwordx4 v[70:71], v[66:69], off offset:256 nt

.LBB7_1012:
	s_or_b64 exec, exec, s[16:17]
	v_ashrrev_i32_e32 v105, 31, v104
	v_lshlrev_b64 v[104:105], 11, v[104:105]
	s_and_saveexec_b64 s[16:17], s[42:43]
	s_cbranch_execz .LBB7_1014
	v_mul_f32_e32 v62, 0xbfb8aa3b, v62
	v_mul_f32_e32 v58, 0xbfb8aa3b, v58
	v_mul_f32_e32 v63, 0xbfb8aa3b, v63
	v_exp_f32_e32 v62, v62
	v_exp_f32_e32 v58, v58
	v_exp_f32_e32 v63, v63
	v_mul_f32_e32 v59, 0xbfb8aa3b, v59
	v_add_f32_e32 v62, 1.0, v62
	v_add_f32_e32 v58, 1.0, v58
	v_add_f32_e32 v63, 1.0, v63
	v_rcp_f32_e32 v62, v62
	v_rcp_f32_e32 v58, v58
	v_rcp_f32_e32 v63, v63
	v_exp_f32_e32 v59, v59
	s_waitcnt vmcnt(0)
	v_lshlrev_b32_e32 v99, 16, v94
	v_and_b32_e32 v94, 0xffff0000, v94
	v_lshlrev_b32_e32 v103, 16, v96
	v_mul_f32_e32 v62, v62, v99
	v_mul_f32_e32 v99, v58, v103
	v_mul_f32_e32 v58, v63, v94
	v_add_f32_e32 v59, 1.0, v59
	v_mul_f32_e32 v63, 0xbfb8aa3b, v64
	v_rcp_f32_e32 v59, v59
	v_exp_f32_e32 v63, v63
	v_and_b32_e32 v96, 0xffff0000, v96
	v_mul_f32_e32 v60, 0xbfb8aa3b, v60
	v_mul_f32_e32 v64, v59, v96
	v_add_f32_e32 v59, 1.0, v63
	v_mul_f32_e32 v63, 0xbfb8aa3b, v65
	v_exp_f32_e32 v60, v60
	v_exp_f32_e32 v63, v63
	v_mul_f32_e32 v61, 0xbfb8aa3b, v61
	v_exp_f32_e32 v61, v61
	v_add_f32_e32 v60, 1.0, v60
	v_add_f32_e32 v63, 1.0, v63
	v_rcp_f32_e32 v60, v60
	v_rcp_f32_e32 v63, v63
	v_add_f32_e32 v61, 1.0, v61
	v_rcp_f32_e32 v59, v59
	v_rcp_f32_e32 v61, v61
	v_lshlrev_b32_e32 v101, 16, v95
	v_and_b32_e32 v95, 0xffff0000, v95
	v_lshlrev_b32_e32 v106, 16, v97
	v_and_b32_e32 v97, 0xffff0000, v97
	v_mul_f32_e32 v65, v60, v106
	v_mul_f32_e32 v60, v63, v95
	v_cvt_pk_bf16_f32 v58, v62, v58
	v_lshl_add_u64 v[62:63], s[64:65], 0, v[104:105]
	v_ashrrev_i32_e32 v185, 31, v184
	v_mul_f32_e32 v59, v59, v101
	v_mul_f32_e32 v61, v61, v97
	v_lshl_add_u64 v[62:63], v[184:185], 1, v[62:63]
	v_cvt_pk_bf16_f32 v59, v59, v60
	v_cvt_pk_bf16_f32 v60, v99, v64
	v_cvt_pk_bf16_f32 v61, v65, v61
	global_store_dwordx4 v[62:63], v[58:61], off nt
.LBB7_1014:
	s_or_b64 exec, exec, s[16:17]
	s_and_saveexec_b64 s[16:17], vcc
	s_cbranch_execz .LBB7_1016
	v_mul_f32_e32 v54, 0xbfb8aa3b, v54
	v_mul_f32_e32 v50, 0xbfb8aa3b, v50
	v_mul_f32_e32 v55, 0xbfb8aa3b, v55
	v_exp_f32_e32 v54, v54
	v_exp_f32_e32 v50, v50
	v_exp_f32_e32 v55, v55
	v_mul_f32_e32 v51, 0xbfb8aa3b, v51
	v_add_f32_e32 v54, 1.0, v54
	v_add_f32_e32 v50, 1.0, v50
	v_add_f32_e32 v55, 1.0, v55
	v_rcp_f32_e32 v54, v54
	v_rcp_f32_e32 v50, v50
	v_rcp_f32_e32 v55, v55
	v_exp_f32_e32 v51, v51
	s_waitcnt vmcnt(0)
	v_lshlrev_b32_e32 v58, 16, v90
	v_and_b32_e32 v59, 0xffff0000, v90
	v_lshlrev_b32_e32 v62, 16, v92
	v_mul_f32_e32 v54, v54, v58
	v_mul_f32_e32 v58, v50, v62
	v_mul_f32_e32 v50, v55, v59
	v_add_f32_e32 v51, 1.0, v51
	v_mul_f32_e32 v55, 0xbfb8aa3b, v56
	v_rcp_f32_e32 v51, v51
	v_exp_f32_e32 v55, v55
	v_and_b32_e32 v63, 0xffff0000, v92
	v_mul_f32_e32 v52, 0xbfb8aa3b, v52
	v_mul_f32_e32 v56, v51, v63
	v_add_f32_e32 v51, 1.0, v55
	v_mul_f32_e32 v55, 0xbfb8aa3b, v57
	v_exp_f32_e32 v52, v52
	v_exp_f32_e32 v55, v55
	v_mul_f32_e32 v53, 0xbfb8aa3b, v53
	v_exp_f32_e32 v53, v53
	v_add_f32_e32 v52, 1.0, v52
	v_add_f32_e32 v55, 1.0, v55
	v_rcp_f32_e32 v52, v52
	v_rcp_f32_e32 v55, v55
	v_add_f32_e32 v53, 1.0, v53
	v_rcp_f32_e32 v51, v51
	v_rcp_f32_e32 v53, v53
	v_and_b32_e32 v61, 0xffff0000, v91
	v_lshlrev_b32_e32 v64, 16, v93
	v_lshlrev_b32_e32 v60, 16, v91
	v_and_b32_e32 v65, 0xffff0000, v93
	v_mul_f32_e32 v57, v52, v64
	v_mul_f32_e32 v52, v55, v61
	v_cvt_pk_bf16_f32 v50, v54, v50
	v_lshl_add_u64 v[54:55], s[64:65], 0, v[104:105]
	v_ashrrev_i32_e32 v185, 31, v184
	v_mul_f32_e32 v51, v51, v60
	v_mul_f32_e32 v53, v53, v65
	v_lshl_add_u64 v[54:55], v[184:185], 1, v[54:55]
	v_cvt_pk_bf16_f32 v51, v51, v52
	v_cvt_pk_bf16_f32 v52, v58, v56
	v_cvt_pk_bf16_f32 v53, v57, v53
	global_store_dwordx4 v[54:55], v[50:53], off offset:256 nt

.LBB7_1107:
	s_waitcnt lgkmcnt(0)
	v_lshl_or_b32 v2, s57, 8, v206
	v_lshl_add_u32 v184, s88, 8, v204
	v_ashrrev_i32_e32 v3, 31, v2
	v_lshlrev_b64 v[132:133], 1, v[2:3]
	v_ashrrev_i32_e32 v185, 31, v184
	v_lshl_add_u64 v[190:191], s[68:69], 0, v[132:133]
	v_lshlrev_b64 v[134:135], 11, v[184:185]
	v_lshl_add_u64 v[136:137], v[190:191], 0, v[134:135]
	global_load_dwordx4 v[196:199], v[136:137], off
	global_load_dwordx4 v[208:211], v[136:137], off offset:256
	v_or_b32_e32 v192, 16, v184
	v_or_b32_e32 v186, 32, v184
	v_or_b32_e32 v156, 48, v184
	v_ashrrev_i32_e32 v193, 31, v192
	v_ashrrev_i32_e32 v187, 31, v186
	v_ashrrev_i32_e32 v157, 31, v156
	v_lshlrev_b64 v[194:195], 11, v[192:193]
	v_lshlrev_b64 v[188:189], 11, v[186:187]
	v_lshlrev_b64 v[158:159], 11, v[156:157]
	v_lshl_add_u64 v[134:135], s[68:69], 0, v[134:135]
	v_lshl_add_u64 v[136:137], v[190:191], 0, v[194:195]
	v_lshl_add_u64 v[138:139], v[190:191], 0, v[188:189]
	v_lshl_add_u64 v[170:171], v[190:191], 0, v[158:159]
	v_lshl_add_u64 v[172:173], v[134:135], 0, v[132:133]
	global_load_dwordx4 v[152:155], v[136:137], off
	global_load_dwordx4 v[148:151], v[136:137], off offset:256
	global_load_dwordx4 v[144:147], v[138:139], off
	global_load_dwordx4 v[140:143], v[138:139], off offset:256
	s_nop 0
	global_load_dwordx4 v[136:139], v[170:171], off
	global_load_dwordx4 v[132:135], v[170:171], off offset:256
	v_add_u32_e32 v248, 0x80, v184
	v_ashrrev_i32_e32 v249, 31, v248
	v_lshlrev_b64 v[248:249], 11, v[248:249]
	v_lshl_add_u64 v[248:249], v[190:191], 0, v[248:249]
	global_load_dwordx4 v[232:235], v[248:249], off
	global_load_dwordx4 v[236:239], v[248:249], off offset:256
	s_mov_b64 s[72:73], 0x8000
	v_lshl_add_u64 v[248:249], v[248:249], 0, s[72:73]
	global_load_dwordx4 v[240:243], v[248:249], off
	global_load_dwordx4 v[244:247], v[248:249], off offset:256
	s_waitcnt vmcnt(0)
	v_lshlrev_b32_e32 v212, 16, v198
	v_and_b32_e32 v213, 0xffff0000, v198
	v_lshlrev_b32_e32 v198, 16, v199
	v_and_b32_e32 v199, 0xffff0000, v199
	v_lshlrev_b32_e32 v170, 16, v196
	v_and_b32_e32 v171, 0xffff0000, v196
	v_lshlrev_b32_e32 v196, 16, v197
	v_and_b32_e32 v197, 0xffff0000, v197
	v_pk_add_f32 v[220:221], v[126:127], v[198:199]
	v_pk_add_f32 v[198:199], v[124:125], v[212:213]
	v_lshlrev_b32_e32 v214, 16, v208
	v_and_b32_e32 v215, 0xffff0000, v208
	v_lshlrev_b32_e32 v208, 16, v209
	v_and_b32_e32 v209, 0xffff0000, v209
	v_lshlrev_b32_e32 v216, 16, v210
	v_and_b32_e32 v217, 0xffff0000, v210
	v_lshlrev_b32_e32 v210, 16, v211
	v_and_b32_e32 v211, 0xffff0000, v211
	v_pk_add_f32 v[218:219], v[130:131], v[196:197]
	v_pk_add_f32 v[170:171], v[128:129], v[170:171]
	v_pk_add_f32 v[208:209], v[98:99], v[208:209]
	v_cvt_pk_bf16_f32 v196, v170, v171
	v_cvt_pk_bf16_f32 v197, v218, v219
	v_cvt_pk_bf16_f32 v198, v198, v199
	v_cvt_pk_bf16_f32 v199, v220, v221
	v_pk_add_f32 v[212:213], v[96:97], v[214:215]
	v_pk_add_f32 v[214:215], v[94:95], v[210:211]
	global_store_dwordx4 v[172:173], v[196:199], off nt
	v_lshlrev_b32_e32 v0, 16, v196
	v_and_b32_e32 v170, 0xffff0000, v196
	v_lshlrev_b32_e32 v171, 16, v197
	v_and_b32_e32 v196, 0xffff0000, v197
	v_lshlrev_b32_e32 v197, 16, v198
	v_and_b32_e32 v198, 0xffff0000, v198
	v_lshlrev_b32_e32 v218, 16, v199
	v_and_b32_e32 v199, 0xffff0000, v199
	v_pk_add_f32 v[216:217], v[92:93], v[216:217]
	v_cvt_pk_bf16_f32 v210, v212, v213
	v_cvt_pk_bf16_f32 v211, v208, v209
	v_mul_f32_e32 v170, v170, v170
	v_cvt_pk_bf16_f32 v212, v216, v217
	v_cvt_pk_bf16_f32 v213, v214, v215
	v_mul_f32_e32 v196, v196, v196
	v_mul_f32_e32 v198, v198, v198
	v_mul_f32_e32 v199, v199, v199
	v_and_b32_e32 v209, 0xffff0000, v210
	v_and_b32_e32 v215, 0xffff0000, v211
	v_lshlrev_b32_e32 v208, 16, v210
	v_lshlrev_b32_e32 v214, 16, v211
	v_fmac_f32_e32 v170, v0, v0
	v_fmac_f32_e32 v196, v171, v171
	v_fmac_f32_e32 v198, v197, v197
	v_fmac_f32_e32 v199, v218, v218
	v_mul_f32_e32 v0, v209, v209
	v_mul_f32_e32 v171, v215, v215
	v_and_b32_e32 v217, 0xffff0000, v212
	v_and_b32_e32 v220, 0xffff0000, v213
	v_add_f32_e32 v170, v170, v196
	v_add_f32_e32 v196, v198, v199
	v_fmac_f32_e32 v0, v208, v208
	v_fmac_f32_e32 v171, v214, v214
	v_lshlrev_b32_e32 v216, 16, v212
	v_lshlrev_b32_e32 v219, 16, v213
	v_add_f32_e32 v170, v170, v196
	v_add_f32_e32 v0, v0, v171
	v_mul_f32_e32 v171, v217, v217
	v_mul_f32_e32 v196, v220, v220
	v_fmac_f32_e32 v171, v216, v216
	v_fmac_f32_e32 v196, v219, v219
	v_add_f32_e32 v171, v171, v196
	v_add_f32_e32 v0, v0, v171
	v_and_b32_e32 v171, 64, v163
	v_add_f32_e32 v170, v170, v0
	v_xor_b32_e32 v0, 16, v163
	v_add_u32_e32 v171, 64, v171
	v_cmp_lt_i32_e32 vcc, v0, v171
	global_store_dwordx4 v[172:173], v[210:213], off offset:256 nt
	s_nop 0
	v_cndmask_b32_e32 v0, v163, v0, vcc
	v_lshlrev_b32_e32 v0, 2, v0
	v_mov_b32_e32 v196, v170
	s_nop 1
	v_permlane16_swap_b32_e32 v170, v196
	s_waitcnt lgkmcnt(0)
	v_add_f32_e32 v196, v170, v196
	v_xor_b32_e32 v170, 32, v163
	v_cmp_lt_i32_e32 vcc, v170, v171
	s_nop 1
	v_cndmask_b32_e32 v170, v163, v170, vcc
	v_lshlrev_b32_e32 v208, 2, v170
	v_mov_b32_e32 v197, v196
	s_nop 1
	v_permlane32_swap_b32_e32 v196, v197
	s_lshl_b32 vcc_lo, s57, 2
	s_ashr_i32 vcc_hi, vcc_lo, 31
	s_and_saveexec_b64 s[72:73], s[40:41]
	s_cbranch_execz .LBB7_1109
	v_lshlrev_b64 v[170:171], 6, v[184:185]
	v_lshl_add_u64 v[170:171], s[66:67], 0, v[170:171]
	v_lshl_add_u64 v[170:171], vcc, 2, v[170:171]
	s_lshl_b32 s20, s92, 2
	v_lshl_add_u64 v[170:171], v[170:171], 0, s[20:21]
	s_waitcnt lgkmcnt(0)
	v_add_f32_e32 v172, v196, v197
	global_store_dword v[170:171], v172, off
.LBB7_1109:
	s_or_b64 exec, exec, s[72:73]
	v_lshlrev_b32_e32 v170, 16, v152
	v_and_b32_e32 v171, 0xffff0000, v152
	v_lshlrev_b32_e32 v152, 16, v153
	v_and_b32_e32 v153, 0xffff0000, v153
	v_lshlrev_b32_e32 v172, 16, v154
	v_and_b32_e32 v173, 0xffff0000, v154
	v_lshlrev_b32_e32 v154, 16, v155
	v_and_b32_e32 v155, 0xffff0000, v155
	s_waitcnt lgkmcnt(0)
	v_pk_add_f32 v[196:197], v[122:123], v[152:153]
	v_pk_add_f32 v[152:153], v[120:121], v[170:171]
	v_pk_add_f32 v[170:171], v[118:119], v[154:155]
	v_pk_add_f32 v[154:155], v[116:117], v[172:173]
	v_cvt_pk_bf16_f32 v152, v152, v153
	v_cvt_pk_bf16_f32 v153, v196, v197
	s_nop 0
	v_cvt_pk_bf16_f32 v154, v154, v155
	v_cvt_pk_bf16_f32 v155, v170, v171
	v_lshl_add_u64 v[170:171], s[68:69], 0, v[194:195]
	v_lshl_add_u64 v[170:171], v[2:3], 1, v[170:171]
	global_store_dwordx4 v[170:171], v[152:155], off nt
	v_lshlrev_b32_e32 v172, 16, v152
	v_lshlrev_b32_e32 v173, 16, v153
	v_and_b32_e32 v152, 0xffff0000, v152
	v_and_b32_e32 v153, 0xffff0000, v153
	v_mul_f32_e32 v152, v152, v152
	v_mul_f32_e32 v153, v153, v153
	v_lshlrev_b32_e32 v185, 16, v154
	v_and_b32_e32 v154, 0xffff0000, v154
	v_lshlrev_b32_e32 v194, 16, v155
	v_and_b32_e32 v155, 0xffff0000, v155
	v_fmac_f32_e32 v152, v172, v172
	v_fmac_f32_e32 v153, v173, v173
	v_add_f32_e32 v152, v152, v153
	v_mul_f32_e32 v153, v154, v154
	v_mul_f32_e32 v154, v155, v155
	v_fmac_f32_e32 v153, v185, v185
	v_fmac_f32_e32 v154, v194, v194
	v_add_f32_e32 v153, v153, v154
	v_add_f32_e32 v185, v152, v153
	v_lshlrev_b32_e32 v152, 16, v148
	v_and_b32_e32 v153, 0xffff0000, v148
	v_lshlrev_b32_e32 v148, 16, v149
	v_and_b32_e32 v149, 0xffff0000, v149
	v_lshlrev_b32_e32 v154, 16, v150
	v_and_b32_e32 v155, 0xffff0000, v150
	v_lshlrev_b32_e32 v150, 16, v151
	v_and_b32_e32 v151, 0xffff0000, v151
	v_pk_add_f32 v[148:149], v[90:91], v[148:149]
	v_pk_add_f32 v[152:153], v[88:89], v[152:153]
	v_pk_add_f32 v[172:173], v[86:87], v[150:151]
	v_pk_add_f32 v[154:155], v[84:85], v[154:155]
	v_cvt_pk_bf16_f32 v150, v152, v153
	v_cvt_pk_bf16_f32 v151, v148, v149
	s_nop 0
	v_and_b32_e32 v149, 0xffff0000, v150
	v_cvt_pk_bf16_f32 v152, v154, v155
	v_lshlrev_b32_e32 v148, 16, v150
	v_and_b32_e32 v155, 0xffff0000, v151
	v_mul_f32_e32 v149, v149, v149
	v_lshlrev_b32_e32 v154, 16, v151
	v_fmac_f32_e32 v149, v148, v148
	v_mul_f32_e32 v148, v155, v155
	v_cvt_pk_bf16_f32 v153, v172, v173
	v_and_b32_e32 v173, 0xffff0000, v152
	v_and_b32_e32 v195, 0xffff0000, v153
	v_fmac_f32_e32 v148, v154, v154
	v_lshlrev_b32_e32 v172, 16, v152
	v_lshlrev_b32_e32 v194, 16, v153
	v_add_f32_e32 v148, v149, v148
	v_mul_f32_e32 v149, v173, v173
	v_mul_f32_e32 v154, v195, v195
	v_fmac_f32_e32 v149, v172, v172
	v_fmac_f32_e32 v154, v194, v194
	v_add_f32_e32 v149, v149, v154
	v_add_f32_e32 v148, v148, v149
	v_add_f32_e32 v148, v185, v148
	v_mov_b32_e32 v149, v148
	s_nop 1
	v_permlane16_swap_b32_e32 v148, v149
	global_store_dwordx4 v[170:171], v[150:153], off offset:256 nt
	s_waitcnt lgkmcnt(0)
	v_add_f32_e32 v148, v148, v149
	v_mov_b32_e32 v149, v148
	s_nop 1
	v_permlane32_swap_b32_e32 v148, v149
	s_and_saveexec_b64 s[72:73], s[40:41]
	s_cbranch_execz .LBB7_1111
	v_lshlrev_b64 v[150:151], 6, v[192:193]
	v_lshl_add_u64 v[150:151], s[66:67], 0, v[150:151]
	v_lshl_add_u64 v[150:151], vcc, 2, v[150:151]
	s_lshl_b32 s20, s92, 2
	v_lshl_add_u64 v[150:151], v[150:151], 0, s[20:21]
	s_waitcnt lgkmcnt(0)
	v_add_f32_e32 v148, v148, v149
	global_store_dword v[150:151], v148, off
.LBB7_1111:
	s_or_b64 exec, exec, s[72:73]
	v_lshlrev_b32_e32 v148, 16, v144
	s_waitcnt lgkmcnt(0)
	v_and_b32_e32 v149, 0xffff0000, v144
	v_lshlrev_b32_e32 v144, 16, v145
	v_and_b32_e32 v145, 0xffff0000, v145
	v_lshlrev_b32_e32 v150, 16, v146
	v_and_b32_e32 v151, 0xffff0000, v146
	v_lshlrev_b32_e32 v146, 16, v147
	v_and_b32_e32 v147, 0xffff0000, v147
	v_pk_add_f32 v[152:153], v[114:115], v[144:145]
	v_pk_add_f32 v[144:145], v[112:113], v[148:149]
	v_pk_add_f32 v[148:149], v[110:111], v[146:147]
	v_pk_add_f32 v[146:147], v[108:109], v[150:151]
	v_cvt_pk_bf16_f32 v144, v144, v145
	v_cvt_pk_bf16_f32 v145, v152, v153
	s_nop 0
	v_cvt_pk_bf16_f32 v146, v146, v147
	v_cvt_pk_bf16_f32 v147, v148, v149
	v_lshl_add_u64 v[148:149], s[68:69], 0, v[188:189]
	v_lshl_add_u64 v[148:149], v[2:3], 1, v[148:149]
	global_store_dwordx4 v[148:149], v[144:147], off nt
	v_lshlrev_b32_e32 v150, 16, v144
	v_lshlrev_b32_e32 v151, 16, v145
	v_and_b32_e32 v144, 0xffff0000, v144
	v_and_b32_e32 v145, 0xffff0000, v145
	v_mul_f32_e32 v144, v144, v144
	v_mul_f32_e32 v145, v145, v145
	v_lshlrev_b32_e32 v152, 16, v146
	v_and_b32_e32 v146, 0xffff0000, v146
	v_lshlrev_b32_e32 v153, 16, v147
	v_and_b32_e32 v147, 0xffff0000, v147
	v_fmac_f32_e32 v144, v150, v150
	v_fmac_f32_e32 v145, v151, v151
	v_add_f32_e32 v144, v144, v145
	v_mul_f32_e32 v145, v146, v146
	v_mul_f32_e32 v146, v147, v147
	v_fmac_f32_e32 v145, v152, v152
	v_fmac_f32_e32 v146, v153, v153
	v_add_f32_e32 v145, v145, v146
	v_add_f32_e32 v152, v144, v145
	v_lshlrev_b32_e32 v144, 16, v140
	v_and_b32_e32 v145, 0xffff0000, v140
	v_lshlrev_b32_e32 v140, 16, v141
	v_and_b32_e32 v141, 0xffff0000, v141
	v_lshlrev_b32_e32 v146, 16, v142
	v_and_b32_e32 v147, 0xffff0000, v142
	v_lshlrev_b32_e32 v142, 16, v143
	v_and_b32_e32 v143, 0xffff0000, v143
	v_pk_add_f32 v[140:141], v[82:83], v[140:141]
	v_pk_add_f32 v[144:145], v[80:81], v[144:145]
	v_pk_add_f32 v[150:151], v[78:79], v[142:143]
	v_pk_add_f32 v[146:147], v[76:77], v[146:147]
	v_cvt_pk_bf16_f32 v142, v144, v145
	v_cvt_pk_bf16_f32 v143, v140, v141
	s_nop 0
	v_and_b32_e32 v141, 0xffff0000, v142
	v_cvt_pk_bf16_f32 v144, v146, v147
	v_lshlrev_b32_e32 v140, 16, v142
	v_and_b32_e32 v147, 0xffff0000, v143
	v_mul_f32_e32 v141, v141, v141
	v_lshlrev_b32_e32 v146, 16, v143
	v_fmac_f32_e32 v141, v140, v140
	v_mul_f32_e32 v140, v147, v147
	v_cvt_pk_bf16_f32 v145, v150, v151
	v_and_b32_e32 v151, 0xffff0000, v144
	v_and_b32_e32 v154, 0xffff0000, v145
	v_fmac_f32_e32 v140, v146, v146
	v_lshlrev_b32_e32 v150, 16, v144
	v_lshlrev_b32_e32 v153, 16, v145
	v_add_f32_e32 v140, v141, v140
	v_mul_f32_e32 v141, v151, v151
	v_mul_f32_e32 v146, v154, v154
	v_fmac_f32_e32 v141, v150, v150
	v_fmac_f32_e32 v146, v153, v153
	v_add_f32_e32 v141, v141, v146
	v_add_f32_e32 v140, v140, v141
	v_add_f32_e32 v140, v152, v140
	v_mov_b32_e32 v141, v140
	s_nop 1
	v_permlane16_swap_b32_e32 v140, v141
	global_store_dwordx4 v[148:149], v[142:145], off offset:256 nt
	s_waitcnt lgkmcnt(0)
	v_add_f32_e32 v140, v140, v141
	v_mov_b32_e32 v141, v140
	s_nop 1
	v_permlane32_swap_b32_e32 v140, v141
	s_and_saveexec_b64 s[72:73], s[40:41]
	s_cbranch_execz .LBB7_1113
	v_lshlrev_b64 v[142:143], 6, v[186:187]
	v_lshl_add_u64 v[142:143], s[66:67], 0, v[142:143]
	v_lshl_add_u64 v[142:143], vcc, 2, v[142:143]
	s_lshl_b32 s20, s92, 2
	v_lshl_add_u64 v[142:143], v[142:143], 0, s[20:21]
	s_waitcnt lgkmcnt(0)
	v_add_f32_e32 v140, v140, v141
	global_store_dword v[142:143], v140, off
.LBB7_1113:
	s_or_b64 exec, exec, s[72:73]
	v_lshlrev_b32_e32 v140, 16, v136
	s_waitcnt lgkmcnt(0)
	v_and_b32_e32 v141, 0xffff0000, v136
	v_lshlrev_b32_e32 v136, 16, v137
	v_and_b32_e32 v137, 0xffff0000, v137
	v_lshlrev_b32_e32 v142, 16, v138
	v_and_b32_e32 v143, 0xffff0000, v138
	v_lshlrev_b32_e32 v138, 16, v139
	v_and_b32_e32 v139, 0xffff0000, v139
	v_pk_add_f32 v[144:145], v[106:107], v[136:137]
	v_pk_add_f32 v[136:137], v[104:105], v[140:141]
	v_pk_add_f32 v[140:141], v[102:103], v[138:139]
	v_pk_add_f32 v[138:139], v[100:101], v[142:143]
	v_cvt_pk_bf16_f32 v136, v136, v137
	v_cvt_pk_bf16_f32 v137, v144, v145
	s_nop 0
	v_cvt_pk_bf16_f32 v138, v138, v139
	v_cvt_pk_bf16_f32 v139, v140, v141
	v_lshl_add_u64 v[140:141], s[68:69], 0, v[158:159]
	v_lshl_add_u64 v[140:141], v[2:3], 1, v[140:141]
	global_store_dwordx4 v[140:141], v[136:139], off nt
	v_lshlrev_b32_e32 v142, 16, v136
	v_lshlrev_b32_e32 v143, 16, v137
	v_and_b32_e32 v136, 0xffff0000, v136
	v_and_b32_e32 v137, 0xffff0000, v137
	v_mul_f32_e32 v136, v136, v136
	v_mul_f32_e32 v137, v137, v137
	v_lshlrev_b32_e32 v144, 16, v138
	v_and_b32_e32 v138, 0xffff0000, v138
	v_lshlrev_b32_e32 v145, 16, v139
	v_and_b32_e32 v139, 0xffff0000, v139
	v_fmac_f32_e32 v136, v142, v142
	v_fmac_f32_e32 v137, v143, v143
	v_add_f32_e32 v136, v136, v137
	v_mul_f32_e32 v137, v138, v138
	v_mul_f32_e32 v138, v139, v139
	v_fmac_f32_e32 v137, v144, v144
	v_fmac_f32_e32 v138, v145, v145
	v_add_f32_e32 v137, v137, v138
	v_add_f32_e32 v144, v136, v137
	v_lshlrev_b32_e32 v136, 16, v132
	v_and_b32_e32 v137, 0xffff0000, v132
	v_lshlrev_b32_e32 v132, 16, v133
	v_and_b32_e32 v133, 0xffff0000, v133
	v_lshlrev_b32_e32 v138, 16, v134
	v_and_b32_e32 v139, 0xffff0000, v134
	v_lshlrev_b32_e32 v134, 16, v135
	v_and_b32_e32 v135, 0xffff0000, v135
	v_pk_add_f32 v[132:133], v[74:75], v[132:133]
	v_pk_add_f32 v[136:137], v[72:73], v[136:137]
	v_pk_add_f32 v[142:143], v[70:71], v[134:135]
	v_pk_add_f32 v[138:139], v[68:69], v[138:139]
	v_cvt_pk_bf16_f32 v134, v136, v137
	v_cvt_pk_bf16_f32 v135, v132, v133
	s_nop 0
	v_and_b32_e32 v133, 0xffff0000, v134
	v_cvt_pk_bf16_f32 v136, v138, v139
	v_lshlrev_b32_e32 v132, 16, v134
	v_and_b32_e32 v139, 0xffff0000, v135
	v_mul_f32_e32 v133, v133, v133
	v_lshlrev_b32_e32 v138, 16, v135
	v_fmac_f32_e32 v133, v132, v132
	v_mul_f32_e32 v132, v139, v139
	v_cvt_pk_bf16_f32 v137, v142, v143
	v_and_b32_e32 v143, 0xffff0000, v136
	v_and_b32_e32 v146, 0xffff0000, v137
	v_fmac_f32_e32 v132, v138, v138
	v_lshlrev_b32_e32 v142, 16, v136
	v_lshlrev_b32_e32 v145, 16, v137
	v_add_f32_e32 v132, v133, v132
	v_mul_f32_e32 v133, v143, v143
	v_mul_f32_e32 v138, v146, v146
	v_fmac_f32_e32 v133, v142, v142
	v_fmac_f32_e32 v138, v145, v145
	v_add_f32_e32 v133, v133, v138
	v_add_f32_e32 v132, v132, v133
	v_add_f32_e32 v132, v144, v132
	v_mov_b32_e32 v133, v132
	s_nop 1
	v_permlane16_swap_b32_e32 v132, v133
	global_store_dwordx4 v[140:141], v[134:137], off offset:256 nt
	s_waitcnt lgkmcnt(0)
	v_add_f32_e32 v132, v132, v133
	v_mov_b32_e32 v133, v132
	s_nop 1
	v_permlane32_swap_b32_e32 v132, v133
	s_and_saveexec_b64 s[72:73], s[40:41]
	s_cbranch_execz .LBB7_1115
	v_lshlrev_b64 v[134:135], 6, v[156:157]
	v_lshl_add_u64 v[134:135], s[66:67], 0, v[134:135]
	v_lshl_add_u64 v[134:135], vcc, 2, v[134:135]
	s_lshl_b32 s20, s92, 2
	v_lshl_add_u64 v[134:135], v[134:135], 0, s[20:21]
	s_waitcnt lgkmcnt(0)
	v_add_f32_e32 v132, v132, v133
	global_store_dword v[134:135], v132, off
.LBB7_1115:
	s_or_b64 exec, exec, s[72:73]
	v_add_u32_e32 v198, 0x80, v184
	v_ashrrev_i32_e32 v199, 31, v198
	v_lshlrev_b64 v[170:171], 11, v[198:199]
	s_waitcnt lgkmcnt(0)
	v_lshl_add_u64 v[132:133], v[190:191], 0, v[170:171]
	v_mov_b64_e32 v[210:211], v[232:233]
	v_mov_b64_e32 v[212:213], v[234:235]
	v_mov_b64_e32 v[156:157], v[236:237]
	v_mov_b64_e32 v[158:159], v[238:239]
	v_add_u32_e32 v194, 0x90, v184
	v_ashrrev_i32_e32 v195, 31, v194
	v_add_u32_e32 v188, 0xa0, v184
	v_lshlrev_b64 v[196:197], 11, v[194:195]
	v_ashrrev_i32_e32 v189, 31, v188
	v_add_u32_e32 v184, 0xb0, v184
	v_lshl_add_u64 v[132:133], v[190:191], 0, v[196:197]
	v_lshlrev_b64 v[192:193], 11, v[188:189]
	v_ashrrev_i32_e32 v185, 31, v184
	v_mov_b64_e32 v[152:153], v[240:241]
	v_mov_b64_e32 v[154:155], v[242:243]
	v_mov_b64_e32 v[148:149], v[244:245]
	v_mov_b64_e32 v[150:151], v[246:247]
	v_lshl_add_u64 v[132:133], v[190:191], 0, v[192:193]
	v_lshlrev_b64 v[186:187], 11, v[184:185]
	global_load_dwordx4 v[144:147], v[132:133], off
	global_load_dwordx4 v[140:143], v[132:133], off offset:256
	v_lshl_add_u64 v[132:133], v[190:191], 0, v[186:187]
	global_load_dwordx4 v[136:139], v[132:133], off
	s_nop 0
	global_load_dwordx4 v[132:135], v[132:133], off offset:256
	v_lshl_add_u64 v[170:171], s[68:69], 0, v[170:171]
	v_lshl_add_u64 v[170:171], v[2:3], 1, v[170:171]
	s_waitcnt vmcnt(7)
	v_lshlrev_b32_e32 v172, 16, v210
	v_and_b32_e32 v173, 0xffff0000, v210
	v_lshlrev_b32_e32 v190, 16, v211
	v_and_b32_e32 v191, 0xffff0000, v211
	v_lshlrev_b32_e32 v210, 16, v212
	v_and_b32_e32 v211, 0xffff0000, v212
	v_lshlrev_b32_e32 v212, 16, v213
	v_and_b32_e32 v213, 0xffff0000, v213
	v_pk_add_f32 v[172:173], v[64:65], v[172:173]
	v_pk_add_f32 v[190:191], v[66:67], v[190:191]
	v_pk_add_f32 v[214:215], v[62:63], v[212:213]
	v_pk_add_f32 v[212:213], v[60:61], v[210:211]
	v_cvt_pk_bf16_f32 v210, v172, v173
	v_cvt_pk_bf16_f32 v211, v190, v191
	s_nop 0
	v_and_b32_e32 v173, 0xffff0000, v210
	v_lshlrev_b32_e32 v172, 16, v210
	v_and_b32_e32 v191, 0xffff0000, v211
	v_mul_f32_e32 v173, v173, v173
	v_cvt_pk_bf16_f32 v212, v212, v213
	v_lshlrev_b32_e32 v190, 16, v211
	v_fmac_f32_e32 v173, v172, v172
	v_mul_f32_e32 v172, v191, v191
	v_cvt_pk_bf16_f32 v213, v214, v215
	global_store_dwordx4 v[170:171], v[210:213], off nt
	v_lshlrev_b32_e32 v209, 16, v212
	v_fmac_f32_e32 v172, v190, v190
	v_and_b32_e32 v210, 0xffff0000, v212
	v_and_b32_e32 v212, 0xffff0000, v213
	v_lshlrev_b32_e32 v211, 16, v213
	v_add_f32_e32 v172, v173, v172
	v_mul_f32_e32 v173, v210, v210
	v_mul_f32_e32 v190, v212, v212
	v_fmac_f32_e32 v173, v209, v209
	v_fmac_f32_e32 v190, v211, v211
	v_add_f32_e32 v173, v173, v190
	v_add_f32_e32 v209, v172, v173
	s_waitcnt vmcnt(7)
	v_lshlrev_b32_e32 v172, 16, v156
	v_and_b32_e32 v173, 0xffff0000, v156
	v_lshlrev_b32_e32 v156, 16, v157
	v_and_b32_e32 v157, 0xffff0000, v157
	v_lshlrev_b32_e32 v190, 16, v158
	v_and_b32_e32 v191, 0xffff0000, v158
	v_lshlrev_b32_e32 v158, 16, v159
	v_and_b32_e32 v159, 0xffff0000, v159
	v_pk_add_f32 v[210:211], v[34:35], v[156:157]
	v_pk_add_f32 v[156:157], v[32:33], v[172:173]
	v_pk_add_f32 v[172:173], v[30:31], v[158:159]
	v_pk_add_f32 v[158:159], v[28:29], v[190:191]
	v_cvt_pk_bf16_f32 v156, v156, v157
	v_cvt_pk_bf16_f32 v157, v210, v211
	s_nop 0
	v_cvt_pk_bf16_f32 v158, v158, v159
	v_cvt_pk_bf16_f32 v159, v172, v173
	global_store_dwordx4 v[170:171], v[156:159], off offset:256 nt
	v_lshlrev_b32_e32 v170, 16, v156
	v_lshlrev_b32_e32 v171, 16, v157
	v_and_b32_e32 v156, 0xffff0000, v156
	v_and_b32_e32 v157, 0xffff0000, v157
	v_mul_f32_e32 v156, v156, v156
	v_mul_f32_e32 v157, v157, v157
	v_lshlrev_b32_e32 v172, 16, v158
	v_and_b32_e32 v158, 0xffff0000, v158
	v_lshlrev_b32_e32 v173, 16, v159
	v_and_b32_e32 v159, 0xffff0000, v159
	v_fmac_f32_e32 v156, v170, v170
	v_fmac_f32_e32 v157, v171, v171
	v_add_f32_e32 v156, v156, v157
	v_mul_f32_e32 v157, v158, v158
	v_mul_f32_e32 v158, v159, v159
	v_fmac_f32_e32 v157, v172, v172
	v_fmac_f32_e32 v158, v173, v173
	v_add_f32_e32 v157, v157, v158
	v_add_f32_e32 v156, v156, v157
	v_add_f32_e32 v156, v209, v156
	v_mov_b32_e32 v157, v156
	s_nop 1
	v_permlane16_swap_b32_e32 v156, v157
	s_waitcnt lgkmcnt(0)
	v_add_f32_e32 v156, v156, v157
	v_mov_b32_e32 v157, v156
	s_nop 1
	v_permlane32_swap_b32_e32 v156, v157
	s_and_saveexec_b64 s[72:73], s[40:41]
	s_cbranch_execz .LBB7_1117
	v_lshlrev_b64 v[158:159], 6, v[198:199]
	v_lshl_add_u64 v[158:159], s[66:67], 0, v[158:159]
	v_lshl_add_u64 v[158:159], vcc, 2, v[158:159]
	s_lshl_b32 s20, s92, 2
	v_lshl_add_u64 v[158:159], v[158:159], 0, s[20:21]
	s_waitcnt lgkmcnt(0)
	v_add_f32_e32 v156, v156, v157
	global_store_dword v[158:159], v156, off
.LBB7_1117:
	s_or_b64 exec, exec, s[72:73]
	s_waitcnt vmcnt(7)
	v_lshlrev_b32_e32 v156, 16, v152
	s_waitcnt lgkmcnt(0)
	v_and_b32_e32 v157, 0xffff0000, v152
	v_lshlrev_b32_e32 v152, 16, v153
	v_and_b32_e32 v153, 0xffff0000, v153
	v_lshlrev_b32_e32 v158, 16, v154
	v_and_b32_e32 v159, 0xffff0000, v154
	v_lshlrev_b32_e32 v154, 16, v155
	v_and_b32_e32 v155, 0xffff0000, v155
	v_pk_add_f32 v[170:171], v[58:59], v[152:153]
	v_pk_add_f32 v[152:153], v[56:57], v[156:157]
	v_pk_add_f32 v[156:157], v[54:55], v[154:155]
	v_pk_add_f32 v[154:155], v[52:53], v[158:159]
	v_cvt_pk_bf16_f32 v152, v152, v153
	v_cvt_pk_bf16_f32 v153, v170, v171
	s_nop 0
	v_cvt_pk_bf16_f32 v154, v154, v155
	v_cvt_pk_bf16_f32 v155, v156, v157
	v_lshl_add_u64 v[156:157], s[68:69], 0, v[196:197]
	v_lshl_add_u64 v[156:157], v[2:3], 1, v[156:157]
	global_store_dwordx4 v[156:157], v[152:155], off nt
	v_lshlrev_b32_e32 v158, 16, v152
	v_lshlrev_b32_e32 v159, 16, v153
	v_and_b32_e32 v152, 0xffff0000, v152
	v_and_b32_e32 v153, 0xffff0000, v153
	v_mul_f32_e32 v152, v152, v152
	v_mul_f32_e32 v153, v153, v153
	v_lshlrev_b32_e32 v170, 16, v154
	v_and_b32_e32 v154, 0xffff0000, v154
	v_lshlrev_b32_e32 v171, 16, v155
	v_and_b32_e32 v155, 0xffff0000, v155
	v_fmac_f32_e32 v152, v158, v158
	v_fmac_f32_e32 v153, v159, v159
	v_add_f32_e32 v152, v152, v153
	v_mul_f32_e32 v153, v154, v154
	v_mul_f32_e32 v154, v155, v155
	v_fmac_f32_e32 v153, v170, v170
	v_fmac_f32_e32 v154, v171, v171
	v_add_f32_e32 v153, v153, v154
	v_add_f32_e32 v170, v152, v153
	s_waitcnt vmcnt(7)
	v_lshlrev_b32_e32 v152, 16, v148
	v_and_b32_e32 v153, 0xffff0000, v148
	v_lshlrev_b32_e32 v148, 16, v149
	v_and_b32_e32 v149, 0xffff0000, v149
	v_lshlrev_b32_e32 v154, 16, v150
	v_and_b32_e32 v155, 0xffff0000, v150
	v_lshlrev_b32_e32 v150, 16, v151
	v_and_b32_e32 v151, 0xffff0000, v151
	v_pk_add_f32 v[148:149], v[26:27], v[148:149]
	v_pk_add_f32 v[152:153], v[24:25], v[152:153]
	v_pk_add_f32 v[158:159], v[22:23], v[150:151]
	v_pk_add_f32 v[154:155], v[20:21], v[154:155]
	v_cvt_pk_bf16_f32 v150, v152, v153
	v_cvt_pk_bf16_f32 v151, v148, v149
	s_nop 0
	v_and_b32_e32 v149, 0xffff0000, v150
	v_cvt_pk_bf16_f32 v152, v154, v155
	v_lshlrev_b32_e32 v148, 16, v150
	v_and_b32_e32 v155, 0xffff0000, v151
	v_mul_f32_e32 v149, v149, v149
	v_lshlrev_b32_e32 v154, 16, v151
	v_fmac_f32_e32 v149, v148, v148
	v_mul_f32_e32 v148, v155, v155
	v_cvt_pk_bf16_f32 v153, v158, v159
	v_and_b32_e32 v159, 0xffff0000, v152
	v_and_b32_e32 v172, 0xffff0000, v153
	v_fmac_f32_e32 v148, v154, v154
	v_lshlrev_b32_e32 v158, 16, v152
	v_lshlrev_b32_e32 v171, 16, v153
	v_add_f32_e32 v148, v149, v148
	v_mul_f32_e32 v149, v159, v159
	v_mul_f32_e32 v154, v172, v172
	v_fmac_f32_e32 v149, v158, v158
	v_fmac_f32_e32 v154, v171, v171
	v_add_f32_e32 v149, v149, v154
	v_add_f32_e32 v148, v148, v149
	v_add_f32_e32 v148, v170, v148
	v_mov_b32_e32 v149, v148
	s_nop 1
	v_permlane16_swap_b32_e32 v148, v149
	global_store_dwordx4 v[156:157], v[150:153], off offset:256 nt
	s_waitcnt lgkmcnt(0)
	v_add_f32_e32 v148, v148, v149
	v_mov_b32_e32 v149, v148
	s_nop 1
	v_permlane32_swap_b32_e32 v148, v149
	s_and_saveexec_b64 s[72:73], s[40:41]
	s_cbranch_execz .LBB7_1119
	v_lshlrev_b64 v[150:151], 6, v[194:195]
	v_lshl_add_u64 v[150:151], s[66:67], 0, v[150:151]
	v_lshl_add_u64 v[150:151], vcc, 2, v[150:151]
	s_lshl_b32 s20, s92, 2
	v_lshl_add_u64 v[150:151], v[150:151], 0, s[20:21]
	s_waitcnt lgkmcnt(0)
	v_add_f32_e32 v148, v148, v149
	global_store_dword v[150:151], v148, off
.LBB7_1119:
	s_or_b64 exec, exec, s[72:73]
	s_waitcnt vmcnt(7)
	v_lshlrev_b32_e32 v148, 16, v144
	s_waitcnt lgkmcnt(0)
	v_and_b32_e32 v149, 0xffff0000, v144
	v_lshlrev_b32_e32 v144, 16, v145
	v_and_b32_e32 v145, 0xffff0000, v145
	v_lshlrev_b32_e32 v150, 16, v146
	v_and_b32_e32 v151, 0xffff0000, v146
	v_lshlrev_b32_e32 v146, 16, v147
	v_and_b32_e32 v147, 0xffff0000, v147
	v_pk_add_f32 v[152:153], v[50:51], v[144:145]
	v_pk_add_f32 v[144:145], v[48:49], v[148:149]
	v_pk_add_f32 v[148:149], v[46:47], v[146:147]
	v_pk_add_f32 v[146:147], v[44:45], v[150:151]
	v_cvt_pk_bf16_f32 v144, v144, v145
	v_cvt_pk_bf16_f32 v145, v152, v153
	s_nop 0
	v_cvt_pk_bf16_f32 v146, v146, v147
	v_cvt_pk_bf16_f32 v147, v148, v149
	v_lshl_add_u64 v[148:149], s[68:69], 0, v[192:193]
	v_lshl_add_u64 v[148:149], v[2:3], 1, v[148:149]
	global_store_dwordx4 v[148:149], v[144:147], off nt
	v_lshlrev_b32_e32 v150, 16, v144
	v_lshlrev_b32_e32 v151, 16, v145
	v_and_b32_e32 v144, 0xffff0000, v144
	v_and_b32_e32 v145, 0xffff0000, v145
	v_mul_f32_e32 v144, v144, v144
	v_mul_f32_e32 v145, v145, v145
	v_lshlrev_b32_e32 v152, 16, v146
	v_and_b32_e32 v146, 0xffff0000, v146
	v_lshlrev_b32_e32 v153, 16, v147
	v_and_b32_e32 v147, 0xffff0000, v147
	v_fmac_f32_e32 v144, v150, v150
	v_fmac_f32_e32 v145, v151, v151
	v_add_f32_e32 v144, v144, v145
	v_mul_f32_e32 v145, v146, v146
	v_mul_f32_e32 v146, v147, v147
	v_fmac_f32_e32 v145, v152, v152
	v_fmac_f32_e32 v146, v153, v153
	v_add_f32_e32 v145, v145, v146
	v_add_f32_e32 v152, v144, v145
	s_waitcnt vmcnt(7)
	v_lshlrev_b32_e32 v144, 16, v140
	v_and_b32_e32 v145, 0xffff0000, v140
	v_lshlrev_b32_e32 v140, 16, v141
	v_and_b32_e32 v141, 0xffff0000, v141
	v_lshlrev_b32_e32 v146, 16, v142
	v_and_b32_e32 v147, 0xffff0000, v142
	v_lshlrev_b32_e32 v142, 16, v143
	v_and_b32_e32 v143, 0xffff0000, v143
	v_pk_add_f32 v[140:141], v[18:19], v[140:141]
	v_pk_add_f32 v[144:145], v[16:17], v[144:145]
	v_pk_add_f32 v[150:151], v[14:15], v[142:143]
	v_pk_add_f32 v[146:147], v[12:13], v[146:147]
	v_cvt_pk_bf16_f32 v142, v144, v145
	v_cvt_pk_bf16_f32 v143, v140, v141
	s_nop 0
	v_and_b32_e32 v141, 0xffff0000, v142
	v_cvt_pk_bf16_f32 v144, v146, v147
	v_lshlrev_b32_e32 v140, 16, v142
	v_and_b32_e32 v147, 0xffff0000, v143
	v_mul_f32_e32 v141, v141, v141
	v_lshlrev_b32_e32 v146, 16, v143
	v_fmac_f32_e32 v141, v140, v140
	v_mul_f32_e32 v140, v147, v147
	v_cvt_pk_bf16_f32 v145, v150, v151
	v_and_b32_e32 v151, 0xffff0000, v144
	v_and_b32_e32 v154, 0xffff0000, v145
	v_fmac_f32_e32 v140, v146, v146
	v_lshlrev_b32_e32 v150, 16, v144
	v_lshlrev_b32_e32 v153, 16, v145
	v_add_f32_e32 v140, v141, v140
	v_mul_f32_e32 v141, v151, v151
	v_mul_f32_e32 v146, v154, v154
	v_fmac_f32_e32 v141, v150, v150
	v_fmac_f32_e32 v146, v153, v153
	v_add_f32_e32 v141, v141, v146
	v_add_f32_e32 v140, v140, v141
	v_add_f32_e32 v140, v152, v140
	v_mov_b32_e32 v141, v140
	s_nop 1
	v_permlane16_swap_b32_e32 v140, v141
	global_store_dwordx4 v[148:149], v[142:145], off offset:256 nt
	s_waitcnt lgkmcnt(0)
	v_add_f32_e32 v140, v140, v141
	v_mov_b32_e32 v141, v140
	s_nop 1
	v_permlane32_swap_b32_e32 v140, v141
	s_and_saveexec_b64 s[72:73], s[40:41]
	s_cbranch_execz .LBB7_1121
	v_lshlrev_b64 v[142:143], 6, v[188:189]
	v_lshl_add_u64 v[142:143], s[66:67], 0, v[142:143]
	v_lshl_add_u64 v[142:143], vcc, 2, v[142:143]
	s_lshl_b32 s20, s92, 2
	v_lshl_add_u64 v[142:143], v[142:143], 0, s[20:21]
	s_waitcnt lgkmcnt(0)
	v_add_f32_e32 v140, v140, v141
	global_store_dword v[142:143], v140, off
.LBB7_1121:
	s_or_b64 exec, exec, s[72:73]
	s_waitcnt vmcnt(7)
	v_lshlrev_b32_e32 v140, 16, v136
	s_waitcnt lgkmcnt(0)
	v_and_b32_e32 v141, 0xffff0000, v136
	v_lshlrev_b32_e32 v136, 16, v137
	v_and_b32_e32 v137, 0xffff0000, v137
	v_lshlrev_b32_e32 v142, 16, v138
	v_and_b32_e32 v143, 0xffff0000, v138
	v_lshlrev_b32_e32 v138, 16, v139
	v_and_b32_e32 v139, 0xffff0000, v139
	v_pk_add_f32 v[144:145], v[42:43], v[136:137]
	v_pk_add_f32 v[136:137], v[40:41], v[140:141]
	v_pk_add_f32 v[140:141], v[38:39], v[138:139]
	v_pk_add_f32 v[138:139], v[36:37], v[142:143]
	v_cvt_pk_bf16_f32 v136, v136, v137
	v_cvt_pk_bf16_f32 v137, v144, v145
	s_nop 0
	v_cvt_pk_bf16_f32 v138, v138, v139
	v_cvt_pk_bf16_f32 v139, v140, v141
	v_lshl_add_u64 v[140:141], s[68:69], 0, v[186:187]
	v_lshl_add_u64 v[140:141], v[2:3], 1, v[140:141]
	v_and_b32_e32 v3, 0xffff0000, v136
	global_store_dwordx4 v[140:141], v[136:139], off nt
	v_lshlrev_b32_e32 v2, 16, v136
	v_mul_f32_e32 v3, v3, v3
	v_lshlrev_b32_e32 v136, 16, v137
	v_and_b32_e32 v137, 0xffff0000, v137
	v_fmac_f32_e32 v3, v2, v2
	v_mul_f32_e32 v2, v137, v137
	v_lshlrev_b32_e32 v142, 16, v138
	v_and_b32_e32 v138, 0xffff0000, v138
	v_lshlrev_b32_e32 v143, 16, v139
	v_and_b32_e32 v139, 0xffff0000, v139
	v_fmac_f32_e32 v2, v136, v136
	v_add_f32_e32 v2, v3, v2
	v_mul_f32_e32 v3, v138, v138
	v_mul_f32_e32 v136, v139, v139
	v_fmac_f32_e32 v3, v142, v142
	v_fmac_f32_e32 v136, v143, v143
	v_add_f32_e32 v3, v3, v136
	v_add_f32_e32 v144, v2, v3
	s_waitcnt vmcnt(7)
	v_lshlrev_b32_e32 v2, 16, v132
	v_and_b32_e32 v3, 0xffff0000, v132
	v_lshlrev_b32_e32 v132, 16, v133
	v_and_b32_e32 v133, 0xffff0000, v133
	v_pk_add_f32 v[2:3], v[8:9], v[2:3]
	v_lshlrev_b32_e32 v136, 16, v134
	v_and_b32_e32 v137, 0xffff0000, v134
	v_lshlrev_b32_e32 v134, 16, v135
	v_and_b32_e32 v135, 0xffff0000, v135
	v_pk_add_f32 v[138:139], v[10:11], v[132:133]
	v_cvt_pk_bf16_f32 v132, v2, v3
	v_pk_add_f32 v[142:143], v[6:7], v[134:135]
	v_and_b32_e32 v3, 0xffff0000, v132
	v_pk_add_f32 v[134:135], v[4:5], v[136:137]
	v_cvt_pk_bf16_f32 v133, v138, v139
	v_lshlrev_b32_e32 v2, 16, v132
	v_and_b32_e32 v137, 0xffff0000, v133
	v_mul_f32_e32 v3, v3, v3
	v_lshlrev_b32_e32 v136, 16, v133
	v_fmac_f32_e32 v3, v2, v2
	v_mul_f32_e32 v2, v137, v137
	v_cvt_pk_bf16_f32 v134, v134, v135
	v_cvt_pk_bf16_f32 v135, v142, v143
	v_fmac_f32_e32 v2, v136, v136
	v_and_b32_e32 v139, 0xffff0000, v134
	v_and_b32_e32 v143, 0xffff0000, v135
	v_lshlrev_b32_e32 v138, 16, v134
	v_lshlrev_b32_e32 v142, 16, v135
	v_add_f32_e32 v2, v3, v2
	v_mul_f32_e32 v3, v139, v139
	v_mul_f32_e32 v136, v143, v143
	v_fmac_f32_e32 v3, v138, v138
	v_fmac_f32_e32 v136, v142, v142
	v_add_f32_e32 v3, v3, v136
	v_add_f32_e32 v2, v2, v3
	v_add_f32_e32 v2, v144, v2
	v_mov_b32_e32 v0, v2
	s_nop 1
	v_permlane16_swap_b32_e32 v2, v0
	global_store_dwordx4 v[140:141], v[132:135], off offset:256 nt
	s_waitcnt lgkmcnt(0)
	v_add_f32_e32 v0, v2, v0
	v_mov_b32_e32 v2, v0
	s_nop 1
	v_permlane32_swap_b32_e32 v0, v2
	s_and_saveexec_b64 s[72:73], s[40:41]
	s_cbranch_execz .LBB7_1123
	v_lshlrev_b64 v[132:133], 6, v[184:185]
	v_lshl_add_u64 v[132:133], s[66:67], 0, v[132:133]
	v_lshl_add_u64 v[132:133], vcc, 2, v[132:133]
	s_lshl_b32 s20, s92, 2
	v_lshl_add_u64 v[132:133], v[132:133], 0, s[20:21]
	s_waitcnt lgkmcnt(0)
	v_add_f32_e32 v0, v0, v2
	global_store_dword v[132:133], v0, off

.LBB7_1277:
	v_lshl_add_u32 v144, s39, 8, v140
	v_ashrrev_i32_e32 v145, 31, v144
	v_lshl_or_b32 v152, s38, 8, v142
	v_or_b32_e32 v146, 16, v144
	v_or_b32_e32 v148, 32, v144
	v_or_b32_e32 v150, 48, v144
	v_ashrrev_i32_e32 v153, 31, v152
	v_lshlrev_b64 v[144:145], 11, v[144:145]
	v_lshl_add_u64 v[144:145], s[94:95], 0, v[144:145]
	v_lshlrev_b64 v[152:153], 1, v[152:153]
	v_ashrrev_i32_e32 v147, 31, v146
	v_lshl_add_u64 v[144:145], v[144:145], 0, v[152:153]
	v_cvt_pk_bf16_f32 v126, v126, v127
	v_cvt_pk_bf16_f32 v127, v128, v129
	v_cvt_pk_bf16_f32 v128, v122, v123
	v_cvt_pk_bf16_f32 v129, v124, v125
	global_store_dwordx4 v[144:145], v[126:129], off nt
	v_cvt_pk_bf16_f32 v118, v118, v119
	v_cvt_pk_bf16_f32 v119, v120, v121
	v_cvt_pk_bf16_f32 v120, v114, v115
	v_lshlrev_b64 v[114:115], 11, v[146:147]
	v_lshl_add_u64 v[114:115], s[94:95], 0, v[114:115]
	v_ashrrev_i32_e32 v149, 31, v148
	v_cvt_pk_bf16_f32 v121, v116, v117
	global_store_dwordx4 v[144:145], v[118:121], off offset:256 nt
	v_lshl_add_u64 v[114:115], v[114:115], 0, v[152:153]
	v_cvt_pk_bf16_f32 v110, v110, v111
	v_cvt_pk_bf16_f32 v111, v112, v113
	v_cvt_pk_bf16_f32 v112, v106, v107
	v_cvt_pk_bf16_f32 v113, v108, v109
	global_store_dwordx4 v[114:115], v[110:113], off nt
	v_cvt_pk_bf16_f32 v102, v102, v103
	v_cvt_pk_bf16_f32 v103, v104, v105
	v_cvt_pk_bf16_f32 v104, v98, v99
	v_lshlrev_b64 v[98:99], 11, v[148:149]
	v_lshl_add_u64 v[98:99], s[94:95], 0, v[98:99]
	v_ashrrev_i32_e32 v151, 31, v150
	v_cvt_pk_bf16_f32 v105, v100, v101
	global_store_dwordx4 v[114:115], v[102:105], off offset:256 nt
	v_lshl_add_u64 v[98:99], v[98:99], 0, v[152:153]
	v_cvt_pk_bf16_f32 v94, v94, v95
	v_cvt_pk_bf16_f32 v95, v96, v97
	v_cvt_pk_bf16_f32 v96, v90, v91
	v_cvt_pk_bf16_f32 v97, v92, v93
	global_store_dwordx4 v[98:99], v[94:97], off nt
	v_cvt_pk_bf16_f32 v86, v86, v87
	v_cvt_pk_bf16_f32 v87, v88, v89
	v_cvt_pk_bf16_f32 v88, v82, v83
	v_lshlrev_b64 v[82:83], 11, v[150:151]
	v_lshl_add_u64 v[82:83], s[94:95], 0, v[82:83]
	v_cvt_pk_bf16_f32 v89, v84, v85
	global_store_dwordx4 v[98:99], v[86:89], off offset:256 nt
	v_lshl_add_u64 v[82:83], v[82:83], 0, v[152:153]
	v_cvt_pk_bf16_f32 v78, v78, v79
	v_cvt_pk_bf16_f32 v79, v80, v81
	v_cvt_pk_bf16_f32 v80, v74, v75
	v_cvt_pk_bf16_f32 v81, v76, v77
	global_store_dwordx4 v[82:83], v[78:81], off nt
	v_cvt_pk_bf16_f32 v70, v70, v71
	v_cvt_pk_bf16_f32 v71, v72, v73
	v_cvt_pk_bf16_f32 v72, v66, v67
	v_cvt_pk_bf16_f32 v73, v68, v69
	global_store_dwordx4 v[82:83], v[70:73], off offset:256 nt
	s_mov_b32 s13, 0x40000
	s_mov_b64 s[38:39], 0x40000
	v_cvt_pk_bf16_f32 v62, v62, v63
	v_cvt_pk_bf16_f32 v63, v64, v65
	v_cvt_pk_bf16_f32 v64, v58, v59
	v_add_co_u32_e32 v58, vcc, s13, v144
	v_lshl_add_u64 v[66:67], v[144:145], 0, s[38:39]
	s_nop 0
	v_addc_co_u32_e32 v59, vcc, 0, v145, vcc
	v_cvt_pk_bf16_f32 v65, v60, v61
	global_store_dwordx4 v[58:59], v[62:65], off nt
	v_cvt_pk_bf16_f32 v54, v54, v55
	v_cvt_pk_bf16_f32 v55, v56, v57
	v_cvt_pk_bf16_f32 v56, v50, v51
	v_cvt_pk_bf16_f32 v57, v52, v53
	global_store_dwordx4 v[66:67], v[54:57], off offset:256 nt
	s_mov_b32 s13, 0x48000
	s_mov_b64 s[38:39], 0x48000
	v_cvt_pk_bf16_f32 v46, v46, v47
	v_cvt_pk_bf16_f32 v47, v48, v49
	v_cvt_pk_bf16_f32 v48, v42, v43
	v_add_co_u32_e32 v42, vcc, s13, v144
	v_lshl_add_u64 v[50:51], v[144:145], 0, s[38:39]
	s_nop 0
	v_addc_co_u32_e32 v43, vcc, 0, v145, vcc
	v_cvt_pk_bf16_f32 v49, v44, v45
	global_store_dwordx4 v[42:43], v[46:49], off nt
	v_cvt_pk_bf16_f32 v38, v38, v39
	v_cvt_pk_bf16_f32 v39, v40, v41
	v_cvt_pk_bf16_f32 v40, v34, v35
	v_cvt_pk_bf16_f32 v41, v36, v37
	global_store_dwordx4 v[50:51], v[38:41], off offset:256 nt
	s_mov_b32 s13, 0x50000
	s_mov_b64 s[38:39], 0x50000
	v_cvt_pk_bf16_f32 v30, v30, v31
	v_cvt_pk_bf16_f32 v31, v32, v33
	v_cvt_pk_bf16_f32 v32, v26, v27
	v_add_co_u32_e32 v26, vcc, s13, v144
	v_lshl_add_u64 v[34:35], v[144:145], 0, s[38:39]
	s_nop 0
	v_addc_co_u32_e32 v27, vcc, 0, v145, vcc
	v_cvt_pk_bf16_f32 v33, v28, v29
	global_store_dwordx4 v[26:27], v[30:33], off nt
	v_cvt_pk_bf16_f32 v22, v22, v23
	v_cvt_pk_bf16_f32 v23, v24, v25
	v_cvt_pk_bf16_f32 v24, v18, v19
	v_cvt_pk_bf16_f32 v25, v20, v21
	global_store_dwordx4 v[34:35], v[22:25], off offset:256 nt
	s_mov_b32 s13, 0x58000
	s_mov_b64 s[38:39], 0x58000
	v_cvt_pk_bf16_f32 v14, v14, v15
	v_cvt_pk_bf16_f32 v15, v16, v17
	v_cvt_pk_bf16_f32 v16, v10, v11
	v_add_co_u32_e32 v10, vcc, s13, v144
	v_lshl_add_u64 v[18:19], v[144:145], 0, s[38:39]
	s_nop 0
	v_addc_co_u32_e32 v11, vcc, 0, v145, vcc
	v_cvt_pk_bf16_f32 v17, v12, v13
	global_store_dwordx4 v[10:11], v[14:17], off nt
	v_cvt_pk_bf16_f32 v6, v6, v7
	v_cvt_pk_bf16_f32 v7, v8, v9
	v_cvt_pk_bf16_f32 v8, v2, v3
	v_cvt_pk_bf16_f32 v9, v4, v5
	global_store_dwordx4 v[18:19], v[6:9], off offset:256 nt
	s_andn2_b64 vcc, exec, s[40:41]
	s_mov_b64 s[40:41], -1
	s_cbranch_vccnz .LBB7_1265
	s_andn2_b64 vcc, exec, s[0:1]
	s_cbranch_vccnz .LBB7_1264
	s_barrier
	s_branch .LBB7_1264
